# on top of saddr DMA: removed the redundant post-barrier s_waitcnt lgkmcnt(0) ahead of every MFMA block in all GEMM phases
# speedup vs baseline: 1.0026x; 1.0026x over previous
;     __host__ __device__ bool next(int i, Unit& u) const { if (!StaticOrder::next(i >> 1, u)) return false; u.seg = i & 1; return true; }
;     ...
;         const bool has_next = S.next(ui + 1, nxt);
;         const char* nA = has_next ? PG8_APTR(nxt) : cA; const char* nB = has_next ? PG8_BPTR(nxt) : cB;
;         const char* pfc = PG8_PFPTR(cA, cB); const char* pfn = PG8_PFPTR(nA, nB);
;         PG8_KITER(0);
.LBB0_248:
	s_ashr_i32 s47, s46, 31
	ds_read_b128 v[2:5], v146
	ds_read_b128 v[6:9], v146 offset:1024
	ds_read_b128 v[10:13], v146 offset:2048
	ds_read_b128 v[14:17], v146 offset:3072
	ds_read_b128 v[18:21], v147
	ds_read_b128 v[22:25], v147 offset:1024
	ds_read_b128 v[26:29], v147 offset:2048
	ds_read_b128 v[30:33], v147 offset:3072
	s_lshl_b64 s[14:15], s[46:47], 21
	s_add_u32 s60, s36, s14
	s_addc_u32 s61, s37, s15
	s_and_b64 s[14:15], s[0:1], exec
	s_cselect_b32 s47, s61, s71
	s_cselect_b32 s93, s60, s70
	s_and_b32 s4, s91, 0x7fffffff
	s_lshl_b64 s[14:15], s[4:5], 21
	s_add_u32 s62, s96, s14
	s_addc_u32 s63, s97, s15
	s_and_b64 s[14:15], s[0:1], exec
	s_cselect_b32 s4, s63, s67
	s_cselect_b32 s94, s62, s66
	s_add_u32 s14, s70, 0x100080
	s_addc_u32 s15, s71, 0
	s_mov_b32 m0, s78
	v_lshl_add_u64 v[66:67], s[14:15], 0, v[136:137]
	ds_read_b128 v[34:37], v148
	ds_read_b128 v[38:41], v148 offset:1024
	ds_read_b128 v[42:45], v148 offset:2048
	ds_read_b128 v[46:49], v148 offset:3072
	ds_read_b128 v[50:53], v148 offset:4096
	ds_read_b128 v[54:57], v148 offset:5120
	ds_read_b128 v[58:61], v148 offset:6144
	ds_read_b128 v[62:65], v148 offset:7168
	global_load_lds_dwordx4 v[66:67], off
	v_lshl_add_u64 v[66:67], s[14:15], 0, v[132:133]
	s_mov_b32 m0, s79
	s_nop 0
	global_load_lds_dwordx4 v[66:67], off
	s_waitcnt vmcnt(8)
	s_waitcnt lgkmcnt(0)
	s_barrier
	s_setprio 1
	v_mfma_f32_16x16x32_bf16 v[90:93], v[2:5], v[58:61], 0
	v_mfma_f32_16x16x32_bf16 v[66:69], v[2:5], v[34:37], 0
	v_mfma_f32_16x16x32_bf16 v[70:73], v[10:13], v[34:37], 0
	v_mfma_f32_16x16x32_bf16 v[74:77], v[2:5], v[42:45], 0
	v_mfma_f32_16x16x32_bf16 v[78:81], v[10:13], v[42:45], 0
	v_mfma_f32_16x16x32_bf16 v[82:85], v[2:5], v[50:53], 0
	v_mfma_f32_16x16x32_bf16 v[86:89], v[10:13], v[50:53], 0
	v_mfma_f32_16x16x32_bf16 v[94:97], v[6:9], v[62:65], v[90:93]
	v_mfma_f32_16x16x32_bf16 v[90:93], v[10:13], v[58:61], 0
	v_mfma_f32_16x16x32_bf16 v[66:69], v[6:9], v[38:41], v[66:69]
	v_mfma_f32_16x16x32_bf16 v[70:73], v[14:17], v[38:41], v[70:73]
	v_mfma_f32_16x16x32_bf16 v[74:77], v[6:9], v[46:49], v[74:77]
	v_mfma_f32_16x16x32_bf16 v[78:81], v[14:17], v[46:49], v[78:81]
	v_mfma_f32_16x16x32_bf16 v[82:85], v[6:9], v[54:57], v[82:85]
	v_mfma_f32_16x16x32_bf16 v[86:89], v[14:17], v[54:57], v[86:89]
	v_mfma_f32_16x16x32_bf16 v[102:105], v[14:17], v[62:65], v[90:93]
	s_setprio 0
	s_setprio 1
	v_mfma_f32_16x16x32_bf16 v[90:93], v[18:21], v[34:37], 0
	v_mfma_f32_16x16x32_bf16 v[34:37], v[26:29], v[34:37], 0
	v_mfma_f32_16x16x32_bf16 v[110:113], v[22:25], v[38:41], v[90:93]
	v_mfma_f32_16x16x32_bf16 v[34:37], v[30:33], v[38:41], v[34:37]
	v_mfma_f32_16x16x32_bf16 v[38:41], v[18:21], v[42:45], 0
	v_mfma_f32_16x16x32_bf16 v[42:45], v[26:29], v[42:45], 0
	v_mfma_f32_16x16x32_bf16 v[38:41], v[22:25], v[46:49], v[38:41]
	v_mfma_f32_16x16x32_bf16 v[42:45], v[30:33], v[46:49], v[42:45]
	v_mfma_f32_16x16x32_bf16 v[46:49], v[18:21], v[50:53], 0
	v_mfma_f32_16x16x32_bf16 v[50:53], v[26:29], v[50:53], 0
	v_mfma_f32_16x16x32_bf16 v[46:49], v[22:25], v[54:57], v[46:49]
	v_mfma_f32_16x16x32_bf16 v[50:53], v[30:33], v[54:57], v[50:53]
	v_mfma_f32_16x16x32_bf16 v[54:57], v[18:21], v[58:61], 0
	v_mfma_f32_16x16x32_bf16 v[58:61], v[26:29], v[58:61], 0
	v_mfma_f32_16x16x32_bf16 v[54:57], v[22:25], v[62:65], v[54:57]
	v_mfma_f32_16x16x32_bf16 v[62:65], v[30:33], v[62:65], v[58:61]
	s_setprio 0
	s_barrier
	v_lshl_add_u64 v[248:249], s[66:67], 0, v[134:135]
	s_mov_b32 m0, s81
	v_lshl_add_u64 v[152:153], v[248:249], 0, s[18:19]
	v_lshl_add_u64 v[250:251], s[66:67], 0, v[130:131]
	s_add_u32 s14, s66, 0x100100
	ds_read_b128 v[58:61], v148 offset:16384
	ds_read_b128 v[90:93], v148 offset:17408
	ds_read_b128 v[98:101], v148 offset:18432
	ds_read_b128 v[106:109], v148 offset:19456
	ds_read_b128 v[114:117], v148 offset:20480
	ds_read_b128 v[118:121], v148 offset:21504
	ds_read_b128 v[122:125], v148 offset:22528
	ds_read_b128 v[126:129], v148 offset:23552
	global_load_lds_dwordx4 v[152:153], off
	v_lshl_add_u64 v[152:153], v[250:251], 0, s[18:19]
	s_mov_b32 m0, s82
	s_addc_u32 s15, s67, 0
	global_load_lds_dwordx4 v[152:153], off
	v_lshl_add_u64 v[152:153], s[14:15], 0, v[134:135]
	s_mov_b32 m0, s83
	v_lshl_add_u64 v[252:253], s[70:71], 0, v[136:137]
	global_load_lds_dwordx4 v[152:153], off
	v_lshl_add_u64 v[152:153], s[14:15], 0, v[130:131]
	s_mov_b32 m0, s86
	v_lshl_add_u64 v[142:143], s[70:71], 0, v[132:133]
	global_load_lds_dwordx4 v[152:153], off
	v_lshl_add_u64 v[152:153], v[252:253], 0, s[18:19]
	s_mov_b32 m0, s29
	s_nop 0
	global_load_lds_dwordx4 v[152:153], off
	v_lshl_add_u64 v[152:153], v[142:143], 0, s[18:19]
	s_mov_b32 m0, s33
	s_nop 0
	global_load_lds_dwordx4 v[152:153], off
	s_waitcnt vmcnt(8)
	s_waitcnt lgkmcnt(0)
	s_barrier
	s_setprio 1
	v_mfma_f32_16x16x32_bf16 v[152:155], v[2:5], v[58:61], 0
	v_mfma_f32_16x16x32_bf16 v[160:163], v[2:5], v[98:101], 0
	v_mfma_f32_16x16x32_bf16 v[168:171], v[2:5], v[114:117], 0
	v_mfma_f32_16x16x32_bf16 v[2:5], v[2:5], v[122:125], 0
	v_mfma_f32_16x16x32_bf16 v[152:155], v[6:9], v[90:93], v[152:155]
	v_mfma_f32_16x16x32_bf16 v[160:163], v[6:9], v[106:109], v[160:163]
	v_mfma_f32_16x16x32_bf16 v[168:171], v[6:9], v[118:121], v[168:171]
	v_mfma_f32_16x16x32_bf16 v[2:5], v[6:9], v[126:129], v[2:5]
	v_mfma_f32_16x16x32_bf16 v[6:9], v[10:13], v[122:125], 0
	v_mfma_f32_16x16x32_bf16 v[156:159], v[10:13], v[58:61], 0
	v_mfma_f32_16x16x32_bf16 v[164:167], v[10:13], v[98:101], 0
	v_mfma_f32_16x16x32_bf16 v[172:175], v[10:13], v[114:117], 0
	v_mfma_f32_16x16x32_bf16 v[6:9], v[14:17], v[126:129], v[6:9]
	v_mfma_f32_16x16x32_bf16 v[156:159], v[14:17], v[90:93], v[156:159]
	v_mfma_f32_16x16x32_bf16 v[164:167], v[14:17], v[106:109], v[164:167]
	v_mfma_f32_16x16x32_bf16 v[172:175], v[14:17], v[118:121], v[172:175]
	s_setprio 0
	s_setprio 1
	v_mfma_f32_16x16x32_bf16 v[10:13], v[18:21], v[58:61], 0
	v_mfma_f32_16x16x32_bf16 v[14:17], v[22:25], v[90:93], v[10:13]
	v_mfma_f32_16x16x32_bf16 v[10:13], v[26:29], v[58:61], 0
	v_mfma_f32_16x16x32_bf16 v[176:179], v[30:33], v[90:93], v[10:13]
	v_mfma_f32_16x16x32_bf16 v[10:13], v[18:21], v[98:101], 0
	v_mfma_f32_16x16x32_bf16 v[180:183], v[22:25], v[106:109], v[10:13]
	v_mfma_f32_16x16x32_bf16 v[10:13], v[26:29], v[98:101], 0
	v_mfma_f32_16x16x32_bf16 v[184:187], v[30:33], v[106:109], v[10:13]
	v_mfma_f32_16x16x32_bf16 v[10:13], v[18:21], v[114:117], 0
	v_mfma_f32_16x16x32_bf16 v[188:191], v[22:25], v[118:121], v[10:13]
	v_mfma_f32_16x16x32_bf16 v[10:13], v[26:29], v[114:117], 0
	v_mfma_f32_16x16x32_bf16 v[192:195], v[30:33], v[118:121], v[10:13]
	v_mfma_f32_16x16x32_bf16 v[10:13], v[18:21], v[122:125], 0
	v_mfma_f32_16x16x32_bf16 v[196:199], v[22:25], v[126:129], v[10:13]
	v_mfma_f32_16x16x32_bf16 v[10:13], v[26:29], v[122:125], 0
	v_mfma_f32_16x16x32_bf16 v[200:203], v[30:33], v[126:129], v[10:13]
	s_setprio 0
	s_barrier
	s_nop 4
	ds_read_b128 v[10:13], v149
	ds_read_b128 v[22:25], v149 offset:1024
	ds_read_b128 v[30:33], v149 offset:2048
	ds_read_b128 v[204:207], v149 offset:3072
	ds_read_b128 v[208:211], v150
	ds_read_b128 v[212:215], v150 offset:1024
	ds_read_b128 v[216:219], v150 offset:2048
	ds_read_b128 v[220:223], v150 offset:3072
	s_add_u32 s14, s70, 0x100100
	s_addc_u32 s15, s71, 0
	s_mov_b32 m0, s58
	v_lshl_add_u64 v[58:59], s[14:15], 0, v[136:137]
	ds_read_b128 v[18:21], v148 offset:32768
	ds_read_b128 v[26:29], v148 offset:33792
	ds_read_b128 v[224:227], v148 offset:34816
	ds_read_b128 v[228:231], v148 offset:35840
	ds_read_b128 v[232:235], v148 offset:36864
	ds_read_b128 v[236:239], v148 offset:37888
	ds_read_b128 v[240:243], v148 offset:38912
	ds_read_b128 v[244:247], v148 offset:39936
	global_load_lds_dwordx4 v[58:59], off
	v_lshl_add_u64 v[58:59], s[14:15], 0, v[132:133]
	s_mov_b32 m0, s59
	s_nop 0
	global_load_lds_dwordx4 v[58:59], off
	s_waitcnt vmcnt(8)
	s_waitcnt lgkmcnt(0)
	s_barrier
	s_setprio 1
	v_mfma_f32_16x16x32_bf16 v[58:61], v[10:13], v[18:21], v[66:69]
	v_mfma_f32_16x16x32_bf16 v[122:125], v[22:25], v[26:29], v[58:61]
	v_mfma_f32_16x16x32_bf16 v[58:61], v[30:33], v[18:21], v[70:73]
	v_mfma_f32_16x16x32_bf16 v[114:117], v[204:207], v[26:29], v[58:61]
	v_mfma_f32_16x16x32_bf16 v[58:61], v[10:13], v[224:227], v[74:77]
	v_mfma_f32_16x16x32_bf16 v[106:109], v[22:25], v[228:231], v[58:61]
	v_mfma_f32_16x16x32_bf16 v[58:61], v[30:33], v[224:227], v[78:81]
	v_mfma_f32_16x16x32_bf16 v[98:101], v[204:207], v[228:231], v[58:61]
	v_mfma_f32_16x16x32_bf16 v[58:61], v[10:13], v[232:235], v[82:85]
	v_mfma_f32_16x16x32_bf16 v[90:93], v[22:25], v[236:239], v[58:61]
	v_mfma_f32_16x16x32_bf16 v[58:61], v[30:33], v[232:235], v[86:89]
	v_mfma_f32_16x16x32_bf16 v[82:85], v[204:207], v[236:239], v[58:61]
	v_mfma_f32_16x16x32_bf16 v[58:61], v[10:13], v[240:243], v[94:97]
	v_mfma_f32_16x16x32_bf16 v[74:77], v[22:25], v[244:247], v[58:61]
	v_mfma_f32_16x16x32_bf16 v[58:61], v[30:33], v[240:243], v[102:105]
	v_mfma_f32_16x16x32_bf16 v[58:61], v[204:207], v[244:247], v[58:61]
	s_setprio 0
	s_setprio 1
	v_mfma_f32_16x16x32_bf16 v[66:69], v[208:211], v[18:21], v[110:113]
	v_mfma_f32_16x16x32_bf16 v[18:21], v[216:219], v[18:21], v[34:37]
	v_mfma_f32_16x16x32_bf16 v[118:121], v[220:223], v[26:29], v[18:21]
	v_mfma_f32_16x16x32_bf16 v[18:21], v[208:211], v[224:227], v[38:41]
	v_mfma_f32_16x16x32_bf16 v[110:113], v[212:215], v[228:231], v[18:21]
	v_mfma_f32_16x16x32_bf16 v[18:21], v[216:219], v[224:227], v[42:45]
	v_mfma_f32_16x16x32_bf16 v[102:105], v[220:223], v[228:231], v[18:21]
	v_mfma_f32_16x16x32_bf16 v[18:21], v[208:211], v[232:235], v[46:49]
	v_mfma_f32_16x16x32_bf16 v[94:97], v[212:215], v[236:239], v[18:21]
	v_mfma_f32_16x16x32_bf16 v[18:21], v[216:219], v[232:235], v[50:53]
	v_mfma_f32_16x16x32_bf16 v[86:89], v[220:223], v[236:239], v[18:21]
	v_mfma_f32_16x16x32_bf16 v[18:21], v[208:211], v[240:243], v[54:57]
	v_mfma_f32_16x16x32_bf16 v[78:81], v[212:215], v[244:247], v[18:21]
	v_mfma_f32_16x16x32_bf16 v[18:21], v[216:219], v[240:243], v[62:65]
	v_mfma_f32_16x16x32_bf16 v[126:129], v[212:215], v[26:29], v[66:69]
	v_mfma_f32_16x16x32_bf16 v[66:69], v[220:223], v[244:247], v[18:21]
	s_setprio 0
	s_barrier
;     ...
;         for (int t = 2; t < nt; t += 2) PG8_KITER(t);
	s_mov_b32 m0, s87
	s_nop 2
	v_lshl_add_u64 v[18:19], v[248:249], 0, s[30:31]
	s_add_u32 s14, s66, 0x100180
	ds_read_b128 v[38:41], v148 offset:49152
	ds_read_b128 v[46:49], v148 offset:50176
	ds_read_b128 v[224:227], v148 offset:51200
	ds_read_b128 v[228:231], v148 offset:52224
	ds_read_b128 v[232:235], v148 offset:53248
	ds_read_b128 v[236:239], v148 offset:54272
	ds_read_b128 v[240:243], v148 offset:55296
	ds_read_b128 v[244:247], v148 offset:56320
	global_load_lds_dwordx4 v[18:19], off
	v_lshl_add_u64 v[18:19], v[250:251], 0, s[30:31]
	s_mov_b32 m0, s88
	s_addc_u32 s15, s67, 0
	global_load_lds_dwordx4 v[18:19], off
	v_lshl_add_u64 v[18:19], s[14:15], 0, v[134:135]
	s_mov_b32 m0, s89
	s_add_i32 s56, s89, 0x2000
	global_load_lds_dwordx4 v[18:19], off
	v_lshl_add_u64 v[18:19], s[14:15], 0, v[130:131]
	s_mov_b32 m0, s56
	s_nop 0
	global_load_lds_dwordx4 v[18:19], off
	v_lshl_add_u64 v[18:19], v[252:253], 0, s[30:31]
	s_mov_b32 m0, s65
	s_nop 0
	global_load_lds_dwordx4 v[18:19], off
	v_lshl_add_u64 v[18:19], v[142:143], 0, s[30:31]
	s_mov_b32 m0, s76
	s_nop 0
	global_load_lds_dwordx4 v[18:19], off
	s_waitcnt vmcnt(8)
	s_waitcnt lgkmcnt(0)
	s_barrier
	s_setprio 1
	v_mfma_f32_16x16x32_bf16 v[18:21], v[10:13], v[38:41], v[152:155]
	v_mfma_f32_16x16x32_bf16 v[62:65], v[22:25], v[46:49], v[18:21]
	v_mfma_f32_16x16x32_bf16 v[18:21], v[30:33], v[38:41], v[156:159]
	v_mfma_f32_16x16x32_bf16 v[50:53], v[204:207], v[46:49], v[18:21]
	v_mfma_f32_16x16x32_bf16 v[18:21], v[10:13], v[224:227], v[160:163]
	v_mfma_f32_16x16x32_bf16 v[42:45], v[22:25], v[228:231], v[18:21]
	v_mfma_f32_16x16x32_bf16 v[18:21], v[30:33], v[224:227], v[164:167]
	v_mfma_f32_16x16x32_bf16 v[34:37], v[204:207], v[228:231], v[18:21]
	v_mfma_f32_16x16x32_bf16 v[18:21], v[10:13], v[232:235], v[168:171]
	v_mfma_f32_16x16x32_bf16 v[2:5], v[10:13], v[240:243], v[2:5]
	v_mfma_f32_16x16x32_bf16 v[26:29], v[22:25], v[236:239], v[18:21]
	v_mfma_f32_16x16x32_bf16 v[18:21], v[30:33], v[232:235], v[172:175]
	v_mfma_f32_16x16x32_bf16 v[10:13], v[22:25], v[244:247], v[2:5]
	v_mfma_f32_16x16x32_bf16 v[2:5], v[30:33], v[240:243], v[6:9]
	v_mfma_f32_16x16x32_bf16 v[18:21], v[204:207], v[236:239], v[18:21]
	v_mfma_f32_16x16x32_bf16 v[2:5], v[204:207], v[244:247], v[2:5]
	s_setprio 0
	s_setprio 1
	v_mfma_f32_16x16x32_bf16 v[6:9], v[208:211], v[38:41], v[14:17]
	v_mfma_f32_16x16x32_bf16 v[70:73], v[212:215], v[46:49], v[6:9]
	v_mfma_f32_16x16x32_bf16 v[6:9], v[216:219], v[38:41], v[176:179]
	v_mfma_f32_16x16x32_bf16 v[54:57], v[220:223], v[46:49], v[6:9]
	v_mfma_f32_16x16x32_bf16 v[6:9], v[208:211], v[224:227], v[180:183]
	v_mfma_f32_16x16x32_bf16 v[46:49], v[212:215], v[228:231], v[6:9]
	v_mfma_f32_16x16x32_bf16 v[6:9], v[216:219], v[224:227], v[184:187]
	v_mfma_f32_16x16x32_bf16 v[38:41], v[220:223], v[228:231], v[6:9]
	v_mfma_f32_16x16x32_bf16 v[6:9], v[208:211], v[232:235], v[188:191]
	v_mfma_f32_16x16x32_bf16 v[30:33], v[212:215], v[236:239], v[6:9]
	v_mfma_f32_16x16x32_bf16 v[6:9], v[216:219], v[232:235], v[192:195]
	v_mfma_f32_16x16x32_bf16 v[22:25], v[220:223], v[236:239], v[6:9]
	v_mfma_f32_16x16x32_bf16 v[6:9], v[208:211], v[240:243], v[196:199]
	v_mfma_f32_16x16x32_bf16 v[14:17], v[212:215], v[244:247], v[6:9]
	v_mfma_f32_16x16x32_bf16 v[6:9], v[216:219], v[240:243], v[200:203]
	v_mfma_f32_16x16x32_bf16 v[6:9], v[220:223], v[244:247], v[6:9]
	s_setprio 0
	s_barrier
	s_add_u32 s70, s70, 0x100180
	s_addc_u32 s71, s71, 0
	s_add_u32 s57, s66, 0x200
	s_addc_u32 s14, s67, 0
	s_mov_b32 s15, 0
.LBB0_249:
	ds_read_b128 v[152:155], v146
	ds_read_b128 v[156:159], v146 offset:1024
	ds_read_b128 v[160:163], v146 offset:2048
	ds_read_b128 v[164:167], v146 offset:3072
	ds_read_b128 v[168:171], v147
	ds_read_b128 v[172:175], v147 offset:1024
	ds_read_b128 v[176:179], v147 offset:2048
	ds_read_b128 v[180:183], v147 offset:3072
	s_add_u32 s16, s70, 0xfff00080
	s_addc_u32 s17, s71, -1
	s_cmp_eq_u32 s15, 60
	s_cselect_b32 s75, s47, s17
	s_cselect_b32 s74, s93, s16
	s_cselect_b32 s67, s4, s14
	s_cselect_b32 s66, s94, s57
	s_mov_b32 m0, s78
	ds_read_b128 v[184:187], v148
	ds_read_b128 v[188:191], v148 offset:1024
	ds_read_b128 v[192:195], v148 offset:2048
	ds_read_b128 v[196:199], v148 offset:3072
	ds_read_b128 v[200:203], v148 offset:4096
	ds_read_b128 v[204:207], v148 offset:5120
	ds_read_b128 v[208:211], v148 offset:6144
	ds_read_b128 v[212:215], v148 offset:7168
	global_load_lds_dwordx4 v138, s[70:71]
	s_mov_b32 m0, s79
	s_nop 0
	global_load_lds_dwordx4 v140, s[70:71]
	s_waitcnt vmcnt(8)
	s_waitcnt lgkmcnt(0)
	s_barrier
	s_setprio 1
	v_mfma_f32_16x16x32_bf16 v[122:125], v[152:155], v[184:187], v[122:125]
	v_mfma_f32_16x16x32_bf16 v[114:117], v[160:163], v[184:187], v[114:117]
	v_mfma_f32_16x16x32_bf16 v[106:109], v[152:155], v[192:195], v[106:109]
	v_mfma_f32_16x16x32_bf16 v[98:101], v[160:163], v[192:195], v[98:101]
	v_mfma_f32_16x16x32_bf16 v[90:93], v[152:155], v[200:203], v[90:93]
	v_mfma_f32_16x16x32_bf16 v[82:85], v[160:163], v[200:203], v[82:85]
	v_mfma_f32_16x16x32_bf16 v[74:77], v[152:155], v[208:211], v[74:77]
	v_mfma_f32_16x16x32_bf16 v[58:61], v[160:163], v[208:211], v[58:61]
	v_mfma_f32_16x16x32_bf16 v[122:125], v[156:159], v[188:191], v[122:125]
	v_mfma_f32_16x16x32_bf16 v[114:117], v[164:167], v[188:191], v[114:117]
	v_mfma_f32_16x16x32_bf16 v[106:109], v[156:159], v[196:199], v[106:109]
	v_mfma_f32_16x16x32_bf16 v[98:101], v[164:167], v[196:199], v[98:101]
	v_mfma_f32_16x16x32_bf16 v[90:93], v[156:159], v[204:207], v[90:93]
	v_mfma_f32_16x16x32_bf16 v[82:85], v[164:167], v[204:207], v[82:85]
	v_mfma_f32_16x16x32_bf16 v[74:77], v[156:159], v[212:215], v[74:77]
	v_mfma_f32_16x16x32_bf16 v[58:61], v[164:167], v[212:215], v[58:61]
	s_setprio 0
	s_setprio 1
	v_mfma_f32_16x16x32_bf16 v[126:129], v[168:171], v[184:187], v[126:129]
	v_mfma_f32_16x16x32_bf16 v[118:121], v[176:179], v[184:187], v[118:121]
	v_mfma_f32_16x16x32_bf16 v[110:113], v[168:171], v[192:195], v[110:113]
	v_mfma_f32_16x16x32_bf16 v[102:105], v[176:179], v[192:195], v[102:105]
	v_mfma_f32_16x16x32_bf16 v[94:97], v[168:171], v[200:203], v[94:97]
	v_mfma_f32_16x16x32_bf16 v[86:89], v[176:179], v[200:203], v[86:89]
	v_mfma_f32_16x16x32_bf16 v[78:81], v[168:171], v[208:211], v[78:81]
	v_mfma_f32_16x16x32_bf16 v[66:69], v[176:179], v[208:211], v[66:69]
	v_mfma_f32_16x16x32_bf16 v[126:129], v[172:175], v[188:191], v[126:129]
	v_mfma_f32_16x16x32_bf16 v[118:121], v[180:183], v[188:191], v[118:121]
	v_mfma_f32_16x16x32_bf16 v[110:113], v[172:175], v[196:199], v[110:113]
	v_mfma_f32_16x16x32_bf16 v[102:105], v[180:183], v[196:199], v[102:105]
	v_mfma_f32_16x16x32_bf16 v[94:97], v[172:175], v[204:207], v[94:97]
	v_mfma_f32_16x16x32_bf16 v[86:89], v[180:183], v[204:207], v[86:89]
	v_mfma_f32_16x16x32_bf16 v[78:81], v[172:175], v[212:215], v[78:81]
	v_mfma_f32_16x16x32_bf16 v[66:69], v[180:183], v[212:215], v[66:69]
	s_setprio 0
	s_barrier
	s_mov_b32 m0, s81
	s_mov_b64 s[98:99], s[66:67]
	s_add_u32 s16, s66, 0x100000
	ds_read_b128 v[184:187], v148 offset:16384
	ds_read_b128 v[188:191], v148 offset:17408
	ds_read_b128 v[192:195], v148 offset:18432
	ds_read_b128 v[196:199], v148 offset:19456
	ds_read_b128 v[200:203], v148 offset:20480
	ds_read_b128 v[204:207], v148 offset:21504
	ds_read_b128 v[208:211], v148 offset:22528
	ds_read_b128 v[212:215], v148 offset:23552
	global_load_lds_dwordx4 v134, s[66:67]
	s_mov_b32 m0, s82
	s_addc_u32 s17, s67, 0
	global_load_lds_dwordx4 v130, s[66:67]
	s_mov_b32 m0, s83
	s_mov_b64 s[100:101], s[74:75]
	global_load_lds_dwordx4 v134, s[16:17]
	s_mov_b32 m0, s86
	s_nop 0
	global_load_lds_dwordx4 v130, s[16:17]
	s_mov_b32 m0, s29
	s_nop 0
	global_load_lds_dwordx4 v136, s[74:75]
	s_mov_b32 m0, s33
	s_nop 0
	global_load_lds_dwordx4 v132, s[74:75]
	s_waitcnt vmcnt(8)
	s_waitcnt lgkmcnt(0)
	s_barrier
	s_setprio 1
	v_mfma_f32_16x16x32_bf16 v[62:65], v[152:155], v[184:187], v[62:65]
	v_mfma_f32_16x16x32_bf16 v[50:53], v[160:163], v[184:187], v[50:53]
	v_mfma_f32_16x16x32_bf16 v[42:45], v[152:155], v[192:195], v[42:45]
	v_mfma_f32_16x16x32_bf16 v[34:37], v[160:163], v[192:195], v[34:37]
	v_mfma_f32_16x16x32_bf16 v[26:29], v[152:155], v[200:203], v[26:29]
	v_mfma_f32_16x16x32_bf16 v[18:21], v[160:163], v[200:203], v[18:21]
	v_mfma_f32_16x16x32_bf16 v[10:13], v[152:155], v[208:211], v[10:13]
	v_mfma_f32_16x16x32_bf16 v[2:5], v[160:163], v[208:211], v[2:5]
	v_mfma_f32_16x16x32_bf16 v[62:65], v[156:159], v[188:191], v[62:65]
	v_mfma_f32_16x16x32_bf16 v[50:53], v[164:167], v[188:191], v[50:53]
	v_mfma_f32_16x16x32_bf16 v[42:45], v[156:159], v[196:199], v[42:45]
	v_mfma_f32_16x16x32_bf16 v[34:37], v[164:167], v[196:199], v[34:37]
	v_mfma_f32_16x16x32_bf16 v[26:29], v[156:159], v[204:207], v[26:29]
	v_mfma_f32_16x16x32_bf16 v[18:21], v[164:167], v[204:207], v[18:21]
	v_mfma_f32_16x16x32_bf16 v[10:13], v[156:159], v[212:215], v[10:13]
	v_mfma_f32_16x16x32_bf16 v[2:5], v[164:167], v[212:215], v[2:5]
	s_setprio 0
	s_setprio 1
	v_mfma_f32_16x16x32_bf16 v[70:73], v[168:171], v[184:187], v[70:73]
	v_mfma_f32_16x16x32_bf16 v[54:57], v[176:179], v[184:187], v[54:57]
	v_mfma_f32_16x16x32_bf16 v[46:49], v[168:171], v[192:195], v[46:49]
	v_mfma_f32_16x16x32_bf16 v[38:41], v[176:179], v[192:195], v[38:41]
	v_mfma_f32_16x16x32_bf16 v[30:33], v[168:171], v[200:203], v[30:33]
	v_mfma_f32_16x16x32_bf16 v[22:25], v[176:179], v[200:203], v[22:25]
	v_mfma_f32_16x16x32_bf16 v[14:17], v[168:171], v[208:211], v[14:17]
	v_mfma_f32_16x16x32_bf16 v[6:9], v[176:179], v[208:211], v[6:9]
	v_mfma_f32_16x16x32_bf16 v[70:73], v[172:175], v[188:191], v[70:73]
	v_mfma_f32_16x16x32_bf16 v[54:57], v[180:183], v[188:191], v[54:57]
	v_mfma_f32_16x16x32_bf16 v[46:49], v[172:175], v[196:199], v[46:49]
	v_mfma_f32_16x16x32_bf16 v[38:41], v[180:183], v[196:199], v[38:41]
	v_mfma_f32_16x16x32_bf16 v[30:33], v[172:175], v[204:207], v[30:33]
	v_mfma_f32_16x16x32_bf16 v[22:25], v[180:183], v[204:207], v[22:25]
	v_mfma_f32_16x16x32_bf16 v[14:17], v[172:175], v[212:215], v[14:17]
	v_mfma_f32_16x16x32_bf16 v[6:9], v[180:183], v[212:215], v[6:9]
	s_setprio 0
	s_barrier
;     ...
;         for (int t = 2; t < nt; t += 2) PG8_KITER(t);
	ds_read_b128 v[152:155], v149
	ds_read_b128 v[156:159], v149 offset:1024
	ds_read_b128 v[160:163], v149 offset:2048
	ds_read_b128 v[164:167], v149 offset:3072
	ds_read_b128 v[168:171], v150
	ds_read_b128 v[172:175], v150 offset:1024
	ds_read_b128 v[176:179], v150 offset:2048
	ds_read_b128 v[180:183], v150 offset:3072
	s_add_u32 s16, s74, 0x100000
	s_addc_u32 s17, s75, 0
	s_mov_b32 m0, s58
	ds_read_b128 v[184:187], v148 offset:32768
	ds_read_b128 v[188:191], v148 offset:33792
	ds_read_b128 v[192:195], v148 offset:34816
	ds_read_b128 v[196:199], v148 offset:35840
	ds_read_b128 v[200:203], v148 offset:36864
	ds_read_b128 v[204:207], v148 offset:37888
	ds_read_b128 v[208:211], v148 offset:38912
	ds_read_b128 v[212:215], v148 offset:39936
	global_load_lds_dwordx4 v136, s[16:17]
	s_mov_b32 m0, s59
	s_nop 0
	global_load_lds_dwordx4 v132, s[16:17]
	s_waitcnt vmcnt(8)
	s_waitcnt lgkmcnt(0)
	s_barrier
	s_setprio 1
	v_mfma_f32_16x16x32_bf16 v[122:125], v[152:155], v[184:187], v[122:125]
	v_mfma_f32_16x16x32_bf16 v[114:117], v[160:163], v[184:187], v[114:117]
	v_mfma_f32_16x16x32_bf16 v[106:109], v[152:155], v[192:195], v[106:109]
	v_mfma_f32_16x16x32_bf16 v[98:101], v[160:163], v[192:195], v[98:101]
	v_mfma_f32_16x16x32_bf16 v[90:93], v[152:155], v[200:203], v[90:93]
	v_mfma_f32_16x16x32_bf16 v[82:85], v[160:163], v[200:203], v[82:85]
	v_mfma_f32_16x16x32_bf16 v[74:77], v[152:155], v[208:211], v[74:77]
	v_mfma_f32_16x16x32_bf16 v[58:61], v[160:163], v[208:211], v[58:61]
	v_mfma_f32_16x16x32_bf16 v[122:125], v[156:159], v[188:191], v[122:125]
	v_mfma_f32_16x16x32_bf16 v[114:117], v[164:167], v[188:191], v[114:117]
	v_mfma_f32_16x16x32_bf16 v[106:109], v[156:159], v[196:199], v[106:109]
	v_mfma_f32_16x16x32_bf16 v[98:101], v[164:167], v[196:199], v[98:101]
	v_mfma_f32_16x16x32_bf16 v[90:93], v[156:159], v[204:207], v[90:93]
	v_mfma_f32_16x16x32_bf16 v[82:85], v[164:167], v[204:207], v[82:85]
	v_mfma_f32_16x16x32_bf16 v[74:77], v[156:159], v[212:215], v[74:77]
	v_mfma_f32_16x16x32_bf16 v[58:61], v[164:167], v[212:215], v[58:61]
	s_setprio 0
	s_setprio 1
	v_mfma_f32_16x16x32_bf16 v[126:129], v[168:171], v[184:187], v[126:129]
	v_mfma_f32_16x16x32_bf16 v[118:121], v[176:179], v[184:187], v[118:121]
	v_mfma_f32_16x16x32_bf16 v[110:113], v[168:171], v[192:195], v[110:113]
	v_mfma_f32_16x16x32_bf16 v[102:105], v[176:179], v[192:195], v[102:105]
	v_mfma_f32_16x16x32_bf16 v[94:97], v[168:171], v[200:203], v[94:97]
	v_mfma_f32_16x16x32_bf16 v[86:89], v[176:179], v[200:203], v[86:89]
	v_mfma_f32_16x16x32_bf16 v[78:81], v[168:171], v[208:211], v[78:81]
	v_mfma_f32_16x16x32_bf16 v[66:69], v[176:179], v[208:211], v[66:69]
	v_mfma_f32_16x16x32_bf16 v[126:129], v[172:175], v[188:191], v[126:129]
	v_mfma_f32_16x16x32_bf16 v[118:121], v[180:183], v[188:191], v[118:121]
	v_mfma_f32_16x16x32_bf16 v[110:113], v[172:175], v[196:199], v[110:113]
	v_mfma_f32_16x16x32_bf16 v[102:105], v[180:183], v[196:199], v[102:105]
	v_mfma_f32_16x16x32_bf16 v[94:97], v[172:175], v[204:207], v[94:97]
	v_mfma_f32_16x16x32_bf16 v[86:89], v[180:183], v[204:207], v[86:89]
	v_mfma_f32_16x16x32_bf16 v[78:81], v[172:175], v[212:215], v[78:81]
	v_mfma_f32_16x16x32_bf16 v[66:69], v[180:183], v[212:215], v[66:69]
	s_setprio 0
	s_barrier
	s_mov_b32 m0, s87
	s_add_u32 s98, s98, 0x80
	s_addc_u32 s99, s99, 0
	s_add_u32 s100, s100, 0x80
	s_addc_u32 s101, s101, 0
	s_add_u32 s16, s66, 0x100080
	ds_read_b128 v[184:187], v148 offset:49152
	ds_read_b128 v[188:191], v148 offset:50176
	ds_read_b128 v[192:195], v148 offset:51200
	ds_read_b128 v[196:199], v148 offset:52224
	ds_read_b128 v[200:203], v148 offset:53248
	ds_read_b128 v[204:207], v148 offset:54272
	ds_read_b128 v[208:211], v148 offset:55296
	ds_read_b128 v[212:215], v148 offset:56320
	global_load_lds_dwordx4 v134, s[98:99]
	s_mov_b32 m0, s88
	s_addc_u32 s17, s67, 0
	global_load_lds_dwordx4 v130, s[98:99]
	s_mov_b32 m0, s89
	s_nop 0
	global_load_lds_dwordx4 v134, s[16:17]
	s_mov_b32 m0, s56
	s_nop 0
	global_load_lds_dwordx4 v130, s[16:17]
	s_mov_b32 m0, s65
	s_nop 0
	global_load_lds_dwordx4 v136, s[100:101]
	s_mov_b32 m0, s76
	s_nop 0
	global_load_lds_dwordx4 v132, s[100:101]
	s_waitcnt vmcnt(8)
	s_waitcnt lgkmcnt(0)
	s_barrier
	s_setprio 1
	v_mfma_f32_16x16x32_bf16 v[62:65], v[152:155], v[184:187], v[62:65]
	v_mfma_f32_16x16x32_bf16 v[50:53], v[160:163], v[184:187], v[50:53]
	v_mfma_f32_16x16x32_bf16 v[42:45], v[152:155], v[192:195], v[42:45]
	v_mfma_f32_16x16x32_bf16 v[34:37], v[160:163], v[192:195], v[34:37]
	v_mfma_f32_16x16x32_bf16 v[26:29], v[152:155], v[200:203], v[26:29]
	v_mfma_f32_16x16x32_bf16 v[18:21], v[160:163], v[200:203], v[18:21]
	v_mfma_f32_16x16x32_bf16 v[10:13], v[152:155], v[208:211], v[10:13]
	v_mfma_f32_16x16x32_bf16 v[2:5], v[160:163], v[208:211], v[2:5]
	v_mfma_f32_16x16x32_bf16 v[62:65], v[156:159], v[188:191], v[62:65]
	v_mfma_f32_16x16x32_bf16 v[50:53], v[164:167], v[188:191], v[50:53]
	v_mfma_f32_16x16x32_bf16 v[42:45], v[156:159], v[196:199], v[42:45]
	v_mfma_f32_16x16x32_bf16 v[34:37], v[164:167], v[196:199], v[34:37]
	v_mfma_f32_16x16x32_bf16 v[26:29], v[156:159], v[204:207], v[26:29]
	v_mfma_f32_16x16x32_bf16 v[18:21], v[164:167], v[204:207], v[18:21]
	v_mfma_f32_16x16x32_bf16 v[10:13], v[156:159], v[212:215], v[10:13]
	v_mfma_f32_16x16x32_bf16 v[2:5], v[164:167], v[212:215], v[2:5]
	s_setprio 0
	s_setprio 1
	v_mfma_f32_16x16x32_bf16 v[70:73], v[168:171], v[184:187], v[70:73]
	v_mfma_f32_16x16x32_bf16 v[54:57], v[176:179], v[184:187], v[54:57]
	v_mfma_f32_16x16x32_bf16 v[46:49], v[168:171], v[192:195], v[46:49]
	v_mfma_f32_16x16x32_bf16 v[38:41], v[176:179], v[192:195], v[38:41]
	v_mfma_f32_16x16x32_bf16 v[30:33], v[168:171], v[200:203], v[30:33]
	v_mfma_f32_16x16x32_bf16 v[22:25], v[176:179], v[200:203], v[22:25]
	v_mfma_f32_16x16x32_bf16 v[14:17], v[168:171], v[208:211], v[14:17]
	v_mfma_f32_16x16x32_bf16 v[6:9], v[176:179], v[208:211], v[6:9]
	v_mfma_f32_16x16x32_bf16 v[70:73], v[172:175], v[188:191], v[70:73]
	v_mfma_f32_16x16x32_bf16 v[54:57], v[180:183], v[188:191], v[54:57]
	v_mfma_f32_16x16x32_bf16 v[46:49], v[172:175], v[196:199], v[46:49]
	v_mfma_f32_16x16x32_bf16 v[38:41], v[180:183], v[196:199], v[38:41]
	v_mfma_f32_16x16x32_bf16 v[30:33], v[172:175], v[204:207], v[30:33]
	v_mfma_f32_16x16x32_bf16 v[22:25], v[180:183], v[204:207], v[22:25]
	v_mfma_f32_16x16x32_bf16 v[14:17], v[172:175], v[212:215], v[14:17]
	v_mfma_f32_16x16x32_bf16 v[6:9], v[180:183], v[212:215], v[6:9]
	s_setprio 0
	s_barrier
	s_add_i32 s15, s15, 2
	s_add_u32 s70, s70, 0x100
	s_addc_u32 s71, s71, 0
	s_add_u32 s57, s57, 0x100
	s_addc_u32 s14, s14, 0
	s_cmp_gt_u32 s15, 61
	s_cbranch_scc0 .LBB0_249
	s_and_b64 vcc, exec, s[12:13]
	s_cbranch_vccz .LBB0_252
	s_barrier

.LBB0_330:
	ds_read_b128 v[2:5], v207
	ds_read_b128 v[6:9], v207 offset:1024
	ds_read_b128 v[10:13], v207 offset:2048
	ds_read_b128 v[14:17], v207 offset:3072
	ds_read_b128 v[18:21], v208
	ds_read_b128 v[22:25], v208 offset:1024
	ds_read_b128 v[26:29], v208 offset:2048
	ds_read_b128 v[30:33], v208 offset:3072
	s_add_u32 s14, s66, 0x2b0080
	s_addc_u32 s15, s67, 0
	s_add_i32 s86, s11, 0xc000
	v_lshl_add_u64 v[66:67], s[14:15], 0, v[178:179]
	s_mov_b32 m0, s86
	s_add_i32 s87, s11, 0xe000
	ds_read_b128 v[34:37], v209
	ds_read_b128 v[38:41], v209 offset:1024
	ds_read_b128 v[42:45], v209 offset:2048
	ds_read_b128 v[46:49], v209 offset:3072
	ds_read_b128 v[50:53], v209 offset:4096
	ds_read_b128 v[54:57], v209 offset:5120
	ds_read_b128 v[58:61], v209 offset:6144
	ds_read_b128 v[62:65], v209 offset:7168
	global_load_lds_dwordx4 v[66:67], off
	v_lshl_add_u64 v[66:67], s[14:15], 0, v[182:183]
	s_mov_b32 m0, s87
	s_nop 0
	global_load_lds_dwordx4 v[66:67], off
	s_waitcnt vmcnt(8)
	s_waitcnt lgkmcnt(0)
	s_barrier
	s_setprio 1
	v_mfma_f32_16x16x32_bf16 v[90:93], v[2:5], v[58:61], 0
	v_mfma_f32_16x16x32_bf16 v[66:69], v[2:5], v[34:37], 0
	v_mfma_f32_16x16x32_bf16 v[70:73], v[10:13], v[34:37], 0
	v_mfma_f32_16x16x32_bf16 v[74:77], v[2:5], v[42:45], 0
	v_mfma_f32_16x16x32_bf16 v[78:81], v[10:13], v[42:45], 0
	v_mfma_f32_16x16x32_bf16 v[82:85], v[2:5], v[50:53], 0
	v_mfma_f32_16x16x32_bf16 v[86:89], v[10:13], v[50:53], 0
	v_mfma_f32_16x16x32_bf16 v[98:101], v[6:9], v[62:65], v[90:93]
	v_mfma_f32_16x16x32_bf16 v[90:93], v[10:13], v[58:61], 0
	v_mfma_f32_16x16x32_bf16 v[66:69], v[6:9], v[38:41], v[66:69]
	v_mfma_f32_16x16x32_bf16 v[70:73], v[14:17], v[38:41], v[70:73]
	v_mfma_f32_16x16x32_bf16 v[74:77], v[6:9], v[46:49], v[74:77]
	v_mfma_f32_16x16x32_bf16 v[78:81], v[14:17], v[46:49], v[78:81]
	v_mfma_f32_16x16x32_bf16 v[82:85], v[6:9], v[54:57], v[82:85]
	v_mfma_f32_16x16x32_bf16 v[86:89], v[14:17], v[54:57], v[86:89]
	v_mfma_f32_16x16x32_bf16 v[102:105], v[14:17], v[62:65], v[90:93]
	s_setprio 0
	s_setprio 1
	v_mfma_f32_16x16x32_bf16 v[90:93], v[18:21], v[34:37], 0
	v_mfma_f32_16x16x32_bf16 v[34:37], v[26:29], v[34:37], 0
	v_mfma_f32_16x16x32_bf16 v[114:117], v[22:25], v[38:41], v[90:93]
	v_mfma_f32_16x16x32_bf16 v[34:37], v[30:33], v[38:41], v[34:37]
	v_mfma_f32_16x16x32_bf16 v[38:41], v[18:21], v[42:45], 0
	v_mfma_f32_16x16x32_bf16 v[42:45], v[26:29], v[42:45], 0
	v_mfma_f32_16x16x32_bf16 v[38:41], v[22:25], v[46:49], v[38:41]
	v_mfma_f32_16x16x32_bf16 v[42:45], v[30:33], v[46:49], v[42:45]
	v_mfma_f32_16x16x32_bf16 v[46:49], v[18:21], v[50:53], 0
	v_mfma_f32_16x16x32_bf16 v[50:53], v[26:29], v[50:53], 0
	v_mfma_f32_16x16x32_bf16 v[46:49], v[22:25], v[54:57], v[46:49]
	v_mfma_f32_16x16x32_bf16 v[50:53], v[30:33], v[54:57], v[50:53]
	v_mfma_f32_16x16x32_bf16 v[54:57], v[18:21], v[58:61], 0
	v_mfma_f32_16x16x32_bf16 v[58:61], v[26:29], v[58:61], 0
	v_mfma_f32_16x16x32_bf16 v[54:57], v[22:25], v[62:65], v[54:57]
	v_mfma_f32_16x16x32_bf16 v[58:61], v[30:33], v[62:65], v[58:61]
	s_setprio 0
	s_barrier
	s_add_i32 s88, s78, s10
	v_lshl_add_u64 v[176:177], s[70:71], 0, v[180:181]
	s_add_i32 s84, s88, 0x2000
	v_lshl_add_u64 v[130:131], v[176:177], 0, s[60:61]
	s_mov_b32 m0, s88
	v_lshl_add_u64 v[250:251], s[70:71], 0, v[184:185]
	s_add_u32 s14, s70, 0x2b0100
	ds_read_b128 v[62:65], v209 offset:16384
	ds_read_b128 v[90:93], v209 offset:17408
	ds_read_b128 v[94:97], v209 offset:18432
	ds_read_b128 v[106:109], v209 offset:19456
	ds_read_b128 v[110:113], v209 offset:20480
	ds_read_b128 v[118:121], v209 offset:21504
	ds_read_b128 v[122:125], v209 offset:22528
	ds_read_b128 v[126:129], v209 offset:23552
	global_load_lds_dwordx4 v[130:131], off
	v_lshl_add_u64 v[130:131], v[250:251], 0, s[60:61]
	s_mov_b32 m0, s84
	s_addc_u32 s15, s71, 0
	s_add_i32 s85, s79, s10
	global_load_lds_dwordx4 v[130:131], off
	v_lshl_add_u64 v[130:131], s[14:15], 0, v[180:181]
	s_mov_b32 m0, s85
	s_add_i32 s46, s85, 0x2000
	global_load_lds_dwordx4 v[130:131], off
	v_lshl_add_u64 v[130:131], s[14:15], 0, v[184:185]
	s_mov_b32 m0, s46
	v_lshl_add_u64 v[252:253], s[66:67], 0, v[178:179]
	global_load_lds_dwordx4 v[130:131], off
	v_lshl_add_u64 v[130:131], v[252:253], 0, s[60:61]
	s_mov_b32 m0, s11
	v_lshl_add_u64 v[190:191], s[66:67], 0, v[182:183]
	global_load_lds_dwordx4 v[130:131], off
	v_lshl_add_u64 v[130:131], v[190:191], 0, s[60:61]
	s_mov_b32 m0, s12
	s_nop 0
	global_load_lds_dwordx4 v[130:131], off
	s_waitcnt vmcnt(8)
	s_waitcnt lgkmcnt(0)
	s_barrier
	s_setprio 1
	v_mfma_f32_16x16x32_bf16 v[130:133], v[2:5], v[62:65], 0
	v_mfma_f32_16x16x32_bf16 v[140:143], v[2:5], v[94:97], 0
	v_mfma_f32_16x16x32_bf16 v[148:151], v[2:5], v[110:113], 0
	v_mfma_f32_16x16x32_bf16 v[2:5], v[2:5], v[122:125], 0
	v_mfma_f32_16x16x32_bf16 v[132:135], v[6:9], v[90:93], v[130:133]
	v_mfma_f32_16x16x32_bf16 v[140:143], v[6:9], v[106:109], v[140:143]
	v_mfma_f32_16x16x32_bf16 v[148:151], v[6:9], v[118:121], v[148:151]
	v_mfma_f32_16x16x32_bf16 v[2:5], v[6:9], v[126:129], v[2:5]
	v_mfma_f32_16x16x32_bf16 v[6:9], v[10:13], v[122:125], 0
	v_mfma_f32_16x16x32_bf16 v[136:139], v[10:13], v[62:65], 0
	v_mfma_f32_16x16x32_bf16 v[144:147], v[10:13], v[94:97], 0
	v_mfma_f32_16x16x32_bf16 v[152:155], v[10:13], v[110:113], 0
	v_mfma_f32_16x16x32_bf16 v[6:9], v[14:17], v[126:129], v[6:9]
	v_mfma_f32_16x16x32_bf16 v[136:139], v[14:17], v[90:93], v[136:139]
	v_mfma_f32_16x16x32_bf16 v[144:147], v[14:17], v[106:109], v[144:147]
	v_mfma_f32_16x16x32_bf16 v[152:155], v[14:17], v[118:121], v[152:155]
	s_setprio 0
	s_setprio 1
	v_mfma_f32_16x16x32_bf16 v[10:13], v[18:21], v[62:65], 0
	v_mfma_f32_16x16x32_bf16 v[156:159], v[22:25], v[90:93], v[10:13]
	v_mfma_f32_16x16x32_bf16 v[10:13], v[26:29], v[62:65], 0
	v_mfma_f32_16x16x32_bf16 v[160:163], v[30:33], v[90:93], v[10:13]
	v_mfma_f32_16x16x32_bf16 v[10:13], v[18:21], v[94:97], 0
	v_mfma_f32_16x16x32_bf16 v[164:167], v[22:25], v[106:109], v[10:13]
	v_mfma_f32_16x16x32_bf16 v[10:13], v[26:29], v[94:97], 0
	v_mfma_f32_16x16x32_bf16 v[168:171], v[30:33], v[106:109], v[10:13]
	v_mfma_f32_16x16x32_bf16 v[10:13], v[18:21], v[110:113], 0
	v_mfma_f32_16x16x32_bf16 v[172:175], v[22:25], v[118:121], v[10:13]
	v_mfma_f32_16x16x32_bf16 v[10:13], v[26:29], v[110:113], 0
	v_mfma_f32_16x16x32_bf16 v[194:197], v[30:33], v[118:121], v[10:13]
	v_mfma_f32_16x16x32_bf16 v[10:13], v[18:21], v[122:125], 0
	v_mfma_f32_16x16x32_bf16 v[198:201], v[22:25], v[126:129], v[10:13]
	v_mfma_f32_16x16x32_bf16 v[10:13], v[26:29], v[122:125], 0
	v_mfma_f32_16x16x32_bf16 v[202:205], v[30:33], v[126:129], v[10:13]
	s_setprio 0
	s_barrier
	s_add_i32 s47, 0, 0x18000
	s_add_i32 s56, 0, 0x1c000
	v_add_u32_e32 v130, s47, v206
	v_add_u32_e32 v131, s56, v206
	s_nop 0
	ds_read_b128 v[10:13], v130
	ds_read_b128 v[14:17], v130 offset:1024
	ds_read_b128 v[18:21], v130 offset:2048
	ds_read_b128 v[22:25], v130 offset:3072
	ds_read_b128 v[210:213], v131
	ds_read_b128 v[214:217], v131 offset:1024
	ds_read_b128 v[218:221], v131 offset:2048
	ds_read_b128 v[222:225], v131 offset:3072
	s_add_u32 s14, s66, 0x2b0100
	s_addc_u32 s15, s67, 0
	s_mov_b32 m0, s13
	v_lshl_add_u64 v[90:91], s[14:15], 0, v[178:179]
	ds_read_b128 v[26:29], v209 offset:32768
	ds_read_b128 v[30:33], v209 offset:33792
	ds_read_b128 v[62:65], v209 offset:34816
	ds_read_b128 v[226:229], v209 offset:35840
	ds_read_b128 v[230:233], v209 offset:36864
	ds_read_b128 v[234:237], v209 offset:37888
	ds_read_b128 v[238:241], v209 offset:38912
	ds_read_b128 v[242:245], v209 offset:39936
	global_load_lds_dwordx4 v[90:91], off
	v_lshl_add_u64 v[90:91], s[14:15], 0, v[182:183]
	s_mov_b32 m0, s29
	s_nop 0
	global_load_lds_dwordx4 v[90:91], off
	s_waitcnt vmcnt(8)
	s_waitcnt lgkmcnt(0)
	s_barrier
	s_setprio 1
	v_mfma_f32_16x16x32_bf16 v[66:69], v[10:13], v[26:29], v[66:69]
	v_mfma_f32_16x16x32_bf16 v[122:125], v[14:17], v[30:33], v[66:69]
	v_mfma_f32_16x16x32_bf16 v[66:69], v[18:21], v[26:29], v[70:73]
	v_mfma_f32_16x16x32_bf16 v[118:121], v[22:25], v[30:33], v[66:69]
	v_mfma_f32_16x16x32_bf16 v[66:69], v[10:13], v[62:65], v[74:77]
	v_mfma_f32_16x16x32_bf16 v[110:113], v[14:17], v[226:229], v[66:69]
	v_mfma_f32_16x16x32_bf16 v[66:69], v[18:21], v[62:65], v[78:81]
	v_mfma_f32_16x16x32_bf16 v[106:109], v[22:25], v[226:229], v[66:69]
	v_mfma_f32_16x16x32_bf16 v[66:69], v[10:13], v[230:233], v[82:85]
	v_mfma_f32_16x16x32_bf16 v[94:97], v[14:17], v[234:237], v[66:69]
	v_mfma_f32_16x16x32_bf16 v[66:69], v[18:21], v[230:233], v[86:89]
	v_mfma_f32_16x16x32_bf16 v[90:93], v[22:25], v[234:237], v[66:69]
	v_mfma_f32_16x16x32_bf16 v[66:69], v[10:13], v[238:241], v[98:101]
	v_mfma_f32_16x16x32_bf16 v[78:81], v[14:17], v[242:245], v[66:69]
	v_mfma_f32_16x16x32_bf16 v[66:69], v[18:21], v[238:241], v[102:105]
	v_mfma_f32_16x16x32_bf16 v[74:77], v[22:25], v[242:245], v[66:69]
	s_setprio 0
	s_setprio 1
	v_mfma_f32_16x16x32_bf16 v[66:69], v[210:213], v[26:29], v[114:117]
	v_mfma_f32_16x16x32_bf16 v[26:29], v[218:221], v[26:29], v[34:37]
	v_mfma_f32_16x16x32_bf16 v[114:117], v[222:225], v[30:33], v[26:29]
	v_mfma_f32_16x16x32_bf16 v[26:29], v[210:213], v[62:65], v[38:41]
	v_mfma_f32_16x16x32_bf16 v[102:105], v[214:217], v[226:229], v[26:29]
	v_mfma_f32_16x16x32_bf16 v[26:29], v[218:221], v[62:65], v[42:45]
	v_mfma_f32_16x16x32_bf16 v[98:101], v[222:225], v[226:229], v[26:29]
	v_mfma_f32_16x16x32_bf16 v[26:29], v[210:213], v[230:233], v[46:49]
	v_mfma_f32_16x16x32_bf16 v[86:89], v[214:217], v[234:237], v[26:29]
	v_mfma_f32_16x16x32_bf16 v[26:29], v[218:221], v[230:233], v[50:53]
	v_mfma_f32_16x16x32_bf16 v[82:85], v[222:225], v[234:237], v[26:29]
	v_mfma_f32_16x16x32_bf16 v[26:29], v[210:213], v[238:241], v[54:57]
	v_mfma_f32_16x16x32_bf16 v[70:73], v[214:217], v[242:245], v[26:29]
	v_mfma_f32_16x16x32_bf16 v[26:29], v[218:221], v[238:241], v[58:61]
	v_mfma_f32_16x16x32_bf16 v[126:129], v[214:217], v[30:33], v[66:69]
	v_mfma_f32_16x16x32_bf16 v[66:69], v[222:225], v[242:245], v[26:29]
	s_setprio 0
	s_barrier
	s_add_i32 s47, s47, s10
	s_add_i32 s89, s47, 0x2000
	s_nop 1
	v_lshl_add_u64 v[26:27], v[176:177], 0, s[62:63]
	s_mov_b32 m0, s47
	s_add_u32 s14, s70, 0x2b0180
	ds_read_b128 v[34:37], v209 offset:49152
	ds_read_b128 v[38:41], v209 offset:50176
	ds_read_b128 v[226:229], v209 offset:51200
	ds_read_b128 v[230:233], v209 offset:52224
	ds_read_b128 v[234:237], v209 offset:53248
	ds_read_b128 v[238:241], v209 offset:54272
	ds_read_b128 v[242:245], v209 offset:55296
	ds_read_b128 v[246:249], v209 offset:56320
	global_load_lds_dwordx4 v[26:27], off
	v_lshl_add_u64 v[26:27], v[250:251], 0, s[62:63]
	s_mov_b32 m0, s89
	s_addc_u32 s15, s71, 0
	s_add_i32 s56, s56, s10
	global_load_lds_dwordx4 v[26:27], off
	v_lshl_add_u64 v[26:27], s[14:15], 0, v[180:181]
	s_mov_b32 m0, s56
	s_add_i32 s57, s56, 0x2000
	global_load_lds_dwordx4 v[26:27], off
	v_lshl_add_u64 v[26:27], s[14:15], 0, v[184:185]
	s_mov_b32 m0, s57
	s_nop 0
	global_load_lds_dwordx4 v[26:27], off
	v_lshl_add_u64 v[26:27], v[252:253], 0, s[62:63]
	s_mov_b32 m0, s58
	s_nop 0
	global_load_lds_dwordx4 v[26:27], off
	v_lshl_add_u64 v[26:27], v[190:191], 0, s[62:63]
	s_mov_b32 m0, s59
	s_nop 0
	global_load_lds_dwordx4 v[26:27], off
	s_waitcnt vmcnt(8)
	s_waitcnt lgkmcnt(0)
	s_barrier
	s_setprio 1
	v_mfma_f32_16x16x32_bf16 v[26:29], v[10:13], v[34:37], v[132:135]
	v_mfma_f32_16x16x32_bf16 v[58:61], v[14:17], v[38:41], v[26:29]
	v_mfma_f32_16x16x32_bf16 v[26:29], v[18:21], v[34:37], v[136:139]
	v_mfma_f32_16x16x32_bf16 v[54:57], v[22:25], v[38:41], v[26:29]
	v_mfma_f32_16x16x32_bf16 v[26:29], v[10:13], v[226:229], v[140:143]
	v_mfma_f32_16x16x32_bf16 v[46:49], v[14:17], v[230:233], v[26:29]
	v_mfma_f32_16x16x32_bf16 v[26:29], v[18:21], v[226:229], v[144:147]
	v_mfma_f32_16x16x32_bf16 v[42:45], v[22:25], v[230:233], v[26:29]
	v_mfma_f32_16x16x32_bf16 v[26:29], v[10:13], v[234:237], v[148:151]
	v_mfma_f32_16x16x32_bf16 v[2:5], v[10:13], v[242:245], v[2:5]
	v_mfma_f32_16x16x32_bf16 v[30:33], v[14:17], v[238:241], v[26:29]
	v_mfma_f32_16x16x32_bf16 v[26:29], v[18:21], v[234:237], v[152:155]
	v_mfma_f32_16x16x32_bf16 v[14:17], v[14:17], v[246:249], v[2:5]
	v_mfma_f32_16x16x32_bf16 v[2:5], v[18:21], v[242:245], v[6:9]
	v_mfma_f32_16x16x32_bf16 v[26:29], v[22:25], v[238:241], v[26:29]
	v_mfma_f32_16x16x32_bf16 v[10:13], v[22:25], v[246:249], v[2:5]
	s_setprio 0
	s_setprio 1
	v_mfma_f32_16x16x32_bf16 v[2:5], v[210:213], v[34:37], v[156:159]
	v_mfma_f32_16x16x32_bf16 v[62:65], v[214:217], v[38:41], v[2:5]
	v_mfma_f32_16x16x32_bf16 v[2:5], v[218:221], v[34:37], v[160:163]
	v_mfma_f32_16x16x32_bf16 v[50:53], v[222:225], v[38:41], v[2:5]
	v_mfma_f32_16x16x32_bf16 v[2:5], v[210:213], v[226:229], v[164:167]
	v_mfma_f32_16x16x32_bf16 v[38:41], v[214:217], v[230:233], v[2:5]
	v_mfma_f32_16x16x32_bf16 v[2:5], v[218:221], v[226:229], v[168:171]
	v_mfma_f32_16x16x32_bf16 v[34:37], v[222:225], v[230:233], v[2:5]
	v_mfma_f32_16x16x32_bf16 v[2:5], v[210:213], v[234:237], v[172:175]
	v_mfma_f32_16x16x32_bf16 v[22:25], v[214:217], v[238:241], v[2:5]
	v_mfma_f32_16x16x32_bf16 v[2:5], v[218:221], v[234:237], v[194:197]
	v_mfma_f32_16x16x32_bf16 v[18:21], v[222:225], v[238:241], v[2:5]
	v_mfma_f32_16x16x32_bf16 v[2:5], v[210:213], v[242:245], v[198:201]
	v_mfma_f32_16x16x32_bf16 v[6:9], v[214:217], v[246:249], v[2:5]
	v_mfma_f32_16x16x32_bf16 v[2:5], v[218:221], v[242:245], v[202:205]
	v_mfma_f32_16x16x32_bf16 v[2:5], v[222:225], v[246:249], v[2:5]
	s_setprio 0
	s_barrier
	s_add_u32 s90, s70, 0x200
	s_addc_u32 s14, s71, 0
	s_mov_b32 s15, 0
.LBB0_331:
	ds_read_b128 v[132:135], v207
	ds_read_b128 v[136:139], v207 offset:1024
	ds_read_b128 v[140:143], v207 offset:2048
	ds_read_b128 v[144:147], v207 offset:3072
	ds_read_b128 v[148:151], v208
	ds_read_b128 v[152:155], v208 offset:1024
	ds_read_b128 v[156:159], v208 offset:2048
	ds_read_b128 v[160:163], v208 offset:3072
	s_add_u32 s16, s66, 0x200
	s_addc_u32 s17, s67, 0
	s_cmpk_eq_i32 s15, 0xa8
	s_cselect_b32 s75, s1, s17
	s_cselect_b32 s74, s0, s16
	s_cselect_b32 s71, s65, s14
	s_cselect_b32 s70, s64, s90
	s_mov_b32 m0, s86
	ds_read_b128 v[164:167], v209
	ds_read_b128 v[168:171], v209 offset:1024
	ds_read_b128 v[172:175], v209 offset:2048
	ds_read_b128 v[194:197], v209 offset:3072
	ds_read_b128 v[198:201], v209 offset:4096
	ds_read_b128 v[202:205], v209 offset:5120
	ds_read_b128 v[210:213], v209 offset:6144
	ds_read_b128 v[214:217], v209 offset:7168
	global_load_lds_dwordx4 v186, s[66:67]
	s_mov_b32 m0, s87
	s_nop 0
	global_load_lds_dwordx4 v188, s[66:67]
	s_waitcnt vmcnt(8)
	s_waitcnt lgkmcnt(0)
	s_barrier
	s_setprio 1
	v_mfma_f32_16x16x32_bf16 v[122:125], v[132:135], v[164:167], v[122:125]
	v_mfma_f32_16x16x32_bf16 v[118:121], v[140:143], v[164:167], v[118:121]
	v_mfma_f32_16x16x32_bf16 v[110:113], v[132:135], v[172:175], v[110:113]
	v_mfma_f32_16x16x32_bf16 v[106:109], v[140:143], v[172:175], v[106:109]
	v_mfma_f32_16x16x32_bf16 v[94:97], v[132:135], v[198:201], v[94:97]
	v_mfma_f32_16x16x32_bf16 v[90:93], v[140:143], v[198:201], v[90:93]
	v_mfma_f32_16x16x32_bf16 v[78:81], v[132:135], v[210:213], v[78:81]
	v_mfma_f32_16x16x32_bf16 v[74:77], v[140:143], v[210:213], v[74:77]
	v_mfma_f32_16x16x32_bf16 v[122:125], v[136:139], v[168:171], v[122:125]
	v_mfma_f32_16x16x32_bf16 v[118:121], v[144:147], v[168:171], v[118:121]
	v_mfma_f32_16x16x32_bf16 v[110:113], v[136:139], v[194:197], v[110:113]
	v_mfma_f32_16x16x32_bf16 v[106:109], v[144:147], v[194:197], v[106:109]
	v_mfma_f32_16x16x32_bf16 v[94:97], v[136:139], v[202:205], v[94:97]
	v_mfma_f32_16x16x32_bf16 v[90:93], v[144:147], v[202:205], v[90:93]
	v_mfma_f32_16x16x32_bf16 v[78:81], v[136:139], v[214:217], v[78:81]
	v_mfma_f32_16x16x32_bf16 v[74:77], v[144:147], v[214:217], v[74:77]
	s_setprio 0
	s_setprio 1
	v_mfma_f32_16x16x32_bf16 v[126:129], v[148:151], v[164:167], v[126:129]
	v_mfma_f32_16x16x32_bf16 v[114:117], v[156:159], v[164:167], v[114:117]
	v_mfma_f32_16x16x32_bf16 v[102:105], v[148:151], v[172:175], v[102:105]
	v_mfma_f32_16x16x32_bf16 v[98:101], v[156:159], v[172:175], v[98:101]
	v_mfma_f32_16x16x32_bf16 v[86:89], v[148:151], v[198:201], v[86:89]
	v_mfma_f32_16x16x32_bf16 v[82:85], v[156:159], v[198:201], v[82:85]
	v_mfma_f32_16x16x32_bf16 v[70:73], v[148:151], v[210:213], v[70:73]
	v_mfma_f32_16x16x32_bf16 v[66:69], v[156:159], v[210:213], v[66:69]
	v_mfma_f32_16x16x32_bf16 v[126:129], v[152:155], v[168:171], v[126:129]
	v_mfma_f32_16x16x32_bf16 v[114:117], v[160:163], v[168:171], v[114:117]
	v_mfma_f32_16x16x32_bf16 v[102:105], v[152:155], v[194:197], v[102:105]
	v_mfma_f32_16x16x32_bf16 v[98:101], v[160:163], v[194:197], v[98:101]
	v_mfma_f32_16x16x32_bf16 v[86:89], v[152:155], v[202:205], v[86:89]
	v_mfma_f32_16x16x32_bf16 v[82:85], v[160:163], v[202:205], v[82:85]
	v_mfma_f32_16x16x32_bf16 v[70:73], v[152:155], v[214:217], v[70:73]
	v_mfma_f32_16x16x32_bf16 v[66:69], v[160:163], v[214:217], v[66:69]
	s_setprio 0
	s_barrier
	s_mov_b32 m0, s88
	s_mov_b64 s[98:99], s[70:71]
	s_add_u32 s16, s70, 0x2b0000
	ds_read_b128 v[164:167], v209 offset:16384
	ds_read_b128 v[168:171], v209 offset:17408
	ds_read_b128 v[172:175], v209 offset:18432
	ds_read_b128 v[194:197], v209 offset:19456
	ds_read_b128 v[198:201], v209 offset:20480
	ds_read_b128 v[202:205], v209 offset:21504
	ds_read_b128 v[210:213], v209 offset:22528
	ds_read_b128 v[214:217], v209 offset:23552
	global_load_lds_dwordx4 v180, s[70:71]
	s_mov_b32 m0, s84
	s_addc_u32 s17, s71, 0
	global_load_lds_dwordx4 v184, s[70:71]
	s_mov_b32 m0, s85
	s_mov_b64 s[100:101], s[74:75]
	global_load_lds_dwordx4 v180, s[16:17]
	s_mov_b32 m0, s46
	s_nop 0
	global_load_lds_dwordx4 v184, s[16:17]
	s_mov_b32 m0, s11
	s_nop 0
	global_load_lds_dwordx4 v178, s[74:75]
	s_mov_b32 m0, s12
	s_nop 0
	global_load_lds_dwordx4 v182, s[74:75]
	s_waitcnt vmcnt(8)
	s_waitcnt lgkmcnt(0)
	s_barrier
	s_setprio 1
	v_mfma_f32_16x16x32_bf16 v[58:61], v[132:135], v[164:167], v[58:61]
	v_mfma_f32_16x16x32_bf16 v[54:57], v[140:143], v[164:167], v[54:57]
	v_mfma_f32_16x16x32_bf16 v[46:49], v[132:135], v[172:175], v[46:49]
	v_mfma_f32_16x16x32_bf16 v[42:45], v[140:143], v[172:175], v[42:45]
	v_mfma_f32_16x16x32_bf16 v[30:33], v[132:135], v[198:201], v[30:33]
	v_mfma_f32_16x16x32_bf16 v[26:29], v[140:143], v[198:201], v[26:29]
	v_mfma_f32_16x16x32_bf16 v[14:17], v[132:135], v[210:213], v[14:17]
	v_mfma_f32_16x16x32_bf16 v[10:13], v[140:143], v[210:213], v[10:13]
	v_mfma_f32_16x16x32_bf16 v[58:61], v[136:139], v[168:171], v[58:61]
	v_mfma_f32_16x16x32_bf16 v[54:57], v[144:147], v[168:171], v[54:57]
	v_mfma_f32_16x16x32_bf16 v[46:49], v[136:139], v[194:197], v[46:49]
	v_mfma_f32_16x16x32_bf16 v[42:45], v[144:147], v[194:197], v[42:45]
	v_mfma_f32_16x16x32_bf16 v[30:33], v[136:139], v[202:205], v[30:33]
	v_mfma_f32_16x16x32_bf16 v[26:29], v[144:147], v[202:205], v[26:29]
	v_mfma_f32_16x16x32_bf16 v[14:17], v[136:139], v[214:217], v[14:17]
	v_mfma_f32_16x16x32_bf16 v[10:13], v[144:147], v[214:217], v[10:13]
	s_setprio 0
	s_setprio 1
	v_mfma_f32_16x16x32_bf16 v[62:65], v[148:151], v[164:167], v[62:65]
	v_mfma_f32_16x16x32_bf16 v[50:53], v[156:159], v[164:167], v[50:53]
	v_mfma_f32_16x16x32_bf16 v[38:41], v[148:151], v[172:175], v[38:41]
	v_mfma_f32_16x16x32_bf16 v[34:37], v[156:159], v[172:175], v[34:37]
	v_mfma_f32_16x16x32_bf16 v[22:25], v[148:151], v[198:201], v[22:25]
	v_mfma_f32_16x16x32_bf16 v[18:21], v[156:159], v[198:201], v[18:21]
	v_mfma_f32_16x16x32_bf16 v[6:9], v[148:151], v[210:213], v[6:9]
	v_mfma_f32_16x16x32_bf16 v[2:5], v[156:159], v[210:213], v[2:5]
	v_mfma_f32_16x16x32_bf16 v[62:65], v[152:155], v[168:171], v[62:65]
	v_mfma_f32_16x16x32_bf16 v[50:53], v[160:163], v[168:171], v[50:53]
	v_mfma_f32_16x16x32_bf16 v[38:41], v[152:155], v[194:197], v[38:41]
	v_mfma_f32_16x16x32_bf16 v[34:37], v[160:163], v[194:197], v[34:37]
	v_mfma_f32_16x16x32_bf16 v[22:25], v[152:155], v[202:205], v[22:25]
	v_mfma_f32_16x16x32_bf16 v[18:21], v[160:163], v[202:205], v[18:21]
	v_mfma_f32_16x16x32_bf16 v[6:9], v[152:155], v[214:217], v[6:9]
	v_mfma_f32_16x16x32_bf16 v[2:5], v[160:163], v[214:217], v[2:5]
	s_setprio 0
	s_barrier
; #define PG8_BAR __builtin_amdgcn_s_barrier()
;     ...
;         for (int t = 2; t < nt; t += 2) PG8_KITER(t);
;         if constexpr (ALIGN_EPI) { if (wr == 0) PG8_BAR; }
	ds_read_b128 v[132:135], v130
	ds_read_b128 v[136:139], v130 offset:1024
	ds_read_b128 v[140:143], v130 offset:2048
	ds_read_b128 v[144:147], v130 offset:3072
	ds_read_b128 v[148:151], v131
	ds_read_b128 v[152:155], v131 offset:1024
	ds_read_b128 v[156:159], v131 offset:2048
	ds_read_b128 v[160:163], v131 offset:3072
	s_add_u32 s16, s74, 0x2b0000
	s_addc_u32 s17, s75, 0
	s_mov_b32 m0, s13
	ds_read_b128 v[164:167], v209 offset:32768
	ds_read_b128 v[168:171], v209 offset:33792
	ds_read_b128 v[172:175], v209 offset:34816
	ds_read_b128 v[194:197], v209 offset:35840
	ds_read_b128 v[198:201], v209 offset:36864
	ds_read_b128 v[202:205], v209 offset:37888
	ds_read_b128 v[210:213], v209 offset:38912
	ds_read_b128 v[214:217], v209 offset:39936
	global_load_lds_dwordx4 v178, s[16:17]
	s_mov_b32 m0, s29
	s_nop 0
	global_load_lds_dwordx4 v182, s[16:17]
	s_waitcnt vmcnt(8)
	s_waitcnt lgkmcnt(0)
	s_barrier
	s_setprio 1
	v_mfma_f32_16x16x32_bf16 v[122:125], v[132:135], v[164:167], v[122:125]
	v_mfma_f32_16x16x32_bf16 v[118:121], v[140:143], v[164:167], v[118:121]
	v_mfma_f32_16x16x32_bf16 v[110:113], v[132:135], v[172:175], v[110:113]
	v_mfma_f32_16x16x32_bf16 v[106:109], v[140:143], v[172:175], v[106:109]
	v_mfma_f32_16x16x32_bf16 v[94:97], v[132:135], v[198:201], v[94:97]
	v_mfma_f32_16x16x32_bf16 v[90:93], v[140:143], v[198:201], v[90:93]
	v_mfma_f32_16x16x32_bf16 v[78:81], v[132:135], v[210:213], v[78:81]
	v_mfma_f32_16x16x32_bf16 v[74:77], v[140:143], v[210:213], v[74:77]
	v_mfma_f32_16x16x32_bf16 v[122:125], v[136:139], v[168:171], v[122:125]
	v_mfma_f32_16x16x32_bf16 v[118:121], v[144:147], v[168:171], v[118:121]
	v_mfma_f32_16x16x32_bf16 v[110:113], v[136:139], v[194:197], v[110:113]
	v_mfma_f32_16x16x32_bf16 v[106:109], v[144:147], v[194:197], v[106:109]
	v_mfma_f32_16x16x32_bf16 v[94:97], v[136:139], v[202:205], v[94:97]
	v_mfma_f32_16x16x32_bf16 v[90:93], v[144:147], v[202:205], v[90:93]
	v_mfma_f32_16x16x32_bf16 v[78:81], v[136:139], v[214:217], v[78:81]
	v_mfma_f32_16x16x32_bf16 v[74:77], v[144:147], v[214:217], v[74:77]
	s_setprio 0
	s_setprio 1
	v_mfma_f32_16x16x32_bf16 v[126:129], v[148:151], v[164:167], v[126:129]
	v_mfma_f32_16x16x32_bf16 v[114:117], v[156:159], v[164:167], v[114:117]
	v_mfma_f32_16x16x32_bf16 v[102:105], v[148:151], v[172:175], v[102:105]
	v_mfma_f32_16x16x32_bf16 v[98:101], v[156:159], v[172:175], v[98:101]
	v_mfma_f32_16x16x32_bf16 v[86:89], v[148:151], v[198:201], v[86:89]
	v_mfma_f32_16x16x32_bf16 v[82:85], v[156:159], v[198:201], v[82:85]
	v_mfma_f32_16x16x32_bf16 v[70:73], v[148:151], v[210:213], v[70:73]
	v_mfma_f32_16x16x32_bf16 v[66:69], v[156:159], v[210:213], v[66:69]
	v_mfma_f32_16x16x32_bf16 v[126:129], v[152:155], v[168:171], v[126:129]
	v_mfma_f32_16x16x32_bf16 v[114:117], v[160:163], v[168:171], v[114:117]
	v_mfma_f32_16x16x32_bf16 v[102:105], v[152:155], v[194:197], v[102:105]
	v_mfma_f32_16x16x32_bf16 v[98:101], v[160:163], v[194:197], v[98:101]
	v_mfma_f32_16x16x32_bf16 v[86:89], v[152:155], v[202:205], v[86:89]
	v_mfma_f32_16x16x32_bf16 v[82:85], v[160:163], v[202:205], v[82:85]
	v_mfma_f32_16x16x32_bf16 v[70:73], v[152:155], v[214:217], v[70:73]
	v_mfma_f32_16x16x32_bf16 v[66:69], v[160:163], v[214:217], v[66:69]
	s_setprio 0
	s_barrier
	s_mov_b32 m0, s47
	s_add_u32 s98, s98, 0x80
	s_addc_u32 s99, s99, 0
	s_add_u32 s100, s100, 0x80
	s_addc_u32 s101, s101, 0
	s_add_u32 s16, s70, 0x2b0080
	ds_read_b128 v[164:167], v209 offset:49152
	ds_read_b128 v[168:171], v209 offset:50176
	ds_read_b128 v[172:175], v209 offset:51200
	ds_read_b128 v[194:197], v209 offset:52224
	ds_read_b128 v[198:201], v209 offset:53248
	ds_read_b128 v[202:205], v209 offset:54272
	ds_read_b128 v[210:213], v209 offset:55296
	ds_read_b128 v[214:217], v209 offset:56320
	global_load_lds_dwordx4 v180, s[98:99]
	s_mov_b32 m0, s89
	s_addc_u32 s17, s71, 0
	global_load_lds_dwordx4 v184, s[98:99]
	s_mov_b32 m0, s56
	s_nop 0
	global_load_lds_dwordx4 v180, s[16:17]
	s_mov_b32 m0, s57
	s_nop 0
	global_load_lds_dwordx4 v184, s[16:17]
	s_mov_b32 m0, s58
	s_nop 0
	global_load_lds_dwordx4 v178, s[100:101]
	s_mov_b32 m0, s59
	s_nop 0
	global_load_lds_dwordx4 v182, s[100:101]
	s_waitcnt vmcnt(8)
	s_waitcnt lgkmcnt(0)
	s_barrier
	s_setprio 1
	v_mfma_f32_16x16x32_bf16 v[58:61], v[132:135], v[164:167], v[58:61]
	v_mfma_f32_16x16x32_bf16 v[54:57], v[140:143], v[164:167], v[54:57]
	v_mfma_f32_16x16x32_bf16 v[46:49], v[132:135], v[172:175], v[46:49]
	v_mfma_f32_16x16x32_bf16 v[42:45], v[140:143], v[172:175], v[42:45]
	v_mfma_f32_16x16x32_bf16 v[30:33], v[132:135], v[198:201], v[30:33]
	v_mfma_f32_16x16x32_bf16 v[26:29], v[140:143], v[198:201], v[26:29]
	v_mfma_f32_16x16x32_bf16 v[14:17], v[132:135], v[210:213], v[14:17]
	v_mfma_f32_16x16x32_bf16 v[10:13], v[140:143], v[210:213], v[10:13]
	v_mfma_f32_16x16x32_bf16 v[58:61], v[136:139], v[168:171], v[58:61]
	v_mfma_f32_16x16x32_bf16 v[54:57], v[144:147], v[168:171], v[54:57]
	v_mfma_f32_16x16x32_bf16 v[46:49], v[136:139], v[194:197], v[46:49]
	v_mfma_f32_16x16x32_bf16 v[42:45], v[144:147], v[194:197], v[42:45]
	v_mfma_f32_16x16x32_bf16 v[30:33], v[136:139], v[202:205], v[30:33]
	v_mfma_f32_16x16x32_bf16 v[26:29], v[144:147], v[202:205], v[26:29]
	v_mfma_f32_16x16x32_bf16 v[14:17], v[136:139], v[214:217], v[14:17]
	v_mfma_f32_16x16x32_bf16 v[10:13], v[144:147], v[214:217], v[10:13]
	s_setprio 0
	s_setprio 1
	v_mfma_f32_16x16x32_bf16 v[62:65], v[148:151], v[164:167], v[62:65]
	v_mfma_f32_16x16x32_bf16 v[50:53], v[156:159], v[164:167], v[50:53]
	v_mfma_f32_16x16x32_bf16 v[38:41], v[148:151], v[172:175], v[38:41]
	v_mfma_f32_16x16x32_bf16 v[34:37], v[156:159], v[172:175], v[34:37]
	v_mfma_f32_16x16x32_bf16 v[22:25], v[148:151], v[198:201], v[22:25]
	v_mfma_f32_16x16x32_bf16 v[18:21], v[156:159], v[198:201], v[18:21]
	v_mfma_f32_16x16x32_bf16 v[6:9], v[148:151], v[210:213], v[6:9]
	v_mfma_f32_16x16x32_bf16 v[2:5], v[156:159], v[210:213], v[2:5]
	v_mfma_f32_16x16x32_bf16 v[62:65], v[152:155], v[168:171], v[62:65]
	v_mfma_f32_16x16x32_bf16 v[50:53], v[160:163], v[168:171], v[50:53]
	v_mfma_f32_16x16x32_bf16 v[38:41], v[152:155], v[194:197], v[38:41]
	v_mfma_f32_16x16x32_bf16 v[34:37], v[160:163], v[194:197], v[34:37]
	v_mfma_f32_16x16x32_bf16 v[22:25], v[152:155], v[202:205], v[22:25]
	v_mfma_f32_16x16x32_bf16 v[18:21], v[160:163], v[202:205], v[18:21]
	v_mfma_f32_16x16x32_bf16 v[6:9], v[152:155], v[214:217], v[6:9]
	v_mfma_f32_16x16x32_bf16 v[2:5], v[160:163], v[214:217], v[2:5]
	s_setprio 0
	s_barrier
	s_add_i32 s15, s15, 2
	s_add_u32 s66, s66, 0x100
	s_addc_u32 s67, s67, 0
	s_add_u32 s90, s90, 0x100
	s_addc_u32 s14, s14, 0
	s_cmpk_gt_u32 s15, 0xa9
	s_cbranch_scc0 .LBB0_331
	s_and_b64 vcc, exec, s[30:31]
	s_cbranch_vccz .LBB0_334
	s_barrier

;     __host__ __device__ bool next(int i, Unit& u) const { if (!StaticOrder::next(i >> 1, u)) return false; u.seg = i & 1; return true; }
;     ...
;         const bool has_next = S.next(ui + 1, nxt);
;         const char* nA = has_next ? PG8_APTR(nxt) : cA; const char* nB = has_next ? PG8_BPTR(nxt) : cB;
.LBB0_414:
	s_ashr_i32 s75, s74, 31
	ds_read_b128 v[2:5], v163
	ds_read_b128 v[6:9], v163 offset:1024
	ds_read_b128 v[10:13], v163 offset:2048
	ds_read_b128 v[14:17], v163 offset:3072
	ds_read_b128 v[18:21], v164
	ds_read_b128 v[22:25], v164 offset:1024
	ds_read_b128 v[26:29], v164 offset:2048
	ds_read_b128 v[30:33], v164 offset:3072
	s_lshl_b64 s[14:15], s[74:75], 21
	s_add_u32 s76, s36, s14
	s_addc_u32 s77, s37, s15
	s_and_b64 s[14:15], s[4:5], exec
	s_cselect_b32 s1, s77, s81
	s_cselect_b32 s75, s76, s80
	s_and_b32 s18, s10, 0x7fffffff
	s_lshl_b64 s[14:15], s[18:19], 21
	s_add_u32 s78, s33, s14
	s_addc_u32 s79, s71, s15
	s_and_b64 s[14:15], s[4:5], exec
	s_cselect_b32 s18, s79, s7
	s_cselect_b32 vcc_lo, s78, s6
	s_add_u32 s14, s80, 0x100080
	s_addc_u32 s15, s81, 0
	s_mov_b32 m0, s89
	v_lshl_add_u64 v[66:67], s[14:15], 0, v[136:137]
	ds_read_b128 v[34:37], v165
	ds_read_b128 v[38:41], v165 offset:1024
	ds_read_b128 v[42:45], v165 offset:2048
	ds_read_b128 v[46:49], v165 offset:3072
	ds_read_b128 v[50:53], v165 offset:4096
	ds_read_b128 v[54:57], v165 offset:5120
	ds_read_b128 v[58:61], v165 offset:6144
	ds_read_b128 v[62:65], v165 offset:7168
	global_load_lds_dwordx4 v[66:67], off
	v_lshl_add_u64 v[66:67], s[14:15], 0, v[132:133]
	s_mov_b32 m0, s92
	s_nop 0
	global_load_lds_dwordx4 v[66:67], off
	s_waitcnt vmcnt(8)
	s_waitcnt lgkmcnt(0)
	s_barrier
	s_setprio 1
	v_mfma_f32_16x16x32_bf16 v[86:89], v[10:13], v[50:53], 0
	v_mfma_f32_16x16x32_bf16 v[90:93], v[14:17], v[54:57], v[86:89]
	v_mfma_f32_16x16x32_bf16 v[86:89], v[2:5], v[58:61], 0
	v_mfma_f32_16x16x32_bf16 v[66:69], v[2:5], v[34:37], 0
	v_mfma_f32_16x16x32_bf16 v[70:73], v[10:13], v[34:37], 0
	v_mfma_f32_16x16x32_bf16 v[74:77], v[2:5], v[42:45], 0
	v_mfma_f32_16x16x32_bf16 v[78:81], v[10:13], v[42:45], 0
	v_mfma_f32_16x16x32_bf16 v[82:85], v[2:5], v[50:53], 0
	v_mfma_f32_16x16x32_bf16 v[94:97], v[6:9], v[62:65], v[86:89]
	v_mfma_f32_16x16x32_bf16 v[86:89], v[10:13], v[58:61], 0
	v_mfma_f32_16x16x32_bf16 v[66:69], v[6:9], v[38:41], v[66:69]
	v_mfma_f32_16x16x32_bf16 v[70:73], v[14:17], v[38:41], v[70:73]
	v_mfma_f32_16x16x32_bf16 v[74:77], v[6:9], v[46:49], v[74:77]
	v_mfma_f32_16x16x32_bf16 v[78:81], v[14:17], v[46:49], v[78:81]
	v_mfma_f32_16x16x32_bf16 v[82:85], v[6:9], v[54:57], v[82:85]
	v_mfma_f32_16x16x32_bf16 v[106:109], v[14:17], v[62:65], v[86:89]
	s_setprio 0
	s_setprio 1
	v_mfma_f32_16x16x32_bf16 v[86:89], v[18:21], v[34:37], 0
	v_mfma_f32_16x16x32_bf16 v[34:37], v[26:29], v[34:37], 0
	v_mfma_f32_16x16x32_bf16 v[110:113], v[22:25], v[38:41], v[86:89]
	v_mfma_f32_16x16x32_bf16 v[34:37], v[30:33], v[38:41], v[34:37]
	v_mfma_f32_16x16x32_bf16 v[38:41], v[18:21], v[42:45], 0
	v_mfma_f32_16x16x32_bf16 v[42:45], v[26:29], v[42:45], 0
	v_mfma_f32_16x16x32_bf16 v[38:41], v[22:25], v[46:49], v[38:41]
	v_mfma_f32_16x16x32_bf16 v[42:45], v[30:33], v[46:49], v[42:45]
	v_mfma_f32_16x16x32_bf16 v[46:49], v[18:21], v[50:53], 0
	v_mfma_f32_16x16x32_bf16 v[50:53], v[26:29], v[50:53], 0
	v_mfma_f32_16x16x32_bf16 v[46:49], v[22:25], v[54:57], v[46:49]
	v_mfma_f32_16x16x32_bf16 v[50:53], v[30:33], v[54:57], v[50:53]
	v_mfma_f32_16x16x32_bf16 v[54:57], v[18:21], v[58:61], 0
	v_mfma_f32_16x16x32_bf16 v[58:61], v[26:29], v[58:61], 0
	v_mfma_f32_16x16x32_bf16 v[54:57], v[22:25], v[62:65], v[54:57]
	v_mfma_f32_16x16x32_bf16 v[58:61], v[30:33], v[62:65], v[58:61]
	s_setprio 0
	s_barrier
	s_add_i32 vcc_hi, s59, s29
	v_lshl_add_u64 v[248:249], s[6:7], 0, v[134:135]
	s_add_i32 s84, vcc_hi, 0x2000
	v_lshl_add_u64 v[148:149], v[248:249], 0, s[66:67]
	s_mov_b32 m0, vcc_hi
	v_lshl_add_u64 v[250:251], s[6:7], 0, v[130:131]
	s_add_u32 s14, s6, 0x100100
	ds_read_b128 v[62:65], v165 offset:16384
	ds_read_b128 v[86:89], v165 offset:17408
	ds_read_b128 v[98:101], v165 offset:18432
	ds_read_b128 v[102:105], v165 offset:19456
	ds_read_b128 v[114:117], v165 offset:20480
	ds_read_b128 v[118:121], v165 offset:21504
	ds_read_b128 v[122:125], v165 offset:22528
	ds_read_b128 v[126:129], v165 offset:23552
	global_load_lds_dwordx4 v[148:149], off
	v_lshl_add_u64 v[148:149], v[250:251], 0, s[66:67]
	s_mov_b32 m0, s84
	s_addc_u32 s15, s7, 0
	s_add_i32 s85, s88, s29
	global_load_lds_dwordx4 v[148:149], off
	v_lshl_add_u64 v[148:149], s[14:15], 0, v[134:135]
	s_mov_b32 m0, s85
	s_add_i32 s46, s85, 0x2000
	global_load_lds_dwordx4 v[148:149], off
	v_lshl_add_u64 v[148:149], s[14:15], 0, v[130:131]
	s_mov_b32 m0, s46
	v_lshl_add_u64 v[252:253], s[80:81], 0, v[136:137]
	global_load_lds_dwordx4 v[148:149], off
	v_lshl_add_u64 v[148:149], v[252:253], 0, s[66:67]
	s_mov_b32 m0, s86
	v_lshl_add_u64 v[144:145], s[80:81], 0, v[132:133]
	global_load_lds_dwordx4 v[148:149], off
	v_lshl_add_u64 v[148:149], v[144:145], 0, s[66:67]
	s_mov_b32 m0, s93
	s_nop 0
	global_load_lds_dwordx4 v[148:149], off
	s_waitcnt vmcnt(8)
	s_waitcnt lgkmcnt(0)
	s_barrier
	s_setprio 1
	v_mfma_f32_16x16x32_bf16 v[148:151], v[2:5], v[62:65], 0
	v_mfma_f32_16x16x32_bf16 v[158:161], v[2:5], v[98:101], 0
	v_mfma_f32_16x16x32_bf16 v[172:175], v[2:5], v[114:117], 0
	v_mfma_f32_16x16x32_bf16 v[2:5], v[2:5], v[122:125], 0
	v_mfma_f32_16x16x32_bf16 v[150:153], v[6:9], v[86:89], v[148:151]
	v_mfma_f32_16x16x32_bf16 v[158:161], v[6:9], v[102:105], v[158:161]
	v_mfma_f32_16x16x32_bf16 v[172:175], v[6:9], v[118:121], v[172:175]
	v_mfma_f32_16x16x32_bf16 v[2:5], v[6:9], v[126:129], v[2:5]
	v_mfma_f32_16x16x32_bf16 v[6:9], v[10:13], v[122:125], 0
	v_mfma_f32_16x16x32_bf16 v[154:157], v[10:13], v[62:65], 0
	v_mfma_f32_16x16x32_bf16 v[168:171], v[10:13], v[98:101], 0
	v_mfma_f32_16x16x32_bf16 v[176:179], v[10:13], v[114:117], 0
	v_mfma_f32_16x16x32_bf16 v[10:13], v[14:17], v[126:129], v[6:9]
	v_mfma_f32_16x16x32_bf16 v[154:157], v[14:17], v[86:89], v[154:157]
	v_mfma_f32_16x16x32_bf16 v[168:171], v[14:17], v[102:105], v[168:171]
	v_mfma_f32_16x16x32_bf16 v[176:179], v[14:17], v[118:121], v[176:179]
	s_setprio 0
	s_setprio 1
	v_mfma_f32_16x16x32_bf16 v[6:9], v[18:21], v[62:65], 0
	v_mfma_f32_16x16x32_bf16 v[14:17], v[22:25], v[86:89], v[6:9]
	v_mfma_f32_16x16x32_bf16 v[6:9], v[26:29], v[62:65], 0
	v_mfma_f32_16x16x32_bf16 v[180:183], v[30:33], v[86:89], v[6:9]
	v_mfma_f32_16x16x32_bf16 v[6:9], v[18:21], v[98:101], 0
	v_mfma_f32_16x16x32_bf16 v[184:187], v[22:25], v[102:105], v[6:9]
	v_mfma_f32_16x16x32_bf16 v[6:9], v[26:29], v[98:101], 0
	v_mfma_f32_16x16x32_bf16 v[188:191], v[30:33], v[102:105], v[6:9]
	v_mfma_f32_16x16x32_bf16 v[6:9], v[18:21], v[114:117], 0
	v_mfma_f32_16x16x32_bf16 v[192:195], v[22:25], v[118:121], v[6:9]
	v_mfma_f32_16x16x32_bf16 v[6:9], v[26:29], v[114:117], 0
	v_mfma_f32_16x16x32_bf16 v[196:199], v[30:33], v[118:121], v[6:9]
	v_mfma_f32_16x16x32_bf16 v[6:9], v[18:21], v[122:125], 0
	v_mfma_f32_16x16x32_bf16 v[200:203], v[22:25], v[126:129], v[6:9]
	v_mfma_f32_16x16x32_bf16 v[6:9], v[26:29], v[122:125], 0
	v_mfma_f32_16x16x32_bf16 v[204:207], v[30:33], v[126:129], v[6:9]
	s_setprio 0
	s_barrier
	s_add_i32 s47, 0, 0x18000
	s_add_i32 s56, 0, 0x1c000
	v_add_u32_e32 v138, s47, v162
	v_add_u32_e32 v148, s56, v162
	s_nop 0
	ds_read_b128 v[6:9], v138
	ds_read_b128 v[26:29], v138 offset:1024
	ds_read_b128 v[30:33], v138 offset:2048
	ds_read_b128 v[62:65], v138 offset:3072
	ds_read_b128 v[208:211], v148
	ds_read_b128 v[212:215], v148 offset:1024
	ds_read_b128 v[216:219], v148 offset:2048
	ds_read_b128 v[220:223], v148 offset:3072
	s_add_u32 s14, s80, 0x100100
	s_addc_u32 s15, s81, 0
	s_mov_b32 m0, s94
	v_lshl_add_u64 v[86:87], s[14:15], 0, v[136:137]
	ds_read_b128 v[18:21], v165 offset:32768
	ds_read_b128 v[22:25], v165 offset:33792
	ds_read_b128 v[224:227], v165 offset:34816
	ds_read_b128 v[228:231], v165 offset:35840
	ds_read_b128 v[232:235], v165 offset:36864
	ds_read_b128 v[236:239], v165 offset:37888
	ds_read_b128 v[240:243], v165 offset:38912
	ds_read_b128 v[244:247], v165 offset:39936
	global_load_lds_dwordx4 v[86:87], off
	v_lshl_add_u64 v[86:87], s[14:15], 0, v[132:133]
	s_mov_b32 m0, s95
	s_nop 0
	global_load_lds_dwordx4 v[86:87], off
	s_waitcnt vmcnt(8)
	s_waitcnt lgkmcnt(0)
	s_barrier
	s_setprio 1
	v_mfma_f32_16x16x32_bf16 v[66:69], v[6:9], v[18:21], v[66:69]
	v_mfma_f32_16x16x32_bf16 v[118:121], v[26:29], v[22:25], v[66:69]
	v_mfma_f32_16x16x32_bf16 v[66:69], v[30:33], v[18:21], v[70:73]
	v_mfma_f32_16x16x32_bf16 v[114:117], v[62:65], v[22:25], v[66:69]
	v_mfma_f32_16x16x32_bf16 v[66:69], v[6:9], v[224:227], v[74:77]
	v_mfma_f32_16x16x32_bf16 v[102:105], v[26:29], v[228:231], v[66:69]
	v_mfma_f32_16x16x32_bf16 v[66:69], v[30:33], v[224:227], v[78:81]
	v_mfma_f32_16x16x32_bf16 v[98:101], v[62:65], v[228:231], v[66:69]
	v_mfma_f32_16x16x32_bf16 v[66:69], v[6:9], v[232:235], v[82:85]
	v_mfma_f32_16x16x32_bf16 v[86:89], v[26:29], v[236:239], v[66:69]
	v_mfma_f32_16x16x32_bf16 v[66:69], v[30:33], v[232:235], v[90:93]
	v_mfma_f32_16x16x32_bf16 v[82:85], v[62:65], v[236:239], v[66:69]
	v_mfma_f32_16x16x32_bf16 v[66:69], v[6:9], v[240:243], v[94:97]
	v_mfma_f32_16x16x32_bf16 v[70:73], v[26:29], v[244:247], v[66:69]
	v_mfma_f32_16x16x32_bf16 v[66:69], v[30:33], v[240:243], v[106:109]
	v_mfma_f32_16x16x32_bf16 v[66:69], v[62:65], v[244:247], v[66:69]
	s_setprio 0
	s_setprio 1
	v_mfma_f32_16x16x32_bf16 v[74:77], v[208:211], v[18:21], v[110:113]
	v_mfma_f32_16x16x32_bf16 v[18:21], v[216:219], v[18:21], v[34:37]
	v_mfma_f32_16x16x32_bf16 v[122:125], v[220:223], v[22:25], v[18:21]
	v_mfma_f32_16x16x32_bf16 v[18:21], v[208:211], v[224:227], v[38:41]
	v_mfma_f32_16x16x32_bf16 v[110:113], v[212:215], v[228:231], v[18:21]
	v_mfma_f32_16x16x32_bf16 v[18:21], v[216:219], v[224:227], v[42:45]
	v_mfma_f32_16x16x32_bf16 v[106:109], v[220:223], v[228:231], v[18:21]
	v_mfma_f32_16x16x32_bf16 v[18:21], v[208:211], v[232:235], v[46:49]
	v_mfma_f32_16x16x32_bf16 v[94:97], v[212:215], v[236:239], v[18:21]
	v_mfma_f32_16x16x32_bf16 v[18:21], v[216:219], v[232:235], v[50:53]
	v_mfma_f32_16x16x32_bf16 v[90:93], v[220:223], v[236:239], v[18:21]
	v_mfma_f32_16x16x32_bf16 v[18:21], v[208:211], v[240:243], v[54:57]
	v_mfma_f32_16x16x32_bf16 v[78:81], v[212:215], v[244:247], v[18:21]
	v_mfma_f32_16x16x32_bf16 v[18:21], v[216:219], v[240:243], v[58:61]
	v_mfma_f32_16x16x32_bf16 v[126:129], v[212:215], v[22:25], v[74:77]
	v_mfma_f32_16x16x32_bf16 v[74:77], v[220:223], v[244:247], v[18:21]
	s_setprio 0
	s_barrier
	s_add_i32 s47, s47, s29
	s_add_i32 s91, s47, 0x2000
	s_nop 1
	v_lshl_add_u64 v[18:19], v[248:249], 0, s[68:69]
	s_mov_b32 m0, s47
	s_add_u32 s14, s6, 0x100180
	ds_read_b128 v[42:45], v165 offset:49152
	ds_read_b128 v[46:49], v165 offset:50176
	ds_read_b128 v[224:227], v165 offset:51200
	ds_read_b128 v[228:231], v165 offset:52224
	ds_read_b128 v[232:235], v165 offset:53248
	ds_read_b128 v[236:239], v165 offset:54272
	ds_read_b128 v[240:243], v165 offset:55296
	ds_read_b128 v[244:247], v165 offset:56320
	global_load_lds_dwordx4 v[18:19], off
	v_lshl_add_u64 v[18:19], v[250:251], 0, s[68:69]
	s_mov_b32 m0, s91
	s_addc_u32 s15, s7, 0
	s_add_i32 s56, s56, s29
	global_load_lds_dwordx4 v[18:19], off
	v_lshl_add_u64 v[18:19], s[14:15], 0, v[134:135]
	s_mov_b32 m0, s56
	s_add_i32 s57, s56, 0x2000
	global_load_lds_dwordx4 v[18:19], off
	v_lshl_add_u64 v[18:19], s[14:15], 0, v[130:131]
	s_mov_b32 m0, s57
	s_nop 0
	global_load_lds_dwordx4 v[18:19], off
	v_lshl_add_u64 v[18:19], v[252:253], 0, s[68:69]
	s_mov_b32 m0, s96
	s_nop 0
	global_load_lds_dwordx4 v[18:19], off
	v_lshl_add_u64 v[18:19], v[144:145], 0, s[68:69]
	s_mov_b32 m0, s97
	s_nop 0
	global_load_lds_dwordx4 v[18:19], off
	s_waitcnt vmcnt(8)
	s_waitcnt lgkmcnt(0)
	s_barrier
	s_setprio 1
	v_mfma_f32_16x16x32_bf16 v[18:21], v[6:9], v[42:45], v[150:153]
	v_mfma_f32_16x16x32_bf16 v[54:57], v[26:29], v[46:49], v[18:21]
	v_mfma_f32_16x16x32_bf16 v[18:21], v[30:33], v[42:45], v[154:157]
	v_mfma_f32_16x16x32_bf16 v[50:53], v[62:65], v[46:49], v[18:21]
	v_mfma_f32_16x16x32_bf16 v[18:21], v[6:9], v[224:227], v[158:161]
	v_mfma_f32_16x16x32_bf16 v[38:41], v[26:29], v[228:231], v[18:21]
	v_mfma_f32_16x16x32_bf16 v[18:21], v[30:33], v[224:227], v[168:171]
	v_mfma_f32_16x16x32_bf16 v[34:37], v[62:65], v[228:231], v[18:21]
	v_mfma_f32_16x16x32_bf16 v[18:21], v[6:9], v[232:235], v[172:175]
	v_mfma_f32_16x16x32_bf16 v[2:5], v[6:9], v[240:243], v[2:5]
	v_mfma_f32_16x16x32_bf16 v[22:25], v[26:29], v[236:239], v[18:21]
	v_mfma_f32_16x16x32_bf16 v[18:21], v[30:33], v[232:235], v[176:179]
	v_mfma_f32_16x16x32_bf16 v[6:9], v[26:29], v[244:247], v[2:5]
	v_mfma_f32_16x16x32_bf16 v[2:5], v[30:33], v[240:243], v[10:13]
	v_mfma_f32_16x16x32_bf16 v[18:21], v[62:65], v[236:239], v[18:21]
	v_mfma_f32_16x16x32_bf16 v[2:5], v[62:65], v[244:247], v[2:5]
	s_setprio 0
	s_setprio 1
	v_mfma_f32_16x16x32_bf16 v[10:13], v[208:211], v[42:45], v[14:17]
	v_mfma_f32_16x16x32_bf16 v[62:65], v[212:215], v[46:49], v[10:13]
	v_mfma_f32_16x16x32_bf16 v[10:13], v[216:219], v[42:45], v[180:183]
	v_mfma_f32_16x16x32_bf16 v[58:61], v[220:223], v[46:49], v[10:13]
	v_mfma_f32_16x16x32_bf16 v[10:13], v[208:211], v[224:227], v[184:187]
	v_mfma_f32_16x16x32_bf16 v[46:49], v[212:215], v[228:231], v[10:13]
	v_mfma_f32_16x16x32_bf16 v[10:13], v[216:219], v[224:227], v[188:191]
	v_mfma_f32_16x16x32_bf16 v[42:45], v[220:223], v[228:231], v[10:13]
	v_mfma_f32_16x16x32_bf16 v[10:13], v[208:211], v[232:235], v[192:195]
	v_mfma_f32_16x16x32_bf16 v[30:33], v[212:215], v[236:239], v[10:13]
	v_mfma_f32_16x16x32_bf16 v[10:13], v[216:219], v[232:235], v[196:199]
	v_mfma_f32_16x16x32_bf16 v[26:29], v[220:223], v[236:239], v[10:13]
	v_mfma_f32_16x16x32_bf16 v[10:13], v[208:211], v[240:243], v[200:203]
	v_mfma_f32_16x16x32_bf16 v[14:17], v[212:215], v[244:247], v[10:13]
	v_mfma_f32_16x16x32_bf16 v[10:13], v[216:219], v[240:243], v[204:207]
	v_mfma_f32_16x16x32_bf16 v[10:13], v[220:223], v[244:247], v[10:13]
	s_setprio 0
	s_barrier
	s_add_u32 s80, s80, 0x100180
	s_addc_u32 s81, s81, 0
	s_add_u32 s30, s6, 0x200
	s_addc_u32 s14, s7, 0
	s_mov_b32 s15, 0
.LBB0_415:
	ds_read_b128 v[150:153], v163
	ds_read_b128 v[154:157], v163 offset:1024
	ds_read_b128 v[158:161], v163 offset:2048
	ds_read_b128 v[168:171], v163 offset:3072
	ds_read_b128 v[172:175], v164
	ds_read_b128 v[176:179], v164 offset:1024
	ds_read_b128 v[180:183], v164 offset:2048
	ds_read_b128 v[184:187], v164 offset:3072
	s_add_u32 s6, s80, 0xfff00080
	s_addc_u32 s7, s81, -1
	s_cmp_eq_u32 s15, 60
	s_cselect_b32 s83, s1, s7
	s_cselect_b32 s82, s75, s6
	s_cselect_b32 s7, s18, s14
	s_cselect_b32 s6, vcc_lo, s30
	s_mov_b32 m0, s89
	ds_read_b128 v[188:191], v165
	ds_read_b128 v[192:195], v165 offset:1024
	ds_read_b128 v[196:199], v165 offset:2048
	ds_read_b128 v[200:203], v165 offset:3072
	ds_read_b128 v[204:207], v165 offset:4096
	ds_read_b128 v[208:211], v165 offset:5120
	ds_read_b128 v[212:215], v165 offset:6144
	ds_read_b128 v[216:219], v165 offset:7168
	global_load_lds_dwordx4 v140, s[80:81]
	s_mov_b32 m0, s92
	s_nop 0
	global_load_lds_dwordx4 v142, s[80:81]
	s_waitcnt vmcnt(8)
	s_waitcnt lgkmcnt(0)
	s_barrier
	s_setprio 1
	v_mfma_f32_16x16x32_bf16 v[118:121], v[150:153], v[188:191], v[118:121]
	v_mfma_f32_16x16x32_bf16 v[114:117], v[158:161], v[188:191], v[114:117]
	v_mfma_f32_16x16x32_bf16 v[102:105], v[150:153], v[196:199], v[102:105]
	v_mfma_f32_16x16x32_bf16 v[98:101], v[158:161], v[196:199], v[98:101]
	v_mfma_f32_16x16x32_bf16 v[86:89], v[150:153], v[204:207], v[86:89]
	v_mfma_f32_16x16x32_bf16 v[82:85], v[158:161], v[204:207], v[82:85]
	v_mfma_f32_16x16x32_bf16 v[70:73], v[150:153], v[212:215], v[70:73]
	v_mfma_f32_16x16x32_bf16 v[66:69], v[158:161], v[212:215], v[66:69]
	v_mfma_f32_16x16x32_bf16 v[118:121], v[154:157], v[192:195], v[118:121]
	v_mfma_f32_16x16x32_bf16 v[114:117], v[168:171], v[192:195], v[114:117]
	v_mfma_f32_16x16x32_bf16 v[102:105], v[154:157], v[200:203], v[102:105]
	v_mfma_f32_16x16x32_bf16 v[98:101], v[168:171], v[200:203], v[98:101]
	v_mfma_f32_16x16x32_bf16 v[86:89], v[154:157], v[208:211], v[86:89]
	v_mfma_f32_16x16x32_bf16 v[82:85], v[168:171], v[208:211], v[82:85]
	v_mfma_f32_16x16x32_bf16 v[70:73], v[154:157], v[216:219], v[70:73]
	v_mfma_f32_16x16x32_bf16 v[66:69], v[168:171], v[216:219], v[66:69]
	s_setprio 0
	s_setprio 1
	v_mfma_f32_16x16x32_bf16 v[126:129], v[172:175], v[188:191], v[126:129]
	v_mfma_f32_16x16x32_bf16 v[122:125], v[180:183], v[188:191], v[122:125]
	v_mfma_f32_16x16x32_bf16 v[110:113], v[172:175], v[196:199], v[110:113]
	v_mfma_f32_16x16x32_bf16 v[106:109], v[180:183], v[196:199], v[106:109]
	v_mfma_f32_16x16x32_bf16 v[94:97], v[172:175], v[204:207], v[94:97]
	v_mfma_f32_16x16x32_bf16 v[90:93], v[180:183], v[204:207], v[90:93]
	v_mfma_f32_16x16x32_bf16 v[78:81], v[172:175], v[212:215], v[78:81]
	v_mfma_f32_16x16x32_bf16 v[74:77], v[180:183], v[212:215], v[74:77]
	v_mfma_f32_16x16x32_bf16 v[126:129], v[176:179], v[192:195], v[126:129]
	v_mfma_f32_16x16x32_bf16 v[122:125], v[184:187], v[192:195], v[122:125]
	v_mfma_f32_16x16x32_bf16 v[110:113], v[176:179], v[200:203], v[110:113]
	v_mfma_f32_16x16x32_bf16 v[106:109], v[184:187], v[200:203], v[106:109]
	v_mfma_f32_16x16x32_bf16 v[94:97], v[176:179], v[208:211], v[94:97]
	v_mfma_f32_16x16x32_bf16 v[90:93], v[184:187], v[208:211], v[90:93]
	v_mfma_f32_16x16x32_bf16 v[78:81], v[176:179], v[216:219], v[78:81]
	v_mfma_f32_16x16x32_bf16 v[74:77], v[184:187], v[216:219], v[74:77]
	s_setprio 0
	s_barrier
	s_mov_b32 m0, vcc_hi
	s_mov_b64 s[98:99], s[6:7]
	s_add_u32 s16, s6, 0x100000
	ds_read_b128 v[188:191], v165 offset:16384
	ds_read_b128 v[192:195], v165 offset:17408
	ds_read_b128 v[196:199], v165 offset:18432
	ds_read_b128 v[200:203], v165 offset:19456
	ds_read_b128 v[204:207], v165 offset:20480
	ds_read_b128 v[208:211], v165 offset:21504
	ds_read_b128 v[212:215], v165 offset:22528
	ds_read_b128 v[216:219], v165 offset:23552
	global_load_lds_dwordx4 v134, s[6:7]
	s_mov_b32 m0, s84
	s_addc_u32 s17, s7, 0
	global_load_lds_dwordx4 v130, s[6:7]
	s_mov_b32 m0, s85
	s_mov_b64 s[100:101], s[82:83]
	global_load_lds_dwordx4 v134, s[16:17]
	s_mov_b32 m0, s46
	s_nop 0
	global_load_lds_dwordx4 v130, s[16:17]
	s_mov_b32 m0, s86
	s_nop 0
	global_load_lds_dwordx4 v136, s[82:83]
	s_mov_b32 m0, s93
	s_nop 0
	global_load_lds_dwordx4 v132, s[82:83]
	s_waitcnt vmcnt(8)
	s_waitcnt lgkmcnt(0)
	s_barrier
	s_setprio 1
	v_mfma_f32_16x16x32_bf16 v[54:57], v[150:153], v[188:191], v[54:57]
	v_mfma_f32_16x16x32_bf16 v[50:53], v[158:161], v[188:191], v[50:53]
	v_mfma_f32_16x16x32_bf16 v[38:41], v[150:153], v[196:199], v[38:41]
	v_mfma_f32_16x16x32_bf16 v[34:37], v[158:161], v[196:199], v[34:37]
	v_mfma_f32_16x16x32_bf16 v[22:25], v[150:153], v[204:207], v[22:25]
	v_mfma_f32_16x16x32_bf16 v[18:21], v[158:161], v[204:207], v[18:21]
	v_mfma_f32_16x16x32_bf16 v[6:9], v[150:153], v[212:215], v[6:9]
	v_mfma_f32_16x16x32_bf16 v[2:5], v[158:161], v[212:215], v[2:5]
	v_mfma_f32_16x16x32_bf16 v[54:57], v[154:157], v[192:195], v[54:57]
	v_mfma_f32_16x16x32_bf16 v[50:53], v[168:171], v[192:195], v[50:53]
	v_mfma_f32_16x16x32_bf16 v[38:41], v[154:157], v[200:203], v[38:41]
	v_mfma_f32_16x16x32_bf16 v[34:37], v[168:171], v[200:203], v[34:37]
	v_mfma_f32_16x16x32_bf16 v[22:25], v[154:157], v[208:211], v[22:25]
	v_mfma_f32_16x16x32_bf16 v[18:21], v[168:171], v[208:211], v[18:21]
	v_mfma_f32_16x16x32_bf16 v[6:9], v[154:157], v[216:219], v[6:9]
	v_mfma_f32_16x16x32_bf16 v[2:5], v[168:171], v[216:219], v[2:5]
	s_setprio 0
	s_setprio 1
	v_mfma_f32_16x16x32_bf16 v[62:65], v[172:175], v[188:191], v[62:65]
	v_mfma_f32_16x16x32_bf16 v[58:61], v[180:183], v[188:191], v[58:61]
	v_mfma_f32_16x16x32_bf16 v[46:49], v[172:175], v[196:199], v[46:49]
	v_mfma_f32_16x16x32_bf16 v[42:45], v[180:183], v[196:199], v[42:45]
	v_mfma_f32_16x16x32_bf16 v[30:33], v[172:175], v[204:207], v[30:33]
	v_mfma_f32_16x16x32_bf16 v[26:29], v[180:183], v[204:207], v[26:29]
	v_mfma_f32_16x16x32_bf16 v[14:17], v[172:175], v[212:215], v[14:17]
	v_mfma_f32_16x16x32_bf16 v[10:13], v[180:183], v[212:215], v[10:13]
	v_mfma_f32_16x16x32_bf16 v[62:65], v[176:179], v[192:195], v[62:65]
	v_mfma_f32_16x16x32_bf16 v[58:61], v[184:187], v[192:195], v[58:61]
	v_mfma_f32_16x16x32_bf16 v[46:49], v[176:179], v[200:203], v[46:49]
	v_mfma_f32_16x16x32_bf16 v[42:45], v[184:187], v[200:203], v[42:45]
	v_mfma_f32_16x16x32_bf16 v[30:33], v[176:179], v[208:211], v[30:33]
	v_mfma_f32_16x16x32_bf16 v[26:29], v[184:187], v[208:211], v[26:29]
	v_mfma_f32_16x16x32_bf16 v[14:17], v[176:179], v[216:219], v[14:17]
	v_mfma_f32_16x16x32_bf16 v[10:13], v[184:187], v[216:219], v[10:13]
	s_setprio 0
	s_barrier
; #define PG8_BAR __builtin_amdgcn_s_barrier()
;     ...
;         for (int t = 2; t < nt; t += 2) PG8_KITER(t);
;         if constexpr (ALIGN_EPI) { if (wr == 0) PG8_BAR; }
	ds_read_b128 v[150:153], v138
	ds_read_b128 v[154:157], v138 offset:1024
	ds_read_b128 v[158:161], v138 offset:2048
	ds_read_b128 v[168:171], v138 offset:3072
	ds_read_b128 v[172:175], v148
	ds_read_b128 v[176:179], v148 offset:1024
	ds_read_b128 v[180:183], v148 offset:2048
	ds_read_b128 v[184:187], v148 offset:3072
	s_add_u32 s16, s82, 0x100000
	s_addc_u32 s17, s83, 0
	s_mov_b32 m0, s94
	ds_read_b128 v[188:191], v165 offset:32768
	ds_read_b128 v[192:195], v165 offset:33792
	ds_read_b128 v[196:199], v165 offset:34816
	ds_read_b128 v[200:203], v165 offset:35840
	ds_read_b128 v[204:207], v165 offset:36864
	ds_read_b128 v[208:211], v165 offset:37888
	ds_read_b128 v[212:215], v165 offset:38912
	ds_read_b128 v[216:219], v165 offset:39936
	global_load_lds_dwordx4 v136, s[16:17]
	s_mov_b32 m0, s95
	s_nop 0
	global_load_lds_dwordx4 v132, s[16:17]
	s_waitcnt vmcnt(8)
	s_waitcnt lgkmcnt(0)
	s_barrier
	s_setprio 1
	v_mfma_f32_16x16x32_bf16 v[118:121], v[150:153], v[188:191], v[118:121]
	v_mfma_f32_16x16x32_bf16 v[114:117], v[158:161], v[188:191], v[114:117]
	v_mfma_f32_16x16x32_bf16 v[102:105], v[150:153], v[196:199], v[102:105]
	v_mfma_f32_16x16x32_bf16 v[98:101], v[158:161], v[196:199], v[98:101]
	v_mfma_f32_16x16x32_bf16 v[86:89], v[150:153], v[204:207], v[86:89]
	v_mfma_f32_16x16x32_bf16 v[82:85], v[158:161], v[204:207], v[82:85]
	v_mfma_f32_16x16x32_bf16 v[70:73], v[150:153], v[212:215], v[70:73]
	v_mfma_f32_16x16x32_bf16 v[66:69], v[158:161], v[212:215], v[66:69]
	v_mfma_f32_16x16x32_bf16 v[118:121], v[154:157], v[192:195], v[118:121]
	v_mfma_f32_16x16x32_bf16 v[114:117], v[168:171], v[192:195], v[114:117]
	v_mfma_f32_16x16x32_bf16 v[102:105], v[154:157], v[200:203], v[102:105]
	v_mfma_f32_16x16x32_bf16 v[98:101], v[168:171], v[200:203], v[98:101]
	v_mfma_f32_16x16x32_bf16 v[86:89], v[154:157], v[208:211], v[86:89]
	v_mfma_f32_16x16x32_bf16 v[82:85], v[168:171], v[208:211], v[82:85]
	v_mfma_f32_16x16x32_bf16 v[70:73], v[154:157], v[216:219], v[70:73]
	v_mfma_f32_16x16x32_bf16 v[66:69], v[168:171], v[216:219], v[66:69]
	s_setprio 0
	s_setprio 1
	v_mfma_f32_16x16x32_bf16 v[126:129], v[172:175], v[188:191], v[126:129]
	v_mfma_f32_16x16x32_bf16 v[122:125], v[180:183], v[188:191], v[122:125]
	v_mfma_f32_16x16x32_bf16 v[110:113], v[172:175], v[196:199], v[110:113]
	v_mfma_f32_16x16x32_bf16 v[106:109], v[180:183], v[196:199], v[106:109]
	v_mfma_f32_16x16x32_bf16 v[94:97], v[172:175], v[204:207], v[94:97]
	v_mfma_f32_16x16x32_bf16 v[90:93], v[180:183], v[204:207], v[90:93]
	v_mfma_f32_16x16x32_bf16 v[78:81], v[172:175], v[212:215], v[78:81]
	v_mfma_f32_16x16x32_bf16 v[74:77], v[180:183], v[212:215], v[74:77]
	v_mfma_f32_16x16x32_bf16 v[126:129], v[176:179], v[192:195], v[126:129]
	v_mfma_f32_16x16x32_bf16 v[122:125], v[184:187], v[192:195], v[122:125]
	v_mfma_f32_16x16x32_bf16 v[110:113], v[176:179], v[200:203], v[110:113]
	v_mfma_f32_16x16x32_bf16 v[106:109], v[184:187], v[200:203], v[106:109]
	v_mfma_f32_16x16x32_bf16 v[94:97], v[176:179], v[208:211], v[94:97]
	v_mfma_f32_16x16x32_bf16 v[90:93], v[184:187], v[208:211], v[90:93]
	v_mfma_f32_16x16x32_bf16 v[78:81], v[176:179], v[216:219], v[78:81]
	v_mfma_f32_16x16x32_bf16 v[74:77], v[184:187], v[216:219], v[74:77]
	s_setprio 0
	s_barrier
	s_mov_b32 m0, s47
	s_add_u32 s98, s98, 0x80
	s_addc_u32 s99, s99, 0
	s_add_u32 s100, s100, 0x80
	s_addc_u32 s101, s101, 0
	s_add_u32 s6, s6, 0x100080
	ds_read_b128 v[188:191], v165 offset:49152
	ds_read_b128 v[192:195], v165 offset:50176
	ds_read_b128 v[196:199], v165 offset:51200
	ds_read_b128 v[200:203], v165 offset:52224
	ds_read_b128 v[204:207], v165 offset:53248
	ds_read_b128 v[208:211], v165 offset:54272
	ds_read_b128 v[212:215], v165 offset:55296
	ds_read_b128 v[216:219], v165 offset:56320
	global_load_lds_dwordx4 v134, s[98:99]
	s_mov_b32 m0, s91
	s_addc_u32 s7, s7, 0
	global_load_lds_dwordx4 v130, s[98:99]
	s_mov_b32 m0, s56
	s_nop 0
	global_load_lds_dwordx4 v134, s[6:7]
	s_mov_b32 m0, s57
	s_nop 0
	global_load_lds_dwordx4 v130, s[6:7]
	s_mov_b32 m0, s96
	s_nop 0
	global_load_lds_dwordx4 v136, s[100:101]
	s_mov_b32 m0, s97
	s_nop 0
	global_load_lds_dwordx4 v132, s[100:101]
	s_waitcnt vmcnt(8)
	s_waitcnt lgkmcnt(0)
	s_barrier
	s_setprio 1
	v_mfma_f32_16x16x32_bf16 v[54:57], v[150:153], v[188:191], v[54:57]
	v_mfma_f32_16x16x32_bf16 v[50:53], v[158:161], v[188:191], v[50:53]
	v_mfma_f32_16x16x32_bf16 v[38:41], v[150:153], v[196:199], v[38:41]
	v_mfma_f32_16x16x32_bf16 v[34:37], v[158:161], v[196:199], v[34:37]
	v_mfma_f32_16x16x32_bf16 v[22:25], v[150:153], v[204:207], v[22:25]
	v_mfma_f32_16x16x32_bf16 v[18:21], v[158:161], v[204:207], v[18:21]
	v_mfma_f32_16x16x32_bf16 v[6:9], v[150:153], v[212:215], v[6:9]
	v_mfma_f32_16x16x32_bf16 v[2:5], v[158:161], v[212:215], v[2:5]
	v_mfma_f32_16x16x32_bf16 v[54:57], v[154:157], v[192:195], v[54:57]
	v_mfma_f32_16x16x32_bf16 v[50:53], v[168:171], v[192:195], v[50:53]
	v_mfma_f32_16x16x32_bf16 v[38:41], v[154:157], v[200:203], v[38:41]
	v_mfma_f32_16x16x32_bf16 v[34:37], v[168:171], v[200:203], v[34:37]
	v_mfma_f32_16x16x32_bf16 v[22:25], v[154:157], v[208:211], v[22:25]
	v_mfma_f32_16x16x32_bf16 v[18:21], v[168:171], v[208:211], v[18:21]
	v_mfma_f32_16x16x32_bf16 v[6:9], v[154:157], v[216:219], v[6:9]
	v_mfma_f32_16x16x32_bf16 v[2:5], v[168:171], v[216:219], v[2:5]
	s_setprio 0
	s_setprio 1
	v_mfma_f32_16x16x32_bf16 v[62:65], v[172:175], v[188:191], v[62:65]
	v_mfma_f32_16x16x32_bf16 v[58:61], v[180:183], v[188:191], v[58:61]
	v_mfma_f32_16x16x32_bf16 v[46:49], v[172:175], v[196:199], v[46:49]
	v_mfma_f32_16x16x32_bf16 v[42:45], v[180:183], v[196:199], v[42:45]
	v_mfma_f32_16x16x32_bf16 v[30:33], v[172:175], v[204:207], v[30:33]
	v_mfma_f32_16x16x32_bf16 v[26:29], v[180:183], v[204:207], v[26:29]
	v_mfma_f32_16x16x32_bf16 v[14:17], v[172:175], v[212:215], v[14:17]
	v_mfma_f32_16x16x32_bf16 v[10:13], v[180:183], v[212:215], v[10:13]
	v_mfma_f32_16x16x32_bf16 v[62:65], v[176:179], v[192:195], v[62:65]
	v_mfma_f32_16x16x32_bf16 v[58:61], v[184:187], v[192:195], v[58:61]
	v_mfma_f32_16x16x32_bf16 v[46:49], v[176:179], v[200:203], v[46:49]
	v_mfma_f32_16x16x32_bf16 v[42:45], v[184:187], v[200:203], v[42:45]
	v_mfma_f32_16x16x32_bf16 v[30:33], v[176:179], v[208:211], v[30:33]
	v_mfma_f32_16x16x32_bf16 v[26:29], v[184:187], v[208:211], v[26:29]
	v_mfma_f32_16x16x32_bf16 v[14:17], v[176:179], v[216:219], v[14:17]
	v_mfma_f32_16x16x32_bf16 v[10:13], v[184:187], v[216:219], v[10:13]
	s_setprio 0
	s_barrier
	s_add_i32 s15, s15, 2
	s_add_u32 s80, s80, 0x100
	s_addc_u32 s81, s81, 0
	s_add_u32 s30, s30, 0x100
	s_addc_u32 s14, s14, 0
	s_cmp_gt_u32 s15, 61
	s_cbranch_scc0 .LBB0_415
	s_and_b64 vcc, exec, s[64:65]
	s_cbranch_vccz .LBB0_418
	s_barrier

;     __host__ __device__ bool next(int i, Unit& u) const { if (!StaticOrder::next(i >> 1, u)) return false; u.seg = i & 1; return true; }
;     ...
;         const bool has_next = S.next(ui + 1, nxt);
;         const char* nA = has_next ? PG8_APTR(nxt) : cA; const char* nB = has_next ? PG8_BPTR(nxt) : cB;
.LBB0_434:
	s_ashr_i32 s67, s66, 31
	ds_read_b128 v[2:5], v141
	ds_read_b128 v[6:9], v141 offset:1024
	ds_read_b128 v[10:13], v141 offset:2048
	ds_read_b128 v[14:17], v141 offset:3072
	ds_read_b128 v[18:21], v142
	ds_read_b128 v[22:25], v142 offset:1024
	ds_read_b128 v[26:29], v142 offset:2048
	ds_read_b128 v[30:33], v142 offset:3072
	s_lshl_b64 s[14:15], s[66:67], 21
	s_add_u32 s70, s11, s14
	s_addc_u32 s71, s12, s15
	s_and_b64 s[14:15], s[68:69], exec
	s_cselect_b32 s9, s71, s79
	s_cselect_b32 s67, s70, s78
	s_and_b32 s18, s94, 0x7fffffff
	s_lshl_b64 s[14:15], s[18:19], 21
	s_add_u32 s74, s13, s14
	s_addc_u32 s75, s29, s15
	s_and_b64 s[14:15], s[68:69], exec
	s_cselect_b32 s18, s75, s77
	s_cselect_b32 s95, s74, s76
	s_add_u32 s14, s78, 0x100080
	s_addc_u32 s15, s79, 0
	s_add_i32 s96, s59, 0xc000
	v_lshl_add_u64 v[66:67], s[14:15], 0, v[132:133]
	s_mov_b32 m0, s96
	s_add_i32 s97, s59, 0xe000
	ds_read_b128 v[34:37], v143
	ds_read_b128 v[38:41], v143 offset:1024
	ds_read_b128 v[42:45], v143 offset:2048
	ds_read_b128 v[46:49], v143 offset:3072
	ds_read_b128 v[50:53], v143 offset:4096
	ds_read_b128 v[54:57], v143 offset:5120
	ds_read_b128 v[58:61], v143 offset:6144
	ds_read_b128 v[62:65], v143 offset:7168
	global_load_lds_dwordx4 v[66:67], off
	v_lshl_add_u64 v[66:67], s[14:15], 0, v[130:131]
	s_mov_b32 m0, s97
	s_nop 0
	global_load_lds_dwordx4 v[66:67], off
	s_waitcnt vmcnt(8)
	s_waitcnt lgkmcnt(0)
	s_barrier
	s_setprio 1
	v_mfma_f32_16x16x32_bf16 v[66:69], v[2:5], v[34:37], 0
	v_mfma_f32_16x16x32_bf16 v[70:73], v[10:13], v[34:37], 0
	v_mfma_f32_16x16x32_bf16 v[74:77], v[2:5], v[42:45], 0
	v_mfma_f32_16x16x32_bf16 v[78:81], v[10:13], v[42:45], 0
	v_mfma_f32_16x16x32_bf16 v[82:85], v[2:5], v[50:53], 0
	v_mfma_f32_16x16x32_bf16 v[86:89], v[10:13], v[50:53], 0
	v_mfma_f32_16x16x32_bf16 v[90:93], v[2:5], v[58:61], 0
	v_mfma_f32_16x16x32_bf16 v[94:97], v[10:13], v[58:61], 0
	v_mfma_f32_16x16x32_bf16 v[66:69], v[6:9], v[38:41], v[66:69]
	v_mfma_f32_16x16x32_bf16 v[70:73], v[14:17], v[38:41], v[70:73]
	v_mfma_f32_16x16x32_bf16 v[74:77], v[6:9], v[46:49], v[74:77]
	v_mfma_f32_16x16x32_bf16 v[78:81], v[14:17], v[46:49], v[78:81]
	v_mfma_f32_16x16x32_bf16 v[82:85], v[6:9], v[54:57], v[82:85]
	v_mfma_f32_16x16x32_bf16 v[86:89], v[14:17], v[54:57], v[86:89]
	v_mfma_f32_16x16x32_bf16 v[90:93], v[6:9], v[62:65], v[90:93]
	v_mfma_f32_16x16x32_bf16 v[94:97], v[14:17], v[62:65], v[94:97]
	s_setprio 0
	s_setprio 1
	v_mfma_f32_16x16x32_bf16 v[98:101], v[18:21], v[34:37], 0
	v_mfma_f32_16x16x32_bf16 v[34:37], v[26:29], v[34:37], 0
	v_mfma_f32_16x16x32_bf16 v[102:105], v[30:33], v[38:41], v[34:37]
	v_mfma_f32_16x16x32_bf16 v[34:37], v[18:21], v[42:45], 0
	v_mfma_f32_16x16x32_bf16 v[106:109], v[22:25], v[46:49], v[34:37]
	v_mfma_f32_16x16x32_bf16 v[34:37], v[26:29], v[42:45], 0
	v_mfma_f32_16x16x32_bf16 v[42:45], v[30:33], v[46:49], v[34:37]
	v_mfma_f32_16x16x32_bf16 v[34:37], v[18:21], v[50:53], 0
	v_mfma_f32_16x16x32_bf16 v[46:49], v[22:25], v[54:57], v[34:37]
	v_mfma_f32_16x16x32_bf16 v[34:37], v[26:29], v[50:53], 0
	v_mfma_f32_16x16x32_bf16 v[50:53], v[30:33], v[54:57], v[34:37]
	v_mfma_f32_16x16x32_bf16 v[34:37], v[18:21], v[58:61], 0
	v_mfma_f32_16x16x32_bf16 v[110:113], v[22:25], v[62:65], v[34:37]
	v_mfma_f32_16x16x32_bf16 v[34:37], v[26:29], v[58:61], 0
	v_mfma_f32_16x16x32_bf16 v[98:101], v[22:25], v[38:41], v[98:101]
	v_mfma_f32_16x16x32_bf16 v[58:61], v[30:33], v[62:65], v[34:37]
	s_setprio 0
	s_barrier
	s_add_i32 vcc_lo, s91, s33
	v_lshl_add_u64 v[246:247], s[76:77], 0, v[132:133]
	s_add_i32 s84, vcc_lo, 0x2000
	v_lshl_add_u64 v[144:145], v[246:247], 0, s[62:63]
	s_mov_b32 m0, vcc_lo
	v_lshl_add_u64 v[248:249], s[76:77], 0, v[130:131]
	s_add_u32 s14, s76, 0x100100
	ds_read_b128 v[34:37], v143 offset:16384
	ds_read_b128 v[38:41], v143 offset:17408
	ds_read_b128 v[54:57], v143 offset:18432
	ds_read_b128 v[62:65], v143 offset:19456
	ds_read_b128 v[114:117], v143 offset:20480
	ds_read_b128 v[118:121], v143 offset:21504
	ds_read_b128 v[122:125], v143 offset:22528
	ds_read_b128 v[126:129], v143 offset:23552
	global_load_lds_dwordx4 v[144:145], off
	v_lshl_add_u64 v[144:145], v[248:249], 0, s[62:63]
	s_mov_b32 m0, s84
	s_addc_u32 s15, s77, 0
	s_add_i32 s85, s92, s33
	global_load_lds_dwordx4 v[144:145], off
	v_lshl_add_u64 v[144:145], s[14:15], 0, v[132:133]
	s_mov_b32 m0, s85
	s_add_i32 s46, s85, 0x2000
	global_load_lds_dwordx4 v[144:145], off
	v_lshl_add_u64 v[144:145], s[14:15], 0, v[130:131]
	s_mov_b32 m0, s46
	v_lshl_add_u64 v[250:251], s[78:79], 0, v[132:133]
	global_load_lds_dwordx4 v[144:145], off
	v_lshl_add_u64 v[144:145], v[250:251], 0, s[62:63]
	s_mov_b32 m0, s59
	v_lshl_add_u64 v[252:253], s[78:79], 0, v[130:131]
	global_load_lds_dwordx4 v[144:145], off
	v_lshl_add_u64 v[144:145], v[252:253], 0, s[62:63]
	s_mov_b32 m0, s82
	s_nop 0
	global_load_lds_dwordx4 v[144:145], off
	s_waitcnt vmcnt(8)
	s_waitcnt lgkmcnt(0)
	s_barrier
	s_setprio 1
	v_mfma_f32_16x16x32_bf16 v[144:147], v[2:5], v[34:37], 0
	v_mfma_f32_16x16x32_bf16 v[154:157], v[2:5], v[54:57], 0
	v_mfma_f32_16x16x32_bf16 v[162:165], v[2:5], v[114:117], 0
	v_mfma_f32_16x16x32_bf16 v[2:5], v[2:5], v[122:125], 0
	v_mfma_f32_16x16x32_bf16 v[150:153], v[10:13], v[34:37], 0
	v_mfma_f32_16x16x32_bf16 v[158:161], v[10:13], v[54:57], 0
	v_mfma_f32_16x16x32_bf16 v[166:169], v[10:13], v[114:117], 0
	v_mfma_f32_16x16x32_bf16 v[170:173], v[6:9], v[126:129], v[2:5]
	v_mfma_f32_16x16x32_bf16 v[2:5], v[10:13], v[122:125], 0
	v_mfma_f32_16x16x32_bf16 v[146:149], v[6:9], v[38:41], v[144:147]
	v_mfma_f32_16x16x32_bf16 v[150:153], v[14:17], v[38:41], v[150:153]
	v_mfma_f32_16x16x32_bf16 v[154:157], v[6:9], v[62:65], v[154:157]
	v_mfma_f32_16x16x32_bf16 v[158:161], v[14:17], v[62:65], v[158:161]
	v_mfma_f32_16x16x32_bf16 v[162:165], v[6:9], v[118:121], v[162:165]
	v_mfma_f32_16x16x32_bf16 v[166:169], v[14:17], v[118:121], v[166:169]
	v_mfma_f32_16x16x32_bf16 v[174:177], v[14:17], v[126:129], v[2:5]
	s_setprio 0
	s_setprio 1
	v_mfma_f32_16x16x32_bf16 v[2:5], v[18:21], v[34:37], 0
	v_mfma_f32_16x16x32_bf16 v[178:181], v[22:25], v[38:41], v[2:5]
	v_mfma_f32_16x16x32_bf16 v[2:5], v[26:29], v[34:37], 0
	v_mfma_f32_16x16x32_bf16 v[182:185], v[30:33], v[38:41], v[2:5]
	v_mfma_f32_16x16x32_bf16 v[2:5], v[18:21], v[54:57], 0
	v_mfma_f32_16x16x32_bf16 v[186:189], v[22:25], v[62:65], v[2:5]
	v_mfma_f32_16x16x32_bf16 v[2:5], v[26:29], v[54:57], 0
	v_mfma_f32_16x16x32_bf16 v[190:193], v[30:33], v[62:65], v[2:5]
	v_mfma_f32_16x16x32_bf16 v[2:5], v[18:21], v[114:117], 0
	v_mfma_f32_16x16x32_bf16 v[194:197], v[22:25], v[118:121], v[2:5]
	v_mfma_f32_16x16x32_bf16 v[2:5], v[26:29], v[114:117], 0
	v_mfma_f32_16x16x32_bf16 v[198:201], v[30:33], v[118:121], v[2:5]
	v_mfma_f32_16x16x32_bf16 v[2:5], v[18:21], v[122:125], 0
	v_mfma_f32_16x16x32_bf16 v[202:205], v[22:25], v[126:129], v[2:5]
	v_mfma_f32_16x16x32_bf16 v[2:5], v[26:29], v[122:125], 0
	v_mfma_f32_16x16x32_bf16 v[206:209], v[30:33], v[126:129], v[2:5]
	s_setprio 0
	s_barrier
	s_add_i32 s47, 0, 0x18000
	s_add_i32 s56, 0, 0x1c000
	v_add_u32_e32 v134, s47, v140
	v_add_u32_e32 v144, s56, v140
	ds_read_b128 v[114:117], v134
	ds_read_b128 v[118:121], v134 offset:1024
	ds_read_b128 v[122:125], v134 offset:2048
	ds_read_b128 v[126:129], v134 offset:3072
	ds_read_b128 v[210:213], v144
	ds_read_b128 v[214:217], v144 offset:1024
	ds_read_b128 v[218:221], v144 offset:2048
	ds_read_b128 v[222:225], v144 offset:3072
	s_add_u32 s14, s78, 0x100100
	s_addc_u32 s15, s79, 0
	s_mov_b32 m0, s83
	v_lshl_add_u64 v[2:3], s[14:15], 0, v[132:133]
	ds_read_b128 v[26:29], v143 offset:32768
	ds_read_b128 v[30:33], v143 offset:33792
	ds_read_b128 v[62:65], v143 offset:34816
	ds_read_b128 v[226:229], v143 offset:35840
	ds_read_b128 v[230:233], v143 offset:36864
	ds_read_b128 v[234:237], v143 offset:37888
	ds_read_b128 v[238:241], v143 offset:38912
	ds_read_b128 v[242:245], v143 offset:39936
	global_load_lds_dwordx4 v[2:3], off
	v_lshl_add_u64 v[2:3], s[14:15], 0, v[130:131]
	s_mov_b32 m0, s86
	s_nop 0
	global_load_lds_dwordx4 v[2:3], off
	s_waitcnt vmcnt(8)
	s_waitcnt lgkmcnt(0)
	s_barrier
	s_setprio 1
	v_mfma_f32_16x16x32_bf16 v[2:5], v[114:117], v[26:29], v[66:69]
	v_mfma_f32_16x16x32_bf16 v[34:37], v[118:121], v[30:33], v[2:5]
	v_mfma_f32_16x16x32_bf16 v[2:5], v[122:125], v[26:29], v[70:73]
	v_mfma_f32_16x16x32_bf16 v[38:41], v[126:129], v[30:33], v[2:5]
	v_mfma_f32_16x16x32_bf16 v[2:5], v[114:117], v[62:65], v[74:77]
	v_mfma_f32_16x16x32_bf16 v[18:21], v[118:121], v[226:229], v[2:5]
	v_mfma_f32_16x16x32_bf16 v[2:5], v[122:125], v[62:65], v[78:81]
	v_mfma_f32_16x16x32_bf16 v[22:25], v[126:129], v[226:229], v[2:5]
	v_mfma_f32_16x16x32_bf16 v[2:5], v[114:117], v[230:233], v[82:85]
	v_mfma_f32_16x16x32_bf16 v[10:13], v[118:121], v[234:237], v[2:5]
	v_mfma_f32_16x16x32_bf16 v[2:5], v[122:125], v[230:233], v[86:89]
	v_mfma_f32_16x16x32_bf16 v[14:17], v[126:129], v[234:237], v[2:5]
	v_mfma_f32_16x16x32_bf16 v[2:5], v[114:117], v[238:241], v[90:93]
	v_mfma_f32_16x16x32_bf16 v[6:9], v[122:125], v[238:241], v[94:97]
	v_mfma_f32_16x16x32_bf16 v[2:5], v[118:121], v[242:245], v[2:5]
	v_mfma_f32_16x16x32_bf16 v[6:9], v[126:129], v[242:245], v[6:9]
	s_setprio 0
	s_setprio 1
	v_mfma_f32_16x16x32_bf16 v[54:57], v[210:213], v[26:29], v[98:101]
	v_mfma_f32_16x16x32_bf16 v[26:29], v[218:221], v[26:29], v[102:105]
	v_mfma_f32_16x16x32_bf16 v[70:73], v[222:225], v[30:33], v[26:29]
	v_mfma_f32_16x16x32_bf16 v[26:29], v[210:213], v[62:65], v[106:109]
	v_mfma_f32_16x16x32_bf16 v[66:69], v[214:217], v[30:33], v[54:57]
	v_mfma_f32_16x16x32_bf16 v[54:57], v[214:217], v[226:229], v[26:29]
	v_mfma_f32_16x16x32_bf16 v[26:29], v[218:221], v[62:65], v[42:45]
	v_mfma_f32_16x16x32_bf16 v[62:65], v[222:225], v[226:229], v[26:29]
	v_mfma_f32_16x16x32_bf16 v[26:29], v[210:213], v[230:233], v[46:49]
	v_mfma_f32_16x16x32_bf16 v[42:45], v[214:217], v[234:237], v[26:29]
	v_mfma_f32_16x16x32_bf16 v[26:29], v[218:221], v[230:233], v[50:53]
	v_mfma_f32_16x16x32_bf16 v[46:49], v[222:225], v[234:237], v[26:29]
	v_mfma_f32_16x16x32_bf16 v[26:29], v[210:213], v[238:241], v[110:113]
	v_mfma_f32_16x16x32_bf16 v[30:33], v[218:221], v[238:241], v[58:61]
	v_mfma_f32_16x16x32_bf16 v[26:29], v[214:217], v[242:245], v[26:29]
	v_mfma_f32_16x16x32_bf16 v[30:33], v[222:225], v[242:245], v[30:33]
	s_setprio 0
	s_barrier
	s_add_i32 s47, s47, s33
	s_add_i32 vcc_hi, s47, 0x2000
	v_lshl_add_u64 v[50:51], v[246:247], 0, s[64:65]
	s_mov_b32 m0, s47
	s_add_u32 s14, s76, 0x100180
	ds_read_b128 v[82:85], v143 offset:49152
	ds_read_b128 v[86:89], v143 offset:50176
	ds_read_b128 v[98:101], v143 offset:51200
	ds_read_b128 v[106:109], v143 offset:52224
	ds_read_b128 v[226:229], v143 offset:53248
	ds_read_b128 v[230:233], v143 offset:54272
	ds_read_b128 v[234:237], v143 offset:55296
	ds_read_b128 v[238:241], v143 offset:56320
	global_load_lds_dwordx4 v[50:51], off
	v_lshl_add_u64 v[50:51], v[248:249], 0, s[64:65]
	s_mov_b32 m0, vcc_hi
	s_addc_u32 s15, s77, 0
	s_add_i32 s56, s56, s33
	global_load_lds_dwordx4 v[50:51], off
	v_lshl_add_u64 v[50:51], s[14:15], 0, v[132:133]
	s_mov_b32 m0, s56
	s_add_i32 s57, s56, 0x2000
	global_load_lds_dwordx4 v[50:51], off
	v_lshl_add_u64 v[50:51], s[14:15], 0, v[130:131]
	s_mov_b32 m0, s57
	s_nop 0
	global_load_lds_dwordx4 v[50:51], off
	v_lshl_add_u64 v[50:51], v[250:251], 0, s[64:65]
	s_mov_b32 m0, s88
	s_nop 0
	global_load_lds_dwordx4 v[50:51], off
	v_lshl_add_u64 v[50:51], v[252:253], 0, s[64:65]
	s_mov_b32 m0, s89
	s_nop 0
	global_load_lds_dwordx4 v[50:51], off
	s_waitcnt vmcnt(8)
	s_waitcnt lgkmcnt(0)
	s_barrier
	s_setprio 1
	v_mfma_f32_16x16x32_bf16 v[50:53], v[114:117], v[82:85], v[146:149]
	v_mfma_f32_16x16x32_bf16 v[102:105], v[118:121], v[86:89], v[50:53]
	v_mfma_f32_16x16x32_bf16 v[50:53], v[122:125], v[82:85], v[150:153]
	v_mfma_f32_16x16x32_bf16 v[110:113], v[126:129], v[86:89], v[50:53]
	v_mfma_f32_16x16x32_bf16 v[50:53], v[114:117], v[98:101], v[154:157]
	v_mfma_f32_16x16x32_bf16 v[90:93], v[118:121], v[106:109], v[50:53]
	v_mfma_f32_16x16x32_bf16 v[50:53], v[122:125], v[98:101], v[158:161]
	v_mfma_f32_16x16x32_bf16 v[94:97], v[126:129], v[106:109], v[50:53]
	v_mfma_f32_16x16x32_bf16 v[50:53], v[114:117], v[226:229], v[162:165]
	v_mfma_f32_16x16x32_bf16 v[74:77], v[118:121], v[230:233], v[50:53]
	v_mfma_f32_16x16x32_bf16 v[50:53], v[122:125], v[226:229], v[166:169]
	v_mfma_f32_16x16x32_bf16 v[78:81], v[126:129], v[230:233], v[50:53]
	v_mfma_f32_16x16x32_bf16 v[50:53], v[114:117], v[234:237], v[170:173]
	v_mfma_f32_16x16x32_bf16 v[58:61], v[122:125], v[234:237], v[174:177]
	v_mfma_f32_16x16x32_bf16 v[50:53], v[118:121], v[238:241], v[50:53]
	v_mfma_f32_16x16x32_bf16 v[58:61], v[126:129], v[238:241], v[58:61]
	s_setprio 0
	s_setprio 1
	v_mfma_f32_16x16x32_bf16 v[114:117], v[210:213], v[82:85], v[178:181]
	v_mfma_f32_16x16x32_bf16 v[82:85], v[218:221], v[82:85], v[182:185]
	v_mfma_f32_16x16x32_bf16 v[126:129], v[222:225], v[86:89], v[82:85]
	v_mfma_f32_16x16x32_bf16 v[82:85], v[210:213], v[98:101], v[186:189]
	v_mfma_f32_16x16x32_bf16 v[122:125], v[214:217], v[86:89], v[114:117]
	v_mfma_f32_16x16x32_bf16 v[114:117], v[214:217], v[106:109], v[82:85]
	v_mfma_f32_16x16x32_bf16 v[82:85], v[218:221], v[98:101], v[190:193]
	v_mfma_f32_16x16x32_bf16 v[118:121], v[222:225], v[106:109], v[82:85]
	v_mfma_f32_16x16x32_bf16 v[82:85], v[210:213], v[226:229], v[194:197]
	v_mfma_f32_16x16x32_bf16 v[98:101], v[214:217], v[230:233], v[82:85]
	v_mfma_f32_16x16x32_bf16 v[82:85], v[218:221], v[226:229], v[198:201]
	v_mfma_f32_16x16x32_bf16 v[106:109], v[222:225], v[230:233], v[82:85]
	v_mfma_f32_16x16x32_bf16 v[82:85], v[210:213], v[234:237], v[202:205]
	v_mfma_f32_16x16x32_bf16 v[86:89], v[218:221], v[234:237], v[206:209]
	v_mfma_f32_16x16x32_bf16 v[82:85], v[214:217], v[238:241], v[82:85]
	v_mfma_f32_16x16x32_bf16 v[86:89], v[222:225], v[238:241], v[86:89]
	s_setprio 0
	s_barrier
	s_add_u32 s78, s78, 0x100180
	s_addc_u32 s79, s79, 0
	s_add_u32 s14, s76, 0x200
	s_addc_u32 s15, s77, 0
	s_mov_b32 s16, 0
.LBB0_435:
	ds_read_b128 v[146:149], v141
	ds_read_b128 v[150:153], v141 offset:1024
	ds_read_b128 v[154:157], v141 offset:2048
	ds_read_b128 v[158:161], v141 offset:3072
	ds_read_b128 v[162:165], v142
	ds_read_b128 v[166:169], v142 offset:1024
	ds_read_b128 v[170:173], v142 offset:2048
	ds_read_b128 v[174:177], v142 offset:3072
	s_add_u32 s17, s78, 0xfff00080
	s_addc_u32 s20, s79, -1
	s_cmp_eq_u32 s16, 60
	s_cselect_b32 s81, s9, s20
	s_cselect_b32 s80, s67, s17
	s_cselect_b32 s77, s18, s15
	s_cselect_b32 s76, s95, s14
	s_mov_b32 m0, s96
	ds_read_b128 v[178:181], v143
	ds_read_b128 v[182:185], v143 offset:1024
	ds_read_b128 v[186:189], v143 offset:2048
	ds_read_b128 v[190:193], v143 offset:3072
	ds_read_b128 v[194:197], v143 offset:4096
	ds_read_b128 v[198:201], v143 offset:5120
	ds_read_b128 v[202:205], v143 offset:6144
	ds_read_b128 v[206:209], v143 offset:7168
	global_load_lds_dwordx4 v136, s[78:79]
	s_mov_b32 m0, s97
	s_nop 0
	global_load_lds_dwordx4 v138, s[78:79]
	s_waitcnt vmcnt(8)
	s_waitcnt lgkmcnt(0)
	s_barrier
	s_setprio 1
	v_mfma_f32_16x16x32_bf16 v[34:37], v[146:149], v[178:181], v[34:37]
	v_mfma_f32_16x16x32_bf16 v[38:41], v[154:157], v[178:181], v[38:41]
	v_mfma_f32_16x16x32_bf16 v[18:21], v[146:149], v[186:189], v[18:21]
	v_mfma_f32_16x16x32_bf16 v[22:25], v[154:157], v[186:189], v[22:25]
	v_mfma_f32_16x16x32_bf16 v[10:13], v[146:149], v[194:197], v[10:13]
	v_mfma_f32_16x16x32_bf16 v[14:17], v[154:157], v[194:197], v[14:17]
	v_mfma_f32_16x16x32_bf16 v[2:5], v[146:149], v[202:205], v[2:5]
	v_mfma_f32_16x16x32_bf16 v[6:9], v[154:157], v[202:205], v[6:9]
	v_mfma_f32_16x16x32_bf16 v[34:37], v[150:153], v[182:185], v[34:37]
	v_mfma_f32_16x16x32_bf16 v[38:41], v[158:161], v[182:185], v[38:41]
	v_mfma_f32_16x16x32_bf16 v[18:21], v[150:153], v[190:193], v[18:21]
	v_mfma_f32_16x16x32_bf16 v[22:25], v[158:161], v[190:193], v[22:25]
	v_mfma_f32_16x16x32_bf16 v[10:13], v[150:153], v[198:201], v[10:13]
	v_mfma_f32_16x16x32_bf16 v[14:17], v[158:161], v[198:201], v[14:17]
	v_mfma_f32_16x16x32_bf16 v[2:5], v[150:153], v[206:209], v[2:5]
	v_mfma_f32_16x16x32_bf16 v[6:9], v[158:161], v[206:209], v[6:9]
	s_setprio 0
	s_setprio 1
	v_mfma_f32_16x16x32_bf16 v[66:69], v[162:165], v[178:181], v[66:69]
	v_mfma_f32_16x16x32_bf16 v[70:73], v[170:173], v[178:181], v[70:73]
	v_mfma_f32_16x16x32_bf16 v[54:57], v[162:165], v[186:189], v[54:57]
	v_mfma_f32_16x16x32_bf16 v[62:65], v[170:173], v[186:189], v[62:65]
	v_mfma_f32_16x16x32_bf16 v[42:45], v[162:165], v[194:197], v[42:45]
	v_mfma_f32_16x16x32_bf16 v[46:49], v[170:173], v[194:197], v[46:49]
	v_mfma_f32_16x16x32_bf16 v[26:29], v[162:165], v[202:205], v[26:29]
	v_mfma_f32_16x16x32_bf16 v[30:33], v[170:173], v[202:205], v[30:33]
	v_mfma_f32_16x16x32_bf16 v[66:69], v[166:169], v[182:185], v[66:69]
	v_mfma_f32_16x16x32_bf16 v[70:73], v[174:177], v[182:185], v[70:73]
	v_mfma_f32_16x16x32_bf16 v[54:57], v[166:169], v[190:193], v[54:57]
	v_mfma_f32_16x16x32_bf16 v[62:65], v[174:177], v[190:193], v[62:65]
	v_mfma_f32_16x16x32_bf16 v[42:45], v[166:169], v[198:201], v[42:45]
	v_mfma_f32_16x16x32_bf16 v[46:49], v[174:177], v[198:201], v[46:49]
	v_mfma_f32_16x16x32_bf16 v[26:29], v[166:169], v[206:209], v[26:29]
	v_mfma_f32_16x16x32_bf16 v[30:33], v[174:177], v[206:209], v[30:33]
	s_setprio 0
	s_barrier
	s_mov_b32 m0, vcc_lo
	s_mov_b64 s[98:99], s[76:77]
	s_add_u32 s20, s76, 0x100000
	ds_read_b128 v[178:181], v143 offset:16384
	ds_read_b128 v[182:185], v143 offset:17408
	ds_read_b128 v[186:189], v143 offset:18432
	ds_read_b128 v[190:193], v143 offset:19456
	ds_read_b128 v[194:197], v143 offset:20480
	ds_read_b128 v[198:201], v143 offset:21504
	ds_read_b128 v[202:205], v143 offset:22528
	ds_read_b128 v[206:209], v143 offset:23552
	global_load_lds_dwordx4 v132, s[76:77]
	s_mov_b32 m0, s84
	s_addc_u32 s21, s77, 0
	global_load_lds_dwordx4 v130, s[76:77]
	s_mov_b32 m0, s85
	s_mov_b64 s[100:101], s[80:81]
	global_load_lds_dwordx4 v132, s[20:21]
	s_mov_b32 m0, s46
	s_nop 0
	global_load_lds_dwordx4 v130, s[20:21]
	s_mov_b32 m0, s59
	s_nop 0
	global_load_lds_dwordx4 v132, s[80:81]
	s_mov_b32 m0, s82
	s_nop 0
	global_load_lds_dwordx4 v130, s[80:81]
	s_waitcnt vmcnt(8)
	s_waitcnt lgkmcnt(0)
	s_barrier
	s_setprio 1
	v_mfma_f32_16x16x32_bf16 v[102:105], v[146:149], v[178:181], v[102:105]
	v_mfma_f32_16x16x32_bf16 v[110:113], v[154:157], v[178:181], v[110:113]
	v_mfma_f32_16x16x32_bf16 v[90:93], v[146:149], v[186:189], v[90:93]
	v_mfma_f32_16x16x32_bf16 v[94:97], v[154:157], v[186:189], v[94:97]
	v_mfma_f32_16x16x32_bf16 v[74:77], v[146:149], v[194:197], v[74:77]
	v_mfma_f32_16x16x32_bf16 v[78:81], v[154:157], v[194:197], v[78:81]
	v_mfma_f32_16x16x32_bf16 v[50:53], v[146:149], v[202:205], v[50:53]
	v_mfma_f32_16x16x32_bf16 v[58:61], v[154:157], v[202:205], v[58:61]
	v_mfma_f32_16x16x32_bf16 v[102:105], v[150:153], v[182:185], v[102:105]
	v_mfma_f32_16x16x32_bf16 v[110:113], v[158:161], v[182:185], v[110:113]
	v_mfma_f32_16x16x32_bf16 v[90:93], v[150:153], v[190:193], v[90:93]
	v_mfma_f32_16x16x32_bf16 v[94:97], v[158:161], v[190:193], v[94:97]
	v_mfma_f32_16x16x32_bf16 v[74:77], v[150:153], v[198:201], v[74:77]
	v_mfma_f32_16x16x32_bf16 v[78:81], v[158:161], v[198:201], v[78:81]
	v_mfma_f32_16x16x32_bf16 v[50:53], v[150:153], v[206:209], v[50:53]
	v_mfma_f32_16x16x32_bf16 v[58:61], v[158:161], v[206:209], v[58:61]
	s_setprio 0
	s_setprio 1
	v_mfma_f32_16x16x32_bf16 v[122:125], v[162:165], v[178:181], v[122:125]
	v_mfma_f32_16x16x32_bf16 v[126:129], v[170:173], v[178:181], v[126:129]
	v_mfma_f32_16x16x32_bf16 v[114:117], v[162:165], v[186:189], v[114:117]
	v_mfma_f32_16x16x32_bf16 v[118:121], v[170:173], v[186:189], v[118:121]
	v_mfma_f32_16x16x32_bf16 v[98:101], v[162:165], v[194:197], v[98:101]
	v_mfma_f32_16x16x32_bf16 v[106:109], v[170:173], v[194:197], v[106:109]
	v_mfma_f32_16x16x32_bf16 v[82:85], v[162:165], v[202:205], v[82:85]
	v_mfma_f32_16x16x32_bf16 v[86:89], v[170:173], v[202:205], v[86:89]
	v_mfma_f32_16x16x32_bf16 v[122:125], v[166:169], v[182:185], v[122:125]
	v_mfma_f32_16x16x32_bf16 v[126:129], v[174:177], v[182:185], v[126:129]
	v_mfma_f32_16x16x32_bf16 v[114:117], v[166:169], v[190:193], v[114:117]
	v_mfma_f32_16x16x32_bf16 v[118:121], v[174:177], v[190:193], v[118:121]
	v_mfma_f32_16x16x32_bf16 v[98:101], v[166:169], v[198:201], v[98:101]
	v_mfma_f32_16x16x32_bf16 v[106:109], v[174:177], v[198:201], v[106:109]
	v_mfma_f32_16x16x32_bf16 v[82:85], v[166:169], v[206:209], v[82:85]
	v_mfma_f32_16x16x32_bf16 v[86:89], v[174:177], v[206:209], v[86:89]
	s_setprio 0
	s_barrier
; #define PG8_BAR __builtin_amdgcn_s_barrier()
;     ...
;         for (int t = 2; t < nt; t += 2) PG8_KITER(t);
;         if constexpr (ALIGN_EPI) { if (wr == 0) PG8_BAR; }
	ds_read_b128 v[146:149], v134
	ds_read_b128 v[150:153], v134 offset:1024
	ds_read_b128 v[154:157], v134 offset:2048
	ds_read_b128 v[158:161], v134 offset:3072
	ds_read_b128 v[162:165], v144
	ds_read_b128 v[166:169], v144 offset:1024
	ds_read_b128 v[170:173], v144 offset:2048
	ds_read_b128 v[174:177], v144 offset:3072
	s_add_u32 s20, s80, 0x100000
	s_addc_u32 s21, s81, 0
	s_mov_b32 m0, s83
	ds_read_b128 v[178:181], v143 offset:32768
	ds_read_b128 v[182:185], v143 offset:33792
	ds_read_b128 v[186:189], v143 offset:34816
	ds_read_b128 v[190:193], v143 offset:35840
	ds_read_b128 v[194:197], v143 offset:36864
	ds_read_b128 v[198:201], v143 offset:37888
	ds_read_b128 v[202:205], v143 offset:38912
	ds_read_b128 v[206:209], v143 offset:39936
	global_load_lds_dwordx4 v132, s[20:21]
	s_mov_b32 m0, s86
	s_nop 0
	global_load_lds_dwordx4 v130, s[20:21]
	s_waitcnt vmcnt(8)
	s_waitcnt lgkmcnt(0)
	s_barrier
	s_setprio 1
	v_mfma_f32_16x16x32_bf16 v[34:37], v[146:149], v[178:181], v[34:37]
	v_mfma_f32_16x16x32_bf16 v[38:41], v[154:157], v[178:181], v[38:41]
	v_mfma_f32_16x16x32_bf16 v[18:21], v[146:149], v[186:189], v[18:21]
	v_mfma_f32_16x16x32_bf16 v[22:25], v[154:157], v[186:189], v[22:25]
	v_mfma_f32_16x16x32_bf16 v[10:13], v[146:149], v[194:197], v[10:13]
	v_mfma_f32_16x16x32_bf16 v[14:17], v[154:157], v[194:197], v[14:17]
	v_mfma_f32_16x16x32_bf16 v[2:5], v[146:149], v[202:205], v[2:5]
	v_mfma_f32_16x16x32_bf16 v[6:9], v[154:157], v[202:205], v[6:9]
	v_mfma_f32_16x16x32_bf16 v[34:37], v[150:153], v[182:185], v[34:37]
	v_mfma_f32_16x16x32_bf16 v[38:41], v[158:161], v[182:185], v[38:41]
	v_mfma_f32_16x16x32_bf16 v[18:21], v[150:153], v[190:193], v[18:21]
	v_mfma_f32_16x16x32_bf16 v[22:25], v[158:161], v[190:193], v[22:25]
	v_mfma_f32_16x16x32_bf16 v[10:13], v[150:153], v[198:201], v[10:13]
	v_mfma_f32_16x16x32_bf16 v[14:17], v[158:161], v[198:201], v[14:17]
	v_mfma_f32_16x16x32_bf16 v[2:5], v[150:153], v[206:209], v[2:5]
	v_mfma_f32_16x16x32_bf16 v[6:9], v[158:161], v[206:209], v[6:9]
	s_setprio 0
	s_setprio 1
	v_mfma_f32_16x16x32_bf16 v[66:69], v[162:165], v[178:181], v[66:69]
	v_mfma_f32_16x16x32_bf16 v[70:73], v[170:173], v[178:181], v[70:73]
	v_mfma_f32_16x16x32_bf16 v[54:57], v[162:165], v[186:189], v[54:57]
	v_mfma_f32_16x16x32_bf16 v[62:65], v[170:173], v[186:189], v[62:65]
	v_mfma_f32_16x16x32_bf16 v[42:45], v[162:165], v[194:197], v[42:45]
	v_mfma_f32_16x16x32_bf16 v[46:49], v[170:173], v[194:197], v[46:49]
	v_mfma_f32_16x16x32_bf16 v[26:29], v[162:165], v[202:205], v[26:29]
	v_mfma_f32_16x16x32_bf16 v[30:33], v[170:173], v[202:205], v[30:33]
	v_mfma_f32_16x16x32_bf16 v[66:69], v[166:169], v[182:185], v[66:69]
	v_mfma_f32_16x16x32_bf16 v[70:73], v[174:177], v[182:185], v[70:73]
	v_mfma_f32_16x16x32_bf16 v[54:57], v[166:169], v[190:193], v[54:57]
	v_mfma_f32_16x16x32_bf16 v[62:65], v[174:177], v[190:193], v[62:65]
	v_mfma_f32_16x16x32_bf16 v[42:45], v[166:169], v[198:201], v[42:45]
	v_mfma_f32_16x16x32_bf16 v[46:49], v[174:177], v[198:201], v[46:49]
	v_mfma_f32_16x16x32_bf16 v[26:29], v[166:169], v[206:209], v[26:29]
	v_mfma_f32_16x16x32_bf16 v[30:33], v[174:177], v[206:209], v[30:33]
	s_setprio 0
	s_barrier
	s_mov_b32 m0, s47
	s_add_u32 s98, s98, 0x80
	s_addc_u32 s99, s99, 0
	s_add_u32 s100, s100, 0x80
	s_addc_u32 s101, s101, 0
	s_add_u32 s20, s76, 0x100080
	ds_read_b128 v[178:181], v143 offset:49152
	ds_read_b128 v[182:185], v143 offset:50176
	ds_read_b128 v[186:189], v143 offset:51200
	ds_read_b128 v[190:193], v143 offset:52224
	ds_read_b128 v[194:197], v143 offset:53248
	ds_read_b128 v[198:201], v143 offset:54272
	ds_read_b128 v[202:205], v143 offset:55296
	ds_read_b128 v[206:209], v143 offset:56320
	global_load_lds_dwordx4 v132, s[98:99]
	s_mov_b32 m0, vcc_hi
	s_addc_u32 s21, s77, 0
	global_load_lds_dwordx4 v130, s[98:99]
	s_mov_b32 m0, s56
	s_nop 0
	global_load_lds_dwordx4 v132, s[20:21]
	s_mov_b32 m0, s57
	s_nop 0
	global_load_lds_dwordx4 v130, s[20:21]
	s_mov_b32 m0, s88
	s_nop 0
	global_load_lds_dwordx4 v132, s[100:101]
	s_mov_b32 m0, s89
	s_nop 0
	global_load_lds_dwordx4 v130, s[100:101]
	s_waitcnt vmcnt(8)
	s_waitcnt lgkmcnt(0)
	s_barrier
	s_setprio 1
	v_mfma_f32_16x16x32_bf16 v[102:105], v[146:149], v[178:181], v[102:105]
	v_mfma_f32_16x16x32_bf16 v[110:113], v[154:157], v[178:181], v[110:113]
	v_mfma_f32_16x16x32_bf16 v[90:93], v[146:149], v[186:189], v[90:93]
	v_mfma_f32_16x16x32_bf16 v[94:97], v[154:157], v[186:189], v[94:97]
	v_mfma_f32_16x16x32_bf16 v[74:77], v[146:149], v[194:197], v[74:77]
	v_mfma_f32_16x16x32_bf16 v[78:81], v[154:157], v[194:197], v[78:81]
	v_mfma_f32_16x16x32_bf16 v[50:53], v[146:149], v[202:205], v[50:53]
	v_mfma_f32_16x16x32_bf16 v[58:61], v[154:157], v[202:205], v[58:61]
	v_mfma_f32_16x16x32_bf16 v[102:105], v[150:153], v[182:185], v[102:105]
	v_mfma_f32_16x16x32_bf16 v[110:113], v[158:161], v[182:185], v[110:113]
	v_mfma_f32_16x16x32_bf16 v[90:93], v[150:153], v[190:193], v[90:93]
	v_mfma_f32_16x16x32_bf16 v[94:97], v[158:161], v[190:193], v[94:97]
	v_mfma_f32_16x16x32_bf16 v[74:77], v[150:153], v[198:201], v[74:77]
	v_mfma_f32_16x16x32_bf16 v[78:81], v[158:161], v[198:201], v[78:81]
	v_mfma_f32_16x16x32_bf16 v[50:53], v[150:153], v[206:209], v[50:53]
	v_mfma_f32_16x16x32_bf16 v[58:61], v[158:161], v[206:209], v[58:61]
	s_setprio 0
	s_setprio 1
	v_mfma_f32_16x16x32_bf16 v[122:125], v[162:165], v[178:181], v[122:125]
	v_mfma_f32_16x16x32_bf16 v[126:129], v[170:173], v[178:181], v[126:129]
	v_mfma_f32_16x16x32_bf16 v[114:117], v[162:165], v[186:189], v[114:117]
	v_mfma_f32_16x16x32_bf16 v[118:121], v[170:173], v[186:189], v[118:121]
	v_mfma_f32_16x16x32_bf16 v[98:101], v[162:165], v[194:197], v[98:101]
	v_mfma_f32_16x16x32_bf16 v[106:109], v[170:173], v[194:197], v[106:109]
	v_mfma_f32_16x16x32_bf16 v[82:85], v[162:165], v[202:205], v[82:85]
	v_mfma_f32_16x16x32_bf16 v[86:89], v[170:173], v[202:205], v[86:89]
	v_mfma_f32_16x16x32_bf16 v[122:125], v[166:169], v[182:185], v[122:125]
	v_mfma_f32_16x16x32_bf16 v[126:129], v[174:177], v[182:185], v[126:129]
	v_mfma_f32_16x16x32_bf16 v[114:117], v[166:169], v[190:193], v[114:117]
	v_mfma_f32_16x16x32_bf16 v[118:121], v[174:177], v[190:193], v[118:121]
	v_mfma_f32_16x16x32_bf16 v[98:101], v[166:169], v[198:201], v[98:101]
	v_mfma_f32_16x16x32_bf16 v[106:109], v[174:177], v[198:201], v[106:109]
	v_mfma_f32_16x16x32_bf16 v[82:85], v[166:169], v[206:209], v[82:85]
	v_mfma_f32_16x16x32_bf16 v[86:89], v[174:177], v[206:209], v[86:89]
	s_setprio 0
	s_barrier
	s_add_i32 s16, s16, 2
	s_add_u32 s78, s78, 0x100
	s_addc_u32 s79, s79, 0
	s_add_u32 s14, s14, 0x100
	s_addc_u32 s15, s15, 0
	s_cmp_gt_u32 s16, 61
	s_cbranch_scc0 .LBB0_435
	s_and_b64 vcc, exec, s[30:31]
	s_cbranch_vccz .LBB0_438
	s_barrier

;     __host__ __device__ bool next(int i, Unit& u) const { if (!StaticOrder::next(i >> 1, u)) return false; u.seg = i & 1; return true; }
;     ...
;         const bool has_next = S.next(ui + 1, nxt);
;         const char* nA = has_next ? PG8_APTR(nxt) : cA; const char* nB = has_next ? PG8_BPTR(nxt) : cB;
.LBB0_643:
	s_ashr_i32 s23, s22, 31
	ds_read_b128 v[2:5], v1
	ds_read_b128 v[6:9], v1 offset:1024
	ds_read_b128 v[10:13], v1 offset:2048
	ds_read_b128 v[14:17], v1 offset:3072
	ds_read_b128 v[18:21], v150
	ds_read_b128 v[22:25], v150 offset:1024
	ds_read_b128 v[26:29], v150 offset:2048
	ds_read_b128 v[30:33], v150 offset:3072
	s_lshl_b64 s[14:15], s[22:23], 19
	s_add_u32 s28, s24, s14
	s_addc_u32 s29, s25, s15
	s_and_b64 s[14:15], s[4:5], exec
	s_cselect_b32 s23, s29, s63
	s_cselect_b32 s83, s28, s62
	s_and_b32 s0, s81, 0x7fffffff
	s_lshl_b64 s[14:15], s[0:1], 19
	s_add_u32 s30, s10, s14
	s_addc_u32 s31, s11, s15
	s_and_b64 s[14:15], s[4:5], exec
	s_cselect_b32 s0, s31, s55
	s_cselect_b32 s86, s30, s54
	s_add_u32 s14, s62, 0x40080
	s_addc_u32 s15, s63, 0
	s_mov_b32 m0, s69
	v_lshl_add_u64 v[66:67], s[14:15], 0, v[136:137]
	ds_read_b128 v[34:37], v151
	ds_read_b128 v[38:41], v151 offset:1024
	ds_read_b128 v[42:45], v151 offset:2048
	ds_read_b128 v[46:49], v151 offset:3072
	ds_read_b128 v[50:53], v151 offset:4096
	ds_read_b128 v[54:57], v151 offset:5120
	ds_read_b128 v[58:61], v151 offset:6144
	ds_read_b128 v[62:65], v151 offset:7168
	global_load_lds_dwordx4 v[66:67], off
	v_lshl_add_u64 v[66:67], s[14:15], 0, v[132:133]
	s_mov_b32 m0, s70
	s_nop 0
	global_load_lds_dwordx4 v[66:67], off
	s_waitcnt vmcnt(8)
	s_waitcnt lgkmcnt(0)
	s_barrier
	s_setprio 1
	v_mfma_f32_16x16x32_bf16 v[90:93], v[2:5], v[58:61], 0
	v_mfma_f32_16x16x32_bf16 v[66:69], v[2:5], v[34:37], 0
	v_mfma_f32_16x16x32_bf16 v[70:73], v[10:13], v[34:37], 0
	v_mfma_f32_16x16x32_bf16 v[74:77], v[2:5], v[42:45], 0
	v_mfma_f32_16x16x32_bf16 v[78:81], v[10:13], v[42:45], 0
	v_mfma_f32_16x16x32_bf16 v[82:85], v[2:5], v[50:53], 0
	v_mfma_f32_16x16x32_bf16 v[86:89], v[10:13], v[50:53], 0
	v_mfma_f32_16x16x32_bf16 v[94:97], v[6:9], v[62:65], v[90:93]
	v_mfma_f32_16x16x32_bf16 v[90:93], v[10:13], v[58:61], 0
	v_mfma_f32_16x16x32_bf16 v[66:69], v[6:9], v[38:41], v[66:69]
	v_mfma_f32_16x16x32_bf16 v[70:73], v[14:17], v[38:41], v[70:73]
	v_mfma_f32_16x16x32_bf16 v[74:77], v[6:9], v[46:49], v[74:77]
	v_mfma_f32_16x16x32_bf16 v[78:81], v[14:17], v[46:49], v[78:81]
	v_mfma_f32_16x16x32_bf16 v[82:85], v[6:9], v[54:57], v[82:85]
	v_mfma_f32_16x16x32_bf16 v[86:89], v[14:17], v[54:57], v[86:89]
	v_mfma_f32_16x16x32_bf16 v[102:105], v[14:17], v[62:65], v[90:93]
	s_setprio 0
	s_setprio 1
	v_mfma_f32_16x16x32_bf16 v[90:93], v[18:21], v[34:37], 0
	v_mfma_f32_16x16x32_bf16 v[34:37], v[26:29], v[34:37], 0
	v_mfma_f32_16x16x32_bf16 v[110:113], v[22:25], v[38:41], v[90:93]
	v_mfma_f32_16x16x32_bf16 v[34:37], v[30:33], v[38:41], v[34:37]
	v_mfma_f32_16x16x32_bf16 v[38:41], v[18:21], v[42:45], 0
	v_mfma_f32_16x16x32_bf16 v[42:45], v[26:29], v[42:45], 0
	v_mfma_f32_16x16x32_bf16 v[38:41], v[22:25], v[46:49], v[38:41]
	v_mfma_f32_16x16x32_bf16 v[42:45], v[30:33], v[46:49], v[42:45]
	v_mfma_f32_16x16x32_bf16 v[46:49], v[18:21], v[50:53], 0
	v_mfma_f32_16x16x32_bf16 v[50:53], v[26:29], v[50:53], 0
	v_mfma_f32_16x16x32_bf16 v[46:49], v[22:25], v[54:57], v[46:49]
	v_mfma_f32_16x16x32_bf16 v[54:57], v[30:33], v[54:57], v[50:53]
	v_mfma_f32_16x16x32_bf16 v[50:53], v[18:21], v[58:61], 0
	v_mfma_f32_16x16x32_bf16 v[146:149], v[22:25], v[62:65], v[50:53]
	v_mfma_f32_16x16x32_bf16 v[50:53], v[26:29], v[58:61], 0
	v_mfma_f32_16x16x32_bf16 v[154:157], v[30:33], v[62:65], v[50:53]
	s_setprio 0
	s_barrier
	v_lshl_add_u64 v[250:251], s[54:55], 0, v[134:135]
	s_mov_b32 m0, s72
	v_lshl_add_u64 v[122:123], v[250:251], 0, s[18:19]
	v_lshl_add_u64 v[252:253], s[54:55], 0, v[130:131]
	s_add_u32 s14, s54, 0x40100
	ds_read_b128 v[50:53], v151 offset:16384
	ds_read_b128 v[58:61], v151 offset:17408
	ds_read_b128 v[62:65], v151 offset:18432
	ds_read_b128 v[90:93], v151 offset:19456
	ds_read_b128 v[98:101], v151 offset:20480
	ds_read_b128 v[106:109], v151 offset:21504
	ds_read_b128 v[114:117], v151 offset:22528
	ds_read_b128 v[118:121], v151 offset:23552
	global_load_lds_dwordx4 v[122:123], off
	v_lshl_add_u64 v[122:123], v[252:253], 0, s[18:19]
	s_mov_b32 m0, s73
	s_addc_u32 s15, s55, 0
	global_load_lds_dwordx4 v[122:123], off
	v_lshl_add_u64 v[122:123], s[14:15], 0, v[134:135]
	s_mov_b32 m0, s74
	v_lshl_add_u64 v[142:143], s[62:63], 0, v[136:137]
	global_load_lds_dwordx4 v[122:123], off
	v_lshl_add_u64 v[122:123], s[14:15], 0, v[130:131]
	s_mov_b32 m0, s75
	v_lshl_add_u64 v[144:145], s[62:63], 0, v[132:133]
	global_load_lds_dwordx4 v[122:123], off
	v_lshl_add_u64 v[122:123], v[142:143], 0, s[18:19]
	s_mov_b32 m0, s33
	s_nop 0
	global_load_lds_dwordx4 v[122:123], off
	v_lshl_add_u64 v[122:123], v[144:145], 0, s[18:19]
	s_mov_b32 m0, s41
	s_nop 0
	global_load_lds_dwordx4 v[122:123], off
	s_waitcnt vmcnt(8)
	s_waitcnt lgkmcnt(0)
	s_barrier
	s_setprio 1
	v_mfma_f32_16x16x32_bf16 v[122:125], v[2:5], v[50:53], 0
	v_mfma_f32_16x16x32_bf16 v[158:161], v[6:9], v[58:61], v[122:125]
	v_mfma_f32_16x16x32_bf16 v[122:125], v[10:13], v[50:53], 0
	v_mfma_f32_16x16x32_bf16 v[162:165], v[14:17], v[58:61], v[122:125]
	v_mfma_f32_16x16x32_bf16 v[122:125], v[2:5], v[62:65], 0
	v_mfma_f32_16x16x32_bf16 v[166:169], v[6:9], v[90:93], v[122:125]
	v_mfma_f32_16x16x32_bf16 v[122:125], v[10:13], v[62:65], 0
	v_mfma_f32_16x16x32_bf16 v[170:173], v[14:17], v[90:93], v[122:125]
	v_mfma_f32_16x16x32_bf16 v[122:125], v[2:5], v[98:101], 0
	v_mfma_f32_16x16x32_bf16 v[2:5], v[2:5], v[114:117], 0
	v_mfma_f32_16x16x32_bf16 v[174:177], v[6:9], v[106:109], v[122:125]
	v_mfma_f32_16x16x32_bf16 v[2:5], v[6:9], v[118:121], v[2:5]
	v_mfma_f32_16x16x32_bf16 v[6:9], v[10:13], v[114:117], 0
	v_mfma_f32_16x16x32_bf16 v[122:125], v[10:13], v[98:101], 0
	v_mfma_f32_16x16x32_bf16 v[6:9], v[14:17], v[118:121], v[6:9]
	v_mfma_f32_16x16x32_bf16 v[178:181], v[14:17], v[106:109], v[122:125]
	s_setprio 0
	s_setprio 1
	v_mfma_f32_16x16x32_bf16 v[10:13], v[18:21], v[50:53], 0
	v_mfma_f32_16x16x32_bf16 v[14:17], v[22:25], v[58:61], v[10:13]
	v_mfma_f32_16x16x32_bf16 v[10:13], v[26:29], v[50:53], 0
	v_mfma_f32_16x16x32_bf16 v[182:185], v[30:33], v[58:61], v[10:13]
	v_mfma_f32_16x16x32_bf16 v[10:13], v[18:21], v[62:65], 0
	v_mfma_f32_16x16x32_bf16 v[186:189], v[22:25], v[90:93], v[10:13]
	v_mfma_f32_16x16x32_bf16 v[10:13], v[26:29], v[62:65], 0
	v_mfma_f32_16x16x32_bf16 v[190:193], v[30:33], v[90:93], v[10:13]
	v_mfma_f32_16x16x32_bf16 v[10:13], v[18:21], v[98:101], 0
	v_mfma_f32_16x16x32_bf16 v[194:197], v[22:25], v[106:109], v[10:13]
	v_mfma_f32_16x16x32_bf16 v[10:13], v[26:29], v[98:101], 0
	v_mfma_f32_16x16x32_bf16 v[198:201], v[30:33], v[106:109], v[10:13]
	v_mfma_f32_16x16x32_bf16 v[10:13], v[18:21], v[114:117], 0
	v_mfma_f32_16x16x32_bf16 v[202:205], v[22:25], v[118:121], v[10:13]
	v_mfma_f32_16x16x32_bf16 v[10:13], v[26:29], v[114:117], 0
	v_mfma_f32_16x16x32_bf16 v[206:209], v[30:33], v[118:121], v[10:13]
	s_setprio 0
	s_barrier
	s_nop 4
	ds_read_b128 v[10:13], v152
	ds_read_b128 v[22:25], v152 offset:1024
	ds_read_b128 v[30:33], v152 offset:2048
	ds_read_b128 v[210:213], v152 offset:3072
	ds_read_b128 v[214:217], v153
	ds_read_b128 v[218:221], v153 offset:1024
	ds_read_b128 v[222:225], v153 offset:2048
	ds_read_b128 v[226:229], v153 offset:3072
	s_add_u32 s14, s62, 0x40100
	s_addc_u32 s15, s63, 0
	s_mov_b32 m0, s58
	v_lshl_add_u64 v[50:51], s[14:15], 0, v[136:137]
	ds_read_b128 v[18:21], v151 offset:32768
	ds_read_b128 v[26:29], v151 offset:33792
	ds_read_b128 v[62:65], v151 offset:34816
	ds_read_b128 v[230:233], v151 offset:35840
	ds_read_b128 v[234:237], v151 offset:36864
	ds_read_b128 v[238:241], v151 offset:37888
	ds_read_b128 v[242:245], v151 offset:38912
	ds_read_b128 v[246:249], v151 offset:39936
	global_load_lds_dwordx4 v[50:51], off
	v_lshl_add_u64 v[50:51], s[14:15], 0, v[132:133]
	s_mov_b32 m0, s59
	s_nop 0
	global_load_lds_dwordx4 v[50:51], off
	s_waitcnt vmcnt(8)
	s_waitcnt lgkmcnt(0)
	s_barrier
	s_setprio 1
	v_mfma_f32_16x16x32_bf16 v[50:53], v[10:13], v[18:21], v[66:69]
	v_mfma_f32_16x16x32_bf16 v[122:125], v[22:25], v[26:29], v[50:53]
	v_mfma_f32_16x16x32_bf16 v[50:53], v[30:33], v[18:21], v[70:73]
	v_mfma_f32_16x16x32_bf16 v[114:117], v[210:213], v[26:29], v[50:53]
	v_mfma_f32_16x16x32_bf16 v[50:53], v[10:13], v[62:65], v[74:77]
	v_mfma_f32_16x16x32_bf16 v[106:109], v[22:25], v[230:233], v[50:53]
	v_mfma_f32_16x16x32_bf16 v[50:53], v[30:33], v[62:65], v[78:81]
	v_mfma_f32_16x16x32_bf16 v[98:101], v[210:213], v[230:233], v[50:53]
	v_mfma_f32_16x16x32_bf16 v[50:53], v[10:13], v[234:237], v[82:85]
	v_mfma_f32_16x16x32_bf16 v[90:93], v[22:25], v[238:241], v[50:53]
	v_mfma_f32_16x16x32_bf16 v[50:53], v[30:33], v[234:237], v[86:89]
	v_mfma_f32_16x16x32_bf16 v[82:85], v[210:213], v[238:241], v[50:53]
	v_mfma_f32_16x16x32_bf16 v[50:53], v[10:13], v[242:245], v[94:97]
	v_mfma_f32_16x16x32_bf16 v[58:61], v[22:25], v[246:249], v[50:53]
	v_mfma_f32_16x16x32_bf16 v[50:53], v[30:33], v[242:245], v[102:105]
	v_mfma_f32_16x16x32_bf16 v[50:53], v[210:213], v[246:249], v[50:53]
	s_setprio 0
	s_setprio 1
	v_mfma_f32_16x16x32_bf16 v[66:69], v[214:217], v[18:21], v[110:113]
	v_mfma_f32_16x16x32_bf16 v[18:21], v[222:225], v[18:21], v[34:37]
	v_mfma_f32_16x16x32_bf16 v[118:121], v[226:229], v[26:29], v[18:21]
	v_mfma_f32_16x16x32_bf16 v[18:21], v[214:217], v[62:65], v[38:41]
	v_mfma_f32_16x16x32_bf16 v[110:113], v[218:221], v[230:233], v[18:21]
	v_mfma_f32_16x16x32_bf16 v[18:21], v[222:225], v[62:65], v[42:45]
	v_mfma_f32_16x16x32_bf16 v[102:105], v[226:229], v[230:233], v[18:21]
	v_mfma_f32_16x16x32_bf16 v[18:21], v[214:217], v[234:237], v[46:49]
	v_mfma_f32_16x16x32_bf16 v[94:97], v[218:221], v[238:241], v[18:21]
	v_mfma_f32_16x16x32_bf16 v[18:21], v[222:225], v[234:237], v[54:57]
	v_mfma_f32_16x16x32_bf16 v[86:89], v[226:229], v[238:241], v[18:21]
	v_mfma_f32_16x16x32_bf16 v[18:21], v[214:217], v[242:245], v[146:149]
	v_mfma_f32_16x16x32_bf16 v[62:65], v[218:221], v[246:249], v[18:21]
	v_mfma_f32_16x16x32_bf16 v[18:21], v[222:225], v[242:245], v[154:157]
	v_mfma_f32_16x16x32_bf16 v[126:129], v[218:221], v[26:29], v[66:69]
	v_mfma_f32_16x16x32_bf16 v[54:57], v[226:229], v[246:249], v[18:21]
	s_setprio 0
	s_barrier
	s_mov_b32 m0, s76
	s_nop 2
	v_lshl_add_u64 v[18:19], v[250:251], 0, s[20:21]
	s_add_u32 s14, s54, 0x40180
	ds_read_b128 v[38:41], v151 offset:49152
	ds_read_b128 v[46:49], v151 offset:50176
	ds_read_b128 v[146:149], v151 offset:51200
	ds_read_b128 v[154:157], v151 offset:52224
	ds_read_b128 v[230:233], v151 offset:53248
	ds_read_b128 v[234:237], v151 offset:54272
	ds_read_b128 v[238:241], v151 offset:55296
	ds_read_b128 v[242:245], v151 offset:56320
	global_load_lds_dwordx4 v[18:19], off
	v_lshl_add_u64 v[18:19], v[252:253], 0, s[20:21]
	s_mov_b32 m0, s77
	s_addc_u32 s15, s55, 0
	global_load_lds_dwordx4 v[18:19], off
	v_lshl_add_u64 v[18:19], s[14:15], 0, v[134:135]
	s_mov_b32 m0, s78
	s_nop 0
	global_load_lds_dwordx4 v[18:19], off
	v_lshl_add_u64 v[18:19], s[14:15], 0, v[130:131]
	s_mov_b32 m0, s79
	s_nop 0
	global_load_lds_dwordx4 v[18:19], off
	v_lshl_add_u64 v[18:19], v[142:143], 0, s[20:21]
	s_mov_b32 m0, s66
	s_nop 0
	global_load_lds_dwordx4 v[18:19], off
	v_lshl_add_u64 v[18:19], v[144:145], 0, s[20:21]
	s_mov_b32 m0, s67
	s_nop 0
	global_load_lds_dwordx4 v[18:19], off
	s_waitcnt vmcnt(8)
	s_waitcnt lgkmcnt(0)
	s_barrier
	s_setprio 1
	v_mfma_f32_16x16x32_bf16 v[18:21], v[10:13], v[38:41], v[158:161]
	v_mfma_f32_16x16x32_bf16 v[74:77], v[22:25], v[46:49], v[18:21]
	v_mfma_f32_16x16x32_bf16 v[18:21], v[30:33], v[38:41], v[162:165]
	v_mfma_f32_16x16x32_bf16 v[66:69], v[210:213], v[46:49], v[18:21]
	v_mfma_f32_16x16x32_bf16 v[18:21], v[10:13], v[146:149], v[166:169]
	v_mfma_f32_16x16x32_bf16 v[42:45], v[22:25], v[154:157], v[18:21]
	v_mfma_f32_16x16x32_bf16 v[18:21], v[30:33], v[146:149], v[170:173]
	v_mfma_f32_16x16x32_bf16 v[34:37], v[210:213], v[154:157], v[18:21]
	v_mfma_f32_16x16x32_bf16 v[18:21], v[10:13], v[230:233], v[174:177]
	v_mfma_f32_16x16x32_bf16 v[2:5], v[10:13], v[238:241], v[2:5]
	v_mfma_f32_16x16x32_bf16 v[26:29], v[22:25], v[234:237], v[18:21]
	v_mfma_f32_16x16x32_bf16 v[18:21], v[30:33], v[230:233], v[178:181]
	v_mfma_f32_16x16x32_bf16 v[10:13], v[22:25], v[242:245], v[2:5]
	v_mfma_f32_16x16x32_bf16 v[2:5], v[30:33], v[238:241], v[6:9]
	v_mfma_f32_16x16x32_bf16 v[18:21], v[210:213], v[234:237], v[18:21]
	v_mfma_f32_16x16x32_bf16 v[2:5], v[210:213], v[242:245], v[2:5]
	s_setprio 0
	s_setprio 1
	v_mfma_f32_16x16x32_bf16 v[6:9], v[214:217], v[38:41], v[14:17]
	v_mfma_f32_16x16x32_bf16 v[78:81], v[218:221], v[46:49], v[6:9]
	v_mfma_f32_16x16x32_bf16 v[6:9], v[222:225], v[38:41], v[182:185]
	v_mfma_f32_16x16x32_bf16 v[70:73], v[226:229], v[46:49], v[6:9]
	v_mfma_f32_16x16x32_bf16 v[6:9], v[214:217], v[146:149], v[186:189]
	v_mfma_f32_16x16x32_bf16 v[46:49], v[218:221], v[154:157], v[6:9]
	v_mfma_f32_16x16x32_bf16 v[6:9], v[222:225], v[146:149], v[190:193]
	v_mfma_f32_16x16x32_bf16 v[38:41], v[226:229], v[154:157], v[6:9]
	v_mfma_f32_16x16x32_bf16 v[6:9], v[214:217], v[230:233], v[194:197]
	v_mfma_f32_16x16x32_bf16 v[30:33], v[218:221], v[234:237], v[6:9]
	v_mfma_f32_16x16x32_bf16 v[6:9], v[222:225], v[230:233], v[198:201]
	v_mfma_f32_16x16x32_bf16 v[22:25], v[226:229], v[234:237], v[6:9]
	v_mfma_f32_16x16x32_bf16 v[6:9], v[214:217], v[238:241], v[202:205]
	v_mfma_f32_16x16x32_bf16 v[14:17], v[218:221], v[242:245], v[6:9]
	v_mfma_f32_16x16x32_bf16 v[6:9], v[222:225], v[238:241], v[206:209]
	v_mfma_f32_16x16x32_bf16 v[6:9], v[226:229], v[242:245], v[6:9]
	s_setprio 0
	s_barrier
	s_add_u32 s62, s62, 0x40180
	s_addc_u32 s63, s63, 0
	s_add_u32 s14, s54, 0x200
	s_addc_u32 s15, s55, 0
	s_mov_b32 s26, 0
.LBB0_644:
	ds_read_b128 v[146:149], v1
	ds_read_b128 v[154:157], v1 offset:1024
	ds_read_b128 v[158:161], v1 offset:2048
	ds_read_b128 v[162:165], v1 offset:3072
	ds_read_b128 v[166:169], v150
	ds_read_b128 v[170:173], v150 offset:1024
	ds_read_b128 v[174:177], v150 offset:2048
	ds_read_b128 v[178:181], v150 offset:3072
	s_add_u32 s27, s62, 0xfffc0080
	s_addc_u32 s46, s63, -1
	s_cmp_eq_u32 s26, 12
	s_cselect_b32 s65, s23, s46
	s_cselect_b32 s64, s83, s27
	s_cselect_b32 s55, s0, s15
	s_cselect_b32 s54, s86, s14
	s_mov_b32 m0, s69
	ds_read_b128 v[182:185], v151
	ds_read_b128 v[186:189], v151 offset:1024
	ds_read_b128 v[190:193], v151 offset:2048
	ds_read_b128 v[194:197], v151 offset:3072
	ds_read_b128 v[198:201], v151 offset:4096
	ds_read_b128 v[202:205], v151 offset:5120
	ds_read_b128 v[206:209], v151 offset:6144
	ds_read_b128 v[210:213], v151 offset:7168
	global_load_lds_dwordx4 v138, s[62:63]
	s_mov_b32 m0, s70
	s_nop 0
	global_load_lds_dwordx4 v140, s[62:63]
	s_waitcnt vmcnt(8)
	s_waitcnt lgkmcnt(0)
	s_barrier
	s_setprio 1
	v_mfma_f32_16x16x32_bf16 v[122:125], v[146:149], v[182:185], v[122:125]
	v_mfma_f32_16x16x32_bf16 v[114:117], v[158:161], v[182:185], v[114:117]
	v_mfma_f32_16x16x32_bf16 v[106:109], v[146:149], v[190:193], v[106:109]
	v_mfma_f32_16x16x32_bf16 v[98:101], v[158:161], v[190:193], v[98:101]
	v_mfma_f32_16x16x32_bf16 v[90:93], v[146:149], v[198:201], v[90:93]
	v_mfma_f32_16x16x32_bf16 v[82:85], v[158:161], v[198:201], v[82:85]
	v_mfma_f32_16x16x32_bf16 v[58:61], v[146:149], v[206:209], v[58:61]
	v_mfma_f32_16x16x32_bf16 v[50:53], v[158:161], v[206:209], v[50:53]
	v_mfma_f32_16x16x32_bf16 v[122:125], v[154:157], v[186:189], v[122:125]
	v_mfma_f32_16x16x32_bf16 v[114:117], v[162:165], v[186:189], v[114:117]
	v_mfma_f32_16x16x32_bf16 v[106:109], v[154:157], v[194:197], v[106:109]
	v_mfma_f32_16x16x32_bf16 v[98:101], v[162:165], v[194:197], v[98:101]
	v_mfma_f32_16x16x32_bf16 v[90:93], v[154:157], v[202:205], v[90:93]
	v_mfma_f32_16x16x32_bf16 v[82:85], v[162:165], v[202:205], v[82:85]
	v_mfma_f32_16x16x32_bf16 v[58:61], v[154:157], v[210:213], v[58:61]
	v_mfma_f32_16x16x32_bf16 v[50:53], v[162:165], v[210:213], v[50:53]
	s_setprio 0
	s_setprio 1
	v_mfma_f32_16x16x32_bf16 v[126:129], v[166:169], v[182:185], v[126:129]
	v_mfma_f32_16x16x32_bf16 v[118:121], v[174:177], v[182:185], v[118:121]
	v_mfma_f32_16x16x32_bf16 v[110:113], v[166:169], v[190:193], v[110:113]
	v_mfma_f32_16x16x32_bf16 v[102:105], v[174:177], v[190:193], v[102:105]
	v_mfma_f32_16x16x32_bf16 v[94:97], v[166:169], v[198:201], v[94:97]
	v_mfma_f32_16x16x32_bf16 v[86:89], v[174:177], v[198:201], v[86:89]
	v_mfma_f32_16x16x32_bf16 v[62:65], v[166:169], v[206:209], v[62:65]
	v_mfma_f32_16x16x32_bf16 v[54:57], v[174:177], v[206:209], v[54:57]
	v_mfma_f32_16x16x32_bf16 v[126:129], v[170:173], v[186:189], v[126:129]
	v_mfma_f32_16x16x32_bf16 v[118:121], v[178:181], v[186:189], v[118:121]
	v_mfma_f32_16x16x32_bf16 v[110:113], v[170:173], v[194:197], v[110:113]
	v_mfma_f32_16x16x32_bf16 v[102:105], v[178:181], v[194:197], v[102:105]
	v_mfma_f32_16x16x32_bf16 v[94:97], v[170:173], v[202:205], v[94:97]
	v_mfma_f32_16x16x32_bf16 v[86:89], v[178:181], v[202:205], v[86:89]
	v_mfma_f32_16x16x32_bf16 v[62:65], v[170:173], v[210:213], v[62:65]
	v_mfma_f32_16x16x32_bf16 v[54:57], v[178:181], v[210:213], v[54:57]
	s_setprio 0
	s_barrier
	s_mov_b32 m0, s72
	s_mov_b64 s[98:99], s[54:55]
	s_add_u32 s46, s54, 0x40000
	ds_read_b128 v[182:185], v151 offset:16384
	ds_read_b128 v[186:189], v151 offset:17408
	ds_read_b128 v[190:193], v151 offset:18432
	ds_read_b128 v[194:197], v151 offset:19456
	ds_read_b128 v[198:201], v151 offset:20480
	ds_read_b128 v[202:205], v151 offset:21504
	ds_read_b128 v[206:209], v151 offset:22528
	ds_read_b128 v[210:213], v151 offset:23552
	global_load_lds_dwordx4 v134, s[54:55]
	s_mov_b32 m0, s73
	s_addc_u32 s47, s55, 0
	global_load_lds_dwordx4 v130, s[54:55]
	s_mov_b32 m0, s74
	s_mov_b64 s[100:101], s[64:65]
	global_load_lds_dwordx4 v134, s[46:47]
	s_mov_b32 m0, s75
	s_nop 0
	global_load_lds_dwordx4 v130, s[46:47]
	s_mov_b32 m0, s33
	s_nop 0
	global_load_lds_dwordx4 v136, s[64:65]
	s_mov_b32 m0, s41
	s_nop 0
	global_load_lds_dwordx4 v132, s[64:65]
	s_waitcnt vmcnt(8)
	s_waitcnt lgkmcnt(0)
	s_barrier
	s_setprio 1
	v_mfma_f32_16x16x32_bf16 v[74:77], v[146:149], v[182:185], v[74:77]
	v_mfma_f32_16x16x32_bf16 v[66:69], v[158:161], v[182:185], v[66:69]
	v_mfma_f32_16x16x32_bf16 v[42:45], v[146:149], v[190:193], v[42:45]
	v_mfma_f32_16x16x32_bf16 v[34:37], v[158:161], v[190:193], v[34:37]
	v_mfma_f32_16x16x32_bf16 v[26:29], v[146:149], v[198:201], v[26:29]
	v_mfma_f32_16x16x32_bf16 v[18:21], v[158:161], v[198:201], v[18:21]
	v_mfma_f32_16x16x32_bf16 v[10:13], v[146:149], v[206:209], v[10:13]
	v_mfma_f32_16x16x32_bf16 v[2:5], v[158:161], v[206:209], v[2:5]
	v_mfma_f32_16x16x32_bf16 v[74:77], v[154:157], v[186:189], v[74:77]
	v_mfma_f32_16x16x32_bf16 v[66:69], v[162:165], v[186:189], v[66:69]
	v_mfma_f32_16x16x32_bf16 v[42:45], v[154:157], v[194:197], v[42:45]
	v_mfma_f32_16x16x32_bf16 v[34:37], v[162:165], v[194:197], v[34:37]
	v_mfma_f32_16x16x32_bf16 v[26:29], v[154:157], v[202:205], v[26:29]
	v_mfma_f32_16x16x32_bf16 v[18:21], v[162:165], v[202:205], v[18:21]
	v_mfma_f32_16x16x32_bf16 v[10:13], v[154:157], v[210:213], v[10:13]
	v_mfma_f32_16x16x32_bf16 v[2:5], v[162:165], v[210:213], v[2:5]
	s_setprio 0
	s_setprio 1
	v_mfma_f32_16x16x32_bf16 v[78:81], v[166:169], v[182:185], v[78:81]
	v_mfma_f32_16x16x32_bf16 v[70:73], v[174:177], v[182:185], v[70:73]
	v_mfma_f32_16x16x32_bf16 v[46:49], v[166:169], v[190:193], v[46:49]
	v_mfma_f32_16x16x32_bf16 v[38:41], v[174:177], v[190:193], v[38:41]
	v_mfma_f32_16x16x32_bf16 v[30:33], v[166:169], v[198:201], v[30:33]
	v_mfma_f32_16x16x32_bf16 v[22:25], v[174:177], v[198:201], v[22:25]
	v_mfma_f32_16x16x32_bf16 v[14:17], v[166:169], v[206:209], v[14:17]
	v_mfma_f32_16x16x32_bf16 v[6:9], v[174:177], v[206:209], v[6:9]
	v_mfma_f32_16x16x32_bf16 v[78:81], v[170:173], v[186:189], v[78:81]
	v_mfma_f32_16x16x32_bf16 v[70:73], v[178:181], v[186:189], v[70:73]
	v_mfma_f32_16x16x32_bf16 v[46:49], v[170:173], v[194:197], v[46:49]
	v_mfma_f32_16x16x32_bf16 v[38:41], v[178:181], v[194:197], v[38:41]
	v_mfma_f32_16x16x32_bf16 v[30:33], v[170:173], v[202:205], v[30:33]
	v_mfma_f32_16x16x32_bf16 v[22:25], v[178:181], v[202:205], v[22:25]
	v_mfma_f32_16x16x32_bf16 v[14:17], v[170:173], v[210:213], v[14:17]
	v_mfma_f32_16x16x32_bf16 v[6:9], v[178:181], v[210:213], v[6:9]
	s_setprio 0
	s_barrier
; #define PG8_BAR __builtin_amdgcn_s_barrier()
;     ...
;         for (int t = 2; t < nt; t += 2) PG8_KITER(t);
;         if constexpr (ALIGN_EPI) { if (wr == 0) PG8_BAR; }
	ds_read_b128 v[146:149], v152
	ds_read_b128 v[154:157], v152 offset:1024
	ds_read_b128 v[158:161], v152 offset:2048
	ds_read_b128 v[162:165], v152 offset:3072
	ds_read_b128 v[166:169], v153
	ds_read_b128 v[170:173], v153 offset:1024
	ds_read_b128 v[174:177], v153 offset:2048
	ds_read_b128 v[178:181], v153 offset:3072
	s_add_u32 s46, s64, 0x40000
	s_addc_u32 s47, s65, 0
	s_mov_b32 m0, s58
	ds_read_b128 v[182:185], v151 offset:32768
	ds_read_b128 v[186:189], v151 offset:33792
	ds_read_b128 v[190:193], v151 offset:34816
	ds_read_b128 v[194:197], v151 offset:35840
	ds_read_b128 v[198:201], v151 offset:36864
	ds_read_b128 v[202:205], v151 offset:37888
	ds_read_b128 v[206:209], v151 offset:38912
	ds_read_b128 v[210:213], v151 offset:39936
	global_load_lds_dwordx4 v136, s[46:47]
	s_mov_b32 m0, s59
	s_nop 0
	global_load_lds_dwordx4 v132, s[46:47]
	s_waitcnt vmcnt(8)
	s_waitcnt lgkmcnt(0)
	s_barrier
	s_setprio 1
	v_mfma_f32_16x16x32_bf16 v[122:125], v[146:149], v[182:185], v[122:125]
	v_mfma_f32_16x16x32_bf16 v[114:117], v[158:161], v[182:185], v[114:117]
	v_mfma_f32_16x16x32_bf16 v[106:109], v[146:149], v[190:193], v[106:109]
	v_mfma_f32_16x16x32_bf16 v[98:101], v[158:161], v[190:193], v[98:101]
	v_mfma_f32_16x16x32_bf16 v[90:93], v[146:149], v[198:201], v[90:93]
	v_mfma_f32_16x16x32_bf16 v[82:85], v[158:161], v[198:201], v[82:85]
	v_mfma_f32_16x16x32_bf16 v[58:61], v[146:149], v[206:209], v[58:61]
	v_mfma_f32_16x16x32_bf16 v[50:53], v[158:161], v[206:209], v[50:53]
	v_mfma_f32_16x16x32_bf16 v[122:125], v[154:157], v[186:189], v[122:125]
	v_mfma_f32_16x16x32_bf16 v[114:117], v[162:165], v[186:189], v[114:117]
	v_mfma_f32_16x16x32_bf16 v[106:109], v[154:157], v[194:197], v[106:109]
	v_mfma_f32_16x16x32_bf16 v[98:101], v[162:165], v[194:197], v[98:101]
	v_mfma_f32_16x16x32_bf16 v[90:93], v[154:157], v[202:205], v[90:93]
	v_mfma_f32_16x16x32_bf16 v[82:85], v[162:165], v[202:205], v[82:85]
	v_mfma_f32_16x16x32_bf16 v[58:61], v[154:157], v[210:213], v[58:61]
	v_mfma_f32_16x16x32_bf16 v[50:53], v[162:165], v[210:213], v[50:53]
	s_setprio 0
	s_setprio 1
	v_mfma_f32_16x16x32_bf16 v[126:129], v[166:169], v[182:185], v[126:129]
	v_mfma_f32_16x16x32_bf16 v[118:121], v[174:177], v[182:185], v[118:121]
	v_mfma_f32_16x16x32_bf16 v[110:113], v[166:169], v[190:193], v[110:113]
	v_mfma_f32_16x16x32_bf16 v[102:105], v[174:177], v[190:193], v[102:105]
	v_mfma_f32_16x16x32_bf16 v[94:97], v[166:169], v[198:201], v[94:97]
	v_mfma_f32_16x16x32_bf16 v[86:89], v[174:177], v[198:201], v[86:89]
	v_mfma_f32_16x16x32_bf16 v[62:65], v[166:169], v[206:209], v[62:65]
	v_mfma_f32_16x16x32_bf16 v[54:57], v[174:177], v[206:209], v[54:57]
	v_mfma_f32_16x16x32_bf16 v[126:129], v[170:173], v[186:189], v[126:129]
	v_mfma_f32_16x16x32_bf16 v[118:121], v[178:181], v[186:189], v[118:121]
	v_mfma_f32_16x16x32_bf16 v[110:113], v[170:173], v[194:197], v[110:113]
	v_mfma_f32_16x16x32_bf16 v[102:105], v[178:181], v[194:197], v[102:105]
	v_mfma_f32_16x16x32_bf16 v[94:97], v[170:173], v[202:205], v[94:97]
	v_mfma_f32_16x16x32_bf16 v[86:89], v[178:181], v[202:205], v[86:89]
	v_mfma_f32_16x16x32_bf16 v[62:65], v[170:173], v[210:213], v[62:65]
	v_mfma_f32_16x16x32_bf16 v[54:57], v[178:181], v[210:213], v[54:57]
	s_setprio 0
	s_barrier
	s_mov_b32 m0, s76
	s_add_u32 s98, s98, 0x80
	s_addc_u32 s99, s99, 0
	s_add_u32 s100, s100, 0x80
	s_addc_u32 s101, s101, 0
	s_add_u32 s46, s54, 0x40080
	ds_read_b128 v[182:185], v151 offset:49152
	ds_read_b128 v[186:189], v151 offset:50176
	ds_read_b128 v[190:193], v151 offset:51200
	ds_read_b128 v[194:197], v151 offset:52224
	ds_read_b128 v[198:201], v151 offset:53248
	ds_read_b128 v[202:205], v151 offset:54272
	ds_read_b128 v[206:209], v151 offset:55296
	ds_read_b128 v[210:213], v151 offset:56320
	global_load_lds_dwordx4 v134, s[98:99]
	s_mov_b32 m0, s77
	s_addc_u32 s47, s55, 0
	global_load_lds_dwordx4 v130, s[98:99]
	s_mov_b32 m0, s78
	s_nop 0
	global_load_lds_dwordx4 v134, s[46:47]
	s_mov_b32 m0, s79
	s_nop 0
	global_load_lds_dwordx4 v130, s[46:47]
	s_mov_b32 m0, s66
	s_nop 0
	global_load_lds_dwordx4 v136, s[100:101]
	s_mov_b32 m0, s67
	s_nop 0
	global_load_lds_dwordx4 v132, s[100:101]
	s_waitcnt vmcnt(8)
	s_waitcnt lgkmcnt(0)
	s_barrier
	s_setprio 1
	v_mfma_f32_16x16x32_bf16 v[74:77], v[146:149], v[182:185], v[74:77]
	v_mfma_f32_16x16x32_bf16 v[66:69], v[158:161], v[182:185], v[66:69]
	v_mfma_f32_16x16x32_bf16 v[42:45], v[146:149], v[190:193], v[42:45]
	v_mfma_f32_16x16x32_bf16 v[34:37], v[158:161], v[190:193], v[34:37]
	v_mfma_f32_16x16x32_bf16 v[26:29], v[146:149], v[198:201], v[26:29]
	v_mfma_f32_16x16x32_bf16 v[18:21], v[158:161], v[198:201], v[18:21]
	v_mfma_f32_16x16x32_bf16 v[10:13], v[146:149], v[206:209], v[10:13]
	v_mfma_f32_16x16x32_bf16 v[2:5], v[158:161], v[206:209], v[2:5]
	v_mfma_f32_16x16x32_bf16 v[74:77], v[154:157], v[186:189], v[74:77]
	v_mfma_f32_16x16x32_bf16 v[66:69], v[162:165], v[186:189], v[66:69]
	v_mfma_f32_16x16x32_bf16 v[42:45], v[154:157], v[194:197], v[42:45]
	v_mfma_f32_16x16x32_bf16 v[34:37], v[162:165], v[194:197], v[34:37]
	v_mfma_f32_16x16x32_bf16 v[26:29], v[154:157], v[202:205], v[26:29]
	v_mfma_f32_16x16x32_bf16 v[18:21], v[162:165], v[202:205], v[18:21]
	v_mfma_f32_16x16x32_bf16 v[10:13], v[154:157], v[210:213], v[10:13]
	v_mfma_f32_16x16x32_bf16 v[2:5], v[162:165], v[210:213], v[2:5]
	s_setprio 0
	s_setprio 1
	v_mfma_f32_16x16x32_bf16 v[78:81], v[166:169], v[182:185], v[78:81]
	v_mfma_f32_16x16x32_bf16 v[70:73], v[174:177], v[182:185], v[70:73]
	v_mfma_f32_16x16x32_bf16 v[46:49], v[166:169], v[190:193], v[46:49]
	v_mfma_f32_16x16x32_bf16 v[38:41], v[174:177], v[190:193], v[38:41]
	v_mfma_f32_16x16x32_bf16 v[30:33], v[166:169], v[198:201], v[30:33]
	v_mfma_f32_16x16x32_bf16 v[22:25], v[174:177], v[198:201], v[22:25]
	v_mfma_f32_16x16x32_bf16 v[14:17], v[166:169], v[206:209], v[14:17]
	v_mfma_f32_16x16x32_bf16 v[6:9], v[174:177], v[206:209], v[6:9]
	v_mfma_f32_16x16x32_bf16 v[78:81], v[170:173], v[186:189], v[78:81]
	v_mfma_f32_16x16x32_bf16 v[70:73], v[178:181], v[186:189], v[70:73]
	v_mfma_f32_16x16x32_bf16 v[46:49], v[170:173], v[194:197], v[46:49]
	v_mfma_f32_16x16x32_bf16 v[38:41], v[178:181], v[194:197], v[38:41]
	v_mfma_f32_16x16x32_bf16 v[30:33], v[170:173], v[202:205], v[30:33]
	v_mfma_f32_16x16x32_bf16 v[22:25], v[178:181], v[202:205], v[22:25]
	v_mfma_f32_16x16x32_bf16 v[14:17], v[170:173], v[210:213], v[14:17]
	v_mfma_f32_16x16x32_bf16 v[6:9], v[178:181], v[210:213], v[6:9]
	s_setprio 0
	s_barrier
	s_add_i32 s26, s26, 2
	s_add_u32 s62, s62, 0x100
	s_addc_u32 s63, s63, 0
	s_add_u32 s14, s14, 0x100
	s_addc_u32 s15, s15, 0
	s_cmp_gt_u32 s26, 13
	s_cbranch_scc0 .LBB0_644
	s_and_b64 vcc, exec, s[16:17]
	s_cbranch_vccz .LBB0_647
	s_barrier

;     __host__ __device__ bool next(int i, Unit& u) const { if (!StaticOrder::next(i >> 1, u)) return false; u.seg = i & 1; return true; }
;     ...
;         const bool has_next = S.next(ui + 1, nxt);
;         const char* nA = has_next ? PG8_APTR(nxt) : cA; const char* nB = has_next ? PG8_BPTR(nxt) : cB;
.LBB0_669:
	s_ashr_i32 s29, s28, 31
	ds_read_b128 v[2:5], v158
	ds_read_b128 v[6:9], v158 offset:1024
	ds_read_b128 v[10:13], v158 offset:2048
	ds_read_b128 v[14:17], v158 offset:3072
	ds_read_b128 v[18:21], v159
	ds_read_b128 v[22:25], v159 offset:1024
	ds_read_b128 v[26:29], v159 offset:2048
	ds_read_b128 v[30:33], v159 offset:3072
	s_lshl_b64 s[14:15], s[28:29], 18
	s_add_u32 s30, s10, s14
	s_addc_u32 s31, s11, s15
	s_and_b64 s[14:15], s[4:5], exec
	s_cselect_b32 s29, s31, s65
	s_cselect_b32 s79, s30, s64
	s_and_b32 s0, s77, 0x7fffffff
	s_lshl_b64 s[14:15], s[0:1], 18
	s_add_u32 s40, s12, s14
	s_addc_u32 s41, s13, s15
	s_and_b64 s[14:15], s[4:5], exec
	s_cselect_b32 s0, s41, s7
	s_cselect_b32 s80, s40, s6
	s_add_u32 s14, s64, 0x20080
	s_addc_u32 s15, s65, 0
	s_add_i32 s81, s58, 0xc000
	v_lshl_add_u64 v[66:67], s[14:15], 0, v[138:139]
	s_mov_b32 m0, s81
	s_add_i32 s82, s58, 0xe000
	ds_read_b128 v[34:37], v160
	ds_read_b128 v[38:41], v160 offset:1024
	ds_read_b128 v[42:45], v160 offset:2048
	ds_read_b128 v[46:49], v160 offset:3072
	ds_read_b128 v[50:53], v160 offset:4096
	ds_read_b128 v[54:57], v160 offset:5120
	ds_read_b128 v[58:61], v160 offset:6144
	ds_read_b128 v[62:65], v160 offset:7168
	global_load_lds_dwordx4 v[66:67], off
	v_lshl_add_u64 v[66:67], s[14:15], 0, v[142:143]
	s_mov_b32 m0, s82
	s_nop 0
	global_load_lds_dwordx4 v[66:67], off
	s_waitcnt vmcnt(8)
	s_waitcnt lgkmcnt(0)
	s_barrier
	s_setprio 1
	v_mfma_f32_16x16x32_bf16 v[90:93], v[2:5], v[58:61], 0
	v_mfma_f32_16x16x32_bf16 v[66:69], v[2:5], v[34:37], 0
	v_mfma_f32_16x16x32_bf16 v[70:73], v[10:13], v[34:37], 0
	v_mfma_f32_16x16x32_bf16 v[74:77], v[2:5], v[42:45], 0
	v_mfma_f32_16x16x32_bf16 v[78:81], v[10:13], v[42:45], 0
	v_mfma_f32_16x16x32_bf16 v[82:85], v[2:5], v[50:53], 0
	v_mfma_f32_16x16x32_bf16 v[86:89], v[10:13], v[50:53], 0
	v_mfma_f32_16x16x32_bf16 v[102:105], v[6:9], v[62:65], v[90:93]
	v_mfma_f32_16x16x32_bf16 v[90:93], v[10:13], v[58:61], 0
	v_mfma_f32_16x16x32_bf16 v[66:69], v[6:9], v[38:41], v[66:69]
	v_mfma_f32_16x16x32_bf16 v[70:73], v[14:17], v[38:41], v[70:73]
	v_mfma_f32_16x16x32_bf16 v[74:77], v[6:9], v[46:49], v[74:77]
	v_mfma_f32_16x16x32_bf16 v[78:81], v[14:17], v[46:49], v[78:81]
	v_mfma_f32_16x16x32_bf16 v[82:85], v[6:9], v[54:57], v[82:85]
	v_mfma_f32_16x16x32_bf16 v[86:89], v[14:17], v[54:57], v[86:89]
	v_mfma_f32_16x16x32_bf16 v[106:109], v[14:17], v[62:65], v[90:93]
	s_setprio 0
	s_setprio 1
	v_mfma_f32_16x16x32_bf16 v[90:93], v[18:21], v[34:37], 0
	v_mfma_f32_16x16x32_bf16 v[34:37], v[26:29], v[34:37], 0
	v_mfma_f32_16x16x32_bf16 v[122:125], v[22:25], v[38:41], v[90:93]
	v_mfma_f32_16x16x32_bf16 v[34:37], v[30:33], v[38:41], v[34:37]
	v_mfma_f32_16x16x32_bf16 v[38:41], v[18:21], v[42:45], 0
	v_mfma_f32_16x16x32_bf16 v[42:45], v[26:29], v[42:45], 0
	v_mfma_f32_16x16x32_bf16 v[38:41], v[22:25], v[46:49], v[38:41]
	v_mfma_f32_16x16x32_bf16 v[42:45], v[30:33], v[46:49], v[42:45]
	v_mfma_f32_16x16x32_bf16 v[46:49], v[18:21], v[50:53], 0
	v_mfma_f32_16x16x32_bf16 v[50:53], v[26:29], v[50:53], 0
	v_mfma_f32_16x16x32_bf16 v[46:49], v[22:25], v[54:57], v[46:49]
	v_mfma_f32_16x16x32_bf16 v[50:53], v[30:33], v[54:57], v[50:53]
	v_mfma_f32_16x16x32_bf16 v[54:57], v[18:21], v[58:61], 0
	v_mfma_f32_16x16x32_bf16 v[58:61], v[26:29], v[58:61], 0
	v_mfma_f32_16x16x32_bf16 v[54:57], v[22:25], v[62:65], v[54:57]
	v_mfma_f32_16x16x32_bf16 v[58:61], v[30:33], v[62:65], v[58:61]
	s_setprio 0
	s_barrier
	s_add_i32 s83, s73, s33
	v_lshl_add_u64 v[136:137], s[6:7], 0, v[140:141]
	s_add_i32 s84, s83, 0x2000
	v_lshl_add_u64 v[130:131], v[136:137], 0, s[20:21]
	s_mov_b32 m0, s83
	v_lshl_add_u64 v[250:251], s[6:7], 0, v[144:145]
	s_add_u32 s14, s6, 0x20100
	ds_read_b128 v[62:65], v160 offset:16384
	ds_read_b128 v[90:93], v160 offset:17408
	ds_read_b128 v[94:97], v160 offset:18432
	ds_read_b128 v[98:101], v160 offset:19456
	ds_read_b128 v[110:113], v160 offset:20480
	ds_read_b128 v[114:117], v160 offset:21504
	ds_read_b128 v[118:121], v160 offset:22528
	ds_read_b128 v[126:129], v160 offset:23552
	global_load_lds_dwordx4 v[130:131], off
	v_lshl_add_u64 v[130:131], v[250:251], 0, s[20:21]
	s_mov_b32 m0, s84
	s_addc_u32 s15, s7, 0
	s_add_i32 s85, s74, s33
	global_load_lds_dwordx4 v[130:131], off
	v_lshl_add_u64 v[130:131], s[14:15], 0, v[140:141]
	s_mov_b32 m0, s85
	s_add_i32 s46, s85, 0x2000
	global_load_lds_dwordx4 v[130:131], off
	v_lshl_add_u64 v[130:131], s[14:15], 0, v[144:145]
	s_mov_b32 m0, s46
	v_lshl_add_u64 v[252:253], s[64:65], 0, v[138:139]
	global_load_lds_dwordx4 v[130:131], off
	v_lshl_add_u64 v[130:131], v[252:253], 0, s[20:21]
	s_mov_b32 m0, s58
	v_lshl_add_u64 v[150:151], s[64:65], 0, v[142:143]
	global_load_lds_dwordx4 v[130:131], off
	v_lshl_add_u64 v[130:131], v[150:151], 0, s[20:21]
	s_mov_b32 m0, s59
	s_nop 0
	global_load_lds_dwordx4 v[130:131], off
	s_waitcnt vmcnt(8)
	s_waitcnt lgkmcnt(0)
	s_barrier
	s_setprio 1
	v_mfma_f32_16x16x32_bf16 v[130:133], v[2:5], v[62:65], 0
	v_mfma_f32_16x16x32_bf16 v[162:165], v[2:5], v[94:97], 0
	v_mfma_f32_16x16x32_bf16 v[170:173], v[2:5], v[110:113], 0
	v_mfma_f32_16x16x32_bf16 v[2:5], v[2:5], v[118:121], 0
	v_mfma_f32_16x16x32_bf16 v[132:135], v[6:9], v[90:93], v[130:133]
	v_mfma_f32_16x16x32_bf16 v[162:165], v[6:9], v[98:101], v[162:165]
	v_mfma_f32_16x16x32_bf16 v[170:173], v[6:9], v[114:117], v[170:173]
	v_mfma_f32_16x16x32_bf16 v[2:5], v[6:9], v[126:129], v[2:5]
	v_mfma_f32_16x16x32_bf16 v[6:9], v[10:13], v[118:121], 0
	v_mfma_f32_16x16x32_bf16 v[154:157], v[10:13], v[62:65], 0
	v_mfma_f32_16x16x32_bf16 v[166:169], v[10:13], v[94:97], 0
	v_mfma_f32_16x16x32_bf16 v[174:177], v[10:13], v[110:113], 0
	v_mfma_f32_16x16x32_bf16 v[6:9], v[14:17], v[126:129], v[6:9]
	v_mfma_f32_16x16x32_bf16 v[154:157], v[14:17], v[90:93], v[154:157]
	v_mfma_f32_16x16x32_bf16 v[166:169], v[14:17], v[98:101], v[166:169]
	v_mfma_f32_16x16x32_bf16 v[174:177], v[14:17], v[114:117], v[174:177]
	s_setprio 0
	s_setprio 1
	v_mfma_f32_16x16x32_bf16 v[10:13], v[18:21], v[62:65], 0
	v_mfma_f32_16x16x32_bf16 v[178:181], v[22:25], v[90:93], v[10:13]
	v_mfma_f32_16x16x32_bf16 v[10:13], v[26:29], v[62:65], 0
	v_mfma_f32_16x16x32_bf16 v[182:185], v[30:33], v[90:93], v[10:13]
	v_mfma_f32_16x16x32_bf16 v[10:13], v[18:21], v[94:97], 0
	v_mfma_f32_16x16x32_bf16 v[186:189], v[22:25], v[98:101], v[10:13]
	v_mfma_f32_16x16x32_bf16 v[10:13], v[26:29], v[94:97], 0
	v_mfma_f32_16x16x32_bf16 v[190:193], v[30:33], v[98:101], v[10:13]
	v_mfma_f32_16x16x32_bf16 v[10:13], v[18:21], v[110:113], 0
	v_mfma_f32_16x16x32_bf16 v[194:197], v[22:25], v[114:117], v[10:13]
	v_mfma_f32_16x16x32_bf16 v[10:13], v[26:29], v[110:113], 0
	v_mfma_f32_16x16x32_bf16 v[198:201], v[30:33], v[114:117], v[10:13]
	v_mfma_f32_16x16x32_bf16 v[10:13], v[18:21], v[118:121], 0
	v_mfma_f32_16x16x32_bf16 v[202:205], v[22:25], v[126:129], v[10:13]
	v_mfma_f32_16x16x32_bf16 v[10:13], v[26:29], v[118:121], 0
	v_mfma_f32_16x16x32_bf16 v[206:209], v[30:33], v[126:129], v[10:13]
	s_setprio 0
	s_barrier
	s_add_i32 s47, 0, 0x18000
	s_add_i32 s56, 0, 0x1c000
	v_add_u32_e32 v130, s47, v1
	v_add_u32_e32 v131, s56, v1
	s_nop 0
	ds_read_b128 v[10:13], v130
	ds_read_b128 v[14:17], v130 offset:1024
	ds_read_b128 v[18:21], v130 offset:2048
	ds_read_b128 v[22:25], v130 offset:3072
	ds_read_b128 v[210:213], v131
	ds_read_b128 v[214:217], v131 offset:1024
	ds_read_b128 v[218:221], v131 offset:2048
	ds_read_b128 v[222:225], v131 offset:3072
	s_add_u32 s14, s64, 0x20100
	s_addc_u32 s15, s65, 0
	s_mov_b32 m0, s63
	v_lshl_add_u64 v[90:91], s[14:15], 0, v[138:139]
	ds_read_b128 v[26:29], v160 offset:32768
	ds_read_b128 v[30:33], v160 offset:33792
	ds_read_b128 v[62:65], v160 offset:34816
	ds_read_b128 v[226:229], v160 offset:35840
	ds_read_b128 v[230:233], v160 offset:36864
	ds_read_b128 v[234:237], v160 offset:37888
	ds_read_b128 v[238:241], v160 offset:38912
	ds_read_b128 v[242:245], v160 offset:39936
	global_load_lds_dwordx4 v[90:91], off
	v_lshl_add_u64 v[90:91], s[14:15], 0, v[142:143]
	s_mov_b32 m0, s68
	s_nop 0
	global_load_lds_dwordx4 v[90:91], off
	s_waitcnt vmcnt(8)
	s_waitcnt lgkmcnt(0)
	s_barrier
	s_setprio 1
	v_mfma_f32_16x16x32_bf16 v[66:69], v[10:13], v[26:29], v[66:69]
	v_mfma_f32_16x16x32_bf16 v[118:121], v[14:17], v[30:33], v[66:69]
	v_mfma_f32_16x16x32_bf16 v[66:69], v[18:21], v[26:29], v[70:73]
	v_mfma_f32_16x16x32_bf16 v[114:117], v[22:25], v[30:33], v[66:69]
	v_mfma_f32_16x16x32_bf16 v[66:69], v[10:13], v[62:65], v[74:77]
	v_mfma_f32_16x16x32_bf16 v[110:113], v[14:17], v[226:229], v[66:69]
	v_mfma_f32_16x16x32_bf16 v[66:69], v[18:21], v[62:65], v[78:81]
	v_mfma_f32_16x16x32_bf16 v[98:101], v[22:25], v[226:229], v[66:69]
	v_mfma_f32_16x16x32_bf16 v[66:69], v[10:13], v[230:233], v[82:85]
	v_mfma_f32_16x16x32_bf16 v[94:97], v[14:17], v[234:237], v[66:69]
	v_mfma_f32_16x16x32_bf16 v[66:69], v[18:21], v[230:233], v[86:89]
	v_mfma_f32_16x16x32_bf16 v[90:93], v[22:25], v[234:237], v[66:69]
	v_mfma_f32_16x16x32_bf16 v[66:69], v[10:13], v[238:241], v[102:105]
	v_mfma_f32_16x16x32_bf16 v[78:81], v[14:17], v[242:245], v[66:69]
	v_mfma_f32_16x16x32_bf16 v[66:69], v[18:21], v[238:241], v[106:109]
	v_mfma_f32_16x16x32_bf16 v[70:73], v[22:25], v[242:245], v[66:69]
	s_setprio 0
	s_setprio 1
	v_mfma_f32_16x16x32_bf16 v[66:69], v[210:213], v[26:29], v[122:125]
	v_mfma_f32_16x16x32_bf16 v[26:29], v[218:221], v[26:29], v[34:37]
	v_mfma_f32_16x16x32_bf16 v[122:125], v[222:225], v[30:33], v[26:29]
	v_mfma_f32_16x16x32_bf16 v[26:29], v[210:213], v[62:65], v[38:41]
	v_mfma_f32_16x16x32_bf16 v[106:109], v[214:217], v[226:229], v[26:29]
	v_mfma_f32_16x16x32_bf16 v[26:29], v[218:221], v[62:65], v[42:45]
	v_mfma_f32_16x16x32_bf16 v[102:105], v[222:225], v[226:229], v[26:29]
	v_mfma_f32_16x16x32_bf16 v[26:29], v[210:213], v[230:233], v[46:49]
	v_mfma_f32_16x16x32_bf16 v[86:89], v[214:217], v[234:237], v[26:29]
	v_mfma_f32_16x16x32_bf16 v[26:29], v[218:221], v[230:233], v[50:53]
	v_mfma_f32_16x16x32_bf16 v[82:85], v[222:225], v[234:237], v[26:29]
	v_mfma_f32_16x16x32_bf16 v[26:29], v[210:213], v[238:241], v[54:57]
	v_mfma_f32_16x16x32_bf16 v[62:65], v[214:217], v[242:245], v[26:29]
	v_mfma_f32_16x16x32_bf16 v[26:29], v[218:221], v[238:241], v[58:61]
	v_mfma_f32_16x16x32_bf16 v[126:129], v[214:217], v[30:33], v[66:69]
	v_mfma_f32_16x16x32_bf16 v[58:61], v[222:225], v[242:245], v[26:29]
	s_setprio 0
	s_barrier
	s_add_i32 s47, s47, s33
	s_add_i32 s86, s47, 0x2000
	s_nop 1
	v_lshl_add_u64 v[26:27], v[136:137], 0, s[22:23]
	s_mov_b32 m0, s47
	s_add_u32 s14, s6, 0x20180
	ds_read_b128 v[34:37], v160 offset:49152
	ds_read_b128 v[38:41], v160 offset:50176
	ds_read_b128 v[226:229], v160 offset:51200
	ds_read_b128 v[230:233], v160 offset:52224
	ds_read_b128 v[234:237], v160 offset:53248
	ds_read_b128 v[238:241], v160 offset:54272
	ds_read_b128 v[242:245], v160 offset:55296
	ds_read_b128 v[246:249], v160 offset:56320
	global_load_lds_dwordx4 v[26:27], off
	v_lshl_add_u64 v[26:27], v[250:251], 0, s[22:23]
	s_mov_b32 m0, s86
	s_addc_u32 s15, s7, 0
	s_add_i32 s56, s56, s33
	global_load_lds_dwordx4 v[26:27], off
	v_lshl_add_u64 v[26:27], s[14:15], 0, v[140:141]
	s_mov_b32 m0, s56
	s_add_i32 s57, s56, 0x2000
	global_load_lds_dwordx4 v[26:27], off
	v_lshl_add_u64 v[26:27], s[14:15], 0, v[144:145]
	s_mov_b32 m0, s57
	s_nop 0
	global_load_lds_dwordx4 v[26:27], off
	v_lshl_add_u64 v[26:27], v[252:253], 0, s[22:23]
	s_mov_b32 m0, s69
	s_nop 0
	global_load_lds_dwordx4 v[26:27], off
	v_lshl_add_u64 v[26:27], v[150:151], 0, s[22:23]
	s_mov_b32 m0, s70
	s_nop 0
	global_load_lds_dwordx4 v[26:27], off
	s_waitcnt vmcnt(8)
	s_waitcnt lgkmcnt(0)
	s_barrier
	s_setprio 1
	v_mfma_f32_16x16x32_bf16 v[26:29], v[10:13], v[34:37], v[132:135]
	v_mfma_f32_16x16x32_bf16 v[74:77], v[14:17], v[38:41], v[26:29]
	v_mfma_f32_16x16x32_bf16 v[26:29], v[18:21], v[34:37], v[154:157]
	v_mfma_f32_16x16x32_bf16 v[66:69], v[22:25], v[38:41], v[26:29]
	v_mfma_f32_16x16x32_bf16 v[26:29], v[10:13], v[226:229], v[162:165]
	v_mfma_f32_16x16x32_bf16 v[46:49], v[14:17], v[230:233], v[26:29]
	v_mfma_f32_16x16x32_bf16 v[26:29], v[18:21], v[226:229], v[166:169]
	v_mfma_f32_16x16x32_bf16 v[42:45], v[22:25], v[230:233], v[26:29]
	v_mfma_f32_16x16x32_bf16 v[26:29], v[10:13], v[234:237], v[170:173]
	v_mfma_f32_16x16x32_bf16 v[2:5], v[10:13], v[242:245], v[2:5]
	v_mfma_f32_16x16x32_bf16 v[30:33], v[14:17], v[238:241], v[26:29]
	v_mfma_f32_16x16x32_bf16 v[26:29], v[18:21], v[234:237], v[174:177]
	v_mfma_f32_16x16x32_bf16 v[14:17], v[14:17], v[246:249], v[2:5]
	v_mfma_f32_16x16x32_bf16 v[2:5], v[18:21], v[242:245], v[6:9]
	v_mfma_f32_16x16x32_bf16 v[26:29], v[22:25], v[238:241], v[26:29]
	v_mfma_f32_16x16x32_bf16 v[10:13], v[22:25], v[246:249], v[2:5]
	s_setprio 0
	s_setprio 1
	v_mfma_f32_16x16x32_bf16 v[2:5], v[210:213], v[34:37], v[178:181]
	v_mfma_f32_16x16x32_bf16 v[54:57], v[214:217], v[38:41], v[2:5]
	v_mfma_f32_16x16x32_bf16 v[2:5], v[218:221], v[34:37], v[182:185]
	v_mfma_f32_16x16x32_bf16 v[50:53], v[222:225], v[38:41], v[2:5]
	v_mfma_f32_16x16x32_bf16 v[2:5], v[210:213], v[226:229], v[186:189]
	v_mfma_f32_16x16x32_bf16 v[38:41], v[214:217], v[230:233], v[2:5]
	v_mfma_f32_16x16x32_bf16 v[2:5], v[218:221], v[226:229], v[190:193]
	v_mfma_f32_16x16x32_bf16 v[34:37], v[222:225], v[230:233], v[2:5]
	v_mfma_f32_16x16x32_bf16 v[2:5], v[210:213], v[234:237], v[194:197]
	v_mfma_f32_16x16x32_bf16 v[22:25], v[214:217], v[238:241], v[2:5]
	v_mfma_f32_16x16x32_bf16 v[2:5], v[218:221], v[234:237], v[198:201]
	v_mfma_f32_16x16x32_bf16 v[18:21], v[222:225], v[238:241], v[2:5]
	v_mfma_f32_16x16x32_bf16 v[2:5], v[210:213], v[242:245], v[202:205]
	v_mfma_f32_16x16x32_bf16 v[6:9], v[214:217], v[246:249], v[2:5]
	v_mfma_f32_16x16x32_bf16 v[2:5], v[218:221], v[242:245], v[206:209]
	v_mfma_f32_16x16x32_bf16 v[2:5], v[222:225], v[246:249], v[2:5]
	s_setprio 0
	s_barrier
	s_add_u32 s64, s64, 0x20180
	s_addc_u32 s65, s65, 0
	s_add_u32 s14, s6, 0x200
	s_addc_u32 s15, s7, 0
	s_mov_b32 s26, 0
.LBB0_670:
	ds_read_b128 v[132:135], v158
	ds_read_b128 v[154:157], v158 offset:1024
	ds_read_b128 v[162:165], v158 offset:2048
	ds_read_b128 v[166:169], v158 offset:3072
	ds_read_b128 v[170:173], v159
	ds_read_b128 v[174:177], v159 offset:1024
	ds_read_b128 v[178:181], v159 offset:2048
	ds_read_b128 v[182:185], v159 offset:3072
	s_add_u32 s6, s64, 0xfffe0080
	s_addc_u32 s7, s65, -1
	s_cmp_eq_u32 s26, 4
	s_cselect_b32 s67, s29, s7
	s_cselect_b32 s66, s79, s6
	s_cselect_b32 s7, s0, s15
	s_cselect_b32 s6, s80, s14
	s_mov_b32 m0, s81
	ds_read_b128 v[186:189], v160
	ds_read_b128 v[190:193], v160 offset:1024
	ds_read_b128 v[194:197], v160 offset:2048
	ds_read_b128 v[198:201], v160 offset:3072
	ds_read_b128 v[202:205], v160 offset:4096
	ds_read_b128 v[206:209], v160 offset:5120
	ds_read_b128 v[210:213], v160 offset:6144
	ds_read_b128 v[214:217], v160 offset:7168
	global_load_lds_dwordx4 v146, s[64:65]
	s_mov_b32 m0, s82
	s_nop 0
	global_load_lds_dwordx4 v148, s[64:65]
	s_waitcnt vmcnt(8)
	s_waitcnt lgkmcnt(0)
	s_barrier
	s_setprio 1
	v_mfma_f32_16x16x32_bf16 v[118:121], v[132:135], v[186:189], v[118:121]
	v_mfma_f32_16x16x32_bf16 v[114:117], v[162:165], v[186:189], v[114:117]
	v_mfma_f32_16x16x32_bf16 v[110:113], v[132:135], v[194:197], v[110:113]
	v_mfma_f32_16x16x32_bf16 v[98:101], v[162:165], v[194:197], v[98:101]
	v_mfma_f32_16x16x32_bf16 v[94:97], v[132:135], v[202:205], v[94:97]
	v_mfma_f32_16x16x32_bf16 v[90:93], v[162:165], v[202:205], v[90:93]
	v_mfma_f32_16x16x32_bf16 v[78:81], v[132:135], v[210:213], v[78:81]
	v_mfma_f32_16x16x32_bf16 v[70:73], v[162:165], v[210:213], v[70:73]
	v_mfma_f32_16x16x32_bf16 v[118:121], v[154:157], v[190:193], v[118:121]
	v_mfma_f32_16x16x32_bf16 v[114:117], v[166:169], v[190:193], v[114:117]
	v_mfma_f32_16x16x32_bf16 v[110:113], v[154:157], v[198:201], v[110:113]
	v_mfma_f32_16x16x32_bf16 v[98:101], v[166:169], v[198:201], v[98:101]
	v_mfma_f32_16x16x32_bf16 v[94:97], v[154:157], v[206:209], v[94:97]
	v_mfma_f32_16x16x32_bf16 v[90:93], v[166:169], v[206:209], v[90:93]
	v_mfma_f32_16x16x32_bf16 v[78:81], v[154:157], v[214:217], v[78:81]
	v_mfma_f32_16x16x32_bf16 v[70:73], v[166:169], v[214:217], v[70:73]
	s_setprio 0
	s_setprio 1
	v_mfma_f32_16x16x32_bf16 v[126:129], v[170:173], v[186:189], v[126:129]
	v_mfma_f32_16x16x32_bf16 v[122:125], v[178:181], v[186:189], v[122:125]
	v_mfma_f32_16x16x32_bf16 v[106:109], v[170:173], v[194:197], v[106:109]
	v_mfma_f32_16x16x32_bf16 v[102:105], v[178:181], v[194:197], v[102:105]
	v_mfma_f32_16x16x32_bf16 v[86:89], v[170:173], v[202:205], v[86:89]
	v_mfma_f32_16x16x32_bf16 v[82:85], v[178:181], v[202:205], v[82:85]
	v_mfma_f32_16x16x32_bf16 v[62:65], v[170:173], v[210:213], v[62:65]
	v_mfma_f32_16x16x32_bf16 v[58:61], v[178:181], v[210:213], v[58:61]
	v_mfma_f32_16x16x32_bf16 v[126:129], v[174:177], v[190:193], v[126:129]
	v_mfma_f32_16x16x32_bf16 v[122:125], v[182:185], v[190:193], v[122:125]
	v_mfma_f32_16x16x32_bf16 v[106:109], v[174:177], v[198:201], v[106:109]
	v_mfma_f32_16x16x32_bf16 v[102:105], v[182:185], v[198:201], v[102:105]
	v_mfma_f32_16x16x32_bf16 v[86:89], v[174:177], v[206:209], v[86:89]
	v_mfma_f32_16x16x32_bf16 v[82:85], v[182:185], v[206:209], v[82:85]
	v_mfma_f32_16x16x32_bf16 v[62:65], v[174:177], v[214:217], v[62:65]
	v_mfma_f32_16x16x32_bf16 v[58:61], v[182:185], v[214:217], v[58:61]
	s_setprio 0
	s_barrier
	s_mov_b32 m0, s83
	s_mov_b64 s[98:99], s[6:7]
	s_add_u32 s88, s6, 0x20000
	ds_read_b128 v[186:189], v160 offset:16384
	ds_read_b128 v[190:193], v160 offset:17408
	ds_read_b128 v[194:197], v160 offset:18432
	ds_read_b128 v[198:201], v160 offset:19456
	ds_read_b128 v[202:205], v160 offset:20480
	ds_read_b128 v[206:209], v160 offset:21504
	ds_read_b128 v[210:213], v160 offset:22528
	ds_read_b128 v[214:217], v160 offset:23552
	global_load_lds_dwordx4 v140, s[6:7]
	s_mov_b32 m0, s84
	s_addc_u32 s89, s7, 0
	global_load_lds_dwordx4 v144, s[6:7]
	s_mov_b32 m0, s85
	s_mov_b64 s[100:101], s[66:67]
	global_load_lds_dwordx4 v140, s[88:89]
	s_mov_b32 m0, s46
	s_nop 0
	global_load_lds_dwordx4 v144, s[88:89]
	s_mov_b32 m0, s58
	s_nop 0
	global_load_lds_dwordx4 v138, s[66:67]
	s_mov_b32 m0, s59
	s_nop 0
	global_load_lds_dwordx4 v142, s[66:67]
	s_waitcnt vmcnt(8)
	s_waitcnt lgkmcnt(0)
	s_barrier
	s_setprio 1
	v_mfma_f32_16x16x32_bf16 v[74:77], v[132:135], v[186:189], v[74:77]
	v_mfma_f32_16x16x32_bf16 v[66:69], v[162:165], v[186:189], v[66:69]
	v_mfma_f32_16x16x32_bf16 v[46:49], v[132:135], v[194:197], v[46:49]
	v_mfma_f32_16x16x32_bf16 v[42:45], v[162:165], v[194:197], v[42:45]
	v_mfma_f32_16x16x32_bf16 v[30:33], v[132:135], v[202:205], v[30:33]
	v_mfma_f32_16x16x32_bf16 v[26:29], v[162:165], v[202:205], v[26:29]
	v_mfma_f32_16x16x32_bf16 v[14:17], v[132:135], v[210:213], v[14:17]
	v_mfma_f32_16x16x32_bf16 v[10:13], v[162:165], v[210:213], v[10:13]
	v_mfma_f32_16x16x32_bf16 v[74:77], v[154:157], v[190:193], v[74:77]
	v_mfma_f32_16x16x32_bf16 v[66:69], v[166:169], v[190:193], v[66:69]
	v_mfma_f32_16x16x32_bf16 v[46:49], v[154:157], v[198:201], v[46:49]
	v_mfma_f32_16x16x32_bf16 v[42:45], v[166:169], v[198:201], v[42:45]
	v_mfma_f32_16x16x32_bf16 v[30:33], v[154:157], v[206:209], v[30:33]
	v_mfma_f32_16x16x32_bf16 v[26:29], v[166:169], v[206:209], v[26:29]
	v_mfma_f32_16x16x32_bf16 v[14:17], v[154:157], v[214:217], v[14:17]
	v_mfma_f32_16x16x32_bf16 v[10:13], v[166:169], v[214:217], v[10:13]
	s_setprio 0
	s_setprio 1
	v_mfma_f32_16x16x32_bf16 v[54:57], v[170:173], v[186:189], v[54:57]
	v_mfma_f32_16x16x32_bf16 v[50:53], v[178:181], v[186:189], v[50:53]
	v_mfma_f32_16x16x32_bf16 v[38:41], v[170:173], v[194:197], v[38:41]
	v_mfma_f32_16x16x32_bf16 v[34:37], v[178:181], v[194:197], v[34:37]
	v_mfma_f32_16x16x32_bf16 v[22:25], v[170:173], v[202:205], v[22:25]
	v_mfma_f32_16x16x32_bf16 v[18:21], v[178:181], v[202:205], v[18:21]
	v_mfma_f32_16x16x32_bf16 v[6:9], v[170:173], v[210:213], v[6:9]
	v_mfma_f32_16x16x32_bf16 v[2:5], v[178:181], v[210:213], v[2:5]
	v_mfma_f32_16x16x32_bf16 v[54:57], v[174:177], v[190:193], v[54:57]
	v_mfma_f32_16x16x32_bf16 v[50:53], v[182:185], v[190:193], v[50:53]
	v_mfma_f32_16x16x32_bf16 v[38:41], v[174:177], v[198:201], v[38:41]
	v_mfma_f32_16x16x32_bf16 v[34:37], v[182:185], v[198:201], v[34:37]
	v_mfma_f32_16x16x32_bf16 v[22:25], v[174:177], v[206:209], v[22:25]
	v_mfma_f32_16x16x32_bf16 v[18:21], v[182:185], v[206:209], v[18:21]
	v_mfma_f32_16x16x32_bf16 v[6:9], v[174:177], v[214:217], v[6:9]
	v_mfma_f32_16x16x32_bf16 v[2:5], v[182:185], v[214:217], v[2:5]
	s_setprio 0
	s_barrier
; #define PG8_BAR __builtin_amdgcn_s_barrier()
;     ...
;         for (int t = 2; t < nt; t += 2) PG8_KITER(t);
;         if constexpr (ALIGN_EPI) { if (wr == 0) PG8_BAR; }
	ds_read_b128 v[132:135], v130
	ds_read_b128 v[154:157], v130 offset:1024
	ds_read_b128 v[162:165], v130 offset:2048
	ds_read_b128 v[166:169], v130 offset:3072
	ds_read_b128 v[170:173], v131
	ds_read_b128 v[174:177], v131 offset:1024
	ds_read_b128 v[178:181], v131 offset:2048
	ds_read_b128 v[182:185], v131 offset:3072
	s_add_u32 s66, s66, 0x20000
	s_addc_u32 s67, s67, 0
	s_mov_b32 m0, s63
	ds_read_b128 v[186:189], v160 offset:32768
	ds_read_b128 v[190:193], v160 offset:33792
	ds_read_b128 v[194:197], v160 offset:34816
	ds_read_b128 v[198:201], v160 offset:35840
	ds_read_b128 v[202:205], v160 offset:36864
	ds_read_b128 v[206:209], v160 offset:37888
	ds_read_b128 v[210:213], v160 offset:38912
	ds_read_b128 v[214:217], v160 offset:39936
	global_load_lds_dwordx4 v138, s[66:67]
	s_mov_b32 m0, s68
	s_nop 0
	global_load_lds_dwordx4 v142, s[66:67]
	s_waitcnt vmcnt(8)
	s_waitcnt lgkmcnt(0)
	s_barrier
	s_setprio 1
	v_mfma_f32_16x16x32_bf16 v[118:121], v[132:135], v[186:189], v[118:121]
	v_mfma_f32_16x16x32_bf16 v[114:117], v[162:165], v[186:189], v[114:117]
	v_mfma_f32_16x16x32_bf16 v[110:113], v[132:135], v[194:197], v[110:113]
	v_mfma_f32_16x16x32_bf16 v[98:101], v[162:165], v[194:197], v[98:101]
	v_mfma_f32_16x16x32_bf16 v[94:97], v[132:135], v[202:205], v[94:97]
	v_mfma_f32_16x16x32_bf16 v[90:93], v[162:165], v[202:205], v[90:93]
	v_mfma_f32_16x16x32_bf16 v[78:81], v[132:135], v[210:213], v[78:81]
	v_mfma_f32_16x16x32_bf16 v[70:73], v[162:165], v[210:213], v[70:73]
	v_mfma_f32_16x16x32_bf16 v[118:121], v[154:157], v[190:193], v[118:121]
	v_mfma_f32_16x16x32_bf16 v[114:117], v[166:169], v[190:193], v[114:117]
	v_mfma_f32_16x16x32_bf16 v[110:113], v[154:157], v[198:201], v[110:113]
	v_mfma_f32_16x16x32_bf16 v[98:101], v[166:169], v[198:201], v[98:101]
	v_mfma_f32_16x16x32_bf16 v[94:97], v[154:157], v[206:209], v[94:97]
	v_mfma_f32_16x16x32_bf16 v[90:93], v[166:169], v[206:209], v[90:93]
	v_mfma_f32_16x16x32_bf16 v[78:81], v[154:157], v[214:217], v[78:81]
	v_mfma_f32_16x16x32_bf16 v[70:73], v[166:169], v[214:217], v[70:73]
	s_setprio 0
	s_setprio 1
	v_mfma_f32_16x16x32_bf16 v[126:129], v[170:173], v[186:189], v[126:129]
	v_mfma_f32_16x16x32_bf16 v[122:125], v[178:181], v[186:189], v[122:125]
	v_mfma_f32_16x16x32_bf16 v[106:109], v[170:173], v[194:197], v[106:109]
	v_mfma_f32_16x16x32_bf16 v[102:105], v[178:181], v[194:197], v[102:105]
	v_mfma_f32_16x16x32_bf16 v[86:89], v[170:173], v[202:205], v[86:89]
	v_mfma_f32_16x16x32_bf16 v[82:85], v[178:181], v[202:205], v[82:85]
	v_mfma_f32_16x16x32_bf16 v[62:65], v[170:173], v[210:213], v[62:65]
	v_mfma_f32_16x16x32_bf16 v[58:61], v[178:181], v[210:213], v[58:61]
	v_mfma_f32_16x16x32_bf16 v[126:129], v[174:177], v[190:193], v[126:129]
	v_mfma_f32_16x16x32_bf16 v[122:125], v[182:185], v[190:193], v[122:125]
	v_mfma_f32_16x16x32_bf16 v[106:109], v[174:177], v[198:201], v[106:109]
	v_mfma_f32_16x16x32_bf16 v[102:105], v[182:185], v[198:201], v[102:105]
	v_mfma_f32_16x16x32_bf16 v[86:89], v[174:177], v[206:209], v[86:89]
	v_mfma_f32_16x16x32_bf16 v[82:85], v[182:185], v[206:209], v[82:85]
	v_mfma_f32_16x16x32_bf16 v[62:65], v[174:177], v[214:217], v[62:65]
	v_mfma_f32_16x16x32_bf16 v[58:61], v[182:185], v[214:217], v[58:61]
	s_setprio 0
	s_barrier
	s_mov_b32 m0, s47
	s_add_u32 s98, s98, 0x80
	s_addc_u32 s99, s99, 0
	s_add_u32 s100, s100, 0x80
	s_addc_u32 s101, s101, 0
	s_add_u32 s6, s6, 0x20080
	ds_read_b128 v[186:189], v160 offset:49152
	ds_read_b128 v[190:193], v160 offset:50176
	ds_read_b128 v[194:197], v160 offset:51200
	ds_read_b128 v[198:201], v160 offset:52224
	ds_read_b128 v[202:205], v160 offset:53248
	ds_read_b128 v[206:209], v160 offset:54272
	ds_read_b128 v[210:213], v160 offset:55296
	ds_read_b128 v[214:217], v160 offset:56320
	global_load_lds_dwordx4 v140, s[98:99]
	s_mov_b32 m0, s86
	s_addc_u32 s7, s7, 0
	global_load_lds_dwordx4 v144, s[98:99]
	s_mov_b32 m0, s56
	s_nop 0
	global_load_lds_dwordx4 v140, s[6:7]
	s_mov_b32 m0, s57
	s_nop 0
	global_load_lds_dwordx4 v144, s[6:7]
	s_mov_b32 m0, s69
	s_nop 0
	global_load_lds_dwordx4 v138, s[100:101]
	s_mov_b32 m0, s70
	s_nop 0
	global_load_lds_dwordx4 v142, s[100:101]
	s_waitcnt vmcnt(8)
	s_waitcnt lgkmcnt(0)
	s_barrier
	s_setprio 1
	v_mfma_f32_16x16x32_bf16 v[74:77], v[132:135], v[186:189], v[74:77]
	v_mfma_f32_16x16x32_bf16 v[66:69], v[162:165], v[186:189], v[66:69]
	v_mfma_f32_16x16x32_bf16 v[46:49], v[132:135], v[194:197], v[46:49]
	v_mfma_f32_16x16x32_bf16 v[42:45], v[162:165], v[194:197], v[42:45]
	v_mfma_f32_16x16x32_bf16 v[30:33], v[132:135], v[202:205], v[30:33]
	v_mfma_f32_16x16x32_bf16 v[26:29], v[162:165], v[202:205], v[26:29]
	v_mfma_f32_16x16x32_bf16 v[14:17], v[132:135], v[210:213], v[14:17]
	v_mfma_f32_16x16x32_bf16 v[10:13], v[162:165], v[210:213], v[10:13]
	v_mfma_f32_16x16x32_bf16 v[74:77], v[154:157], v[190:193], v[74:77]
	v_mfma_f32_16x16x32_bf16 v[66:69], v[166:169], v[190:193], v[66:69]
	v_mfma_f32_16x16x32_bf16 v[46:49], v[154:157], v[198:201], v[46:49]
	v_mfma_f32_16x16x32_bf16 v[42:45], v[166:169], v[198:201], v[42:45]
	v_mfma_f32_16x16x32_bf16 v[30:33], v[154:157], v[206:209], v[30:33]
	v_mfma_f32_16x16x32_bf16 v[26:29], v[166:169], v[206:209], v[26:29]
	v_mfma_f32_16x16x32_bf16 v[14:17], v[154:157], v[214:217], v[14:17]
	v_mfma_f32_16x16x32_bf16 v[10:13], v[166:169], v[214:217], v[10:13]
	s_setprio 0
	s_setprio 1
	v_mfma_f32_16x16x32_bf16 v[54:57], v[170:173], v[186:189], v[54:57]
	v_mfma_f32_16x16x32_bf16 v[50:53], v[178:181], v[186:189], v[50:53]
	v_mfma_f32_16x16x32_bf16 v[38:41], v[170:173], v[194:197], v[38:41]
	v_mfma_f32_16x16x32_bf16 v[34:37], v[178:181], v[194:197], v[34:37]
	v_mfma_f32_16x16x32_bf16 v[22:25], v[170:173], v[202:205], v[22:25]
	v_mfma_f32_16x16x32_bf16 v[18:21], v[178:181], v[202:205], v[18:21]
	v_mfma_f32_16x16x32_bf16 v[6:9], v[170:173], v[210:213], v[6:9]
	v_mfma_f32_16x16x32_bf16 v[2:5], v[178:181], v[210:213], v[2:5]
	v_mfma_f32_16x16x32_bf16 v[54:57], v[174:177], v[190:193], v[54:57]
	v_mfma_f32_16x16x32_bf16 v[50:53], v[182:185], v[190:193], v[50:53]
	v_mfma_f32_16x16x32_bf16 v[38:41], v[174:177], v[198:201], v[38:41]
	v_mfma_f32_16x16x32_bf16 v[34:37], v[182:185], v[198:201], v[34:37]
	v_mfma_f32_16x16x32_bf16 v[22:25], v[174:177], v[206:209], v[22:25]
	v_mfma_f32_16x16x32_bf16 v[18:21], v[182:185], v[206:209], v[18:21]
	v_mfma_f32_16x16x32_bf16 v[6:9], v[174:177], v[214:217], v[6:9]
	v_mfma_f32_16x16x32_bf16 v[2:5], v[182:185], v[214:217], v[2:5]
	s_setprio 0
	s_barrier
	s_add_i32 s26, s26, 2
	s_add_u32 s64, s64, 0x100
	s_addc_u32 s65, s65, 0
	s_add_u32 s14, s14, 0x100
	s_addc_u32 s15, s15, 0
	s_cmp_gt_u32 s26, 5
	s_cbranch_scc0 .LBB0_670
	s_and_b64 vcc, exec, s[18:19]
	s_cbranch_vccz .LBB0_673
	s_barrier

.LBB0_715:
	ds_read_b128 v[2:5], v164
	ds_read_b128 v[6:9], v164 offset:1024
	ds_read_b128 v[10:13], v164 offset:2048
	ds_read_b128 v[14:17], v164 offset:3072
	ds_read_b128 v[18:21], v165
	ds_read_b128 v[22:25], v165 offset:1024
	ds_read_b128 v[26:29], v165 offset:2048
	ds_read_b128 v[30:33], v165 offset:3072
	s_add_u32 s14, s62, 0x80080
	s_addc_u32 s15, s63, 0
	s_add_i32 s23, s59, 0xc000
	v_lshl_add_u64 v[66:67], s[14:15], 0, v[146:147]
	s_mov_b32 m0, s23
	s_add_i32 s77, s59, 0xe000
	ds_read_b128 v[34:37], v166
	ds_read_b128 v[38:41], v166 offset:1024
	ds_read_b128 v[42:45], v166 offset:2048
	ds_read_b128 v[46:49], v166 offset:3072
	ds_read_b128 v[50:53], v166 offset:4096
	ds_read_b128 v[54:57], v166 offset:5120
	ds_read_b128 v[58:61], v166 offset:6144
	ds_read_b128 v[62:65], v166 offset:7168
	global_load_lds_dwordx4 v[66:67], off
	v_lshl_add_u64 v[66:67], s[14:15], 0, v[150:151]
	s_mov_b32 m0, s77
	s_nop 0
	global_load_lds_dwordx4 v[66:67], off
	s_waitcnt vmcnt(8)
	s_waitcnt lgkmcnt(0)
	s_barrier
	s_setprio 1
	v_mfma_f32_16x16x32_bf16 v[86:89], v[10:13], v[50:53], 0
	v_mfma_f32_16x16x32_bf16 v[106:109], v[14:17], v[54:57], v[86:89]
	v_mfma_f32_16x16x32_bf16 v[86:89], v[2:5], v[58:61], 0
	v_mfma_f32_16x16x32_bf16 v[66:69], v[2:5], v[34:37], 0
	v_mfma_f32_16x16x32_bf16 v[70:73], v[10:13], v[34:37], 0
	v_mfma_f32_16x16x32_bf16 v[74:77], v[2:5], v[42:45], 0
	v_mfma_f32_16x16x32_bf16 v[78:81], v[10:13], v[42:45], 0
	v_mfma_f32_16x16x32_bf16 v[82:85], v[2:5], v[50:53], 0
	v_mfma_f32_16x16x32_bf16 v[110:113], v[6:9], v[62:65], v[86:89]
	v_mfma_f32_16x16x32_bf16 v[86:89], v[10:13], v[58:61], 0
	v_mfma_f32_16x16x32_bf16 v[66:69], v[6:9], v[38:41], v[66:69]
	v_mfma_f32_16x16x32_bf16 v[70:73], v[14:17], v[38:41], v[70:73]
	v_mfma_f32_16x16x32_bf16 v[74:77], v[6:9], v[46:49], v[74:77]
	v_mfma_f32_16x16x32_bf16 v[78:81], v[14:17], v[46:49], v[78:81]
	v_mfma_f32_16x16x32_bf16 v[82:85], v[6:9], v[54:57], v[82:85]
	v_mfma_f32_16x16x32_bf16 v[114:117], v[14:17], v[62:65], v[86:89]
	s_setprio 0
	s_setprio 1
	v_mfma_f32_16x16x32_bf16 v[86:89], v[18:21], v[34:37], 0
	v_mfma_f32_16x16x32_bf16 v[34:37], v[26:29], v[34:37], 0
	v_mfma_f32_16x16x32_bf16 v[118:121], v[22:25], v[38:41], v[86:89]
	v_mfma_f32_16x16x32_bf16 v[34:37], v[30:33], v[38:41], v[34:37]
	v_mfma_f32_16x16x32_bf16 v[38:41], v[18:21], v[42:45], 0
	v_mfma_f32_16x16x32_bf16 v[42:45], v[26:29], v[42:45], 0
	v_mfma_f32_16x16x32_bf16 v[38:41], v[22:25], v[46:49], v[38:41]
	v_mfma_f32_16x16x32_bf16 v[42:45], v[30:33], v[46:49], v[42:45]
	v_mfma_f32_16x16x32_bf16 v[46:49], v[18:21], v[50:53], 0
	v_mfma_f32_16x16x32_bf16 v[50:53], v[26:29], v[50:53], 0
	v_mfma_f32_16x16x32_bf16 v[46:49], v[22:25], v[54:57], v[46:49]
	v_mfma_f32_16x16x32_bf16 v[50:53], v[30:33], v[54:57], v[50:53]
	v_mfma_f32_16x16x32_bf16 v[54:57], v[18:21], v[58:61], 0
	v_mfma_f32_16x16x32_bf16 v[58:61], v[26:29], v[58:61], 0
	v_mfma_f32_16x16x32_bf16 v[54:57], v[22:25], v[62:65], v[54:57]
	v_mfma_f32_16x16x32_bf16 v[58:61], v[30:33], v[62:65], v[58:61]
	s_setprio 0
	s_barrier
	s_add_i32 s78, s72, s58
	v_lshl_add_u64 v[144:145], s[50:51], 0, v[148:149]
	s_add_i32 s79, s78, 0x2000
	v_lshl_add_u64 v[130:131], v[144:145], 0, s[18:19]
	s_mov_b32 m0, s78
	v_lshl_add_u64 v[162:163], s[50:51], 0, v[152:153]
	s_add_u32 s14, s50, 0x80100
	ds_read_b128 v[62:65], v166 offset:16384
	ds_read_b128 v[86:89], v166 offset:17408
	ds_read_b128 v[90:93], v166 offset:18432
	ds_read_b128 v[94:97], v166 offset:19456
	ds_read_b128 v[98:101], v166 offset:20480
	ds_read_b128 v[102:105], v166 offset:21504
	ds_read_b128 v[122:125], v166 offset:22528
	ds_read_b128 v[126:129], v166 offset:23552
	global_load_lds_dwordx4 v[130:131], off
	v_lshl_add_u64 v[130:131], v[162:163], 0, s[18:19]
	s_mov_b32 m0, s79
	s_addc_u32 s15, s51, 0
	s_add_i32 s80, s73, s58
	global_load_lds_dwordx4 v[130:131], off
	v_lshl_add_u64 v[130:131], s[14:15], 0, v[148:149]
	s_mov_b32 m0, s80
	s_add_i32 s46, s80, 0x2000
	global_load_lds_dwordx4 v[130:131], off
	v_lshl_add_u64 v[130:131], s[14:15], 0, v[152:153]
	s_mov_b32 m0, s46
	v_lshl_add_u64 v[252:253], s[62:63], 0, v[146:147]
	global_load_lds_dwordx4 v[130:131], off
	v_lshl_add_u64 v[130:131], v[252:253], 0, s[18:19]
	s_mov_b32 m0, s59
	v_lshl_add_u64 v[158:159], s[62:63], 0, v[150:151]
	global_load_lds_dwordx4 v[130:131], off
	v_lshl_add_u64 v[130:131], v[158:159], 0, s[18:19]
	s_mov_b32 m0, s31
	s_nop 0
	global_load_lds_dwordx4 v[130:131], off
	s_waitcnt vmcnt(8)
	s_waitcnt lgkmcnt(0)
	s_barrier
	s_setprio 1
	v_mfma_f32_16x16x32_bf16 v[130:133], v[2:5], v[62:65], 0
	v_mfma_f32_16x16x32_bf16 v[140:143], v[2:5], v[90:93], 0
	v_mfma_f32_16x16x32_bf16 v[172:175], v[2:5], v[98:101], 0
	v_mfma_f32_16x16x32_bf16 v[2:5], v[2:5], v[122:125], 0
	v_mfma_f32_16x16x32_bf16 v[132:135], v[6:9], v[86:89], v[130:133]
	v_mfma_f32_16x16x32_bf16 v[140:143], v[6:9], v[94:97], v[140:143]
	v_mfma_f32_16x16x32_bf16 v[172:175], v[6:9], v[102:105], v[172:175]
	v_mfma_f32_16x16x32_bf16 v[2:5], v[6:9], v[126:129], v[2:5]
	v_mfma_f32_16x16x32_bf16 v[6:9], v[10:13], v[122:125], 0
	v_mfma_f32_16x16x32_bf16 v[136:139], v[10:13], v[62:65], 0
	v_mfma_f32_16x16x32_bf16 v[168:171], v[10:13], v[90:93], 0
	v_mfma_f32_16x16x32_bf16 v[176:179], v[10:13], v[98:101], 0
	v_mfma_f32_16x16x32_bf16 v[6:9], v[14:17], v[126:129], v[6:9]
	v_mfma_f32_16x16x32_bf16 v[136:139], v[14:17], v[86:89], v[136:139]
	v_mfma_f32_16x16x32_bf16 v[168:171], v[14:17], v[94:97], v[168:171]
	v_mfma_f32_16x16x32_bf16 v[176:179], v[14:17], v[102:105], v[176:179]
	s_setprio 0
	s_setprio 1
	v_mfma_f32_16x16x32_bf16 v[10:13], v[18:21], v[62:65], 0
	v_mfma_f32_16x16x32_bf16 v[180:183], v[22:25], v[86:89], v[10:13]
	v_mfma_f32_16x16x32_bf16 v[10:13], v[26:29], v[62:65], 0
	v_mfma_f32_16x16x32_bf16 v[184:187], v[30:33], v[86:89], v[10:13]
	v_mfma_f32_16x16x32_bf16 v[10:13], v[18:21], v[90:93], 0
	v_mfma_f32_16x16x32_bf16 v[188:191], v[22:25], v[94:97], v[10:13]
	v_mfma_f32_16x16x32_bf16 v[10:13], v[26:29], v[90:93], 0
	v_mfma_f32_16x16x32_bf16 v[192:195], v[30:33], v[94:97], v[10:13]
	v_mfma_f32_16x16x32_bf16 v[10:13], v[18:21], v[98:101], 0
	v_mfma_f32_16x16x32_bf16 v[196:199], v[22:25], v[102:105], v[10:13]
	v_mfma_f32_16x16x32_bf16 v[10:13], v[26:29], v[98:101], 0
	v_mfma_f32_16x16x32_bf16 v[200:203], v[30:33], v[102:105], v[10:13]
	v_mfma_f32_16x16x32_bf16 v[10:13], v[18:21], v[122:125], 0
	v_mfma_f32_16x16x32_bf16 v[204:207], v[22:25], v[126:129], v[10:13]
	v_mfma_f32_16x16x32_bf16 v[10:13], v[26:29], v[122:125], 0
	v_mfma_f32_16x16x32_bf16 v[208:211], v[30:33], v[126:129], v[10:13]
	s_setprio 0
	s_barrier
;     ...
;         for (int t = 2; t < nt; t += 2) PG8_KITER(t);
	s_add_i32 s47, 0, 0x18000
	s_add_i32 s56, 0, 0x1c000
	v_add_u32_e32 v130, s47, v1
	v_add_u32_e32 v131, s56, v1
	s_nop 0
	ds_read_b128 v[10:13], v130
	ds_read_b128 v[14:17], v130 offset:1024
	ds_read_b128 v[18:21], v130 offset:2048
	ds_read_b128 v[22:25], v130 offset:3072
	ds_read_b128 v[212:215], v131
	ds_read_b128 v[216:219], v131 offset:1024
	ds_read_b128 v[220:223], v131 offset:2048
	ds_read_b128 v[224:227], v131 offset:3072
	s_add_u32 s14, s62, 0x80100
	s_addc_u32 s15, s63, 0
	s_mov_b32 m0, s66
	v_lshl_add_u64 v[62:63], s[14:15], 0, v[146:147]
	ds_read_b128 v[26:29], v166 offset:32768
	ds_read_b128 v[30:33], v166 offset:33792
	ds_read_b128 v[228:231], v166 offset:34816
	ds_read_b128 v[232:235], v166 offset:35840
	ds_read_b128 v[236:239], v166 offset:36864
	ds_read_b128 v[240:243], v166 offset:37888
	ds_read_b128 v[244:247], v166 offset:38912
	ds_read_b128 v[248:251], v166 offset:39936
	global_load_lds_dwordx4 v[62:63], off
	v_lshl_add_u64 v[62:63], s[14:15], 0, v[150:151]
	s_mov_b32 m0, s67
	s_nop 0
	global_load_lds_dwordx4 v[62:63], off
	s_waitcnt vmcnt(8)
	s_waitcnt lgkmcnt(0)
	s_barrier
	s_setprio 1
	v_mfma_f32_16x16x32_bf16 v[62:65], v[10:13], v[26:29], v[66:69]
	v_mfma_f32_16x16x32_bf16 v[102:105], v[14:17], v[30:33], v[62:65]
	v_mfma_f32_16x16x32_bf16 v[62:65], v[18:21], v[26:29], v[70:73]
	v_mfma_f32_16x16x32_bf16 v[98:101], v[22:25], v[30:33], v[62:65]
	v_mfma_f32_16x16x32_bf16 v[62:65], v[10:13], v[228:231], v[74:77]
	v_mfma_f32_16x16x32_bf16 v[94:97], v[14:17], v[232:235], v[62:65]
	v_mfma_f32_16x16x32_bf16 v[62:65], v[18:21], v[228:231], v[78:81]
	v_mfma_f32_16x16x32_bf16 v[90:93], v[22:25], v[232:235], v[62:65]
	v_mfma_f32_16x16x32_bf16 v[62:65], v[10:13], v[236:239], v[82:85]
	v_mfma_f32_16x16x32_bf16 v[86:89], v[14:17], v[240:243], v[62:65]
	v_mfma_f32_16x16x32_bf16 v[62:65], v[18:21], v[236:239], v[106:109]
	v_mfma_f32_16x16x32_bf16 v[82:85], v[22:25], v[240:243], v[62:65]
	v_mfma_f32_16x16x32_bf16 v[62:65], v[10:13], v[244:247], v[110:113]
	v_mfma_f32_16x16x32_bf16 v[78:81], v[14:17], v[248:251], v[62:65]
	v_mfma_f32_16x16x32_bf16 v[62:65], v[18:21], v[244:247], v[114:117]
	v_mfma_f32_16x16x32_bf16 v[62:65], v[22:25], v[248:251], v[62:65]
	s_setprio 0
	s_setprio 1
	v_mfma_f32_16x16x32_bf16 v[66:69], v[212:215], v[26:29], v[118:121]
	v_mfma_f32_16x16x32_bf16 v[26:29], v[220:223], v[26:29], v[34:37]
	v_mfma_f32_16x16x32_bf16 v[122:125], v[224:227], v[30:33], v[26:29]
	v_mfma_f32_16x16x32_bf16 v[26:29], v[212:215], v[228:231], v[38:41]
	v_mfma_f32_16x16x32_bf16 v[118:121], v[216:219], v[232:235], v[26:29]
	v_mfma_f32_16x16x32_bf16 v[26:29], v[220:223], v[228:231], v[42:45]
	v_mfma_f32_16x16x32_bf16 v[114:117], v[224:227], v[232:235], v[26:29]
	v_mfma_f32_16x16x32_bf16 v[26:29], v[212:215], v[236:239], v[46:49]
	v_mfma_f32_16x16x32_bf16 v[110:113], v[216:219], v[240:243], v[26:29]
	v_mfma_f32_16x16x32_bf16 v[26:29], v[220:223], v[236:239], v[50:53]
	v_mfma_f32_16x16x32_bf16 v[106:109], v[224:227], v[240:243], v[26:29]
	v_mfma_f32_16x16x32_bf16 v[26:29], v[212:215], v[244:247], v[54:57]
	v_mfma_f32_16x16x32_bf16 v[54:57], v[216:219], v[248:251], v[26:29]
	v_mfma_f32_16x16x32_bf16 v[26:29], v[220:223], v[244:247], v[58:61]
	v_mfma_f32_16x16x32_bf16 v[126:129], v[216:219], v[30:33], v[66:69]
	v_mfma_f32_16x16x32_bf16 v[50:53], v[224:227], v[248:251], v[26:29]
	s_setprio 0
	s_barrier
	s_add_i32 s47, s47, s58
	s_add_i32 s81, s47, 0x2000
	s_nop 1
	v_lshl_add_u64 v[26:27], v[144:145], 0, s[20:21]
	s_mov_b32 m0, s47
	s_add_u32 s14, s50, 0x80180
	ds_read_b128 v[34:37], v166 offset:49152
	ds_read_b128 v[38:41], v166 offset:50176
	ds_read_b128 v[228:231], v166 offset:51200
	ds_read_b128 v[232:235], v166 offset:52224
	ds_read_b128 v[236:239], v166 offset:53248
	ds_read_b128 v[240:243], v166 offset:54272
	ds_read_b128 v[244:247], v166 offset:55296
	ds_read_b128 v[248:251], v166 offset:56320
	global_load_lds_dwordx4 v[26:27], off
	v_lshl_add_u64 v[26:27], v[162:163], 0, s[20:21]
	s_mov_b32 m0, s81
	s_addc_u32 s15, s51, 0
	s_add_i32 s56, s56, s58
	global_load_lds_dwordx4 v[26:27], off
	v_lshl_add_u64 v[26:27], s[14:15], 0, v[148:149]
	s_mov_b32 m0, s56
	s_add_i32 s57, s56, 0x2000
	global_load_lds_dwordx4 v[26:27], off
	v_lshl_add_u64 v[26:27], s[14:15], 0, v[152:153]
	s_mov_b32 m0, s57
	s_nop 0
	global_load_lds_dwordx4 v[26:27], off
	v_lshl_add_u64 v[26:27], v[252:253], 0, s[20:21]
	s_mov_b32 m0, s69
	s_nop 0
	global_load_lds_dwordx4 v[26:27], off
	v_lshl_add_u64 v[26:27], v[158:159], 0, s[20:21]
	s_mov_b32 m0, s70
	s_nop 0
	global_load_lds_dwordx4 v[26:27], off
	s_waitcnt vmcnt(8)
	s_waitcnt lgkmcnt(0)
	s_barrier
	s_setprio 1
	v_mfma_f32_16x16x32_bf16 v[26:29], v[10:13], v[34:37], v[132:135]
	v_mfma_f32_16x16x32_bf16 v[74:77], v[14:17], v[38:41], v[26:29]
	v_mfma_f32_16x16x32_bf16 v[26:29], v[18:21], v[34:37], v[136:139]
	v_mfma_f32_16x16x32_bf16 v[70:73], v[22:25], v[38:41], v[26:29]
	v_mfma_f32_16x16x32_bf16 v[26:29], v[10:13], v[228:231], v[140:143]
	v_mfma_f32_16x16x32_bf16 v[46:49], v[14:17], v[232:235], v[26:29]
	v_mfma_f32_16x16x32_bf16 v[26:29], v[18:21], v[228:231], v[168:171]
	v_mfma_f32_16x16x32_bf16 v[42:45], v[22:25], v[232:235], v[26:29]
	v_mfma_f32_16x16x32_bf16 v[26:29], v[10:13], v[236:239], v[172:175]
	v_mfma_f32_16x16x32_bf16 v[2:5], v[10:13], v[244:247], v[2:5]
	v_mfma_f32_16x16x32_bf16 v[30:33], v[14:17], v[240:243], v[26:29]
	v_mfma_f32_16x16x32_bf16 v[26:29], v[18:21], v[236:239], v[176:179]
	v_mfma_f32_16x16x32_bf16 v[14:17], v[14:17], v[248:251], v[2:5]
	v_mfma_f32_16x16x32_bf16 v[2:5], v[18:21], v[244:247], v[6:9]
	v_mfma_f32_16x16x32_bf16 v[26:29], v[22:25], v[240:243], v[26:29]
	v_mfma_f32_16x16x32_bf16 v[10:13], v[22:25], v[248:251], v[2:5]
	s_setprio 0
	s_setprio 1
	v_mfma_f32_16x16x32_bf16 v[2:5], v[212:215], v[34:37], v[180:183]
	v_mfma_f32_16x16x32_bf16 v[66:69], v[216:219], v[38:41], v[2:5]
	v_mfma_f32_16x16x32_bf16 v[2:5], v[220:223], v[34:37], v[184:187]
	v_mfma_f32_16x16x32_bf16 v[58:61], v[224:227], v[38:41], v[2:5]
	v_mfma_f32_16x16x32_bf16 v[2:5], v[212:215], v[228:231], v[188:191]
	v_mfma_f32_16x16x32_bf16 v[38:41], v[216:219], v[232:235], v[2:5]
	v_mfma_f32_16x16x32_bf16 v[2:5], v[220:223], v[228:231], v[192:195]
	v_mfma_f32_16x16x32_bf16 v[34:37], v[224:227], v[232:235], v[2:5]
	v_mfma_f32_16x16x32_bf16 v[2:5], v[212:215], v[236:239], v[196:199]
	v_mfma_f32_16x16x32_bf16 v[22:25], v[216:219], v[240:243], v[2:5]
	v_mfma_f32_16x16x32_bf16 v[2:5], v[220:223], v[236:239], v[200:203]
	v_mfma_f32_16x16x32_bf16 v[18:21], v[224:227], v[240:243], v[2:5]
	v_mfma_f32_16x16x32_bf16 v[2:5], v[212:215], v[244:247], v[204:207]
	v_mfma_f32_16x16x32_bf16 v[6:9], v[216:219], v[248:251], v[2:5]
	v_mfma_f32_16x16x32_bf16 v[2:5], v[220:223], v[244:247], v[208:211]
	v_mfma_f32_16x16x32_bf16 v[2:5], v[224:227], v[248:251], v[2:5]
	s_setprio 0
	s_barrier
	s_add_u32 s62, s62, 0x80180
	s_addc_u32 s63, s63, 0
	s_add_u32 s14, s50, 0x200
	s_addc_u32 s15, s51, 0
	s_mov_b32 s26, 0
.LBB0_716:
	ds_read_b128 v[132:135], v164
	ds_read_b128 v[136:139], v164 offset:1024
	ds_read_b128 v[140:143], v164 offset:2048
	ds_read_b128 v[168:171], v164 offset:3072
	ds_read_b128 v[172:175], v165
	ds_read_b128 v[176:179], v165 offset:1024
	ds_read_b128 v[180:183], v165 offset:2048
	ds_read_b128 v[184:187], v165 offset:3072
	s_add_u32 s27, s62, 0xfff80080
	s_addc_u32 s50, s63, -1
	s_cmp_eq_u32 s26, 4
	s_cselect_b32 s65, s1, s50
	s_cselect_b32 s64, s0, s27
	s_cselect_b32 s51, s29, s15
	s_cselect_b32 s50, s28, s14
	s_mov_b32 m0, s23
	ds_read_b128 v[188:191], v166
	ds_read_b128 v[192:195], v166 offset:1024
	ds_read_b128 v[196:199], v166 offset:2048
	ds_read_b128 v[200:203], v166 offset:3072
	ds_read_b128 v[204:207], v166 offset:4096
	ds_read_b128 v[208:211], v166 offset:5120
	ds_read_b128 v[212:215], v166 offset:6144
	ds_read_b128 v[216:219], v166 offset:7168
	global_load_lds_dwordx4 v154, s[62:63]
	s_mov_b32 m0, s77
	s_nop 0
	global_load_lds_dwordx4 v156, s[62:63]
	s_waitcnt vmcnt(8)
	s_waitcnt lgkmcnt(0)
	s_barrier
	s_setprio 1
	v_mfma_f32_16x16x32_bf16 v[102:105], v[132:135], v[188:191], v[102:105]
	v_mfma_f32_16x16x32_bf16 v[98:101], v[140:143], v[188:191], v[98:101]
	v_mfma_f32_16x16x32_bf16 v[94:97], v[132:135], v[196:199], v[94:97]
	v_mfma_f32_16x16x32_bf16 v[90:93], v[140:143], v[196:199], v[90:93]
	v_mfma_f32_16x16x32_bf16 v[86:89], v[132:135], v[204:207], v[86:89]
	v_mfma_f32_16x16x32_bf16 v[82:85], v[140:143], v[204:207], v[82:85]
	v_mfma_f32_16x16x32_bf16 v[78:81], v[132:135], v[212:215], v[78:81]
	v_mfma_f32_16x16x32_bf16 v[62:65], v[140:143], v[212:215], v[62:65]
	v_mfma_f32_16x16x32_bf16 v[102:105], v[136:139], v[192:195], v[102:105]
	v_mfma_f32_16x16x32_bf16 v[98:101], v[168:171], v[192:195], v[98:101]
	v_mfma_f32_16x16x32_bf16 v[94:97], v[136:139], v[200:203], v[94:97]
	v_mfma_f32_16x16x32_bf16 v[90:93], v[168:171], v[200:203], v[90:93]
	v_mfma_f32_16x16x32_bf16 v[86:89], v[136:139], v[208:211], v[86:89]
	v_mfma_f32_16x16x32_bf16 v[82:85], v[168:171], v[208:211], v[82:85]
	v_mfma_f32_16x16x32_bf16 v[78:81], v[136:139], v[216:219], v[78:81]
	v_mfma_f32_16x16x32_bf16 v[62:65], v[168:171], v[216:219], v[62:65]
	s_setprio 0
	s_setprio 1
	v_mfma_f32_16x16x32_bf16 v[126:129], v[172:175], v[188:191], v[126:129]
	v_mfma_f32_16x16x32_bf16 v[122:125], v[180:183], v[188:191], v[122:125]
	v_mfma_f32_16x16x32_bf16 v[118:121], v[172:175], v[196:199], v[118:121]
	v_mfma_f32_16x16x32_bf16 v[114:117], v[180:183], v[196:199], v[114:117]
	v_mfma_f32_16x16x32_bf16 v[110:113], v[172:175], v[204:207], v[110:113]
	v_mfma_f32_16x16x32_bf16 v[106:109], v[180:183], v[204:207], v[106:109]
	v_mfma_f32_16x16x32_bf16 v[54:57], v[172:175], v[212:215], v[54:57]
	v_mfma_f32_16x16x32_bf16 v[50:53], v[180:183], v[212:215], v[50:53]
	v_mfma_f32_16x16x32_bf16 v[126:129], v[176:179], v[192:195], v[126:129]
	v_mfma_f32_16x16x32_bf16 v[122:125], v[184:187], v[192:195], v[122:125]
	v_mfma_f32_16x16x32_bf16 v[118:121], v[176:179], v[200:203], v[118:121]
	v_mfma_f32_16x16x32_bf16 v[114:117], v[184:187], v[200:203], v[114:117]
	v_mfma_f32_16x16x32_bf16 v[110:113], v[176:179], v[208:211], v[110:113]
	v_mfma_f32_16x16x32_bf16 v[106:109], v[184:187], v[208:211], v[106:109]
	v_mfma_f32_16x16x32_bf16 v[54:57], v[176:179], v[216:219], v[54:57]
	v_mfma_f32_16x16x32_bf16 v[50:53], v[184:187], v[216:219], v[50:53]
	s_setprio 0
	s_barrier
	s_mov_b32 m0, s78
	s_mov_b64 s[98:99], s[50:51]
	s_add_u32 s82, s50, 0x80000
	ds_read_b128 v[188:191], v166 offset:16384
	ds_read_b128 v[192:195], v166 offset:17408
	ds_read_b128 v[196:199], v166 offset:18432
	ds_read_b128 v[200:203], v166 offset:19456
	ds_read_b128 v[204:207], v166 offset:20480
	ds_read_b128 v[208:211], v166 offset:21504
	ds_read_b128 v[212:215], v166 offset:22528
	ds_read_b128 v[216:219], v166 offset:23552
	global_load_lds_dwordx4 v148, s[50:51]
	s_mov_b32 m0, s79
	s_addc_u32 s83, s51, 0
	global_load_lds_dwordx4 v152, s[50:51]
	s_mov_b32 m0, s80
	s_mov_b64 s[100:101], s[64:65]
	global_load_lds_dwordx4 v148, s[82:83]
	s_mov_b32 m0, s46
	s_nop 0
	global_load_lds_dwordx4 v152, s[82:83]
	s_mov_b32 m0, s59
	s_nop 0
	global_load_lds_dwordx4 v146, s[64:65]
	s_mov_b32 m0, s31
	s_nop 0
	global_load_lds_dwordx4 v150, s[64:65]
	s_waitcnt vmcnt(8)
	s_waitcnt lgkmcnt(0)
	s_barrier
	s_setprio 1
	v_mfma_f32_16x16x32_bf16 v[74:77], v[132:135], v[188:191], v[74:77]
	v_mfma_f32_16x16x32_bf16 v[70:73], v[140:143], v[188:191], v[70:73]
	v_mfma_f32_16x16x32_bf16 v[46:49], v[132:135], v[196:199], v[46:49]
	v_mfma_f32_16x16x32_bf16 v[42:45], v[140:143], v[196:199], v[42:45]
	v_mfma_f32_16x16x32_bf16 v[30:33], v[132:135], v[204:207], v[30:33]
	v_mfma_f32_16x16x32_bf16 v[26:29], v[140:143], v[204:207], v[26:29]
	v_mfma_f32_16x16x32_bf16 v[14:17], v[132:135], v[212:215], v[14:17]
	v_mfma_f32_16x16x32_bf16 v[10:13], v[140:143], v[212:215], v[10:13]
	v_mfma_f32_16x16x32_bf16 v[74:77], v[136:139], v[192:195], v[74:77]
	v_mfma_f32_16x16x32_bf16 v[70:73], v[168:171], v[192:195], v[70:73]
	v_mfma_f32_16x16x32_bf16 v[46:49], v[136:139], v[200:203], v[46:49]
	v_mfma_f32_16x16x32_bf16 v[42:45], v[168:171], v[200:203], v[42:45]
	v_mfma_f32_16x16x32_bf16 v[30:33], v[136:139], v[208:211], v[30:33]
	v_mfma_f32_16x16x32_bf16 v[26:29], v[168:171], v[208:211], v[26:29]
	v_mfma_f32_16x16x32_bf16 v[14:17], v[136:139], v[216:219], v[14:17]
	v_mfma_f32_16x16x32_bf16 v[10:13], v[168:171], v[216:219], v[10:13]
	s_setprio 0
	s_setprio 1
	v_mfma_f32_16x16x32_bf16 v[66:69], v[172:175], v[188:191], v[66:69]
	v_mfma_f32_16x16x32_bf16 v[58:61], v[180:183], v[188:191], v[58:61]
	v_mfma_f32_16x16x32_bf16 v[38:41], v[172:175], v[196:199], v[38:41]
	v_mfma_f32_16x16x32_bf16 v[34:37], v[180:183], v[196:199], v[34:37]
	v_mfma_f32_16x16x32_bf16 v[22:25], v[172:175], v[204:207], v[22:25]
	v_mfma_f32_16x16x32_bf16 v[18:21], v[180:183], v[204:207], v[18:21]
	v_mfma_f32_16x16x32_bf16 v[6:9], v[172:175], v[212:215], v[6:9]
	v_mfma_f32_16x16x32_bf16 v[2:5], v[180:183], v[212:215], v[2:5]
	v_mfma_f32_16x16x32_bf16 v[66:69], v[176:179], v[192:195], v[66:69]
	v_mfma_f32_16x16x32_bf16 v[58:61], v[184:187], v[192:195], v[58:61]
	v_mfma_f32_16x16x32_bf16 v[38:41], v[176:179], v[200:203], v[38:41]
	v_mfma_f32_16x16x32_bf16 v[34:37], v[184:187], v[200:203], v[34:37]
	v_mfma_f32_16x16x32_bf16 v[22:25], v[176:179], v[208:211], v[22:25]
	v_mfma_f32_16x16x32_bf16 v[18:21], v[184:187], v[208:211], v[18:21]
	v_mfma_f32_16x16x32_bf16 v[6:9], v[176:179], v[216:219], v[6:9]
	v_mfma_f32_16x16x32_bf16 v[2:5], v[184:187], v[216:219], v[2:5]
	s_setprio 0
	s_barrier
; #define PG8_BAR __builtin_amdgcn_s_barrier()
;     ...
;         for (int t = 2; t < nt; t += 2) PG8_KITER(t);
;         if constexpr (ALIGN_EPI) { if (wr == 0) PG8_BAR; }
	ds_read_b128 v[132:135], v130
	ds_read_b128 v[136:139], v130 offset:1024
	ds_read_b128 v[140:143], v130 offset:2048
	ds_read_b128 v[168:171], v130 offset:3072
	ds_read_b128 v[172:175], v131
	ds_read_b128 v[176:179], v131 offset:1024
	ds_read_b128 v[180:183], v131 offset:2048
	ds_read_b128 v[184:187], v131 offset:3072
	s_add_u32 s64, s64, 0x80000
	s_addc_u32 s65, s65, 0
	s_mov_b32 m0, s66
	ds_read_b128 v[188:191], v166 offset:32768
	ds_read_b128 v[192:195], v166 offset:33792
	ds_read_b128 v[196:199], v166 offset:34816
	ds_read_b128 v[200:203], v166 offset:35840
	ds_read_b128 v[204:207], v166 offset:36864
	ds_read_b128 v[208:211], v166 offset:37888
	ds_read_b128 v[212:215], v166 offset:38912
	ds_read_b128 v[216:219], v166 offset:39936
	global_load_lds_dwordx4 v146, s[64:65]
	s_mov_b32 m0, s67
	s_nop 0
	global_load_lds_dwordx4 v150, s[64:65]
	s_waitcnt vmcnt(8)
	s_waitcnt lgkmcnt(0)
	s_barrier
	s_setprio 1
	v_mfma_f32_16x16x32_bf16 v[102:105], v[132:135], v[188:191], v[102:105]
	v_mfma_f32_16x16x32_bf16 v[98:101], v[140:143], v[188:191], v[98:101]
	v_mfma_f32_16x16x32_bf16 v[94:97], v[132:135], v[196:199], v[94:97]
	v_mfma_f32_16x16x32_bf16 v[90:93], v[140:143], v[196:199], v[90:93]
	v_mfma_f32_16x16x32_bf16 v[86:89], v[132:135], v[204:207], v[86:89]
	v_mfma_f32_16x16x32_bf16 v[82:85], v[140:143], v[204:207], v[82:85]
	v_mfma_f32_16x16x32_bf16 v[78:81], v[132:135], v[212:215], v[78:81]
	v_mfma_f32_16x16x32_bf16 v[62:65], v[140:143], v[212:215], v[62:65]
	v_mfma_f32_16x16x32_bf16 v[102:105], v[136:139], v[192:195], v[102:105]
	v_mfma_f32_16x16x32_bf16 v[98:101], v[168:171], v[192:195], v[98:101]
	v_mfma_f32_16x16x32_bf16 v[94:97], v[136:139], v[200:203], v[94:97]
	v_mfma_f32_16x16x32_bf16 v[90:93], v[168:171], v[200:203], v[90:93]
	v_mfma_f32_16x16x32_bf16 v[86:89], v[136:139], v[208:211], v[86:89]
	v_mfma_f32_16x16x32_bf16 v[82:85], v[168:171], v[208:211], v[82:85]
	v_mfma_f32_16x16x32_bf16 v[78:81], v[136:139], v[216:219], v[78:81]
	v_mfma_f32_16x16x32_bf16 v[62:65], v[168:171], v[216:219], v[62:65]
	s_setprio 0
	s_setprio 1
	v_mfma_f32_16x16x32_bf16 v[126:129], v[172:175], v[188:191], v[126:129]
	v_mfma_f32_16x16x32_bf16 v[122:125], v[180:183], v[188:191], v[122:125]
	v_mfma_f32_16x16x32_bf16 v[118:121], v[172:175], v[196:199], v[118:121]
	v_mfma_f32_16x16x32_bf16 v[114:117], v[180:183], v[196:199], v[114:117]
	v_mfma_f32_16x16x32_bf16 v[110:113], v[172:175], v[204:207], v[110:113]
	v_mfma_f32_16x16x32_bf16 v[106:109], v[180:183], v[204:207], v[106:109]
	v_mfma_f32_16x16x32_bf16 v[54:57], v[172:175], v[212:215], v[54:57]
	v_mfma_f32_16x16x32_bf16 v[50:53], v[180:183], v[212:215], v[50:53]
	v_mfma_f32_16x16x32_bf16 v[126:129], v[176:179], v[192:195], v[126:129]
	v_mfma_f32_16x16x32_bf16 v[122:125], v[184:187], v[192:195], v[122:125]
	v_mfma_f32_16x16x32_bf16 v[118:121], v[176:179], v[200:203], v[118:121]
	v_mfma_f32_16x16x32_bf16 v[114:117], v[184:187], v[200:203], v[114:117]
	v_mfma_f32_16x16x32_bf16 v[110:113], v[176:179], v[208:211], v[110:113]
	v_mfma_f32_16x16x32_bf16 v[106:109], v[184:187], v[208:211], v[106:109]
	v_mfma_f32_16x16x32_bf16 v[54:57], v[176:179], v[216:219], v[54:57]
	v_mfma_f32_16x16x32_bf16 v[50:53], v[184:187], v[216:219], v[50:53]
	s_setprio 0
	s_barrier
	s_mov_b32 m0, s47
	s_add_u32 s98, s98, 0x80
	s_addc_u32 s99, s99, 0
	s_add_u32 s100, s100, 0x80
	s_addc_u32 s101, s101, 0
	s_add_u32 s50, s50, 0x80080
	ds_read_b128 v[188:191], v166 offset:49152
	ds_read_b128 v[192:195], v166 offset:50176
	ds_read_b128 v[196:199], v166 offset:51200
	ds_read_b128 v[200:203], v166 offset:52224
	ds_read_b128 v[204:207], v166 offset:53248
	ds_read_b128 v[208:211], v166 offset:54272
	ds_read_b128 v[212:215], v166 offset:55296
	ds_read_b128 v[216:219], v166 offset:56320
	global_load_lds_dwordx4 v148, s[98:99]
	s_mov_b32 m0, s81
	s_addc_u32 s51, s51, 0
	global_load_lds_dwordx4 v152, s[98:99]
	s_mov_b32 m0, s56
	s_nop 0
	global_load_lds_dwordx4 v148, s[50:51]
	s_mov_b32 m0, s57
	s_nop 0
	global_load_lds_dwordx4 v152, s[50:51]
	s_mov_b32 m0, s69
	s_nop 0
	global_load_lds_dwordx4 v146, s[100:101]
	s_mov_b32 m0, s70
	s_nop 0
	global_load_lds_dwordx4 v150, s[100:101]
	s_waitcnt vmcnt(8)
	s_waitcnt lgkmcnt(0)
	s_barrier
	s_setprio 1
	v_mfma_f32_16x16x32_bf16 v[74:77], v[132:135], v[188:191], v[74:77]
	v_mfma_f32_16x16x32_bf16 v[70:73], v[140:143], v[188:191], v[70:73]
	v_mfma_f32_16x16x32_bf16 v[46:49], v[132:135], v[196:199], v[46:49]
	v_mfma_f32_16x16x32_bf16 v[42:45], v[140:143], v[196:199], v[42:45]
	v_mfma_f32_16x16x32_bf16 v[30:33], v[132:135], v[204:207], v[30:33]
	v_mfma_f32_16x16x32_bf16 v[26:29], v[140:143], v[204:207], v[26:29]
	v_mfma_f32_16x16x32_bf16 v[14:17], v[132:135], v[212:215], v[14:17]
	v_mfma_f32_16x16x32_bf16 v[10:13], v[140:143], v[212:215], v[10:13]
	v_mfma_f32_16x16x32_bf16 v[74:77], v[136:139], v[192:195], v[74:77]
	v_mfma_f32_16x16x32_bf16 v[70:73], v[168:171], v[192:195], v[70:73]
	v_mfma_f32_16x16x32_bf16 v[46:49], v[136:139], v[200:203], v[46:49]
	v_mfma_f32_16x16x32_bf16 v[42:45], v[168:171], v[200:203], v[42:45]
	v_mfma_f32_16x16x32_bf16 v[30:33], v[136:139], v[208:211], v[30:33]
	v_mfma_f32_16x16x32_bf16 v[26:29], v[168:171], v[208:211], v[26:29]
	v_mfma_f32_16x16x32_bf16 v[14:17], v[136:139], v[216:219], v[14:17]
	v_mfma_f32_16x16x32_bf16 v[10:13], v[168:171], v[216:219], v[10:13]
	s_setprio 0
	s_setprio 1
	v_mfma_f32_16x16x32_bf16 v[66:69], v[172:175], v[188:191], v[66:69]
	v_mfma_f32_16x16x32_bf16 v[58:61], v[180:183], v[188:191], v[58:61]
	v_mfma_f32_16x16x32_bf16 v[38:41], v[172:175], v[196:199], v[38:41]
	v_mfma_f32_16x16x32_bf16 v[34:37], v[180:183], v[196:199], v[34:37]
	v_mfma_f32_16x16x32_bf16 v[22:25], v[172:175], v[204:207], v[22:25]
	v_mfma_f32_16x16x32_bf16 v[18:21], v[180:183], v[204:207], v[18:21]
	v_mfma_f32_16x16x32_bf16 v[6:9], v[172:175], v[212:215], v[6:9]
	v_mfma_f32_16x16x32_bf16 v[2:5], v[180:183], v[212:215], v[2:5]
	v_mfma_f32_16x16x32_bf16 v[66:69], v[176:179], v[192:195], v[66:69]
	v_mfma_f32_16x16x32_bf16 v[58:61], v[184:187], v[192:195], v[58:61]
	v_mfma_f32_16x16x32_bf16 v[38:41], v[176:179], v[200:203], v[38:41]
	v_mfma_f32_16x16x32_bf16 v[34:37], v[184:187], v[200:203], v[34:37]
	v_mfma_f32_16x16x32_bf16 v[22:25], v[176:179], v[208:211], v[22:25]
	v_mfma_f32_16x16x32_bf16 v[18:21], v[184:187], v[208:211], v[18:21]
	v_mfma_f32_16x16x32_bf16 v[6:9], v[176:179], v[216:219], v[6:9]
	v_mfma_f32_16x16x32_bf16 v[2:5], v[184:187], v[216:219], v[2:5]
	s_setprio 0
	s_barrier
	s_add_i32 s26, s26, 2
	s_add_u32 s62, s62, 0x100
	s_addc_u32 s63, s63, 0
	s_add_u32 s14, s14, 0x100
	s_addc_u32 s15, s15, 0
	s_cmp_gt_u32 s26, 5
	s_cbranch_scc0 .LBB0_716
	s_and_b64 vcc, exec, s[16:17]
	s_cbranch_vccz .LBB0_719
	s_barrier

.LBB0_929:
	v_add_u32_e32 v130, s79, v1
	v_add_u32_e32 v131, s80, v1
	ds_read_b128 v[132:135], v130
	ds_read_b128 v[136:139], v130 offset:1024
	ds_read_b128 v[140:143], v130 offset:2048
	ds_read_b128 v[144:147], v130 offset:3072
	ds_read_b128 v[168:171], v131
	ds_read_b128 v[174:177], v131 offset:1024
	ds_read_b128 v[178:181], v131 offset:2048
	ds_read_b128 v[182:185], v131 offset:3072
	s_add_u32 s12, s62, 0x80080
	s_addc_u32 s13, s63, 0
	s_add_i32 s0, s69, 0xc000
	v_lshl_add_u64 v[148:149], s[12:13], 0, v[150:151]
	s_mov_b32 m0, s0
	s_add_i32 s11, s69, 0xe000
	ds_read_b128 v[186:189], v172
	ds_read_b128 v[190:193], v172 offset:1024
	ds_read_b128 v[194:197], v172 offset:2048
	ds_read_b128 v[198:201], v172 offset:3072
	ds_read_b128 v[202:205], v172 offset:4096
	ds_read_b128 v[206:209], v172 offset:5120
	ds_read_b128 v[210:213], v172 offset:6144
	ds_read_b128 v[214:217], v172 offset:7168
	global_load_lds_dwordx4 v[148:149], off
	v_lshl_add_u64 v[148:149], s[12:13], 0, v[154:155]
	s_mov_b32 m0, s11
	s_nop 0
	global_load_lds_dwordx4 v[148:149], off
	s_waitcnt vmcnt(8)
	s_waitcnt lgkmcnt(0)
	s_barrier
	s_setprio 1
	v_mfma_f32_16x16x32_bf16 v[126:129], v[132:135], v[186:189], v[126:129]
	v_mfma_f32_16x16x32_bf16 v[122:125], v[140:143], v[186:189], v[122:125]
	v_mfma_f32_16x16x32_bf16 v[118:121], v[132:135], v[194:197], v[118:121]
	v_mfma_f32_16x16x32_bf16 v[114:117], v[140:143], v[194:197], v[114:117]
	v_mfma_f32_16x16x32_bf16 v[110:113], v[132:135], v[202:205], v[110:113]
	v_mfma_f32_16x16x32_bf16 v[106:109], v[140:143], v[202:205], v[106:109]
	v_mfma_f32_16x16x32_bf16 v[102:105], v[132:135], v[210:213], v[102:105]
	v_mfma_f32_16x16x32_bf16 v[98:101], v[140:143], v[210:213], v[98:101]
	v_mfma_f32_16x16x32_bf16 v[126:129], v[136:139], v[190:193], v[126:129]
	v_mfma_f32_16x16x32_bf16 v[122:125], v[144:147], v[190:193], v[122:125]
	v_mfma_f32_16x16x32_bf16 v[118:121], v[136:139], v[198:201], v[118:121]
	v_mfma_f32_16x16x32_bf16 v[114:117], v[144:147], v[198:201], v[114:117]
	v_mfma_f32_16x16x32_bf16 v[110:113], v[136:139], v[206:209], v[110:113]
	v_mfma_f32_16x16x32_bf16 v[106:109], v[144:147], v[206:209], v[106:109]
	v_mfma_f32_16x16x32_bf16 v[102:105], v[136:139], v[214:217], v[102:105]
	v_mfma_f32_16x16x32_bf16 v[98:101], v[144:147], v[214:217], v[98:101]
	s_setprio 0
	s_setprio 1
	v_mfma_f32_16x16x32_bf16 v[94:97], v[168:171], v[186:189], v[94:97]
	v_mfma_f32_16x16x32_bf16 v[90:93], v[178:181], v[186:189], v[90:93]
	v_mfma_f32_16x16x32_bf16 v[86:89], v[168:171], v[194:197], v[86:89]
	v_mfma_f32_16x16x32_bf16 v[82:85], v[178:181], v[194:197], v[82:85]
	v_mfma_f32_16x16x32_bf16 v[78:81], v[168:171], v[202:205], v[78:81]
	v_mfma_f32_16x16x32_bf16 v[74:77], v[178:181], v[202:205], v[74:77]
	v_mfma_f32_16x16x32_bf16 v[70:73], v[168:171], v[210:213], v[70:73]
	v_mfma_f32_16x16x32_bf16 v[66:69], v[178:181], v[210:213], v[66:69]
	v_mfma_f32_16x16x32_bf16 v[94:97], v[174:177], v[190:193], v[94:97]
	v_mfma_f32_16x16x32_bf16 v[90:93], v[182:185], v[190:193], v[90:93]
	v_mfma_f32_16x16x32_bf16 v[86:89], v[174:177], v[198:201], v[86:89]
	v_mfma_f32_16x16x32_bf16 v[82:85], v[182:185], v[198:201], v[82:85]
	v_mfma_f32_16x16x32_bf16 v[78:81], v[174:177], v[206:209], v[78:81]
	v_mfma_f32_16x16x32_bf16 v[74:77], v[182:185], v[206:209], v[74:77]
	v_mfma_f32_16x16x32_bf16 v[70:73], v[174:177], v[214:217], v[70:73]
	v_mfma_f32_16x16x32_bf16 v[66:69], v[182:185], v[214:217], v[66:69]
	s_setprio 0
	s_barrier
	s_add_i32 s12, s79, s68
	v_lshl_add_u64 v[218:219], s[50:51], 0, v[152:153]
	s_add_i32 s13, s12, 0x2000
	v_lshl_add_u64 v[148:149], v[218:219], 0, s[22:23]
	s_mov_b32 m0, s12
	v_lshl_add_u64 v[220:221], s[50:51], 0, v[156:157]
	s_add_u32 s14, s50, 0x80100
	ds_read_b128 v[186:189], v172 offset:16384
	ds_read_b128 v[190:193], v172 offset:17408
	ds_read_b128 v[194:197], v172 offset:18432
	ds_read_b128 v[198:201], v172 offset:19456
	ds_read_b128 v[202:205], v172 offset:20480
	ds_read_b128 v[206:209], v172 offset:21504
	ds_read_b128 v[210:213], v172 offset:22528
	ds_read_b128 v[214:217], v172 offset:23552
	global_load_lds_dwordx4 v[148:149], off
	v_lshl_add_u64 v[148:149], v[220:221], 0, s[22:23]
	s_mov_b32 m0, s13
	s_addc_u32 s15, s51, 0
	s_add_i32 s43, s80, s68
	global_load_lds_dwordx4 v[148:149], off
	v_lshl_add_u64 v[148:149], s[14:15], 0, v[152:153]
	s_mov_b32 m0, s43
	s_add_i32 s46, s43, 0x2000
	global_load_lds_dwordx4 v[148:149], off
	v_lshl_add_u64 v[148:149], s[14:15], 0, v[156:157]
	s_mov_b32 m0, s46
	v_lshl_add_u64 v[222:223], s[62:63], 0, v[150:151]
	global_load_lds_dwordx4 v[148:149], off
	v_lshl_add_u64 v[148:149], v[222:223], 0, s[22:23]
	s_mov_b32 m0, s69
	v_lshl_add_u64 v[224:225], s[62:63], 0, v[154:155]
	global_load_lds_dwordx4 v[148:149], off
	v_lshl_add_u64 v[148:149], v[224:225], 0, s[22:23]
	s_mov_b32 m0, s70
	s_nop 0
	global_load_lds_dwordx4 v[148:149], off
	s_waitcnt vmcnt(8)
	s_waitcnt lgkmcnt(0)
	s_barrier
	s_setprio 1
	v_mfma_f32_16x16x32_bf16 v[62:65], v[132:135], v[186:189], v[62:65]
	v_mfma_f32_16x16x32_bf16 v[58:61], v[140:143], v[186:189], v[58:61]
	v_mfma_f32_16x16x32_bf16 v[54:57], v[132:135], v[194:197], v[54:57]
	v_mfma_f32_16x16x32_bf16 v[50:53], v[140:143], v[194:197], v[50:53]
	v_mfma_f32_16x16x32_bf16 v[46:49], v[132:135], v[202:205], v[46:49]
	v_mfma_f32_16x16x32_bf16 v[42:45], v[140:143], v[202:205], v[42:45]
	v_mfma_f32_16x16x32_bf16 v[38:41], v[132:135], v[210:213], v[38:41]
	v_mfma_f32_16x16x32_bf16 v[34:37], v[140:143], v[210:213], v[34:37]
	v_mfma_f32_16x16x32_bf16 v[62:65], v[136:139], v[190:193], v[62:65]
	v_mfma_f32_16x16x32_bf16 v[58:61], v[144:147], v[190:193], v[58:61]
	v_mfma_f32_16x16x32_bf16 v[54:57], v[136:139], v[198:201], v[54:57]
	v_mfma_f32_16x16x32_bf16 v[50:53], v[144:147], v[198:201], v[50:53]
	v_mfma_f32_16x16x32_bf16 v[46:49], v[136:139], v[206:209], v[46:49]
	v_mfma_f32_16x16x32_bf16 v[42:45], v[144:147], v[206:209], v[42:45]
	v_mfma_f32_16x16x32_bf16 v[38:41], v[136:139], v[214:217], v[38:41]
	v_mfma_f32_16x16x32_bf16 v[34:37], v[144:147], v[214:217], v[34:37]
	s_setprio 0
	s_setprio 1
	v_mfma_f32_16x16x32_bf16 v[30:33], v[168:171], v[186:189], v[30:33]
	v_mfma_f32_16x16x32_bf16 v[26:29], v[178:181], v[186:189], v[26:29]
	v_mfma_f32_16x16x32_bf16 v[22:25], v[168:171], v[194:197], v[22:25]
	v_mfma_f32_16x16x32_bf16 v[18:21], v[178:181], v[194:197], v[18:21]
	v_mfma_f32_16x16x32_bf16 v[14:17], v[168:171], v[202:205], v[14:17]
	v_mfma_f32_16x16x32_bf16 v[10:13], v[178:181], v[202:205], v[10:13]
	v_mfma_f32_16x16x32_bf16 v[6:9], v[168:171], v[210:213], v[6:9]
	v_mfma_f32_16x16x32_bf16 v[2:5], v[178:181], v[210:213], v[2:5]
	v_mfma_f32_16x16x32_bf16 v[30:33], v[174:177], v[190:193], v[30:33]
	v_mfma_f32_16x16x32_bf16 v[26:29], v[182:185], v[190:193], v[26:29]
	v_mfma_f32_16x16x32_bf16 v[22:25], v[174:177], v[198:201], v[22:25]
	v_mfma_f32_16x16x32_bf16 v[18:21], v[182:185], v[198:201], v[18:21]
	v_mfma_f32_16x16x32_bf16 v[14:17], v[174:177], v[206:209], v[14:17]
	v_mfma_f32_16x16x32_bf16 v[10:13], v[182:185], v[206:209], v[10:13]
	v_mfma_f32_16x16x32_bf16 v[6:9], v[174:177], v[214:217], v[6:9]
	v_mfma_f32_16x16x32_bf16 v[2:5], v[182:185], v[214:217], v[2:5]
	s_setprio 0
	s_barrier
	s_add_i32 s47, 0, 0x18000
	s_add_i32 s55, 0, 0x1c000
	v_add_u32_e32 v132, s47, v1
	v_add_u32_e32 v133, s55, v1
	ds_read_b128 v[134:137], v132
	ds_read_b128 v[138:141], v132 offset:1024
	ds_read_b128 v[142:145], v132 offset:2048
	ds_read_b128 v[146:149], v132 offset:3072
	ds_read_b128 v[168:171], v133
	ds_read_b128 v[174:177], v133 offset:1024
	ds_read_b128 v[178:181], v133 offset:2048
	ds_read_b128 v[182:185], v133 offset:3072
	s_add_u32 s14, s62, 0x80100
	s_addc_u32 s15, s63, 0
	s_mov_b32 m0, s71
	v_lshl_add_u64 v[226:227], s[14:15], 0, v[150:151]
	ds_read_b128 v[186:189], v172 offset:32768
	ds_read_b128 v[190:193], v172 offset:33792
	ds_read_b128 v[194:197], v172 offset:34816
	ds_read_b128 v[198:201], v172 offset:35840
	ds_read_b128 v[202:205], v172 offset:36864
	ds_read_b128 v[206:209], v172 offset:37888
	ds_read_b128 v[210:213], v172 offset:38912
	ds_read_b128 v[214:217], v172 offset:39936
	global_load_lds_dwordx4 v[226:227], off
	v_lshl_add_u64 v[226:227], s[14:15], 0, v[154:155]
	s_mov_b32 m0, s72
	s_nop 0
	global_load_lds_dwordx4 v[226:227], off
	s_waitcnt vmcnt(8)
	s_waitcnt lgkmcnt(0)
	s_barrier
	s_setprio 1
	v_mfma_f32_16x16x32_bf16 v[126:129], v[134:137], v[186:189], v[126:129]
	v_mfma_f32_16x16x32_bf16 v[122:125], v[142:145], v[186:189], v[122:125]
	v_mfma_f32_16x16x32_bf16 v[118:121], v[134:137], v[194:197], v[118:121]
	v_mfma_f32_16x16x32_bf16 v[114:117], v[142:145], v[194:197], v[114:117]
	v_mfma_f32_16x16x32_bf16 v[110:113], v[134:137], v[202:205], v[110:113]
	v_mfma_f32_16x16x32_bf16 v[106:109], v[142:145], v[202:205], v[106:109]
	v_mfma_f32_16x16x32_bf16 v[102:105], v[134:137], v[210:213], v[102:105]
	v_mfma_f32_16x16x32_bf16 v[98:101], v[142:145], v[210:213], v[98:101]
	v_mfma_f32_16x16x32_bf16 v[126:129], v[138:141], v[190:193], v[126:129]
	v_mfma_f32_16x16x32_bf16 v[122:125], v[146:149], v[190:193], v[122:125]
	v_mfma_f32_16x16x32_bf16 v[118:121], v[138:141], v[198:201], v[118:121]
	v_mfma_f32_16x16x32_bf16 v[114:117], v[146:149], v[198:201], v[114:117]
	v_mfma_f32_16x16x32_bf16 v[110:113], v[138:141], v[206:209], v[110:113]
	v_mfma_f32_16x16x32_bf16 v[106:109], v[146:149], v[206:209], v[106:109]
	v_mfma_f32_16x16x32_bf16 v[102:105], v[138:141], v[214:217], v[102:105]
	v_mfma_f32_16x16x32_bf16 v[98:101], v[146:149], v[214:217], v[98:101]
	s_setprio 0
	s_setprio 1
	v_mfma_f32_16x16x32_bf16 v[94:97], v[168:171], v[186:189], v[94:97]
	v_mfma_f32_16x16x32_bf16 v[90:93], v[178:181], v[186:189], v[90:93]
	v_mfma_f32_16x16x32_bf16 v[86:89], v[168:171], v[194:197], v[86:89]
	v_mfma_f32_16x16x32_bf16 v[82:85], v[178:181], v[194:197], v[82:85]
	v_mfma_f32_16x16x32_bf16 v[78:81], v[168:171], v[202:205], v[78:81]
	v_mfma_f32_16x16x32_bf16 v[74:77], v[178:181], v[202:205], v[74:77]
	v_mfma_f32_16x16x32_bf16 v[70:73], v[168:171], v[210:213], v[70:73]
	v_mfma_f32_16x16x32_bf16 v[66:69], v[178:181], v[210:213], v[66:69]
	v_mfma_f32_16x16x32_bf16 v[94:97], v[174:177], v[190:193], v[94:97]
	v_mfma_f32_16x16x32_bf16 v[90:93], v[182:185], v[190:193], v[90:93]
	v_mfma_f32_16x16x32_bf16 v[86:89], v[174:177], v[198:201], v[86:89]
	v_mfma_f32_16x16x32_bf16 v[82:85], v[182:185], v[198:201], v[82:85]
	v_mfma_f32_16x16x32_bf16 v[78:81], v[174:177], v[206:209], v[78:81]
	v_mfma_f32_16x16x32_bf16 v[74:77], v[182:185], v[206:209], v[74:77]
	v_mfma_f32_16x16x32_bf16 v[70:73], v[174:177], v[214:217], v[70:73]
	v_mfma_f32_16x16x32_bf16 v[66:69], v[182:185], v[214:217], v[66:69]
	s_setprio 0
	s_barrier
	s_add_i32 s47, s47, s68
	s_add_i32 s53, s47, 0x2000
	v_lshl_add_u64 v[218:219], v[218:219], 0, s[28:29]
	s_mov_b32 m0, s47
	s_add_u32 s14, s50, 0x80180
	ds_read_b128 v[186:189], v172 offset:49152
	ds_read_b128 v[190:193], v172 offset:50176
	ds_read_b128 v[194:197], v172 offset:51200
	ds_read_b128 v[198:201], v172 offset:52224
	ds_read_b128 v[202:205], v172 offset:53248
	ds_read_b128 v[206:209], v172 offset:54272
	ds_read_b128 v[210:213], v172 offset:55296
	ds_read_b128 v[214:217], v172 offset:56320
	global_load_lds_dwordx4 v[218:219], off
	v_lshl_add_u64 v[218:219], v[220:221], 0, s[28:29]
	s_mov_b32 m0, s53
	s_addc_u32 s15, s51, 0
	s_add_i32 s55, s55, s68
	global_load_lds_dwordx4 v[218:219], off
	v_lshl_add_u64 v[218:219], s[14:15], 0, v[152:153]
	s_mov_b32 m0, s55
	s_add_i32 s56, s55, 0x2000
	global_load_lds_dwordx4 v[218:219], off
	v_lshl_add_u64 v[218:219], s[14:15], 0, v[156:157]
	s_mov_b32 m0, s56
	s_nop 0
	global_load_lds_dwordx4 v[218:219], off
	v_lshl_add_u64 v[218:219], v[222:223], 0, s[28:29]
	s_mov_b32 m0, s77
	s_nop 0
	global_load_lds_dwordx4 v[218:219], off
	v_lshl_add_u64 v[218:219], v[224:225], 0, s[28:29]
	s_mov_b32 m0, s78
	s_nop 0
	global_load_lds_dwordx4 v[218:219], off
	s_waitcnt vmcnt(8)
	s_waitcnt lgkmcnt(0)
	s_barrier
	s_setprio 1
	v_mfma_f32_16x16x32_bf16 v[62:65], v[134:137], v[186:189], v[62:65]
	v_mfma_f32_16x16x32_bf16 v[58:61], v[142:145], v[186:189], v[58:61]
	v_mfma_f32_16x16x32_bf16 v[54:57], v[134:137], v[194:197], v[54:57]
	v_mfma_f32_16x16x32_bf16 v[50:53], v[142:145], v[194:197], v[50:53]
	v_mfma_f32_16x16x32_bf16 v[46:49], v[134:137], v[202:205], v[46:49]
	v_mfma_f32_16x16x32_bf16 v[42:45], v[142:145], v[202:205], v[42:45]
	v_mfma_f32_16x16x32_bf16 v[38:41], v[134:137], v[210:213], v[38:41]
	v_mfma_f32_16x16x32_bf16 v[34:37], v[142:145], v[210:213], v[34:37]
	v_mfma_f32_16x16x32_bf16 v[62:65], v[138:141], v[190:193], v[62:65]
	v_mfma_f32_16x16x32_bf16 v[58:61], v[146:149], v[190:193], v[58:61]
	v_mfma_f32_16x16x32_bf16 v[54:57], v[138:141], v[198:201], v[54:57]
	v_mfma_f32_16x16x32_bf16 v[50:53], v[146:149], v[198:201], v[50:53]
	v_mfma_f32_16x16x32_bf16 v[46:49], v[138:141], v[206:209], v[46:49]
	v_mfma_f32_16x16x32_bf16 v[42:45], v[146:149], v[206:209], v[42:45]
	v_mfma_f32_16x16x32_bf16 v[38:41], v[138:141], v[214:217], v[38:41]
	v_mfma_f32_16x16x32_bf16 v[34:37], v[146:149], v[214:217], v[34:37]
	s_setprio 0
	s_setprio 1
	v_mfma_f32_16x16x32_bf16 v[30:33], v[168:171], v[186:189], v[30:33]
	v_mfma_f32_16x16x32_bf16 v[26:29], v[178:181], v[186:189], v[26:29]
	v_mfma_f32_16x16x32_bf16 v[22:25], v[168:171], v[194:197], v[22:25]
	v_mfma_f32_16x16x32_bf16 v[18:21], v[178:181], v[194:197], v[18:21]
	v_mfma_f32_16x16x32_bf16 v[14:17], v[168:171], v[202:205], v[14:17]
	v_mfma_f32_16x16x32_bf16 v[10:13], v[178:181], v[202:205], v[10:13]
	v_mfma_f32_16x16x32_bf16 v[6:9], v[168:171], v[210:213], v[6:9]
	v_mfma_f32_16x16x32_bf16 v[2:5], v[178:181], v[210:213], v[2:5]
	v_mfma_f32_16x16x32_bf16 v[30:33], v[174:177], v[190:193], v[30:33]
	v_mfma_f32_16x16x32_bf16 v[26:29], v[182:185], v[190:193], v[26:29]
	v_mfma_f32_16x16x32_bf16 v[22:25], v[174:177], v[198:201], v[22:25]
	v_mfma_f32_16x16x32_bf16 v[18:21], v[182:185], v[198:201], v[18:21]
	v_mfma_f32_16x16x32_bf16 v[14:17], v[174:177], v[206:209], v[14:17]
	v_mfma_f32_16x16x32_bf16 v[10:13], v[182:185], v[206:209], v[10:13]
	v_mfma_f32_16x16x32_bf16 v[6:9], v[174:177], v[214:217], v[6:9]
	v_mfma_f32_16x16x32_bf16 v[2:5], v[182:185], v[214:217], v[2:5]
	s_setprio 0
	s_barrier
	s_add_u32 s62, s62, 0x80180
	s_addc_u32 s63, s63, 0
	s_add_u32 s14, s50, 0x200
	s_addc_u32 s15, s51, 0
	s_mov_b32 s26, 0
.LBB0_930:
	ds_read_b128 v[134:137], v130
	ds_read_b128 v[138:141], v130 offset:1024
	ds_read_b128 v[142:145], v130 offset:2048
	ds_read_b128 v[146:149], v130 offset:3072
	ds_read_b128 v[168:171], v131
	ds_read_b128 v[174:177], v131 offset:1024
	ds_read_b128 v[178:181], v131 offset:2048
	ds_read_b128 v[182:185], v131 offset:3072
	s_add_u32 s27, s62, 0xfff80080
	s_addc_u32 s50, s63, -1
	s_cmp_eq_u32 s26, 28
	s_cselect_b32 s65, s7, s50
	s_cselect_b32 s64, s6, s27
	s_cselect_b32 s51, s49, s15
	s_cselect_b32 s50, s48, s14
	s_mov_b32 m0, s0
	ds_read_b128 v[186:189], v172
	ds_read_b128 v[190:193], v172 offset:1024
	ds_read_b128 v[194:197], v172 offset:2048
	ds_read_b128 v[198:201], v172 offset:3072
	ds_read_b128 v[202:205], v172 offset:4096
	ds_read_b128 v[206:209], v172 offset:5120
	ds_read_b128 v[210:213], v172 offset:6144
	ds_read_b128 v[214:217], v172 offset:7168
	global_load_lds_dwordx4 v160, s[62:63]
	s_mov_b32 m0, s11
	s_nop 0
	global_load_lds_dwordx4 v162, s[62:63]
	s_waitcnt vmcnt(8)
	s_waitcnt lgkmcnt(0)
	s_barrier
	s_setprio 1
	v_mfma_f32_16x16x32_bf16 v[126:129], v[134:137], v[186:189], v[126:129]
	v_mfma_f32_16x16x32_bf16 v[122:125], v[142:145], v[186:189], v[122:125]
	v_mfma_f32_16x16x32_bf16 v[118:121], v[134:137], v[194:197], v[118:121]
	v_mfma_f32_16x16x32_bf16 v[114:117], v[142:145], v[194:197], v[114:117]
	v_mfma_f32_16x16x32_bf16 v[110:113], v[134:137], v[202:205], v[110:113]
	v_mfma_f32_16x16x32_bf16 v[106:109], v[142:145], v[202:205], v[106:109]
	v_mfma_f32_16x16x32_bf16 v[102:105], v[134:137], v[210:213], v[102:105]
	v_mfma_f32_16x16x32_bf16 v[98:101], v[142:145], v[210:213], v[98:101]
	v_mfma_f32_16x16x32_bf16 v[126:129], v[138:141], v[190:193], v[126:129]
	v_mfma_f32_16x16x32_bf16 v[122:125], v[146:149], v[190:193], v[122:125]
	v_mfma_f32_16x16x32_bf16 v[118:121], v[138:141], v[198:201], v[118:121]
	v_mfma_f32_16x16x32_bf16 v[114:117], v[146:149], v[198:201], v[114:117]
	v_mfma_f32_16x16x32_bf16 v[110:113], v[138:141], v[206:209], v[110:113]
	v_mfma_f32_16x16x32_bf16 v[106:109], v[146:149], v[206:209], v[106:109]
	v_mfma_f32_16x16x32_bf16 v[102:105], v[138:141], v[214:217], v[102:105]
	v_mfma_f32_16x16x32_bf16 v[98:101], v[146:149], v[214:217], v[98:101]
	s_setprio 0
	s_setprio 1
	v_mfma_f32_16x16x32_bf16 v[94:97], v[168:171], v[186:189], v[94:97]
	v_mfma_f32_16x16x32_bf16 v[90:93], v[178:181], v[186:189], v[90:93]
	v_mfma_f32_16x16x32_bf16 v[86:89], v[168:171], v[194:197], v[86:89]
	v_mfma_f32_16x16x32_bf16 v[82:85], v[178:181], v[194:197], v[82:85]
	v_mfma_f32_16x16x32_bf16 v[78:81], v[168:171], v[202:205], v[78:81]
	v_mfma_f32_16x16x32_bf16 v[74:77], v[178:181], v[202:205], v[74:77]
	v_mfma_f32_16x16x32_bf16 v[70:73], v[168:171], v[210:213], v[70:73]
	v_mfma_f32_16x16x32_bf16 v[66:69], v[178:181], v[210:213], v[66:69]
	v_mfma_f32_16x16x32_bf16 v[94:97], v[174:177], v[190:193], v[94:97]
	v_mfma_f32_16x16x32_bf16 v[90:93], v[182:185], v[190:193], v[90:93]
	v_mfma_f32_16x16x32_bf16 v[86:89], v[174:177], v[198:201], v[86:89]
	v_mfma_f32_16x16x32_bf16 v[82:85], v[182:185], v[198:201], v[82:85]
	v_mfma_f32_16x16x32_bf16 v[78:81], v[174:177], v[206:209], v[78:81]
	v_mfma_f32_16x16x32_bf16 v[74:77], v[182:185], v[206:209], v[74:77]
	v_mfma_f32_16x16x32_bf16 v[70:73], v[174:177], v[214:217], v[70:73]
	v_mfma_f32_16x16x32_bf16 v[66:69], v[182:185], v[214:217], v[66:69]
	s_setprio 0
	s_barrier
	s_mov_b32 m0, s12
	s_mov_b64 s[98:99], s[50:51]
	s_add_u32 s58, s50, 0x80000
	ds_read_b128 v[186:189], v172 offset:16384
	ds_read_b128 v[190:193], v172 offset:17408
	ds_read_b128 v[194:197], v172 offset:18432
	ds_read_b128 v[198:201], v172 offset:19456
	ds_read_b128 v[202:205], v172 offset:20480
	ds_read_b128 v[206:209], v172 offset:21504
	ds_read_b128 v[210:213], v172 offset:22528
	ds_read_b128 v[214:217], v172 offset:23552
	global_load_lds_dwordx4 v152, s[50:51]
	s_mov_b32 m0, s13
	s_addc_u32 s59, s51, 0
	global_load_lds_dwordx4 v156, s[50:51]
	s_mov_b32 m0, s43
	s_mov_b64 s[100:101], s[64:65]
	global_load_lds_dwordx4 v152, s[58:59]
	s_mov_b32 m0, s46
	s_nop 0
	global_load_lds_dwordx4 v156, s[58:59]
	s_mov_b32 m0, s69
	s_nop 0
	global_load_lds_dwordx4 v150, s[64:65]
	s_mov_b32 m0, s70
	s_nop 0
	global_load_lds_dwordx4 v154, s[64:65]
	s_waitcnt vmcnt(8)
	s_waitcnt lgkmcnt(0)
	s_barrier
	s_setprio 1
	v_mfma_f32_16x16x32_bf16 v[62:65], v[134:137], v[186:189], v[62:65]
	v_mfma_f32_16x16x32_bf16 v[58:61], v[142:145], v[186:189], v[58:61]
	v_mfma_f32_16x16x32_bf16 v[54:57], v[134:137], v[194:197], v[54:57]
	v_mfma_f32_16x16x32_bf16 v[50:53], v[142:145], v[194:197], v[50:53]
	v_mfma_f32_16x16x32_bf16 v[46:49], v[134:137], v[202:205], v[46:49]
	v_mfma_f32_16x16x32_bf16 v[42:45], v[142:145], v[202:205], v[42:45]
	v_mfma_f32_16x16x32_bf16 v[38:41], v[134:137], v[210:213], v[38:41]
	v_mfma_f32_16x16x32_bf16 v[34:37], v[142:145], v[210:213], v[34:37]
	v_mfma_f32_16x16x32_bf16 v[62:65], v[138:141], v[190:193], v[62:65]
	v_mfma_f32_16x16x32_bf16 v[58:61], v[146:149], v[190:193], v[58:61]
	v_mfma_f32_16x16x32_bf16 v[54:57], v[138:141], v[198:201], v[54:57]
	v_mfma_f32_16x16x32_bf16 v[50:53], v[146:149], v[198:201], v[50:53]
	v_mfma_f32_16x16x32_bf16 v[46:49], v[138:141], v[206:209], v[46:49]
	v_mfma_f32_16x16x32_bf16 v[42:45], v[146:149], v[206:209], v[42:45]
	v_mfma_f32_16x16x32_bf16 v[38:41], v[138:141], v[214:217], v[38:41]
	v_mfma_f32_16x16x32_bf16 v[34:37], v[146:149], v[214:217], v[34:37]
	s_setprio 0
	s_setprio 1
	v_mfma_f32_16x16x32_bf16 v[30:33], v[168:171], v[186:189], v[30:33]
	v_mfma_f32_16x16x32_bf16 v[26:29], v[178:181], v[186:189], v[26:29]
	v_mfma_f32_16x16x32_bf16 v[22:25], v[168:171], v[194:197], v[22:25]
	v_mfma_f32_16x16x32_bf16 v[18:21], v[178:181], v[194:197], v[18:21]
	v_mfma_f32_16x16x32_bf16 v[14:17], v[168:171], v[202:205], v[14:17]
	v_mfma_f32_16x16x32_bf16 v[10:13], v[178:181], v[202:205], v[10:13]
	v_mfma_f32_16x16x32_bf16 v[6:9], v[168:171], v[210:213], v[6:9]
	v_mfma_f32_16x16x32_bf16 v[2:5], v[178:181], v[210:213], v[2:5]
	v_mfma_f32_16x16x32_bf16 v[30:33], v[174:177], v[190:193], v[30:33]
	v_mfma_f32_16x16x32_bf16 v[26:29], v[182:185], v[190:193], v[26:29]
	v_mfma_f32_16x16x32_bf16 v[22:25], v[174:177], v[198:201], v[22:25]
	v_mfma_f32_16x16x32_bf16 v[18:21], v[182:185], v[198:201], v[18:21]
	v_mfma_f32_16x16x32_bf16 v[14:17], v[174:177], v[206:209], v[14:17]
	v_mfma_f32_16x16x32_bf16 v[10:13], v[182:185], v[206:209], v[10:13]
	v_mfma_f32_16x16x32_bf16 v[6:9], v[174:177], v[214:217], v[6:9]
	v_mfma_f32_16x16x32_bf16 v[2:5], v[182:185], v[214:217], v[2:5]
	s_setprio 0
	s_barrier
; #define PG8_BAR __builtin_amdgcn_s_barrier()
;     ...
;         for (int t = 2; t < nt; t += 2) PG8_KITER(t);
;         if constexpr (ALIGN_EPI) { if (wr == 0) PG8_BAR; }
	ds_read_b128 v[134:137], v132
	ds_read_b128 v[138:141], v132 offset:1024
	ds_read_b128 v[142:145], v132 offset:2048
	ds_read_b128 v[146:149], v132 offset:3072
	ds_read_b128 v[168:171], v133
	ds_read_b128 v[174:177], v133 offset:1024
	ds_read_b128 v[178:181], v133 offset:2048
	ds_read_b128 v[182:185], v133 offset:3072
	s_add_u32 s58, s64, 0x80000
	s_addc_u32 s59, s65, 0
	s_mov_b32 m0, s71
	ds_read_b128 v[186:189], v172 offset:32768
	ds_read_b128 v[190:193], v172 offset:33792
	ds_read_b128 v[194:197], v172 offset:34816
	ds_read_b128 v[198:201], v172 offset:35840
	ds_read_b128 v[202:205], v172 offset:36864
	ds_read_b128 v[206:209], v172 offset:37888
	ds_read_b128 v[210:213], v172 offset:38912
	ds_read_b128 v[214:217], v172 offset:39936
	global_load_lds_dwordx4 v150, s[58:59]
	s_mov_b32 m0, s72
	s_nop 0
	global_load_lds_dwordx4 v154, s[58:59]
	s_waitcnt vmcnt(8)
	s_waitcnt lgkmcnt(0)
	s_barrier
	s_setprio 1
	v_mfma_f32_16x16x32_bf16 v[126:129], v[134:137], v[186:189], v[126:129]
	v_mfma_f32_16x16x32_bf16 v[122:125], v[142:145], v[186:189], v[122:125]
	v_mfma_f32_16x16x32_bf16 v[118:121], v[134:137], v[194:197], v[118:121]
	v_mfma_f32_16x16x32_bf16 v[114:117], v[142:145], v[194:197], v[114:117]
	v_mfma_f32_16x16x32_bf16 v[110:113], v[134:137], v[202:205], v[110:113]
	v_mfma_f32_16x16x32_bf16 v[106:109], v[142:145], v[202:205], v[106:109]
	v_mfma_f32_16x16x32_bf16 v[102:105], v[134:137], v[210:213], v[102:105]
	v_mfma_f32_16x16x32_bf16 v[98:101], v[142:145], v[210:213], v[98:101]
	v_mfma_f32_16x16x32_bf16 v[126:129], v[138:141], v[190:193], v[126:129]
	v_mfma_f32_16x16x32_bf16 v[122:125], v[146:149], v[190:193], v[122:125]
	v_mfma_f32_16x16x32_bf16 v[118:121], v[138:141], v[198:201], v[118:121]
	v_mfma_f32_16x16x32_bf16 v[114:117], v[146:149], v[198:201], v[114:117]
	v_mfma_f32_16x16x32_bf16 v[110:113], v[138:141], v[206:209], v[110:113]
	v_mfma_f32_16x16x32_bf16 v[106:109], v[146:149], v[206:209], v[106:109]
	v_mfma_f32_16x16x32_bf16 v[102:105], v[138:141], v[214:217], v[102:105]
	v_mfma_f32_16x16x32_bf16 v[98:101], v[146:149], v[214:217], v[98:101]
	s_setprio 0
	s_setprio 1
	v_mfma_f32_16x16x32_bf16 v[94:97], v[168:171], v[186:189], v[94:97]
	v_mfma_f32_16x16x32_bf16 v[90:93], v[178:181], v[186:189], v[90:93]
	v_mfma_f32_16x16x32_bf16 v[86:89], v[168:171], v[194:197], v[86:89]
	v_mfma_f32_16x16x32_bf16 v[82:85], v[178:181], v[194:197], v[82:85]
	v_mfma_f32_16x16x32_bf16 v[78:81], v[168:171], v[202:205], v[78:81]
	v_mfma_f32_16x16x32_bf16 v[74:77], v[178:181], v[202:205], v[74:77]
	v_mfma_f32_16x16x32_bf16 v[70:73], v[168:171], v[210:213], v[70:73]
	v_mfma_f32_16x16x32_bf16 v[66:69], v[178:181], v[210:213], v[66:69]
	v_mfma_f32_16x16x32_bf16 v[94:97], v[174:177], v[190:193], v[94:97]
	v_mfma_f32_16x16x32_bf16 v[90:93], v[182:185], v[190:193], v[90:93]
	v_mfma_f32_16x16x32_bf16 v[86:89], v[174:177], v[198:201], v[86:89]
	v_mfma_f32_16x16x32_bf16 v[82:85], v[182:185], v[198:201], v[82:85]
	v_mfma_f32_16x16x32_bf16 v[78:81], v[174:177], v[206:209], v[78:81]
	v_mfma_f32_16x16x32_bf16 v[74:77], v[182:185], v[206:209], v[74:77]
	v_mfma_f32_16x16x32_bf16 v[70:73], v[174:177], v[214:217], v[70:73]
	v_mfma_f32_16x16x32_bf16 v[66:69], v[182:185], v[214:217], v[66:69]
	s_setprio 0
	s_barrier
	s_mov_b32 m0, s47
	s_add_u32 s98, s98, 0x80
	s_addc_u32 s99, s99, 0
	s_add_u32 s100, s100, 0x80
	s_addc_u32 s101, s101, 0
	s_add_u32 s50, s50, 0x80080
	ds_read_b128 v[186:189], v172 offset:49152
	ds_read_b128 v[190:193], v172 offset:50176
	ds_read_b128 v[194:197], v172 offset:51200
	ds_read_b128 v[198:201], v172 offset:52224
	ds_read_b128 v[202:205], v172 offset:53248
	ds_read_b128 v[206:209], v172 offset:54272
	ds_read_b128 v[210:213], v172 offset:55296
	ds_read_b128 v[214:217], v172 offset:56320
	global_load_lds_dwordx4 v152, s[98:99]
	s_mov_b32 m0, s53
	s_addc_u32 s51, s51, 0
	global_load_lds_dwordx4 v156, s[98:99]
	s_mov_b32 m0, s55
	s_nop 0
	global_load_lds_dwordx4 v152, s[50:51]
	s_mov_b32 m0, s56
	s_nop 0
	global_load_lds_dwordx4 v156, s[50:51]
	s_mov_b32 m0, s77
	s_nop 0
	global_load_lds_dwordx4 v150, s[100:101]
	s_mov_b32 m0, s78
	s_nop 0
	global_load_lds_dwordx4 v154, s[100:101]
	s_waitcnt vmcnt(8)
	s_waitcnt lgkmcnt(0)
	s_barrier
	s_setprio 1
	v_mfma_f32_16x16x32_bf16 v[62:65], v[134:137], v[186:189], v[62:65]
	v_mfma_f32_16x16x32_bf16 v[58:61], v[142:145], v[186:189], v[58:61]
	v_mfma_f32_16x16x32_bf16 v[54:57], v[134:137], v[194:197], v[54:57]
	v_mfma_f32_16x16x32_bf16 v[50:53], v[142:145], v[194:197], v[50:53]
	v_mfma_f32_16x16x32_bf16 v[46:49], v[134:137], v[202:205], v[46:49]
	v_mfma_f32_16x16x32_bf16 v[42:45], v[142:145], v[202:205], v[42:45]
	v_mfma_f32_16x16x32_bf16 v[38:41], v[134:137], v[210:213], v[38:41]
	v_mfma_f32_16x16x32_bf16 v[34:37], v[142:145], v[210:213], v[34:37]
	v_mfma_f32_16x16x32_bf16 v[62:65], v[138:141], v[190:193], v[62:65]
	v_mfma_f32_16x16x32_bf16 v[58:61], v[146:149], v[190:193], v[58:61]
	v_mfma_f32_16x16x32_bf16 v[54:57], v[138:141], v[198:201], v[54:57]
	v_mfma_f32_16x16x32_bf16 v[50:53], v[146:149], v[198:201], v[50:53]
	v_mfma_f32_16x16x32_bf16 v[46:49], v[138:141], v[206:209], v[46:49]
	v_mfma_f32_16x16x32_bf16 v[42:45], v[146:149], v[206:209], v[42:45]
	v_mfma_f32_16x16x32_bf16 v[38:41], v[138:141], v[214:217], v[38:41]
	v_mfma_f32_16x16x32_bf16 v[34:37], v[146:149], v[214:217], v[34:37]
	s_setprio 0
	s_setprio 1
	v_mfma_f32_16x16x32_bf16 v[30:33], v[168:171], v[186:189], v[30:33]
	v_mfma_f32_16x16x32_bf16 v[26:29], v[178:181], v[186:189], v[26:29]
	v_mfma_f32_16x16x32_bf16 v[22:25], v[168:171], v[194:197], v[22:25]
	v_mfma_f32_16x16x32_bf16 v[18:21], v[178:181], v[194:197], v[18:21]
	v_mfma_f32_16x16x32_bf16 v[14:17], v[168:171], v[202:205], v[14:17]
	v_mfma_f32_16x16x32_bf16 v[10:13], v[178:181], v[202:205], v[10:13]
	v_mfma_f32_16x16x32_bf16 v[6:9], v[168:171], v[210:213], v[6:9]
	v_mfma_f32_16x16x32_bf16 v[2:5], v[178:181], v[210:213], v[2:5]
	v_mfma_f32_16x16x32_bf16 v[30:33], v[174:177], v[190:193], v[30:33]
	v_mfma_f32_16x16x32_bf16 v[26:29], v[182:185], v[190:193], v[26:29]
	v_mfma_f32_16x16x32_bf16 v[22:25], v[174:177], v[198:201], v[22:25]
	v_mfma_f32_16x16x32_bf16 v[18:21], v[182:185], v[198:201], v[18:21]
	v_mfma_f32_16x16x32_bf16 v[14:17], v[174:177], v[206:209], v[14:17]
	v_mfma_f32_16x16x32_bf16 v[10:13], v[182:185], v[206:209], v[10:13]
	v_mfma_f32_16x16x32_bf16 v[6:9], v[174:177], v[214:217], v[6:9]
	v_mfma_f32_16x16x32_bf16 v[2:5], v[182:185], v[214:217], v[2:5]
	s_setprio 0
	s_barrier
	s_add_i32 s26, s26, 2
	s_add_u32 s62, s62, 0x100
	s_addc_u32 s63, s63, 0
	s_add_u32 s14, s14, 0x100
	s_addc_u32 s15, s15, 0
	s_cmp_gt_u32 s26, 29
	s_cbranch_scc0 .LBB0_930
	s_and_b64 vcc, exec, s[18:19]
	s_cbranch_vccz .LBB0_933
	s_barrier

;     __host__ __device__ bool next(int i, Unit& u) const { if (!StaticOrder::next(i >> 1, u)) return false; u.seg = i & 1; return true; }
;     ...
;         const bool has_next = S.next(ui + 1, nxt);
;         const char* nA = has_next ? PG8_APTR(nxt) : cA; const char* nB = has_next ? PG8_BPTR(nxt) : cB;
.LBB0_1013:
	s_ashr_i32 s29, s28, 31
	ds_read_b128 v[2:5], v182
	ds_read_b128 v[6:9], v182 offset:1024
	ds_read_b128 v[10:13], v182 offset:2048
	ds_read_b128 v[14:17], v182 offset:3072
	ds_read_b128 v[18:21], v183
	ds_read_b128 v[22:25], v183 offset:1024
	ds_read_b128 v[26:29], v183 offset:2048
	ds_read_b128 v[30:33], v183 offset:3072
	s_lshl_b64 s[14:15], s[28:29], 21
	s_add_u32 s30, s24, s14
	s_addc_u32 s31, s25, s15
	s_and_b64 s[14:15], s[4:5], exec
	s_cselect_b32 s29, s31, s49
	s_cselect_b32 s41, s30, s48
	s_and_b32 s0, s66, 0x7fffffff
	s_lshl_b64 s[14:15], s[0:1], 21
	s_add_u32 s38, s10, s14
	s_addc_u32 s39, s11, s15
	s_and_b64 s[14:15], s[4:5], exec
	s_cselect_b32 s0, s39, s43
	s_cselect_b32 s68, s38, s42
	s_add_u32 s14, s48, 0x100080
	s_addc_u32 s15, s49, 0
	s_mov_b32 m0, s61
	v_lshl_add_u64 v[66:67], s[14:15], 0, v[154:155]
	ds_read_b128 v[34:37], v184
	ds_read_b128 v[38:41], v184 offset:1024
	ds_read_b128 v[42:45], v184 offset:2048
	ds_read_b128 v[46:49], v184 offset:3072
	ds_read_b128 v[50:53], v184 offset:4096
	ds_read_b128 v[54:57], v184 offset:5120
	ds_read_b128 v[58:61], v184 offset:6144
	ds_read_b128 v[62:65], v184 offset:7168
	global_load_lds_dwordx4 v[66:67], off
	v_lshl_add_u64 v[66:67], s[14:15], 0, v[158:159]
	s_mov_b32 m0, s62
	s_nop 0
	global_load_lds_dwordx4 v[66:67], off
	s_waitcnt vmcnt(8)
	s_waitcnt lgkmcnt(0)
	s_barrier
	s_setprio 1
	v_mfma_f32_16x16x32_bf16 v[90:93], v[2:5], v[58:61], 0
	v_mfma_f32_16x16x32_bf16 v[66:69], v[2:5], v[34:37], 0
	v_mfma_f32_16x16x32_bf16 v[70:73], v[10:13], v[34:37], 0
	v_mfma_f32_16x16x32_bf16 v[74:77], v[2:5], v[42:45], 0
	v_mfma_f32_16x16x32_bf16 v[78:81], v[10:13], v[42:45], 0
	v_mfma_f32_16x16x32_bf16 v[82:85], v[2:5], v[50:53], 0
	v_mfma_f32_16x16x32_bf16 v[86:89], v[10:13], v[50:53], 0
	v_mfma_f32_16x16x32_bf16 v[98:101], v[6:9], v[62:65], v[90:93]
	v_mfma_f32_16x16x32_bf16 v[90:93], v[10:13], v[58:61], 0
	v_mfma_f32_16x16x32_bf16 v[66:69], v[6:9], v[38:41], v[66:69]
	v_mfma_f32_16x16x32_bf16 v[70:73], v[14:17], v[38:41], v[70:73]
	v_mfma_f32_16x16x32_bf16 v[74:77], v[6:9], v[46:49], v[74:77]
	v_mfma_f32_16x16x32_bf16 v[78:81], v[14:17], v[46:49], v[78:81]
	v_mfma_f32_16x16x32_bf16 v[82:85], v[6:9], v[54:57], v[82:85]
	v_mfma_f32_16x16x32_bf16 v[86:89], v[14:17], v[54:57], v[86:89]
	v_mfma_f32_16x16x32_bf16 v[102:105], v[14:17], v[62:65], v[90:93]
	s_setprio 0
	s_setprio 1
	v_mfma_f32_16x16x32_bf16 v[90:93], v[18:21], v[34:37], 0
	v_mfma_f32_16x16x32_bf16 v[34:37], v[26:29], v[34:37], 0
	v_mfma_f32_16x16x32_bf16 v[114:117], v[22:25], v[38:41], v[90:93]
	v_mfma_f32_16x16x32_bf16 v[34:37], v[30:33], v[38:41], v[34:37]
	v_mfma_f32_16x16x32_bf16 v[38:41], v[18:21], v[42:45], 0
	v_mfma_f32_16x16x32_bf16 v[42:45], v[26:29], v[42:45], 0
	v_mfma_f32_16x16x32_bf16 v[38:41], v[22:25], v[46:49], v[38:41]
	v_mfma_f32_16x16x32_bf16 v[42:45], v[30:33], v[46:49], v[42:45]
	v_mfma_f32_16x16x32_bf16 v[46:49], v[18:21], v[50:53], 0
	v_mfma_f32_16x16x32_bf16 v[50:53], v[26:29], v[50:53], 0
	v_mfma_f32_16x16x32_bf16 v[46:49], v[22:25], v[54:57], v[46:49]
	v_mfma_f32_16x16x32_bf16 v[50:53], v[30:33], v[54:57], v[50:53]
	v_mfma_f32_16x16x32_bf16 v[54:57], v[18:21], v[58:61], 0
	v_mfma_f32_16x16x32_bf16 v[58:61], v[26:29], v[58:61], 0
	v_mfma_f32_16x16x32_bf16 v[54:57], v[22:25], v[62:65], v[54:57]
	v_mfma_f32_16x16x32_bf16 v[58:61], v[30:33], v[62:65], v[58:61]
	s_setprio 0
	s_barrier
	v_lshl_add_u64 v[152:153], s[42:43], 0, v[156:157]
	s_mov_b32 m0, s63
	v_lshl_add_u64 v[130:131], v[152:153], 0, s[20:21]
	v_lshl_add_u64 v[250:251], s[42:43], 0, v[160:161]
	s_add_u32 s14, s42, 0x100100
	ds_read_b128 v[62:65], v184 offset:16384
	ds_read_b128 v[90:93], v184 offset:17408
	ds_read_b128 v[94:97], v184 offset:18432
	ds_read_b128 v[106:109], v184 offset:19456
	ds_read_b128 v[110:113], v184 offset:20480
	ds_read_b128 v[118:121], v184 offset:21504
	ds_read_b128 v[122:125], v184 offset:22528
	ds_read_b128 v[126:129], v184 offset:23552
	global_load_lds_dwordx4 v[130:131], off
	v_lshl_add_u64 v[130:131], v[250:251], 0, s[20:21]
	s_mov_b32 m0, s64
	s_addc_u32 s15, s43, 0
	s_add_i32 s69, s60, s12
	global_load_lds_dwordx4 v[130:131], off
	v_lshl_add_u64 v[130:131], s[14:15], 0, v[156:157]
	s_mov_b32 m0, s69
	s_add_i32 s46, s69, 0x2000
	global_load_lds_dwordx4 v[130:131], off
	v_lshl_add_u64 v[130:131], s[14:15], 0, v[160:161]
	s_mov_b32 m0, s46
	v_lshl_add_u64 v[252:253], s[48:49], 0, v[154:155]
	global_load_lds_dwordx4 v[130:131], off
	v_lshl_add_u64 v[130:131], v[252:253], 0, s[20:21]
	s_mov_b32 m0, s13
	v_lshl_add_u64 v[166:167], s[48:49], 0, v[158:159]
	global_load_lds_dwordx4 v[130:131], off
	v_lshl_add_u64 v[130:131], v[166:167], 0, s[20:21]
	s_mov_b32 m0, s33
	s_nop 0
	global_load_lds_dwordx4 v[130:131], off
	s_waitcnt vmcnt(8)
	s_waitcnt lgkmcnt(0)
	s_barrier
	s_setprio 1
	v_mfma_f32_16x16x32_bf16 v[130:133], v[2:5], v[62:65], 0
	v_mfma_f32_16x16x32_bf16 v[140:143], v[2:5], v[94:97], 0
	v_mfma_f32_16x16x32_bf16 v[148:151], v[2:5], v[110:113], 0
	v_mfma_f32_16x16x32_bf16 v[2:5], v[2:5], v[122:125], 0
	v_mfma_f32_16x16x32_bf16 v[132:135], v[6:9], v[90:93], v[130:133]
	v_mfma_f32_16x16x32_bf16 v[140:143], v[6:9], v[106:109], v[140:143]
	v_mfma_f32_16x16x32_bf16 v[148:151], v[6:9], v[118:121], v[148:151]
	v_mfma_f32_16x16x32_bf16 v[2:5], v[6:9], v[126:129], v[2:5]
	v_mfma_f32_16x16x32_bf16 v[6:9], v[10:13], v[122:125], 0
	v_mfma_f32_16x16x32_bf16 v[136:139], v[10:13], v[62:65], 0
	v_mfma_f32_16x16x32_bf16 v[144:147], v[10:13], v[94:97], 0
	v_mfma_f32_16x16x32_bf16 v[170:173], v[10:13], v[110:113], 0
	v_mfma_f32_16x16x32_bf16 v[6:9], v[14:17], v[126:129], v[6:9]
	v_mfma_f32_16x16x32_bf16 v[136:139], v[14:17], v[90:93], v[136:139]
	v_mfma_f32_16x16x32_bf16 v[144:147], v[14:17], v[106:109], v[144:147]
	v_mfma_f32_16x16x32_bf16 v[170:173], v[14:17], v[118:121], v[170:173]
	s_setprio 0
	s_setprio 1
	v_mfma_f32_16x16x32_bf16 v[10:13], v[18:21], v[62:65], 0
	v_mfma_f32_16x16x32_bf16 v[174:177], v[22:25], v[90:93], v[10:13]
	v_mfma_f32_16x16x32_bf16 v[10:13], v[26:29], v[62:65], 0
	v_mfma_f32_16x16x32_bf16 v[178:181], v[30:33], v[90:93], v[10:13]
	v_mfma_f32_16x16x32_bf16 v[10:13], v[18:21], v[94:97], 0
	v_mfma_f32_16x16x32_bf16 v[186:189], v[22:25], v[106:109], v[10:13]
	v_mfma_f32_16x16x32_bf16 v[10:13], v[26:29], v[94:97], 0
	v_mfma_f32_16x16x32_bf16 v[190:193], v[30:33], v[106:109], v[10:13]
	v_mfma_f32_16x16x32_bf16 v[10:13], v[18:21], v[110:113], 0
	v_mfma_f32_16x16x32_bf16 v[194:197], v[22:25], v[118:121], v[10:13]
	v_mfma_f32_16x16x32_bf16 v[10:13], v[26:29], v[110:113], 0
	v_mfma_f32_16x16x32_bf16 v[198:201], v[30:33], v[118:121], v[10:13]
	v_mfma_f32_16x16x32_bf16 v[10:13], v[18:21], v[122:125], 0
	v_mfma_f32_16x16x32_bf16 v[202:205], v[22:25], v[126:129], v[10:13]
	v_mfma_f32_16x16x32_bf16 v[10:13], v[26:29], v[122:125], 0
	v_mfma_f32_16x16x32_bf16 v[206:209], v[30:33], v[126:129], v[10:13]
	s_setprio 0
	s_barrier
	s_add_i32 s47, 0, 0x18000
	s_add_i32 s56, 0, 0x1c000
	v_add_u32_e32 v130, s47, v1
	v_add_u32_e32 v131, s56, v1
	s_nop 0
	ds_read_b128 v[10:13], v130
	ds_read_b128 v[14:17], v130 offset:1024
	ds_read_b128 v[18:21], v130 offset:2048
	ds_read_b128 v[22:25], v130 offset:3072
	ds_read_b128 v[210:213], v131
	ds_read_b128 v[214:217], v131 offset:1024
	ds_read_b128 v[218:221], v131 offset:2048
	ds_read_b128 v[222:225], v131 offset:3072
	s_add_u32 s14, s48, 0x100100
	s_addc_u32 s15, s49, 0
	s_mov_b32 m0, s52
	v_lshl_add_u64 v[90:91], s[14:15], 0, v[154:155]
	ds_read_b128 v[26:29], v184 offset:32768
	ds_read_b128 v[30:33], v184 offset:33792
	ds_read_b128 v[62:65], v184 offset:34816
	ds_read_b128 v[226:229], v184 offset:35840
	ds_read_b128 v[230:233], v184 offset:36864
	ds_read_b128 v[234:237], v184 offset:37888
	ds_read_b128 v[238:241], v184 offset:38912
	ds_read_b128 v[242:245], v184 offset:39936
	global_load_lds_dwordx4 v[90:91], off
	v_lshl_add_u64 v[90:91], s[14:15], 0, v[158:159]
	s_mov_b32 m0, s53
	s_nop 0
	global_load_lds_dwordx4 v[90:91], off
	s_waitcnt vmcnt(8)
	s_waitcnt lgkmcnt(0)
	s_barrier
	s_setprio 1
	v_mfma_f32_16x16x32_bf16 v[66:69], v[10:13], v[26:29], v[66:69]
	v_mfma_f32_16x16x32_bf16 v[122:125], v[14:17], v[30:33], v[66:69]
	v_mfma_f32_16x16x32_bf16 v[66:69], v[18:21], v[26:29], v[70:73]
	v_mfma_f32_16x16x32_bf16 v[118:121], v[22:25], v[30:33], v[66:69]
	v_mfma_f32_16x16x32_bf16 v[66:69], v[10:13], v[62:65], v[74:77]
	v_mfma_f32_16x16x32_bf16 v[110:113], v[14:17], v[226:229], v[66:69]
	v_mfma_f32_16x16x32_bf16 v[66:69], v[18:21], v[62:65], v[78:81]
	v_mfma_f32_16x16x32_bf16 v[106:109], v[22:25], v[226:229], v[66:69]
	v_mfma_f32_16x16x32_bf16 v[66:69], v[10:13], v[230:233], v[82:85]
	v_mfma_f32_16x16x32_bf16 v[94:97], v[14:17], v[234:237], v[66:69]
	v_mfma_f32_16x16x32_bf16 v[66:69], v[18:21], v[230:233], v[86:89]
	v_mfma_f32_16x16x32_bf16 v[90:93], v[22:25], v[234:237], v[66:69]
	v_mfma_f32_16x16x32_bf16 v[66:69], v[10:13], v[238:241], v[98:101]
	v_mfma_f32_16x16x32_bf16 v[78:81], v[14:17], v[242:245], v[66:69]
	v_mfma_f32_16x16x32_bf16 v[66:69], v[18:21], v[238:241], v[102:105]
	v_mfma_f32_16x16x32_bf16 v[74:77], v[22:25], v[242:245], v[66:69]
	s_setprio 0
	s_setprio 1
	v_mfma_f32_16x16x32_bf16 v[66:69], v[210:213], v[26:29], v[114:117]
	v_mfma_f32_16x16x32_bf16 v[26:29], v[218:221], v[26:29], v[34:37]
	v_mfma_f32_16x16x32_bf16 v[114:117], v[222:225], v[30:33], v[26:29]
	v_mfma_f32_16x16x32_bf16 v[26:29], v[210:213], v[62:65], v[38:41]
	v_mfma_f32_16x16x32_bf16 v[102:105], v[214:217], v[226:229], v[26:29]
	v_mfma_f32_16x16x32_bf16 v[26:29], v[218:221], v[62:65], v[42:45]
	v_mfma_f32_16x16x32_bf16 v[98:101], v[222:225], v[226:229], v[26:29]
	v_mfma_f32_16x16x32_bf16 v[26:29], v[210:213], v[230:233], v[46:49]
	v_mfma_f32_16x16x32_bf16 v[86:89], v[214:217], v[234:237], v[26:29]
	v_mfma_f32_16x16x32_bf16 v[26:29], v[218:221], v[230:233], v[50:53]
	v_mfma_f32_16x16x32_bf16 v[82:85], v[222:225], v[234:237], v[26:29]
	v_mfma_f32_16x16x32_bf16 v[26:29], v[210:213], v[238:241], v[54:57]
	v_mfma_f32_16x16x32_bf16 v[70:73], v[214:217], v[242:245], v[26:29]
	v_mfma_f32_16x16x32_bf16 v[26:29], v[218:221], v[238:241], v[58:61]
	v_mfma_f32_16x16x32_bf16 v[126:129], v[214:217], v[30:33], v[66:69]
	v_mfma_f32_16x16x32_bf16 v[66:69], v[222:225], v[242:245], v[26:29]
	s_setprio 0
	s_barrier
	s_add_i32 s47, s47, s12
	s_add_i32 s70, s47, 0x2000
	s_nop 1
	v_lshl_add_u64 v[26:27], v[152:153], 0, s[22:23]
	s_mov_b32 m0, s47
	s_add_u32 s14, s42, 0x100180
	ds_read_b128 v[34:37], v184 offset:49152
	ds_read_b128 v[38:41], v184 offset:50176
	ds_read_b128 v[226:229], v184 offset:51200
	ds_read_b128 v[230:233], v184 offset:52224
	ds_read_b128 v[234:237], v184 offset:53248
	ds_read_b128 v[238:241], v184 offset:54272
	ds_read_b128 v[242:245], v184 offset:55296
	ds_read_b128 v[246:249], v184 offset:56320
	global_load_lds_dwordx4 v[26:27], off
	v_lshl_add_u64 v[26:27], v[250:251], 0, s[22:23]
	s_mov_b32 m0, s70
	s_addc_u32 s15, s43, 0
	s_add_i32 s56, s56, s12
	global_load_lds_dwordx4 v[26:27], off
	v_lshl_add_u64 v[26:27], s[14:15], 0, v[156:157]
	s_mov_b32 m0, s56
	s_add_i32 s57, s56, 0x2000
	global_load_lds_dwordx4 v[26:27], off
	v_lshl_add_u64 v[26:27], s[14:15], 0, v[160:161]
	s_mov_b32 m0, s57
	s_nop 0
	global_load_lds_dwordx4 v[26:27], off
	v_lshl_add_u64 v[26:27], v[252:253], 0, s[22:23]
	s_mov_b32 m0, s54
	s_nop 0
	global_load_lds_dwordx4 v[26:27], off
	v_lshl_add_u64 v[26:27], v[166:167], 0, s[22:23]
	s_mov_b32 m0, s55
	s_nop 0
	global_load_lds_dwordx4 v[26:27], off
	s_waitcnt vmcnt(8)
	s_waitcnt lgkmcnt(0)
	s_barrier
	s_setprio 1
	v_mfma_f32_16x16x32_bf16 v[26:29], v[10:13], v[34:37], v[132:135]
	v_mfma_f32_16x16x32_bf16 v[58:61], v[14:17], v[38:41], v[26:29]
	v_mfma_f32_16x16x32_bf16 v[26:29], v[18:21], v[34:37], v[136:139]
	v_mfma_f32_16x16x32_bf16 v[54:57], v[22:25], v[38:41], v[26:29]
	v_mfma_f32_16x16x32_bf16 v[26:29], v[10:13], v[226:229], v[140:143]
	v_mfma_f32_16x16x32_bf16 v[46:49], v[14:17], v[230:233], v[26:29]
	v_mfma_f32_16x16x32_bf16 v[26:29], v[18:21], v[226:229], v[144:147]
	v_mfma_f32_16x16x32_bf16 v[42:45], v[22:25], v[230:233], v[26:29]
	v_mfma_f32_16x16x32_bf16 v[26:29], v[10:13], v[234:237], v[148:151]
	v_mfma_f32_16x16x32_bf16 v[2:5], v[10:13], v[242:245], v[2:5]
	v_mfma_f32_16x16x32_bf16 v[30:33], v[14:17], v[238:241], v[26:29]
	v_mfma_f32_16x16x32_bf16 v[26:29], v[18:21], v[234:237], v[170:173]
	v_mfma_f32_16x16x32_bf16 v[14:17], v[14:17], v[246:249], v[2:5]
	v_mfma_f32_16x16x32_bf16 v[2:5], v[18:21], v[242:245], v[6:9]
	v_mfma_f32_16x16x32_bf16 v[26:29], v[22:25], v[238:241], v[26:29]
	v_mfma_f32_16x16x32_bf16 v[10:13], v[22:25], v[246:249], v[2:5]
	s_setprio 0
	s_setprio 1
	v_mfma_f32_16x16x32_bf16 v[2:5], v[210:213], v[34:37], v[174:177]
	v_mfma_f32_16x16x32_bf16 v[62:65], v[214:217], v[38:41], v[2:5]
	v_mfma_f32_16x16x32_bf16 v[2:5], v[218:221], v[34:37], v[178:181]
	v_mfma_f32_16x16x32_bf16 v[50:53], v[222:225], v[38:41], v[2:5]
	v_mfma_f32_16x16x32_bf16 v[2:5], v[210:213], v[226:229], v[186:189]
	v_mfma_f32_16x16x32_bf16 v[38:41], v[214:217], v[230:233], v[2:5]
	v_mfma_f32_16x16x32_bf16 v[2:5], v[218:221], v[226:229], v[190:193]
	v_mfma_f32_16x16x32_bf16 v[34:37], v[222:225], v[230:233], v[2:5]
	v_mfma_f32_16x16x32_bf16 v[2:5], v[210:213], v[234:237], v[194:197]
	v_mfma_f32_16x16x32_bf16 v[22:25], v[214:217], v[238:241], v[2:5]
	v_mfma_f32_16x16x32_bf16 v[2:5], v[218:221], v[234:237], v[198:201]
	v_mfma_f32_16x16x32_bf16 v[18:21], v[222:225], v[238:241], v[2:5]
	v_mfma_f32_16x16x32_bf16 v[2:5], v[210:213], v[242:245], v[202:205]
	v_mfma_f32_16x16x32_bf16 v[6:9], v[214:217], v[246:249], v[2:5]
	v_mfma_f32_16x16x32_bf16 v[2:5], v[218:221], v[242:245], v[206:209]
	v_mfma_f32_16x16x32_bf16 v[2:5], v[222:225], v[246:249], v[2:5]
	s_setprio 0
	s_barrier
	s_add_u32 s48, s48, 0x100180
	s_addc_u32 s49, s49, 0
	s_add_u32 s14, s42, 0x200
	s_addc_u32 s15, s43, 0
	s_mov_b32 s26, 0
.LBB0_1014:
	ds_read_b128 v[132:135], v182
	ds_read_b128 v[136:139], v182 offset:1024
	ds_read_b128 v[140:143], v182 offset:2048
	ds_read_b128 v[144:147], v182 offset:3072
	ds_read_b128 v[148:151], v183
	ds_read_b128 v[170:173], v183 offset:1024
	ds_read_b128 v[174:177], v183 offset:2048
	ds_read_b128 v[178:181], v183 offset:3072
	s_add_u32 s27, s48, 0xfff00080
	s_addc_u32 s42, s49, -1
	s_cmp_eq_u32 s26, 60
	s_cselect_b32 s51, s29, s42
	s_cselect_b32 s50, s41, s27
	s_cselect_b32 s43, s0, s15
	s_cselect_b32 s42, s68, s14
	s_mov_b32 m0, s61
	ds_read_b128 v[186:189], v184
	ds_read_b128 v[190:193], v184 offset:1024
	ds_read_b128 v[194:197], v184 offset:2048
	ds_read_b128 v[198:201], v184 offset:3072
	ds_read_b128 v[202:205], v184 offset:4096
	ds_read_b128 v[206:209], v184 offset:5120
	ds_read_b128 v[210:213], v184 offset:6144
	ds_read_b128 v[214:217], v184 offset:7168
	global_load_lds_dwordx4 v162, s[48:49]
	s_mov_b32 m0, s62
	s_nop 0
	global_load_lds_dwordx4 v164, s[48:49]
	s_waitcnt vmcnt(8)
	s_waitcnt lgkmcnt(0)
	s_barrier
	s_setprio 1
	v_mfma_f32_16x16x32_bf16 v[122:125], v[132:135], v[186:189], v[122:125]
	v_mfma_f32_16x16x32_bf16 v[118:121], v[140:143], v[186:189], v[118:121]
	v_mfma_f32_16x16x32_bf16 v[110:113], v[132:135], v[194:197], v[110:113]
	v_mfma_f32_16x16x32_bf16 v[106:109], v[140:143], v[194:197], v[106:109]
	v_mfma_f32_16x16x32_bf16 v[94:97], v[132:135], v[202:205], v[94:97]
	v_mfma_f32_16x16x32_bf16 v[90:93], v[140:143], v[202:205], v[90:93]
	v_mfma_f32_16x16x32_bf16 v[78:81], v[132:135], v[210:213], v[78:81]
	v_mfma_f32_16x16x32_bf16 v[74:77], v[140:143], v[210:213], v[74:77]
	v_mfma_f32_16x16x32_bf16 v[122:125], v[136:139], v[190:193], v[122:125]
	v_mfma_f32_16x16x32_bf16 v[118:121], v[144:147], v[190:193], v[118:121]
	v_mfma_f32_16x16x32_bf16 v[110:113], v[136:139], v[198:201], v[110:113]
	v_mfma_f32_16x16x32_bf16 v[106:109], v[144:147], v[198:201], v[106:109]
	v_mfma_f32_16x16x32_bf16 v[94:97], v[136:139], v[206:209], v[94:97]
	v_mfma_f32_16x16x32_bf16 v[90:93], v[144:147], v[206:209], v[90:93]
	v_mfma_f32_16x16x32_bf16 v[78:81], v[136:139], v[214:217], v[78:81]
	v_mfma_f32_16x16x32_bf16 v[74:77], v[144:147], v[214:217], v[74:77]
	s_setprio 0
	s_setprio 1
	v_mfma_f32_16x16x32_bf16 v[126:129], v[148:151], v[186:189], v[126:129]
	v_mfma_f32_16x16x32_bf16 v[114:117], v[174:177], v[186:189], v[114:117]
	v_mfma_f32_16x16x32_bf16 v[102:105], v[148:151], v[194:197], v[102:105]
	v_mfma_f32_16x16x32_bf16 v[98:101], v[174:177], v[194:197], v[98:101]
	v_mfma_f32_16x16x32_bf16 v[86:89], v[148:151], v[202:205], v[86:89]
	v_mfma_f32_16x16x32_bf16 v[82:85], v[174:177], v[202:205], v[82:85]
	v_mfma_f32_16x16x32_bf16 v[70:73], v[148:151], v[210:213], v[70:73]
	v_mfma_f32_16x16x32_bf16 v[66:69], v[174:177], v[210:213], v[66:69]
	v_mfma_f32_16x16x32_bf16 v[126:129], v[170:173], v[190:193], v[126:129]
	v_mfma_f32_16x16x32_bf16 v[114:117], v[178:181], v[190:193], v[114:117]
	v_mfma_f32_16x16x32_bf16 v[102:105], v[170:173], v[198:201], v[102:105]
	v_mfma_f32_16x16x32_bf16 v[98:101], v[178:181], v[198:201], v[98:101]
	v_mfma_f32_16x16x32_bf16 v[86:89], v[170:173], v[206:209], v[86:89]
	v_mfma_f32_16x16x32_bf16 v[82:85], v[178:181], v[206:209], v[82:85]
	v_mfma_f32_16x16x32_bf16 v[70:73], v[170:173], v[214:217], v[70:73]
	v_mfma_f32_16x16x32_bf16 v[66:69], v[178:181], v[214:217], v[66:69]
	s_setprio 0
	s_barrier
	s_mov_b32 m0, s63
	s_mov_b64 s[98:99], s[42:43]
	s_add_u32 s72, s42, 0x100000
	ds_read_b128 v[186:189], v184 offset:16384
	ds_read_b128 v[190:193], v184 offset:17408
	ds_read_b128 v[194:197], v184 offset:18432
	ds_read_b128 v[198:201], v184 offset:19456
	ds_read_b128 v[202:205], v184 offset:20480
	ds_read_b128 v[206:209], v184 offset:21504
	ds_read_b128 v[210:213], v184 offset:22528
	ds_read_b128 v[214:217], v184 offset:23552
	global_load_lds_dwordx4 v156, s[42:43]
	s_mov_b32 m0, s64
	s_addc_u32 s73, s43, 0
	global_load_lds_dwordx4 v160, s[42:43]
	s_mov_b32 m0, s69
	s_mov_b64 s[100:101], s[50:51]
	global_load_lds_dwordx4 v156, s[72:73]
	s_mov_b32 m0, s46
	s_nop 0
	global_load_lds_dwordx4 v160, s[72:73]
	s_mov_b32 m0, s13
	s_nop 0
	global_load_lds_dwordx4 v154, s[50:51]
	s_mov_b32 m0, s33
	s_nop 0
	global_load_lds_dwordx4 v158, s[50:51]
	s_waitcnt vmcnt(8)
	s_waitcnt lgkmcnt(0)
	s_barrier
	s_setprio 1
	v_mfma_f32_16x16x32_bf16 v[58:61], v[132:135], v[186:189], v[58:61]
	v_mfma_f32_16x16x32_bf16 v[54:57], v[140:143], v[186:189], v[54:57]
	v_mfma_f32_16x16x32_bf16 v[46:49], v[132:135], v[194:197], v[46:49]
	v_mfma_f32_16x16x32_bf16 v[42:45], v[140:143], v[194:197], v[42:45]
	v_mfma_f32_16x16x32_bf16 v[30:33], v[132:135], v[202:205], v[30:33]
	v_mfma_f32_16x16x32_bf16 v[26:29], v[140:143], v[202:205], v[26:29]
	v_mfma_f32_16x16x32_bf16 v[14:17], v[132:135], v[210:213], v[14:17]
	v_mfma_f32_16x16x32_bf16 v[10:13], v[140:143], v[210:213], v[10:13]
	v_mfma_f32_16x16x32_bf16 v[58:61], v[136:139], v[190:193], v[58:61]
	v_mfma_f32_16x16x32_bf16 v[54:57], v[144:147], v[190:193], v[54:57]
	v_mfma_f32_16x16x32_bf16 v[46:49], v[136:139], v[198:201], v[46:49]
	v_mfma_f32_16x16x32_bf16 v[42:45], v[144:147], v[198:201], v[42:45]
	v_mfma_f32_16x16x32_bf16 v[30:33], v[136:139], v[206:209], v[30:33]
	v_mfma_f32_16x16x32_bf16 v[26:29], v[144:147], v[206:209], v[26:29]
	v_mfma_f32_16x16x32_bf16 v[14:17], v[136:139], v[214:217], v[14:17]
	v_mfma_f32_16x16x32_bf16 v[10:13], v[144:147], v[214:217], v[10:13]
	s_setprio 0
	s_setprio 1
	v_mfma_f32_16x16x32_bf16 v[62:65], v[148:151], v[186:189], v[62:65]
	v_mfma_f32_16x16x32_bf16 v[50:53], v[174:177], v[186:189], v[50:53]
	v_mfma_f32_16x16x32_bf16 v[38:41], v[148:151], v[194:197], v[38:41]
	v_mfma_f32_16x16x32_bf16 v[34:37], v[174:177], v[194:197], v[34:37]
	v_mfma_f32_16x16x32_bf16 v[22:25], v[148:151], v[202:205], v[22:25]
	v_mfma_f32_16x16x32_bf16 v[18:21], v[174:177], v[202:205], v[18:21]
	v_mfma_f32_16x16x32_bf16 v[6:9], v[148:151], v[210:213], v[6:9]
	v_mfma_f32_16x16x32_bf16 v[2:5], v[174:177], v[210:213], v[2:5]
	v_mfma_f32_16x16x32_bf16 v[62:65], v[170:173], v[190:193], v[62:65]
	v_mfma_f32_16x16x32_bf16 v[50:53], v[178:181], v[190:193], v[50:53]
	v_mfma_f32_16x16x32_bf16 v[38:41], v[170:173], v[198:201], v[38:41]
	v_mfma_f32_16x16x32_bf16 v[34:37], v[178:181], v[198:201], v[34:37]
	v_mfma_f32_16x16x32_bf16 v[22:25], v[170:173], v[206:209], v[22:25]
	v_mfma_f32_16x16x32_bf16 v[18:21], v[178:181], v[206:209], v[18:21]
	v_mfma_f32_16x16x32_bf16 v[6:9], v[170:173], v[214:217], v[6:9]
	v_mfma_f32_16x16x32_bf16 v[2:5], v[178:181], v[214:217], v[2:5]
	s_setprio 0
	s_barrier
; #define PG8_BAR __builtin_amdgcn_s_barrier()
;     ...
;         for (int t = 2; t < nt; t += 2) PG8_KITER(t);
;         if constexpr (ALIGN_EPI) { if (wr == 0) PG8_BAR; }
	ds_read_b128 v[132:135], v130
	ds_read_b128 v[136:139], v130 offset:1024
	ds_read_b128 v[140:143], v130 offset:2048
	ds_read_b128 v[144:147], v130 offset:3072
	ds_read_b128 v[148:151], v131
	ds_read_b128 v[170:173], v131 offset:1024
	ds_read_b128 v[174:177], v131 offset:2048
	ds_read_b128 v[178:181], v131 offset:3072
	s_add_u32 s50, s50, 0x100000
	s_addc_u32 s51, s51, 0
	s_mov_b32 m0, s52
	ds_read_b128 v[186:189], v184 offset:32768
	ds_read_b128 v[190:193], v184 offset:33792
	ds_read_b128 v[194:197], v184 offset:34816
	ds_read_b128 v[198:201], v184 offset:35840
	ds_read_b128 v[202:205], v184 offset:36864
	ds_read_b128 v[206:209], v184 offset:37888
	ds_read_b128 v[210:213], v184 offset:38912
	ds_read_b128 v[214:217], v184 offset:39936
	global_load_lds_dwordx4 v154, s[50:51]
	s_mov_b32 m0, s53
	s_nop 0
	global_load_lds_dwordx4 v158, s[50:51]
	s_waitcnt vmcnt(8)
	s_waitcnt lgkmcnt(0)
	s_barrier
	s_setprio 1
	v_mfma_f32_16x16x32_bf16 v[122:125], v[132:135], v[186:189], v[122:125]
	v_mfma_f32_16x16x32_bf16 v[118:121], v[140:143], v[186:189], v[118:121]
	v_mfma_f32_16x16x32_bf16 v[110:113], v[132:135], v[194:197], v[110:113]
	v_mfma_f32_16x16x32_bf16 v[106:109], v[140:143], v[194:197], v[106:109]
	v_mfma_f32_16x16x32_bf16 v[94:97], v[132:135], v[202:205], v[94:97]
	v_mfma_f32_16x16x32_bf16 v[90:93], v[140:143], v[202:205], v[90:93]
	v_mfma_f32_16x16x32_bf16 v[78:81], v[132:135], v[210:213], v[78:81]
	v_mfma_f32_16x16x32_bf16 v[74:77], v[140:143], v[210:213], v[74:77]
	v_mfma_f32_16x16x32_bf16 v[122:125], v[136:139], v[190:193], v[122:125]
	v_mfma_f32_16x16x32_bf16 v[118:121], v[144:147], v[190:193], v[118:121]
	v_mfma_f32_16x16x32_bf16 v[110:113], v[136:139], v[198:201], v[110:113]
	v_mfma_f32_16x16x32_bf16 v[106:109], v[144:147], v[198:201], v[106:109]
	v_mfma_f32_16x16x32_bf16 v[94:97], v[136:139], v[206:209], v[94:97]
	v_mfma_f32_16x16x32_bf16 v[90:93], v[144:147], v[206:209], v[90:93]
	v_mfma_f32_16x16x32_bf16 v[78:81], v[136:139], v[214:217], v[78:81]
	v_mfma_f32_16x16x32_bf16 v[74:77], v[144:147], v[214:217], v[74:77]
	s_setprio 0
	s_setprio 1
	v_mfma_f32_16x16x32_bf16 v[126:129], v[148:151], v[186:189], v[126:129]
	v_mfma_f32_16x16x32_bf16 v[114:117], v[174:177], v[186:189], v[114:117]
	v_mfma_f32_16x16x32_bf16 v[102:105], v[148:151], v[194:197], v[102:105]
	v_mfma_f32_16x16x32_bf16 v[98:101], v[174:177], v[194:197], v[98:101]
	v_mfma_f32_16x16x32_bf16 v[86:89], v[148:151], v[202:205], v[86:89]
	v_mfma_f32_16x16x32_bf16 v[82:85], v[174:177], v[202:205], v[82:85]
	v_mfma_f32_16x16x32_bf16 v[70:73], v[148:151], v[210:213], v[70:73]
	v_mfma_f32_16x16x32_bf16 v[66:69], v[174:177], v[210:213], v[66:69]
	v_mfma_f32_16x16x32_bf16 v[126:129], v[170:173], v[190:193], v[126:129]
	v_mfma_f32_16x16x32_bf16 v[114:117], v[178:181], v[190:193], v[114:117]
	v_mfma_f32_16x16x32_bf16 v[102:105], v[170:173], v[198:201], v[102:105]
	v_mfma_f32_16x16x32_bf16 v[98:101], v[178:181], v[198:201], v[98:101]
	v_mfma_f32_16x16x32_bf16 v[86:89], v[170:173], v[206:209], v[86:89]
	v_mfma_f32_16x16x32_bf16 v[82:85], v[178:181], v[206:209], v[82:85]
	v_mfma_f32_16x16x32_bf16 v[70:73], v[170:173], v[214:217], v[70:73]
	v_mfma_f32_16x16x32_bf16 v[66:69], v[178:181], v[214:217], v[66:69]
	s_setprio 0
	s_barrier
	s_mov_b32 m0, s47
	s_add_u32 s98, s98, 0x80
	s_addc_u32 s99, s99, 0
	s_add_u32 s100, s100, 0x80
	s_addc_u32 s101, s101, 0
	s_add_u32 s42, s42, 0x100080
	ds_read_b128 v[186:189], v184 offset:49152
	ds_read_b128 v[190:193], v184 offset:50176
	ds_read_b128 v[194:197], v184 offset:51200
	ds_read_b128 v[198:201], v184 offset:52224
	ds_read_b128 v[202:205], v184 offset:53248
	ds_read_b128 v[206:209], v184 offset:54272
	ds_read_b128 v[210:213], v184 offset:55296
	ds_read_b128 v[214:217], v184 offset:56320
	global_load_lds_dwordx4 v156, s[98:99]
	s_mov_b32 m0, s70
	s_addc_u32 s43, s43, 0
	global_load_lds_dwordx4 v160, s[98:99]
	s_mov_b32 m0, s56
	s_nop 0
	global_load_lds_dwordx4 v156, s[42:43]
	s_mov_b32 m0, s57
	s_nop 0
	global_load_lds_dwordx4 v160, s[42:43]
	s_mov_b32 m0, s54
	s_nop 0
	global_load_lds_dwordx4 v154, s[100:101]
	s_mov_b32 m0, s55
	s_nop 0
	global_load_lds_dwordx4 v158, s[100:101]
	s_waitcnt vmcnt(8)
	s_waitcnt lgkmcnt(0)
	s_barrier
	s_setprio 1
	v_mfma_f32_16x16x32_bf16 v[58:61], v[132:135], v[186:189], v[58:61]
	v_mfma_f32_16x16x32_bf16 v[54:57], v[140:143], v[186:189], v[54:57]
	v_mfma_f32_16x16x32_bf16 v[46:49], v[132:135], v[194:197], v[46:49]
	v_mfma_f32_16x16x32_bf16 v[42:45], v[140:143], v[194:197], v[42:45]
	v_mfma_f32_16x16x32_bf16 v[30:33], v[132:135], v[202:205], v[30:33]
	v_mfma_f32_16x16x32_bf16 v[26:29], v[140:143], v[202:205], v[26:29]
	v_mfma_f32_16x16x32_bf16 v[14:17], v[132:135], v[210:213], v[14:17]
	v_mfma_f32_16x16x32_bf16 v[10:13], v[140:143], v[210:213], v[10:13]
	v_mfma_f32_16x16x32_bf16 v[58:61], v[136:139], v[190:193], v[58:61]
	v_mfma_f32_16x16x32_bf16 v[54:57], v[144:147], v[190:193], v[54:57]
	v_mfma_f32_16x16x32_bf16 v[46:49], v[136:139], v[198:201], v[46:49]
	v_mfma_f32_16x16x32_bf16 v[42:45], v[144:147], v[198:201], v[42:45]
	v_mfma_f32_16x16x32_bf16 v[30:33], v[136:139], v[206:209], v[30:33]
	v_mfma_f32_16x16x32_bf16 v[26:29], v[144:147], v[206:209], v[26:29]
	v_mfma_f32_16x16x32_bf16 v[14:17], v[136:139], v[214:217], v[14:17]
	v_mfma_f32_16x16x32_bf16 v[10:13], v[144:147], v[214:217], v[10:13]
	s_setprio 0
	s_setprio 1
	v_mfma_f32_16x16x32_bf16 v[62:65], v[148:151], v[186:189], v[62:65]
	v_mfma_f32_16x16x32_bf16 v[50:53], v[174:177], v[186:189], v[50:53]
	v_mfma_f32_16x16x32_bf16 v[38:41], v[148:151], v[194:197], v[38:41]
	v_mfma_f32_16x16x32_bf16 v[34:37], v[174:177], v[194:197], v[34:37]
	v_mfma_f32_16x16x32_bf16 v[22:25], v[148:151], v[202:205], v[22:25]
	v_mfma_f32_16x16x32_bf16 v[18:21], v[174:177], v[202:205], v[18:21]
	v_mfma_f32_16x16x32_bf16 v[6:9], v[148:151], v[210:213], v[6:9]
	v_mfma_f32_16x16x32_bf16 v[2:5], v[174:177], v[210:213], v[2:5]
	v_mfma_f32_16x16x32_bf16 v[62:65], v[170:173], v[190:193], v[62:65]
	v_mfma_f32_16x16x32_bf16 v[50:53], v[178:181], v[190:193], v[50:53]
	v_mfma_f32_16x16x32_bf16 v[38:41], v[170:173], v[198:201], v[38:41]
	v_mfma_f32_16x16x32_bf16 v[34:37], v[178:181], v[198:201], v[34:37]
	v_mfma_f32_16x16x32_bf16 v[22:25], v[170:173], v[206:209], v[22:25]
	v_mfma_f32_16x16x32_bf16 v[18:21], v[178:181], v[206:209], v[18:21]
	v_mfma_f32_16x16x32_bf16 v[6:9], v[170:173], v[214:217], v[6:9]
	v_mfma_f32_16x16x32_bf16 v[2:5], v[178:181], v[214:217], v[2:5]
	s_setprio 0
	s_barrier
	s_add_i32 s26, s26, 2
	s_add_u32 s48, s48, 0x100
	s_addc_u32 s49, s49, 0
	s_add_u32 s14, s14, 0x100
	s_addc_u32 s15, s15, 0
	s_cmp_gt_u32 s26, 61
	s_cbranch_scc0 .LBB0_1014
	s_and_b64 vcc, exec, s[18:19]
	s_cbranch_vccz .LBB0_1017
	s_barrier

.LBB0_1109:
	ds_read_b128 v[2:5], v148
	ds_read_b128 v[6:9], v148 offset:1024
	ds_read_b128 v[10:13], v148 offset:2048
	ds_read_b128 v[14:17], v148 offset:3072
	ds_read_b128 v[18:21], v149
	ds_read_b128 v[22:25], v149 offset:1024
	ds_read_b128 v[26:29], v149 offset:2048
	ds_read_b128 v[30:33], v149 offset:3072
	s_add_u32 s0, s54, 0x100080
	s_addc_u32 s1, s55, 0
	s_add_i32 s41, s33, 0xc000
	v_lshl_add_u64 v[66:67], s[0:1], 0, v[130:131]
	s_mov_b32 m0, s41
	s_add_i32 s73, s33, 0xe000
	ds_read_b128 v[34:37], v150
	ds_read_b128 v[38:41], v150 offset:1024
	ds_read_b128 v[42:45], v150 offset:2048
	ds_read_b128 v[46:49], v150 offset:3072
	ds_read_b128 v[50:53], v150 offset:4096
	ds_read_b128 v[54:57], v150 offset:5120
	ds_read_b128 v[58:61], v150 offset:6144
	ds_read_b128 v[62:65], v150 offset:7168
	global_load_lds_dwordx4 v[66:67], off
	v_lshl_add_u64 v[66:67], s[0:1], 0, v[132:133]
	s_mov_b32 m0, s73
	s_nop 0
	global_load_lds_dwordx4 v[66:67], off
	s_waitcnt vmcnt(8)
	s_waitcnt lgkmcnt(0)
	s_barrier
	s_setprio 1
	v_mfma_f32_16x16x32_bf16 v[86:89], v[10:13], v[50:53], 0
	v_mfma_f32_16x16x32_bf16 v[90:93], v[14:17], v[54:57], v[86:89]
	v_mfma_f32_16x16x32_bf16 v[86:89], v[2:5], v[58:61], 0
	v_mfma_f32_16x16x32_bf16 v[66:69], v[2:5], v[34:37], 0
	v_mfma_f32_16x16x32_bf16 v[70:73], v[10:13], v[34:37], 0
	v_mfma_f32_16x16x32_bf16 v[74:77], v[2:5], v[42:45], 0
	v_mfma_f32_16x16x32_bf16 v[78:81], v[10:13], v[42:45], 0
	v_mfma_f32_16x16x32_bf16 v[82:85], v[2:5], v[50:53], 0
	v_mfma_f32_16x16x32_bf16 v[94:97], v[6:9], v[62:65], v[86:89]
	v_mfma_f32_16x16x32_bf16 v[86:89], v[10:13], v[58:61], 0
	v_mfma_f32_16x16x32_bf16 v[66:69], v[6:9], v[38:41], v[66:69]
	v_mfma_f32_16x16x32_bf16 v[70:73], v[14:17], v[38:41], v[70:73]
	v_mfma_f32_16x16x32_bf16 v[74:77], v[6:9], v[46:49], v[74:77]
	v_mfma_f32_16x16x32_bf16 v[78:81], v[14:17], v[46:49], v[78:81]
	v_mfma_f32_16x16x32_bf16 v[82:85], v[6:9], v[54:57], v[82:85]
	v_mfma_f32_16x16x32_bf16 v[106:109], v[14:17], v[62:65], v[86:89]
	s_setprio 0
	s_setprio 1
	v_mfma_f32_16x16x32_bf16 v[86:89], v[18:21], v[34:37], 0
	v_mfma_f32_16x16x32_bf16 v[34:37], v[26:29], v[34:37], 0
	v_mfma_f32_16x16x32_bf16 v[110:113], v[22:25], v[38:41], v[86:89]
	v_mfma_f32_16x16x32_bf16 v[34:37], v[30:33], v[38:41], v[34:37]
	v_mfma_f32_16x16x32_bf16 v[38:41], v[18:21], v[42:45], 0
	v_mfma_f32_16x16x32_bf16 v[42:45], v[26:29], v[42:45], 0
	v_mfma_f32_16x16x32_bf16 v[38:41], v[22:25], v[46:49], v[38:41]
	v_mfma_f32_16x16x32_bf16 v[42:45], v[30:33], v[46:49], v[42:45]
	v_mfma_f32_16x16x32_bf16 v[46:49], v[18:21], v[50:53], 0
	v_mfma_f32_16x16x32_bf16 v[50:53], v[26:29], v[50:53], 0
	v_mfma_f32_16x16x32_bf16 v[46:49], v[22:25], v[54:57], v[46:49]
	v_mfma_f32_16x16x32_bf16 v[50:53], v[30:33], v[54:57], v[50:53]
	v_mfma_f32_16x16x32_bf16 v[54:57], v[18:21], v[58:61], 0
	v_mfma_f32_16x16x32_bf16 v[152:155], v[22:25], v[62:65], v[54:57]
	v_mfma_f32_16x16x32_bf16 v[54:57], v[26:29], v[58:61], 0
	v_mfma_f32_16x16x32_bf16 v[58:61], v[30:33], v[62:65], v[54:57]
	s_setprio 0
	s_barrier
	s_add_i32 s74, s64, s13
	v_lshl_add_u64 v[146:147], s[52:53], 0, v[130:131]
	s_add_i32 s75, s74, 0x2000
	v_lshl_add_u64 v[126:127], v[146:147], 0, s[20:21]
	s_mov_b32 m0, s74
	v_lshl_add_u64 v[248:249], s[52:53], 0, v[132:133]
	s_add_u32 s0, s52, 0x100100
	ds_read_b128 v[54:57], v150 offset:16384
	ds_read_b128 v[62:65], v150 offset:17408
	ds_read_b128 v[86:89], v150 offset:18432
	ds_read_b128 v[98:101], v150 offset:19456
	ds_read_b128 v[102:105], v150 offset:20480
	ds_read_b128 v[114:117], v150 offset:21504
	ds_read_b128 v[118:121], v150 offset:22528
	ds_read_b128 v[122:125], v150 offset:23552
	global_load_lds_dwordx4 v[126:127], off
	v_lshl_add_u64 v[126:127], v[248:249], 0, s[20:21]
	s_mov_b32 m0, s75
	s_addc_u32 s1, s53, 0
	s_add_i32 s76, s65, s13
	global_load_lds_dwordx4 v[126:127], off
	v_lshl_add_u64 v[126:127], s[0:1], 0, v[130:131]
	s_mov_b32 m0, s76
	s_add_i32 s46, s76, 0x2000
	global_load_lds_dwordx4 v[126:127], off
	v_lshl_add_u64 v[126:127], s[0:1], 0, v[132:133]
	s_mov_b32 m0, s46
	v_lshl_add_u64 v[250:251], s[54:55], 0, v[130:131]
	global_load_lds_dwordx4 v[126:127], off
	v_lshl_add_u64 v[126:127], v[250:251], 0, s[20:21]
	s_mov_b32 m0, s33
	v_lshl_add_u64 v[252:253], s[54:55], 0, v[132:133]
	global_load_lds_dwordx4 v[126:127], off
	v_lshl_add_u64 v[126:127], v[252:253], 0, s[20:21]
	s_mov_b32 m0, s51
	s_nop 0
	global_load_lds_dwordx4 v[126:127], off
	s_waitcnt vmcnt(8)
	s_waitcnt lgkmcnt(0)
	s_barrier
	s_setprio 1
	v_mfma_f32_16x16x32_bf16 v[126:129], v[2:5], v[54:57], 0
	v_mfma_f32_16x16x32_bf16 v[156:159], v[6:9], v[62:65], v[126:129]
	v_mfma_f32_16x16x32_bf16 v[126:129], v[10:13], v[54:57], 0
	v_mfma_f32_16x16x32_bf16 v[160:163], v[14:17], v[62:65], v[126:129]
	v_mfma_f32_16x16x32_bf16 v[126:129], v[2:5], v[86:89], 0
	v_mfma_f32_16x16x32_bf16 v[164:167], v[6:9], v[98:101], v[126:129]
	v_mfma_f32_16x16x32_bf16 v[126:129], v[10:13], v[86:89], 0
	v_mfma_f32_16x16x32_bf16 v[168:171], v[14:17], v[98:101], v[126:129]
	v_mfma_f32_16x16x32_bf16 v[126:129], v[2:5], v[102:105], 0
	v_mfma_f32_16x16x32_bf16 v[2:5], v[2:5], v[118:121], 0
	v_mfma_f32_16x16x32_bf16 v[172:175], v[6:9], v[114:117], v[126:129]
	v_mfma_f32_16x16x32_bf16 v[2:5], v[6:9], v[122:125], v[2:5]
	v_mfma_f32_16x16x32_bf16 v[6:9], v[10:13], v[118:121], 0
	v_mfma_f32_16x16x32_bf16 v[126:129], v[10:13], v[102:105], 0
	v_mfma_f32_16x16x32_bf16 v[10:13], v[14:17], v[122:125], v[6:9]
	v_mfma_f32_16x16x32_bf16 v[176:179], v[14:17], v[114:117], v[126:129]
	s_setprio 0
	s_setprio 1
	v_mfma_f32_16x16x32_bf16 v[6:9], v[18:21], v[54:57], 0
	v_mfma_f32_16x16x32_bf16 v[14:17], v[22:25], v[62:65], v[6:9]
	v_mfma_f32_16x16x32_bf16 v[6:9], v[26:29], v[54:57], 0
	v_mfma_f32_16x16x32_bf16 v[180:183], v[30:33], v[62:65], v[6:9]
	v_mfma_f32_16x16x32_bf16 v[6:9], v[18:21], v[86:89], 0
	v_mfma_f32_16x16x32_bf16 v[184:187], v[22:25], v[98:101], v[6:9]
	v_mfma_f32_16x16x32_bf16 v[6:9], v[26:29], v[86:89], 0
	v_mfma_f32_16x16x32_bf16 v[188:191], v[30:33], v[98:101], v[6:9]
	v_mfma_f32_16x16x32_bf16 v[6:9], v[18:21], v[102:105], 0
	v_mfma_f32_16x16x32_bf16 v[192:195], v[22:25], v[114:117], v[6:9]
	v_mfma_f32_16x16x32_bf16 v[6:9], v[26:29], v[102:105], 0
	v_mfma_f32_16x16x32_bf16 v[196:199], v[30:33], v[114:117], v[6:9]
	v_mfma_f32_16x16x32_bf16 v[6:9], v[18:21], v[118:121], 0
	v_mfma_f32_16x16x32_bf16 v[200:203], v[22:25], v[122:125], v[6:9]
	v_mfma_f32_16x16x32_bf16 v[6:9], v[26:29], v[118:121], 0
	v_mfma_f32_16x16x32_bf16 v[204:207], v[30:33], v[122:125], v[6:9]
	s_setprio 0
	s_barrier
	s_add_i32 s47, 0, 0x18000
	s_add_i32 s56, 0, 0x1c000
	v_add_u32_e32 v134, s47, v1
	v_add_u32_e32 v144, s56, v1
	s_nop 0
	ds_read_b128 v[6:9], v134
	ds_read_b128 v[18:21], v134 offset:1024
	ds_read_b128 v[30:33], v134 offset:2048
	ds_read_b128 v[208:211], v134 offset:3072
	ds_read_b128 v[212:215], v144
	ds_read_b128 v[216:219], v144 offset:1024
	ds_read_b128 v[220:223], v144 offset:2048
	ds_read_b128 v[224:227], v144 offset:3072
	s_add_u32 s0, s54, 0x100100
	s_addc_u32 s1, s55, 0
	s_mov_b32 m0, s58
	v_lshl_add_u64 v[54:55], s[0:1], 0, v[130:131]
	ds_read_b128 v[22:25], v150 offset:32768
	ds_read_b128 v[26:29], v150 offset:33792
	ds_read_b128 v[62:65], v150 offset:34816
	ds_read_b128 v[228:231], v150 offset:35840
	ds_read_b128 v[232:235], v150 offset:36864
	ds_read_b128 v[236:239], v150 offset:37888
	ds_read_b128 v[240:243], v150 offset:38912
	ds_read_b128 v[244:247], v150 offset:39936
	global_load_lds_dwordx4 v[54:55], off
	v_lshl_add_u64 v[54:55], s[0:1], 0, v[132:133]
	s_mov_b32 m0, s59
	s_nop 0
	global_load_lds_dwordx4 v[54:55], off
	s_waitcnt vmcnt(8)
	s_waitcnt lgkmcnt(0)
	s_barrier
	s_setprio 1
	v_mfma_f32_16x16x32_bf16 v[54:57], v[6:9], v[22:25], v[66:69]
	v_mfma_f32_16x16x32_bf16 v[118:121], v[18:21], v[26:29], v[54:57]
	v_mfma_f32_16x16x32_bf16 v[54:57], v[30:33], v[22:25], v[70:73]
	v_mfma_f32_16x16x32_bf16 v[114:117], v[208:211], v[26:29], v[54:57]
	v_mfma_f32_16x16x32_bf16 v[54:57], v[6:9], v[62:65], v[74:77]
	v_mfma_f32_16x16x32_bf16 v[102:105], v[18:21], v[228:231], v[54:57]
	v_mfma_f32_16x16x32_bf16 v[54:57], v[30:33], v[62:65], v[78:81]
	v_mfma_f32_16x16x32_bf16 v[98:101], v[208:211], v[228:231], v[54:57]
	v_mfma_f32_16x16x32_bf16 v[54:57], v[6:9], v[232:235], v[82:85]
	v_mfma_f32_16x16x32_bf16 v[86:89], v[18:21], v[236:239], v[54:57]
	v_mfma_f32_16x16x32_bf16 v[54:57], v[30:33], v[232:235], v[90:93]
	v_mfma_f32_16x16x32_bf16 v[82:85], v[208:211], v[236:239], v[54:57]
	v_mfma_f32_16x16x32_bf16 v[54:57], v[6:9], v[240:243], v[94:97]
	v_mfma_f32_16x16x32_bf16 v[74:77], v[18:21], v[244:247], v[54:57]
	v_mfma_f32_16x16x32_bf16 v[54:57], v[30:33], v[240:243], v[106:109]
	v_mfma_f32_16x16x32_bf16 v[54:57], v[208:211], v[244:247], v[54:57]
	s_setprio 0
	s_setprio 1
	v_mfma_f32_16x16x32_bf16 v[66:69], v[212:215], v[22:25], v[110:113]
	v_mfma_f32_16x16x32_bf16 v[22:25], v[220:223], v[22:25], v[34:37]
	v_mfma_f32_16x16x32_bf16 v[122:125], v[224:227], v[26:29], v[22:25]
	v_mfma_f32_16x16x32_bf16 v[22:25], v[212:215], v[62:65], v[38:41]
	v_mfma_f32_16x16x32_bf16 v[110:113], v[216:219], v[228:231], v[22:25]
	v_mfma_f32_16x16x32_bf16 v[22:25], v[220:223], v[62:65], v[42:45]
	v_mfma_f32_16x16x32_bf16 v[106:109], v[224:227], v[228:231], v[22:25]
	v_mfma_f32_16x16x32_bf16 v[22:25], v[212:215], v[232:235], v[46:49]
	v_mfma_f32_16x16x32_bf16 v[94:97], v[216:219], v[236:239], v[22:25]
	v_mfma_f32_16x16x32_bf16 v[22:25], v[220:223], v[232:235], v[50:53]
	v_mfma_f32_16x16x32_bf16 v[90:93], v[224:227], v[236:239], v[22:25]
	v_mfma_f32_16x16x32_bf16 v[22:25], v[212:215], v[240:243], v[152:155]
	v_mfma_f32_16x16x32_bf16 v[70:73], v[216:219], v[244:247], v[22:25]
	v_mfma_f32_16x16x32_bf16 v[22:25], v[220:223], v[240:243], v[58:61]
	v_mfma_f32_16x16x32_bf16 v[126:129], v[216:219], v[26:29], v[66:69]
	v_mfma_f32_16x16x32_bf16 v[50:53], v[224:227], v[244:247], v[22:25]
	s_setprio 0
	s_barrier
	s_add_i32 s47, s47, s13
	s_add_i32 s77, s47, 0x2000
	s_nop 1
	v_lshl_add_u64 v[22:23], v[146:147], 0, s[22:23]
	s_mov_b32 m0, s47
	s_add_u32 s0, s52, 0x100180
	ds_read_b128 v[34:37], v150 offset:49152
	ds_read_b128 v[46:49], v150 offset:50176
	ds_read_b128 v[152:155], v150 offset:51200
	ds_read_b128 v[228:231], v150 offset:52224
	ds_read_b128 v[232:235], v150 offset:53248
	ds_read_b128 v[236:239], v150 offset:54272
	ds_read_b128 v[240:243], v150 offset:55296
	ds_read_b128 v[244:247], v150 offset:56320
	global_load_lds_dwordx4 v[22:23], off
	v_lshl_add_u64 v[22:23], v[248:249], 0, s[22:23]
	s_mov_b32 m0, s77
	s_addc_u32 s1, s53, 0
	s_add_i32 s56, s56, s13
	global_load_lds_dwordx4 v[22:23], off
	v_lshl_add_u64 v[22:23], s[0:1], 0, v[130:131]
	s_mov_b32 m0, s56
	s_add_i32 s57, s56, 0x2000
	global_load_lds_dwordx4 v[22:23], off
	v_lshl_add_u64 v[22:23], s[0:1], 0, v[132:133]
	s_mov_b32 m0, s57
	s_nop 0
	global_load_lds_dwordx4 v[22:23], off
	v_lshl_add_u64 v[22:23], v[250:251], 0, s[22:23]
	s_mov_b32 m0, s61
	s_nop 0
	global_load_lds_dwordx4 v[22:23], off
	v_lshl_add_u64 v[22:23], v[252:253], 0, s[22:23]
	s_mov_b32 m0, s62
	s_nop 0
	global_load_lds_dwordx4 v[22:23], off
	s_waitcnt vmcnt(8)
	s_waitcnt lgkmcnt(0)
	s_barrier
	s_setprio 1
	v_mfma_f32_16x16x32_bf16 v[22:25], v[6:9], v[34:37], v[156:159]
	v_mfma_f32_16x16x32_bf16 v[66:69], v[18:21], v[46:49], v[22:25]
	v_mfma_f32_16x16x32_bf16 v[22:25], v[30:33], v[34:37], v[160:163]
	v_mfma_f32_16x16x32_bf16 v[62:65], v[208:211], v[46:49], v[22:25]
	v_mfma_f32_16x16x32_bf16 v[22:25], v[6:9], v[152:155], v[164:167]
	v_mfma_f32_16x16x32_bf16 v[42:45], v[18:21], v[228:231], v[22:25]
	v_mfma_f32_16x16x32_bf16 v[22:25], v[30:33], v[152:155], v[168:171]
	v_mfma_f32_16x16x32_bf16 v[38:41], v[208:211], v[228:231], v[22:25]
	v_mfma_f32_16x16x32_bf16 v[22:25], v[6:9], v[232:235], v[172:175]
	v_mfma_f32_16x16x32_bf16 v[2:5], v[6:9], v[240:243], v[2:5]
	v_mfma_f32_16x16x32_bf16 v[26:29], v[18:21], v[236:239], v[22:25]
	v_mfma_f32_16x16x32_bf16 v[22:25], v[30:33], v[232:235], v[176:179]
	v_mfma_f32_16x16x32_bf16 v[6:9], v[18:21], v[244:247], v[2:5]
	v_mfma_f32_16x16x32_bf16 v[2:5], v[30:33], v[240:243], v[10:13]
	v_mfma_f32_16x16x32_bf16 v[22:25], v[208:211], v[236:239], v[22:25]
	v_mfma_f32_16x16x32_bf16 v[2:5], v[208:211], v[244:247], v[2:5]
	s_setprio 0
	s_setprio 1
	v_mfma_f32_16x16x32_bf16 v[10:13], v[212:215], v[34:37], v[14:17]
	v_mfma_f32_16x16x32_bf16 v[78:81], v[216:219], v[46:49], v[10:13]
	v_mfma_f32_16x16x32_bf16 v[10:13], v[220:223], v[34:37], v[180:183]
	v_mfma_f32_16x16x32_bf16 v[58:61], v[224:227], v[46:49], v[10:13]
	v_mfma_f32_16x16x32_bf16 v[10:13], v[212:215], v[152:155], v[184:187]
	v_mfma_f32_16x16x32_bf16 v[46:49], v[216:219], v[228:231], v[10:13]
	v_mfma_f32_16x16x32_bf16 v[10:13], v[220:223], v[152:155], v[188:191]
	v_mfma_f32_16x16x32_bf16 v[34:37], v[224:227], v[228:231], v[10:13]
	v_mfma_f32_16x16x32_bf16 v[10:13], v[212:215], v[232:235], v[192:195]
	v_mfma_f32_16x16x32_bf16 v[30:33], v[216:219], v[236:239], v[10:13]
	v_mfma_f32_16x16x32_bf16 v[10:13], v[220:223], v[232:235], v[196:199]
	v_mfma_f32_16x16x32_bf16 v[18:21], v[224:227], v[236:239], v[10:13]
	v_mfma_f32_16x16x32_bf16 v[10:13], v[212:215], v[240:243], v[200:203]
	v_mfma_f32_16x16x32_bf16 v[14:17], v[216:219], v[244:247], v[10:13]
	v_mfma_f32_16x16x32_bf16 v[10:13], v[220:223], v[240:243], v[204:207]
	v_mfma_f32_16x16x32_bf16 v[10:13], v[224:227], v[244:247], v[10:13]
	s_setprio 0
	s_barrier
	s_add_u32 s0, s54, 0x100180
	s_addc_u32 s1, s55, 0
	s_add_u32 s14, s52, 0x200
	s_addc_u32 s15, s53, 0
	s_mov_b32 s26, 0
.LBB0_1110:
	ds_read_b128 v[152:155], v148
	ds_read_b128 v[156:159], v148 offset:1024
	ds_read_b128 v[160:163], v148 offset:2048
	ds_read_b128 v[164:167], v148 offset:3072
	ds_read_b128 v[168:171], v149
	ds_read_b128 v[172:175], v149 offset:1024
	ds_read_b128 v[176:179], v149 offset:2048
	ds_read_b128 v[180:183], v149 offset:3072
	s_add_u32 s27, s0, 0xfff00080
	s_addc_u32 s52, s1, -1
	s_cmp_eq_u32 s26, 28
	s_cselect_b32 s55, s43, s52
	s_cselect_b32 s54, s42, s27
	s_cselect_b32 s53, s49, s15
	s_cselect_b32 s52, s48, s14
	s_mov_b32 m0, s41
	ds_read_b128 v[184:187], v150
	ds_read_b128 v[188:191], v150 offset:1024
	ds_read_b128 v[192:195], v150 offset:2048
	ds_read_b128 v[196:199], v150 offset:3072
	ds_read_b128 v[200:203], v150 offset:4096
	ds_read_b128 v[204:207], v150 offset:5120
	ds_read_b128 v[208:211], v150 offset:6144
	ds_read_b128 v[212:215], v150 offset:7168
	global_load_lds_dwordx4 v136, s[0:1]
	s_mov_b32 m0, s73
	s_nop 0
	global_load_lds_dwordx4 v138, s[0:1]
	s_waitcnt vmcnt(8)
	s_waitcnt lgkmcnt(0)
	s_barrier
	s_setprio 1
	v_mfma_f32_16x16x32_bf16 v[118:121], v[152:155], v[184:187], v[118:121]
	v_mfma_f32_16x16x32_bf16 v[114:117], v[160:163], v[184:187], v[114:117]
	v_mfma_f32_16x16x32_bf16 v[102:105], v[152:155], v[192:195], v[102:105]
	v_mfma_f32_16x16x32_bf16 v[98:101], v[160:163], v[192:195], v[98:101]
	v_mfma_f32_16x16x32_bf16 v[86:89], v[152:155], v[200:203], v[86:89]
	v_mfma_f32_16x16x32_bf16 v[82:85], v[160:163], v[200:203], v[82:85]
	v_mfma_f32_16x16x32_bf16 v[74:77], v[152:155], v[208:211], v[74:77]
	v_mfma_f32_16x16x32_bf16 v[54:57], v[160:163], v[208:211], v[54:57]
	v_mfma_f32_16x16x32_bf16 v[118:121], v[156:159], v[188:191], v[118:121]
	v_mfma_f32_16x16x32_bf16 v[114:117], v[164:167], v[188:191], v[114:117]
	v_mfma_f32_16x16x32_bf16 v[102:105], v[156:159], v[196:199], v[102:105]
	v_mfma_f32_16x16x32_bf16 v[98:101], v[164:167], v[196:199], v[98:101]
	v_mfma_f32_16x16x32_bf16 v[86:89], v[156:159], v[204:207], v[86:89]
	v_mfma_f32_16x16x32_bf16 v[82:85], v[164:167], v[204:207], v[82:85]
	v_mfma_f32_16x16x32_bf16 v[74:77], v[156:159], v[212:215], v[74:77]
	v_mfma_f32_16x16x32_bf16 v[54:57], v[164:167], v[212:215], v[54:57]
	s_setprio 0
	s_setprio 1
	v_mfma_f32_16x16x32_bf16 v[126:129], v[168:171], v[184:187], v[126:129]
	v_mfma_f32_16x16x32_bf16 v[122:125], v[176:179], v[184:187], v[122:125]
	v_mfma_f32_16x16x32_bf16 v[110:113], v[168:171], v[192:195], v[110:113]
	v_mfma_f32_16x16x32_bf16 v[106:109], v[176:179], v[192:195], v[106:109]
	v_mfma_f32_16x16x32_bf16 v[94:97], v[168:171], v[200:203], v[94:97]
	v_mfma_f32_16x16x32_bf16 v[90:93], v[176:179], v[200:203], v[90:93]
	v_mfma_f32_16x16x32_bf16 v[70:73], v[168:171], v[208:211], v[70:73]
	v_mfma_f32_16x16x32_bf16 v[50:53], v[176:179], v[208:211], v[50:53]
	v_mfma_f32_16x16x32_bf16 v[126:129], v[172:175], v[188:191], v[126:129]
	v_mfma_f32_16x16x32_bf16 v[122:125], v[180:183], v[188:191], v[122:125]
	v_mfma_f32_16x16x32_bf16 v[110:113], v[172:175], v[196:199], v[110:113]
	v_mfma_f32_16x16x32_bf16 v[106:109], v[180:183], v[196:199], v[106:109]
	v_mfma_f32_16x16x32_bf16 v[94:97], v[172:175], v[204:207], v[94:97]
	v_mfma_f32_16x16x32_bf16 v[90:93], v[180:183], v[204:207], v[90:93]
	v_mfma_f32_16x16x32_bf16 v[70:73], v[172:175], v[212:215], v[70:73]
	v_mfma_f32_16x16x32_bf16 v[50:53], v[180:183], v[212:215], v[50:53]
	s_setprio 0
	s_barrier
	s_mov_b32 m0, s74
	s_mov_b64 s[98:99], s[52:53]
	s_add_u32 s78, s52, 0x100000
	ds_read_b128 v[184:187], v150 offset:16384
	ds_read_b128 v[188:191], v150 offset:17408
	ds_read_b128 v[192:195], v150 offset:18432
	ds_read_b128 v[196:199], v150 offset:19456
	ds_read_b128 v[200:203], v150 offset:20480
	ds_read_b128 v[204:207], v150 offset:21504
	ds_read_b128 v[208:211], v150 offset:22528
	ds_read_b128 v[212:215], v150 offset:23552
	global_load_lds_dwordx4 v130, s[52:53]
	s_mov_b32 m0, s75
	s_addc_u32 s79, s53, 0
	global_load_lds_dwordx4 v132, s[52:53]
	s_mov_b32 m0, s76
	s_mov_b64 s[100:101], s[54:55]
	global_load_lds_dwordx4 v130, s[78:79]
	s_mov_b32 m0, s46
	s_nop 0
	global_load_lds_dwordx4 v132, s[78:79]
	s_mov_b32 m0, s33
	s_nop 0
	global_load_lds_dwordx4 v130, s[54:55]
	s_mov_b32 m0, s51
	s_nop 0
	global_load_lds_dwordx4 v132, s[54:55]
	s_waitcnt vmcnt(8)
	s_waitcnt lgkmcnt(0)
	s_barrier
	s_setprio 1
	v_mfma_f32_16x16x32_bf16 v[66:69], v[152:155], v[184:187], v[66:69]
	v_mfma_f32_16x16x32_bf16 v[62:65], v[160:163], v[184:187], v[62:65]
	v_mfma_f32_16x16x32_bf16 v[42:45], v[152:155], v[192:195], v[42:45]
	v_mfma_f32_16x16x32_bf16 v[38:41], v[160:163], v[192:195], v[38:41]
	v_mfma_f32_16x16x32_bf16 v[26:29], v[152:155], v[200:203], v[26:29]
	v_mfma_f32_16x16x32_bf16 v[22:25], v[160:163], v[200:203], v[22:25]
	v_mfma_f32_16x16x32_bf16 v[6:9], v[152:155], v[208:211], v[6:9]
	v_mfma_f32_16x16x32_bf16 v[2:5], v[160:163], v[208:211], v[2:5]
	v_mfma_f32_16x16x32_bf16 v[66:69], v[156:159], v[188:191], v[66:69]
	v_mfma_f32_16x16x32_bf16 v[62:65], v[164:167], v[188:191], v[62:65]
	v_mfma_f32_16x16x32_bf16 v[42:45], v[156:159], v[196:199], v[42:45]
	v_mfma_f32_16x16x32_bf16 v[38:41], v[164:167], v[196:199], v[38:41]
	v_mfma_f32_16x16x32_bf16 v[26:29], v[156:159], v[204:207], v[26:29]
	v_mfma_f32_16x16x32_bf16 v[22:25], v[164:167], v[204:207], v[22:25]
	v_mfma_f32_16x16x32_bf16 v[6:9], v[156:159], v[212:215], v[6:9]
	v_mfma_f32_16x16x32_bf16 v[2:5], v[164:167], v[212:215], v[2:5]
	s_setprio 0
	s_setprio 1
	v_mfma_f32_16x16x32_bf16 v[78:81], v[168:171], v[184:187], v[78:81]
	v_mfma_f32_16x16x32_bf16 v[58:61], v[176:179], v[184:187], v[58:61]
	v_mfma_f32_16x16x32_bf16 v[46:49], v[168:171], v[192:195], v[46:49]
	v_mfma_f32_16x16x32_bf16 v[34:37], v[176:179], v[192:195], v[34:37]
	v_mfma_f32_16x16x32_bf16 v[30:33], v[168:171], v[200:203], v[30:33]
	v_mfma_f32_16x16x32_bf16 v[18:21], v[176:179], v[200:203], v[18:21]
	v_mfma_f32_16x16x32_bf16 v[14:17], v[168:171], v[208:211], v[14:17]
	v_mfma_f32_16x16x32_bf16 v[10:13], v[176:179], v[208:211], v[10:13]
	v_mfma_f32_16x16x32_bf16 v[78:81], v[172:175], v[188:191], v[78:81]
	v_mfma_f32_16x16x32_bf16 v[58:61], v[180:183], v[188:191], v[58:61]
	v_mfma_f32_16x16x32_bf16 v[46:49], v[172:175], v[196:199], v[46:49]
	v_mfma_f32_16x16x32_bf16 v[34:37], v[180:183], v[196:199], v[34:37]
	v_mfma_f32_16x16x32_bf16 v[30:33], v[172:175], v[204:207], v[30:33]
	v_mfma_f32_16x16x32_bf16 v[18:21], v[180:183], v[204:207], v[18:21]
	v_mfma_f32_16x16x32_bf16 v[14:17], v[172:175], v[212:215], v[14:17]
	v_mfma_f32_16x16x32_bf16 v[10:13], v[180:183], v[212:215], v[10:13]
	s_setprio 0
	s_barrier
; #define PG8_BAR __builtin_amdgcn_s_barrier()
;     ...
;         for (int t = 2; t < nt; t += 2) PG8_KITER(t);
;         if constexpr (ALIGN_EPI) { if (wr == 0) PG8_BAR; }
	ds_read_b128 v[152:155], v134
	ds_read_b128 v[156:159], v134 offset:1024
	ds_read_b128 v[160:163], v134 offset:2048
	ds_read_b128 v[164:167], v134 offset:3072
	ds_read_b128 v[168:171], v144
	ds_read_b128 v[172:175], v144 offset:1024
	ds_read_b128 v[176:179], v144 offset:2048
	ds_read_b128 v[180:183], v144 offset:3072
	s_add_u32 s54, s54, 0x100000
	s_addc_u32 s55, s55, 0
	s_mov_b32 m0, s58
	ds_read_b128 v[184:187], v150 offset:32768
	ds_read_b128 v[188:191], v150 offset:33792
	ds_read_b128 v[192:195], v150 offset:34816
	ds_read_b128 v[196:199], v150 offset:35840
	ds_read_b128 v[200:203], v150 offset:36864
	ds_read_b128 v[204:207], v150 offset:37888
	ds_read_b128 v[208:211], v150 offset:38912
	ds_read_b128 v[212:215], v150 offset:39936
	global_load_lds_dwordx4 v130, s[54:55]
	s_mov_b32 m0, s59
	s_nop 0
	global_load_lds_dwordx4 v132, s[54:55]
	s_waitcnt vmcnt(8)
	s_waitcnt lgkmcnt(0)
	s_barrier
	s_setprio 1
	v_mfma_f32_16x16x32_bf16 v[118:121], v[152:155], v[184:187], v[118:121]
	v_mfma_f32_16x16x32_bf16 v[114:117], v[160:163], v[184:187], v[114:117]
	v_mfma_f32_16x16x32_bf16 v[102:105], v[152:155], v[192:195], v[102:105]
	v_mfma_f32_16x16x32_bf16 v[98:101], v[160:163], v[192:195], v[98:101]
	v_mfma_f32_16x16x32_bf16 v[86:89], v[152:155], v[200:203], v[86:89]
	v_mfma_f32_16x16x32_bf16 v[82:85], v[160:163], v[200:203], v[82:85]
	v_mfma_f32_16x16x32_bf16 v[74:77], v[152:155], v[208:211], v[74:77]
	v_mfma_f32_16x16x32_bf16 v[54:57], v[160:163], v[208:211], v[54:57]
	v_mfma_f32_16x16x32_bf16 v[118:121], v[156:159], v[188:191], v[118:121]
	v_mfma_f32_16x16x32_bf16 v[114:117], v[164:167], v[188:191], v[114:117]
	v_mfma_f32_16x16x32_bf16 v[102:105], v[156:159], v[196:199], v[102:105]
	v_mfma_f32_16x16x32_bf16 v[98:101], v[164:167], v[196:199], v[98:101]
	v_mfma_f32_16x16x32_bf16 v[86:89], v[156:159], v[204:207], v[86:89]
	v_mfma_f32_16x16x32_bf16 v[82:85], v[164:167], v[204:207], v[82:85]
	v_mfma_f32_16x16x32_bf16 v[74:77], v[156:159], v[212:215], v[74:77]
	v_mfma_f32_16x16x32_bf16 v[54:57], v[164:167], v[212:215], v[54:57]
	s_setprio 0
	s_setprio 1
	v_mfma_f32_16x16x32_bf16 v[126:129], v[168:171], v[184:187], v[126:129]
	v_mfma_f32_16x16x32_bf16 v[122:125], v[176:179], v[184:187], v[122:125]
	v_mfma_f32_16x16x32_bf16 v[110:113], v[168:171], v[192:195], v[110:113]
	v_mfma_f32_16x16x32_bf16 v[106:109], v[176:179], v[192:195], v[106:109]
	v_mfma_f32_16x16x32_bf16 v[94:97], v[168:171], v[200:203], v[94:97]
	v_mfma_f32_16x16x32_bf16 v[90:93], v[176:179], v[200:203], v[90:93]
	v_mfma_f32_16x16x32_bf16 v[70:73], v[168:171], v[208:211], v[70:73]
	v_mfma_f32_16x16x32_bf16 v[50:53], v[176:179], v[208:211], v[50:53]
	v_mfma_f32_16x16x32_bf16 v[126:129], v[172:175], v[188:191], v[126:129]
	v_mfma_f32_16x16x32_bf16 v[122:125], v[180:183], v[188:191], v[122:125]
	v_mfma_f32_16x16x32_bf16 v[110:113], v[172:175], v[196:199], v[110:113]
	v_mfma_f32_16x16x32_bf16 v[106:109], v[180:183], v[196:199], v[106:109]
	v_mfma_f32_16x16x32_bf16 v[94:97], v[172:175], v[204:207], v[94:97]
	v_mfma_f32_16x16x32_bf16 v[90:93], v[180:183], v[204:207], v[90:93]
	v_mfma_f32_16x16x32_bf16 v[70:73], v[172:175], v[212:215], v[70:73]
	v_mfma_f32_16x16x32_bf16 v[50:53], v[180:183], v[212:215], v[50:53]
	s_setprio 0
	s_barrier
	s_mov_b32 m0, s47
	s_add_u32 s98, s98, 0x80
	s_addc_u32 s99, s99, 0
	s_add_u32 s100, s100, 0x80
	s_addc_u32 s101, s101, 0
	s_add_u32 s52, s52, 0x100080
	ds_read_b128 v[184:187], v150 offset:49152
	ds_read_b128 v[188:191], v150 offset:50176
	ds_read_b128 v[192:195], v150 offset:51200
	ds_read_b128 v[196:199], v150 offset:52224
	ds_read_b128 v[200:203], v150 offset:53248
	ds_read_b128 v[204:207], v150 offset:54272
	ds_read_b128 v[208:211], v150 offset:55296
	ds_read_b128 v[212:215], v150 offset:56320
	global_load_lds_dwordx4 v130, s[98:99]
	s_mov_b32 m0, s77
	s_addc_u32 s53, s53, 0
	global_load_lds_dwordx4 v132, s[98:99]
	s_mov_b32 m0, s56
	s_nop 0
	global_load_lds_dwordx4 v130, s[52:53]
	s_mov_b32 m0, s57
	s_nop 0
	global_load_lds_dwordx4 v132, s[52:53]
	s_mov_b32 m0, s61
	s_nop 0
	global_load_lds_dwordx4 v130, s[100:101]
	s_mov_b32 m0, s62
	s_nop 0
	global_load_lds_dwordx4 v132, s[100:101]
	s_waitcnt vmcnt(8)
	s_waitcnt lgkmcnt(0)
	s_barrier
	s_setprio 1
	v_mfma_f32_16x16x32_bf16 v[66:69], v[152:155], v[184:187], v[66:69]
	v_mfma_f32_16x16x32_bf16 v[62:65], v[160:163], v[184:187], v[62:65]
	v_mfma_f32_16x16x32_bf16 v[42:45], v[152:155], v[192:195], v[42:45]
	v_mfma_f32_16x16x32_bf16 v[38:41], v[160:163], v[192:195], v[38:41]
	v_mfma_f32_16x16x32_bf16 v[26:29], v[152:155], v[200:203], v[26:29]
	v_mfma_f32_16x16x32_bf16 v[22:25], v[160:163], v[200:203], v[22:25]
	v_mfma_f32_16x16x32_bf16 v[6:9], v[152:155], v[208:211], v[6:9]
	v_mfma_f32_16x16x32_bf16 v[2:5], v[160:163], v[208:211], v[2:5]
	v_mfma_f32_16x16x32_bf16 v[66:69], v[156:159], v[188:191], v[66:69]
	v_mfma_f32_16x16x32_bf16 v[62:65], v[164:167], v[188:191], v[62:65]
	v_mfma_f32_16x16x32_bf16 v[42:45], v[156:159], v[196:199], v[42:45]
	v_mfma_f32_16x16x32_bf16 v[38:41], v[164:167], v[196:199], v[38:41]
	v_mfma_f32_16x16x32_bf16 v[26:29], v[156:159], v[204:207], v[26:29]
	v_mfma_f32_16x16x32_bf16 v[22:25], v[164:167], v[204:207], v[22:25]
	v_mfma_f32_16x16x32_bf16 v[6:9], v[156:159], v[212:215], v[6:9]
	v_mfma_f32_16x16x32_bf16 v[2:5], v[164:167], v[212:215], v[2:5]
	s_setprio 0
	s_setprio 1
	v_mfma_f32_16x16x32_bf16 v[78:81], v[168:171], v[184:187], v[78:81]
	v_mfma_f32_16x16x32_bf16 v[58:61], v[176:179], v[184:187], v[58:61]
	v_mfma_f32_16x16x32_bf16 v[46:49], v[168:171], v[192:195], v[46:49]
	v_mfma_f32_16x16x32_bf16 v[34:37], v[176:179], v[192:195], v[34:37]
	v_mfma_f32_16x16x32_bf16 v[30:33], v[168:171], v[200:203], v[30:33]
	v_mfma_f32_16x16x32_bf16 v[18:21], v[176:179], v[200:203], v[18:21]
	v_mfma_f32_16x16x32_bf16 v[14:17], v[168:171], v[208:211], v[14:17]
	v_mfma_f32_16x16x32_bf16 v[10:13], v[176:179], v[208:211], v[10:13]
	v_mfma_f32_16x16x32_bf16 v[78:81], v[172:175], v[188:191], v[78:81]
	v_mfma_f32_16x16x32_bf16 v[58:61], v[180:183], v[188:191], v[58:61]
	v_mfma_f32_16x16x32_bf16 v[46:49], v[172:175], v[196:199], v[46:49]
	v_mfma_f32_16x16x32_bf16 v[34:37], v[180:183], v[196:199], v[34:37]
	v_mfma_f32_16x16x32_bf16 v[30:33], v[172:175], v[204:207], v[30:33]
	v_mfma_f32_16x16x32_bf16 v[18:21], v[180:183], v[204:207], v[18:21]
	v_mfma_f32_16x16x32_bf16 v[14:17], v[172:175], v[212:215], v[14:17]
	v_mfma_f32_16x16x32_bf16 v[10:13], v[180:183], v[212:215], v[10:13]
	s_setprio 0
	s_barrier
	s_add_i32 s26, s26, 2
	s_add_u32 s0, s0, 0x100
	s_addc_u32 s1, s1, 0
	s_add_u32 s14, s14, 0x100
	s_addc_u32 s15, s15, 0
	s_cmp_gt_u32 s26, 29
	s_cbranch_scc0 .LBB0_1110
	s_and_b64 vcc, exec, s[18:19]
	s_cbranch_vccz .LBB0_1113
	s_barrier

;     __host__ __device__ bool next(int i, Unit& u) const { if (!StaticOrder::next(i >> 1, u)) return false; u.seg = i & 1; return true; }
;     ...
;         const bool has_next = S.next(ui + 1, nxt);
;         const char* nA = has_next ? PG8_APTR(nxt) : cA; const char* nB = has_next ? PG8_BPTR(nxt) : cB;
.LBB0_1260:
	s_ashr_i32 s23, s22, 31
	ds_read_b128 v[2:5], v182
	ds_read_b128 v[6:9], v182 offset:1024
	ds_read_b128 v[10:13], v182 offset:2048
	ds_read_b128 v[14:17], v182 offset:3072
	ds_read_b128 v[18:21], v183
	ds_read_b128 v[22:25], v183 offset:1024
	ds_read_b128 v[26:29], v183 offset:2048
	ds_read_b128 v[30:33], v183 offset:3072
	s_lshl_b64 s[24:25], s[22:23], 18
	s_add_u32 s24, s10, s24
	s_addc_u32 s25, s11, s25
	s_and_b64 s[26:27], s[4:5], exec
	s_cselect_b32 s23, s25, s41
	s_cselect_b32 s31, s24, s40
	s_and_b32 s0, s64, 0x7fffffff
	s_lshl_b64 s[26:27], s[0:1], 18
	s_add_u32 s28, s12, s26
	s_addc_u32 s29, s13, s27
	s_and_b64 s[26:27], s[4:5], exec
	s_cselect_b32 s0, s29, s39
	s_cselect_b32 s66, s28, s38
	s_add_u32 s26, s40, 0x20080
	s_addc_u32 s27, s41, 0
	s_mov_b32 m0, s59
	v_lshl_add_u64 v[66:67], s[26:27], 0, v[154:155]
	ds_read_b128 v[34:37], v184
	ds_read_b128 v[38:41], v184 offset:1024
	ds_read_b128 v[42:45], v184 offset:2048
	ds_read_b128 v[46:49], v184 offset:3072
	ds_read_b128 v[50:53], v184 offset:4096
	ds_read_b128 v[54:57], v184 offset:5120
	ds_read_b128 v[58:61], v184 offset:6144
	ds_read_b128 v[62:65], v184 offset:7168
	global_load_lds_dwordx4 v[66:67], off
	v_lshl_add_u64 v[66:67], s[26:27], 0, v[158:159]
	s_mov_b32 m0, s60
	s_nop 0
	global_load_lds_dwordx4 v[66:67], off
	s_waitcnt vmcnt(8)
	s_waitcnt lgkmcnt(0)
	s_barrier
	s_setprio 1
	v_mfma_f32_16x16x32_bf16 v[90:93], v[2:5], v[58:61], 0
	v_mfma_f32_16x16x32_bf16 v[66:69], v[2:5], v[34:37], 0
	v_mfma_f32_16x16x32_bf16 v[70:73], v[10:13], v[34:37], 0
	v_mfma_f32_16x16x32_bf16 v[74:77], v[2:5], v[42:45], 0
	v_mfma_f32_16x16x32_bf16 v[78:81], v[10:13], v[42:45], 0
	v_mfma_f32_16x16x32_bf16 v[82:85], v[2:5], v[50:53], 0
	v_mfma_f32_16x16x32_bf16 v[86:89], v[10:13], v[50:53], 0
	v_mfma_f32_16x16x32_bf16 v[98:101], v[6:9], v[62:65], v[90:93]
	v_mfma_f32_16x16x32_bf16 v[90:93], v[10:13], v[58:61], 0
	v_mfma_f32_16x16x32_bf16 v[66:69], v[6:9], v[38:41], v[66:69]
	v_mfma_f32_16x16x32_bf16 v[70:73], v[14:17], v[38:41], v[70:73]
	v_mfma_f32_16x16x32_bf16 v[74:77], v[6:9], v[46:49], v[74:77]
	v_mfma_f32_16x16x32_bf16 v[78:81], v[14:17], v[46:49], v[78:81]
	v_mfma_f32_16x16x32_bf16 v[82:85], v[6:9], v[54:57], v[82:85]
	v_mfma_f32_16x16x32_bf16 v[86:89], v[14:17], v[54:57], v[86:89]
	v_mfma_f32_16x16x32_bf16 v[102:105], v[14:17], v[62:65], v[90:93]
	s_setprio 0
	s_setprio 1
	v_mfma_f32_16x16x32_bf16 v[90:93], v[18:21], v[34:37], 0
	v_mfma_f32_16x16x32_bf16 v[34:37], v[26:29], v[34:37], 0
	v_mfma_f32_16x16x32_bf16 v[114:117], v[22:25], v[38:41], v[90:93]
	v_mfma_f32_16x16x32_bf16 v[34:37], v[30:33], v[38:41], v[34:37]
	v_mfma_f32_16x16x32_bf16 v[38:41], v[18:21], v[42:45], 0
	v_mfma_f32_16x16x32_bf16 v[42:45], v[26:29], v[42:45], 0
	v_mfma_f32_16x16x32_bf16 v[38:41], v[22:25], v[46:49], v[38:41]
	v_mfma_f32_16x16x32_bf16 v[42:45], v[30:33], v[46:49], v[42:45]
	v_mfma_f32_16x16x32_bf16 v[46:49], v[18:21], v[50:53], 0
	v_mfma_f32_16x16x32_bf16 v[50:53], v[26:29], v[50:53], 0
	v_mfma_f32_16x16x32_bf16 v[46:49], v[22:25], v[54:57], v[46:49]
	v_mfma_f32_16x16x32_bf16 v[50:53], v[30:33], v[54:57], v[50:53]
	v_mfma_f32_16x16x32_bf16 v[54:57], v[18:21], v[58:61], 0
	v_mfma_f32_16x16x32_bf16 v[58:61], v[26:29], v[58:61], 0
	v_mfma_f32_16x16x32_bf16 v[54:57], v[22:25], v[62:65], v[54:57]
	v_mfma_f32_16x16x32_bf16 v[58:61], v[30:33], v[62:65], v[58:61]
	s_setprio 0
	s_barrier
	v_lshl_add_u64 v[152:153], s[38:39], 0, v[156:157]
	s_mov_b32 m0, s61
	v_lshl_add_u64 v[130:131], v[152:153], 0, s[18:19]
	v_lshl_add_u64 v[250:251], s[38:39], 0, v[160:161]
	s_add_u32 s26, s38, 0x20100
	ds_read_b128 v[62:65], v184 offset:16384
	ds_read_b128 v[90:93], v184 offset:17408
	ds_read_b128 v[94:97], v184 offset:18432
	ds_read_b128 v[106:109], v184 offset:19456
	ds_read_b128 v[110:113], v184 offset:20480
	ds_read_b128 v[118:121], v184 offset:21504
	ds_read_b128 v[122:125], v184 offset:22528
	ds_read_b128 v[126:129], v184 offset:23552
	global_load_lds_dwordx4 v[130:131], off
	v_lshl_add_u64 v[130:131], v[250:251], 0, s[18:19]
	s_mov_b32 m0, s62
	s_addc_u32 s27, s39, 0
	s_add_i32 s67, s58, s33
	global_load_lds_dwordx4 v[130:131], off
	v_lshl_add_u64 v[130:131], s[26:27], 0, v[156:157]
	s_mov_b32 m0, s67
	s_add_i32 s46, s67, 0x2000
	global_load_lds_dwordx4 v[130:131], off
	v_lshl_add_u64 v[130:131], s[26:27], 0, v[160:161]
	s_mov_b32 m0, s46
	v_lshl_add_u64 v[252:253], s[40:41], 0, v[154:155]
	global_load_lds_dwordx4 v[130:131], off
	v_lshl_add_u64 v[130:131], v[252:253], 0, s[18:19]
	s_mov_b32 m0, s48
	v_lshl_add_u64 v[166:167], s[40:41], 0, v[158:159]
	global_load_lds_dwordx4 v[130:131], off
	v_lshl_add_u64 v[130:131], v[166:167], 0, s[18:19]
	s_mov_b32 m0, s49
	s_nop 0
	global_load_lds_dwordx4 v[130:131], off
	s_waitcnt vmcnt(8)
	s_waitcnt lgkmcnt(0)
	s_barrier
	s_setprio 1
	v_mfma_f32_16x16x32_bf16 v[130:133], v[2:5], v[62:65], 0
	v_mfma_f32_16x16x32_bf16 v[140:143], v[2:5], v[94:97], 0
	v_mfma_f32_16x16x32_bf16 v[148:151], v[2:5], v[110:113], 0
	v_mfma_f32_16x16x32_bf16 v[2:5], v[2:5], v[122:125], 0
	v_mfma_f32_16x16x32_bf16 v[132:135], v[6:9], v[90:93], v[130:133]
	v_mfma_f32_16x16x32_bf16 v[140:143], v[6:9], v[106:109], v[140:143]
	v_mfma_f32_16x16x32_bf16 v[148:151], v[6:9], v[118:121], v[148:151]
	v_mfma_f32_16x16x32_bf16 v[2:5], v[6:9], v[126:129], v[2:5]
	v_mfma_f32_16x16x32_bf16 v[6:9], v[10:13], v[122:125], 0
	v_mfma_f32_16x16x32_bf16 v[136:139], v[10:13], v[62:65], 0
	v_mfma_f32_16x16x32_bf16 v[144:147], v[10:13], v[94:97], 0
	v_mfma_f32_16x16x32_bf16 v[170:173], v[10:13], v[110:113], 0
	v_mfma_f32_16x16x32_bf16 v[6:9], v[14:17], v[126:129], v[6:9]
	v_mfma_f32_16x16x32_bf16 v[136:139], v[14:17], v[90:93], v[136:139]
	v_mfma_f32_16x16x32_bf16 v[144:147], v[14:17], v[106:109], v[144:147]
	v_mfma_f32_16x16x32_bf16 v[170:173], v[14:17], v[118:121], v[170:173]
	s_setprio 0
	s_setprio 1
	v_mfma_f32_16x16x32_bf16 v[10:13], v[18:21], v[62:65], 0
	v_mfma_f32_16x16x32_bf16 v[174:177], v[22:25], v[90:93], v[10:13]
	v_mfma_f32_16x16x32_bf16 v[10:13], v[26:29], v[62:65], 0
	v_mfma_f32_16x16x32_bf16 v[178:181], v[30:33], v[90:93], v[10:13]
	v_mfma_f32_16x16x32_bf16 v[10:13], v[18:21], v[94:97], 0
	v_mfma_f32_16x16x32_bf16 v[186:189], v[22:25], v[106:109], v[10:13]
	v_mfma_f32_16x16x32_bf16 v[10:13], v[26:29], v[94:97], 0
	v_mfma_f32_16x16x32_bf16 v[190:193], v[30:33], v[106:109], v[10:13]
	v_mfma_f32_16x16x32_bf16 v[10:13], v[18:21], v[110:113], 0
	v_mfma_f32_16x16x32_bf16 v[194:197], v[22:25], v[118:121], v[10:13]
	v_mfma_f32_16x16x32_bf16 v[10:13], v[26:29], v[110:113], 0
	v_mfma_f32_16x16x32_bf16 v[198:201], v[30:33], v[118:121], v[10:13]
	v_mfma_f32_16x16x32_bf16 v[10:13], v[18:21], v[122:125], 0
	v_mfma_f32_16x16x32_bf16 v[202:205], v[22:25], v[126:129], v[10:13]
	v_mfma_f32_16x16x32_bf16 v[10:13], v[26:29], v[122:125], 0
	v_mfma_f32_16x16x32_bf16 v[206:209], v[30:33], v[126:129], v[10:13]
	s_setprio 0
	s_barrier
	s_add_i32 s47, 0, 0x18000
	s_add_i32 s56, 0, 0x1c000
	v_add_u32_e32 v130, s47, v1
	v_add_u32_e32 v131, s56, v1
	s_nop 0
	ds_read_b128 v[10:13], v130
	ds_read_b128 v[14:17], v130 offset:1024
	ds_read_b128 v[18:21], v130 offset:2048
	ds_read_b128 v[22:25], v130 offset:3072
	ds_read_b128 v[210:213], v131
	ds_read_b128 v[214:217], v131 offset:1024
	ds_read_b128 v[218:221], v131 offset:2048
	ds_read_b128 v[222:225], v131 offset:3072
	s_add_u32 s26, s40, 0x20100
	s_addc_u32 s27, s41, 0
	s_mov_b32 m0, s50
	v_lshl_add_u64 v[90:91], s[26:27], 0, v[154:155]
	ds_read_b128 v[26:29], v184 offset:32768
	ds_read_b128 v[30:33], v184 offset:33792
	ds_read_b128 v[62:65], v184 offset:34816
	ds_read_b128 v[226:229], v184 offset:35840
	ds_read_b128 v[230:233], v184 offset:36864
	ds_read_b128 v[234:237], v184 offset:37888
	ds_read_b128 v[238:241], v184 offset:38912
	ds_read_b128 v[242:245], v184 offset:39936
	global_load_lds_dwordx4 v[90:91], off
	v_lshl_add_u64 v[90:91], s[26:27], 0, v[158:159]
	s_mov_b32 m0, s51
	s_nop 0
	global_load_lds_dwordx4 v[90:91], off
	s_waitcnt vmcnt(8)
	s_waitcnt lgkmcnt(0)
	s_barrier
	s_setprio 1
	v_mfma_f32_16x16x32_bf16 v[66:69], v[10:13], v[26:29], v[66:69]
	v_mfma_f32_16x16x32_bf16 v[122:125], v[14:17], v[30:33], v[66:69]
	v_mfma_f32_16x16x32_bf16 v[66:69], v[18:21], v[26:29], v[70:73]
	v_mfma_f32_16x16x32_bf16 v[118:121], v[22:25], v[30:33], v[66:69]
	v_mfma_f32_16x16x32_bf16 v[66:69], v[10:13], v[62:65], v[74:77]
	v_mfma_f32_16x16x32_bf16 v[110:113], v[14:17], v[226:229], v[66:69]
	v_mfma_f32_16x16x32_bf16 v[66:69], v[18:21], v[62:65], v[78:81]
	v_mfma_f32_16x16x32_bf16 v[106:109], v[22:25], v[226:229], v[66:69]
	v_mfma_f32_16x16x32_bf16 v[66:69], v[10:13], v[230:233], v[82:85]
	v_mfma_f32_16x16x32_bf16 v[94:97], v[14:17], v[234:237], v[66:69]
	v_mfma_f32_16x16x32_bf16 v[66:69], v[18:21], v[230:233], v[86:89]
	v_mfma_f32_16x16x32_bf16 v[90:93], v[22:25], v[234:237], v[66:69]
	v_mfma_f32_16x16x32_bf16 v[66:69], v[10:13], v[238:241], v[98:101]
	v_mfma_f32_16x16x32_bf16 v[78:81], v[14:17], v[242:245], v[66:69]
	v_mfma_f32_16x16x32_bf16 v[66:69], v[18:21], v[238:241], v[102:105]
	v_mfma_f32_16x16x32_bf16 v[74:77], v[22:25], v[242:245], v[66:69]
	s_setprio 0
	s_setprio 1
	v_mfma_f32_16x16x32_bf16 v[66:69], v[210:213], v[26:29], v[114:117]
	v_mfma_f32_16x16x32_bf16 v[26:29], v[218:221], v[26:29], v[34:37]
	v_mfma_f32_16x16x32_bf16 v[114:117], v[222:225], v[30:33], v[26:29]
	v_mfma_f32_16x16x32_bf16 v[26:29], v[210:213], v[62:65], v[38:41]
	v_mfma_f32_16x16x32_bf16 v[102:105], v[214:217], v[226:229], v[26:29]
	v_mfma_f32_16x16x32_bf16 v[26:29], v[218:221], v[62:65], v[42:45]
	v_mfma_f32_16x16x32_bf16 v[98:101], v[222:225], v[226:229], v[26:29]
	v_mfma_f32_16x16x32_bf16 v[26:29], v[210:213], v[230:233], v[46:49]
	v_mfma_f32_16x16x32_bf16 v[86:89], v[214:217], v[234:237], v[26:29]
	v_mfma_f32_16x16x32_bf16 v[26:29], v[218:221], v[230:233], v[50:53]
	v_mfma_f32_16x16x32_bf16 v[82:85], v[222:225], v[234:237], v[26:29]
	v_mfma_f32_16x16x32_bf16 v[26:29], v[210:213], v[238:241], v[54:57]
	v_mfma_f32_16x16x32_bf16 v[70:73], v[214:217], v[242:245], v[26:29]
	v_mfma_f32_16x16x32_bf16 v[26:29], v[218:221], v[238:241], v[58:61]
	v_mfma_f32_16x16x32_bf16 v[126:129], v[214:217], v[30:33], v[66:69]
	v_mfma_f32_16x16x32_bf16 v[66:69], v[222:225], v[242:245], v[26:29]
	s_setprio 0
	s_barrier
	s_add_i32 s47, s47, s33
	s_add_i32 s68, s47, 0x2000
	s_nop 1
	v_lshl_add_u64 v[26:27], v[152:153], 0, s[20:21]
	s_mov_b32 m0, s47
	s_add_u32 s26, s38, 0x20180
	ds_read_b128 v[34:37], v184 offset:49152
	ds_read_b128 v[38:41], v184 offset:50176
	ds_read_b128 v[226:229], v184 offset:51200
	ds_read_b128 v[230:233], v184 offset:52224
	ds_read_b128 v[234:237], v184 offset:53248
	ds_read_b128 v[238:241], v184 offset:54272
	ds_read_b128 v[242:245], v184 offset:55296
	ds_read_b128 v[246:249], v184 offset:56320
	global_load_lds_dwordx4 v[26:27], off
	v_lshl_add_u64 v[26:27], v[250:251], 0, s[20:21]
	s_mov_b32 m0, s68
	s_addc_u32 s27, s39, 0
	s_add_i32 s56, s56, s33
	global_load_lds_dwordx4 v[26:27], off
	v_lshl_add_u64 v[26:27], s[26:27], 0, v[156:157]
	s_mov_b32 m0, s56
	s_add_i32 s57, s56, 0x2000
	global_load_lds_dwordx4 v[26:27], off
	v_lshl_add_u64 v[26:27], s[26:27], 0, v[160:161]
	s_mov_b32 m0, s57
	s_nop 0
	global_load_lds_dwordx4 v[26:27], off
	v_lshl_add_u64 v[26:27], v[252:253], 0, s[20:21]
	s_mov_b32 m0, s52
	s_nop 0
	global_load_lds_dwordx4 v[26:27], off
	v_lshl_add_u64 v[26:27], v[166:167], 0, s[20:21]
	s_mov_b32 m0, s53
	s_nop 0
	global_load_lds_dwordx4 v[26:27], off
	s_waitcnt vmcnt(8)
	s_waitcnt lgkmcnt(0)
	s_barrier
	s_setprio 1
	v_mfma_f32_16x16x32_bf16 v[26:29], v[10:13], v[34:37], v[132:135]
	v_mfma_f32_16x16x32_bf16 v[58:61], v[14:17], v[38:41], v[26:29]
	v_mfma_f32_16x16x32_bf16 v[26:29], v[18:21], v[34:37], v[136:139]
	v_mfma_f32_16x16x32_bf16 v[54:57], v[22:25], v[38:41], v[26:29]
	v_mfma_f32_16x16x32_bf16 v[26:29], v[10:13], v[226:229], v[140:143]
	v_mfma_f32_16x16x32_bf16 v[46:49], v[14:17], v[230:233], v[26:29]
	v_mfma_f32_16x16x32_bf16 v[26:29], v[18:21], v[226:229], v[144:147]
	v_mfma_f32_16x16x32_bf16 v[42:45], v[22:25], v[230:233], v[26:29]
	v_mfma_f32_16x16x32_bf16 v[26:29], v[10:13], v[234:237], v[148:151]
	v_mfma_f32_16x16x32_bf16 v[2:5], v[10:13], v[242:245], v[2:5]
	v_mfma_f32_16x16x32_bf16 v[30:33], v[14:17], v[238:241], v[26:29]
	v_mfma_f32_16x16x32_bf16 v[26:29], v[18:21], v[234:237], v[170:173]
	v_mfma_f32_16x16x32_bf16 v[14:17], v[14:17], v[246:249], v[2:5]
	v_mfma_f32_16x16x32_bf16 v[2:5], v[18:21], v[242:245], v[6:9]
	v_mfma_f32_16x16x32_bf16 v[26:29], v[22:25], v[238:241], v[26:29]
	v_mfma_f32_16x16x32_bf16 v[10:13], v[22:25], v[246:249], v[2:5]
	s_setprio 0
	s_setprio 1
	v_mfma_f32_16x16x32_bf16 v[2:5], v[210:213], v[34:37], v[174:177]
	v_mfma_f32_16x16x32_bf16 v[62:65], v[214:217], v[38:41], v[2:5]
	v_mfma_f32_16x16x32_bf16 v[2:5], v[218:221], v[34:37], v[178:181]
	v_mfma_f32_16x16x32_bf16 v[50:53], v[222:225], v[38:41], v[2:5]
	v_mfma_f32_16x16x32_bf16 v[2:5], v[210:213], v[226:229], v[186:189]
	v_mfma_f32_16x16x32_bf16 v[38:41], v[214:217], v[230:233], v[2:5]
	v_mfma_f32_16x16x32_bf16 v[2:5], v[218:221], v[226:229], v[190:193]
	v_mfma_f32_16x16x32_bf16 v[34:37], v[222:225], v[230:233], v[2:5]
	v_mfma_f32_16x16x32_bf16 v[2:5], v[210:213], v[234:237], v[194:197]
	v_mfma_f32_16x16x32_bf16 v[22:25], v[214:217], v[238:241], v[2:5]
	v_mfma_f32_16x16x32_bf16 v[2:5], v[218:221], v[234:237], v[198:201]
	v_mfma_f32_16x16x32_bf16 v[18:21], v[222:225], v[238:241], v[2:5]
	v_mfma_f32_16x16x32_bf16 v[2:5], v[210:213], v[242:245], v[202:205]
	v_mfma_f32_16x16x32_bf16 v[6:9], v[214:217], v[246:249], v[2:5]
	v_mfma_f32_16x16x32_bf16 v[2:5], v[218:221], v[242:245], v[206:209]
	v_mfma_f32_16x16x32_bf16 v[2:5], v[222:225], v[246:249], v[2:5]
	s_setprio 0
	s_barrier
	s_add_u32 s40, s40, 0x20180
	s_addc_u32 s41, s41, 0
	s_add_u32 s26, s38, 0x200
	s_addc_u32 s27, s39, 0
	s_mov_b32 s69, 0
.LBB0_1261:
	ds_read_b128 v[132:135], v182
	ds_read_b128 v[136:139], v182 offset:1024
	ds_read_b128 v[140:143], v182 offset:2048
	ds_read_b128 v[144:147], v182 offset:3072
	ds_read_b128 v[148:151], v183
	ds_read_b128 v[170:173], v183 offset:1024
	ds_read_b128 v[174:177], v183 offset:2048
	ds_read_b128 v[178:181], v183 offset:3072
	s_add_u32 s38, s40, 0xfffe0080
	s_addc_u32 s39, s41, -1
	s_cmp_eq_u32 s69, 4
	s_cselect_b32 s43, s23, s39
	s_cselect_b32 s42, s31, s38
	s_cselect_b32 s39, s0, s27
	s_cselect_b32 s38, s66, s26
	s_mov_b32 m0, s59
	ds_read_b128 v[186:189], v184
	ds_read_b128 v[190:193], v184 offset:1024
	ds_read_b128 v[194:197], v184 offset:2048
	ds_read_b128 v[198:201], v184 offset:3072
	ds_read_b128 v[202:205], v184 offset:4096
	ds_read_b128 v[206:209], v184 offset:5120
	ds_read_b128 v[210:213], v184 offset:6144
	ds_read_b128 v[214:217], v184 offset:7168
	global_load_lds_dwordx4 v162, s[40:41]
	s_mov_b32 m0, s60
	s_nop 0
	global_load_lds_dwordx4 v164, s[40:41]
	s_waitcnt vmcnt(8)
	s_waitcnt lgkmcnt(0)
	s_barrier
	s_setprio 1
	v_mfma_f32_16x16x32_bf16 v[122:125], v[132:135], v[186:189], v[122:125]
	v_mfma_f32_16x16x32_bf16 v[118:121], v[140:143], v[186:189], v[118:121]
	v_mfma_f32_16x16x32_bf16 v[110:113], v[132:135], v[194:197], v[110:113]
	v_mfma_f32_16x16x32_bf16 v[106:109], v[140:143], v[194:197], v[106:109]
	v_mfma_f32_16x16x32_bf16 v[94:97], v[132:135], v[202:205], v[94:97]
	v_mfma_f32_16x16x32_bf16 v[90:93], v[140:143], v[202:205], v[90:93]
	v_mfma_f32_16x16x32_bf16 v[78:81], v[132:135], v[210:213], v[78:81]
	v_mfma_f32_16x16x32_bf16 v[74:77], v[140:143], v[210:213], v[74:77]
	v_mfma_f32_16x16x32_bf16 v[122:125], v[136:139], v[190:193], v[122:125]
	v_mfma_f32_16x16x32_bf16 v[118:121], v[144:147], v[190:193], v[118:121]
	v_mfma_f32_16x16x32_bf16 v[110:113], v[136:139], v[198:201], v[110:113]
	v_mfma_f32_16x16x32_bf16 v[106:109], v[144:147], v[198:201], v[106:109]
	v_mfma_f32_16x16x32_bf16 v[94:97], v[136:139], v[206:209], v[94:97]
	v_mfma_f32_16x16x32_bf16 v[90:93], v[144:147], v[206:209], v[90:93]
	v_mfma_f32_16x16x32_bf16 v[78:81], v[136:139], v[214:217], v[78:81]
	v_mfma_f32_16x16x32_bf16 v[74:77], v[144:147], v[214:217], v[74:77]
	s_setprio 0
	s_setprio 1
	v_mfma_f32_16x16x32_bf16 v[126:129], v[148:151], v[186:189], v[126:129]
	v_mfma_f32_16x16x32_bf16 v[114:117], v[174:177], v[186:189], v[114:117]
	v_mfma_f32_16x16x32_bf16 v[102:105], v[148:151], v[194:197], v[102:105]
	v_mfma_f32_16x16x32_bf16 v[98:101], v[174:177], v[194:197], v[98:101]
	v_mfma_f32_16x16x32_bf16 v[86:89], v[148:151], v[202:205], v[86:89]
	v_mfma_f32_16x16x32_bf16 v[82:85], v[174:177], v[202:205], v[82:85]
	v_mfma_f32_16x16x32_bf16 v[70:73], v[148:151], v[210:213], v[70:73]
	v_mfma_f32_16x16x32_bf16 v[66:69], v[174:177], v[210:213], v[66:69]
	v_mfma_f32_16x16x32_bf16 v[126:129], v[170:173], v[190:193], v[126:129]
	v_mfma_f32_16x16x32_bf16 v[114:117], v[178:181], v[190:193], v[114:117]
	v_mfma_f32_16x16x32_bf16 v[102:105], v[170:173], v[198:201], v[102:105]
	v_mfma_f32_16x16x32_bf16 v[98:101], v[178:181], v[198:201], v[98:101]
	v_mfma_f32_16x16x32_bf16 v[86:89], v[170:173], v[206:209], v[86:89]
	v_mfma_f32_16x16x32_bf16 v[82:85], v[178:181], v[206:209], v[82:85]
	v_mfma_f32_16x16x32_bf16 v[70:73], v[170:173], v[214:217], v[70:73]
	v_mfma_f32_16x16x32_bf16 v[66:69], v[178:181], v[214:217], v[66:69]
	s_setprio 0
	s_barrier
	s_mov_b32 m0, s61
	s_mov_b64 s[98:99], s[38:39]
	s_add_u32 s70, s38, 0x20000
	ds_read_b128 v[186:189], v184 offset:16384
	ds_read_b128 v[190:193], v184 offset:17408
	ds_read_b128 v[194:197], v184 offset:18432
	ds_read_b128 v[198:201], v184 offset:19456
	ds_read_b128 v[202:205], v184 offset:20480
	ds_read_b128 v[206:209], v184 offset:21504
	ds_read_b128 v[210:213], v184 offset:22528
	ds_read_b128 v[214:217], v184 offset:23552
	global_load_lds_dwordx4 v156, s[38:39]
	s_mov_b32 m0, s62
	s_addc_u32 s71, s39, 0
	global_load_lds_dwordx4 v160, s[38:39]
	s_mov_b32 m0, s67
	s_mov_b64 s[100:101], s[42:43]
	global_load_lds_dwordx4 v156, s[70:71]
	s_mov_b32 m0, s46
	s_nop 0
	global_load_lds_dwordx4 v160, s[70:71]
	s_mov_b32 m0, s48
	s_nop 0
	global_load_lds_dwordx4 v154, s[42:43]
	s_mov_b32 m0, s49
	s_nop 0
	global_load_lds_dwordx4 v158, s[42:43]
	s_waitcnt vmcnt(8)
	s_waitcnt lgkmcnt(0)
	s_barrier
	s_setprio 1
	v_mfma_f32_16x16x32_bf16 v[58:61], v[132:135], v[186:189], v[58:61]
	v_mfma_f32_16x16x32_bf16 v[54:57], v[140:143], v[186:189], v[54:57]
	v_mfma_f32_16x16x32_bf16 v[46:49], v[132:135], v[194:197], v[46:49]
	v_mfma_f32_16x16x32_bf16 v[42:45], v[140:143], v[194:197], v[42:45]
	v_mfma_f32_16x16x32_bf16 v[30:33], v[132:135], v[202:205], v[30:33]
	v_mfma_f32_16x16x32_bf16 v[26:29], v[140:143], v[202:205], v[26:29]
	v_mfma_f32_16x16x32_bf16 v[14:17], v[132:135], v[210:213], v[14:17]
	v_mfma_f32_16x16x32_bf16 v[10:13], v[140:143], v[210:213], v[10:13]
	v_mfma_f32_16x16x32_bf16 v[58:61], v[136:139], v[190:193], v[58:61]
	v_mfma_f32_16x16x32_bf16 v[54:57], v[144:147], v[190:193], v[54:57]
	v_mfma_f32_16x16x32_bf16 v[46:49], v[136:139], v[198:201], v[46:49]
	v_mfma_f32_16x16x32_bf16 v[42:45], v[144:147], v[198:201], v[42:45]
	v_mfma_f32_16x16x32_bf16 v[30:33], v[136:139], v[206:209], v[30:33]
	v_mfma_f32_16x16x32_bf16 v[26:29], v[144:147], v[206:209], v[26:29]
	v_mfma_f32_16x16x32_bf16 v[14:17], v[136:139], v[214:217], v[14:17]
	v_mfma_f32_16x16x32_bf16 v[10:13], v[144:147], v[214:217], v[10:13]
	s_setprio 0
	s_setprio 1
	v_mfma_f32_16x16x32_bf16 v[62:65], v[148:151], v[186:189], v[62:65]
	v_mfma_f32_16x16x32_bf16 v[50:53], v[174:177], v[186:189], v[50:53]
	v_mfma_f32_16x16x32_bf16 v[38:41], v[148:151], v[194:197], v[38:41]
	v_mfma_f32_16x16x32_bf16 v[34:37], v[174:177], v[194:197], v[34:37]
	v_mfma_f32_16x16x32_bf16 v[22:25], v[148:151], v[202:205], v[22:25]
	v_mfma_f32_16x16x32_bf16 v[18:21], v[174:177], v[202:205], v[18:21]
	v_mfma_f32_16x16x32_bf16 v[6:9], v[148:151], v[210:213], v[6:9]
	v_mfma_f32_16x16x32_bf16 v[2:5], v[174:177], v[210:213], v[2:5]
	v_mfma_f32_16x16x32_bf16 v[62:65], v[170:173], v[190:193], v[62:65]
	v_mfma_f32_16x16x32_bf16 v[50:53], v[178:181], v[190:193], v[50:53]
	v_mfma_f32_16x16x32_bf16 v[38:41], v[170:173], v[198:201], v[38:41]
	v_mfma_f32_16x16x32_bf16 v[34:37], v[178:181], v[198:201], v[34:37]
	v_mfma_f32_16x16x32_bf16 v[22:25], v[170:173], v[206:209], v[22:25]
	v_mfma_f32_16x16x32_bf16 v[18:21], v[178:181], v[206:209], v[18:21]
	v_mfma_f32_16x16x32_bf16 v[6:9], v[170:173], v[214:217], v[6:9]
	v_mfma_f32_16x16x32_bf16 v[2:5], v[178:181], v[214:217], v[2:5]
	s_setprio 0
	s_barrier
	ds_read_b128 v[132:135], v130
	ds_read_b128 v[136:139], v130 offset:1024
	ds_read_b128 v[140:143], v130 offset:2048
	ds_read_b128 v[144:147], v130 offset:3072
	ds_read_b128 v[148:151], v131
	ds_read_b128 v[170:173], v131 offset:1024
	ds_read_b128 v[174:177], v131 offset:2048
	ds_read_b128 v[178:181], v131 offset:3072
	s_add_u32 s42, s42, 0x20000
	s_addc_u32 s43, s43, 0
	s_mov_b32 m0, s50
	ds_read_b128 v[186:189], v184 offset:32768
	ds_read_b128 v[190:193], v184 offset:33792
	ds_read_b128 v[194:197], v184 offset:34816
	ds_read_b128 v[198:201], v184 offset:35840
	ds_read_b128 v[202:205], v184 offset:36864
	ds_read_b128 v[206:209], v184 offset:37888
	ds_read_b128 v[210:213], v184 offset:38912
	ds_read_b128 v[214:217], v184 offset:39936
	global_load_lds_dwordx4 v154, s[42:43]
	s_mov_b32 m0, s51
	s_nop 0
	global_load_lds_dwordx4 v158, s[42:43]
	s_waitcnt vmcnt(8)
	s_waitcnt lgkmcnt(0)
	s_barrier
	s_setprio 1
	v_mfma_f32_16x16x32_bf16 v[122:125], v[132:135], v[186:189], v[122:125]
	v_mfma_f32_16x16x32_bf16 v[118:121], v[140:143], v[186:189], v[118:121]
	v_mfma_f32_16x16x32_bf16 v[110:113], v[132:135], v[194:197], v[110:113]
	v_mfma_f32_16x16x32_bf16 v[106:109], v[140:143], v[194:197], v[106:109]
	v_mfma_f32_16x16x32_bf16 v[94:97], v[132:135], v[202:205], v[94:97]
	v_mfma_f32_16x16x32_bf16 v[90:93], v[140:143], v[202:205], v[90:93]
	v_mfma_f32_16x16x32_bf16 v[78:81], v[132:135], v[210:213], v[78:81]
	v_mfma_f32_16x16x32_bf16 v[74:77], v[140:143], v[210:213], v[74:77]
	v_mfma_f32_16x16x32_bf16 v[122:125], v[136:139], v[190:193], v[122:125]
	v_mfma_f32_16x16x32_bf16 v[118:121], v[144:147], v[190:193], v[118:121]
	v_mfma_f32_16x16x32_bf16 v[110:113], v[136:139], v[198:201], v[110:113]
	v_mfma_f32_16x16x32_bf16 v[106:109], v[144:147], v[198:201], v[106:109]
	v_mfma_f32_16x16x32_bf16 v[94:97], v[136:139], v[206:209], v[94:97]
	v_mfma_f32_16x16x32_bf16 v[90:93], v[144:147], v[206:209], v[90:93]
	v_mfma_f32_16x16x32_bf16 v[78:81], v[136:139], v[214:217], v[78:81]
	v_mfma_f32_16x16x32_bf16 v[74:77], v[144:147], v[214:217], v[74:77]
	s_setprio 0
	s_setprio 1
	v_mfma_f32_16x16x32_bf16 v[126:129], v[148:151], v[186:189], v[126:129]
	v_mfma_f32_16x16x32_bf16 v[114:117], v[174:177], v[186:189], v[114:117]
	v_mfma_f32_16x16x32_bf16 v[102:105], v[148:151], v[194:197], v[102:105]
	v_mfma_f32_16x16x32_bf16 v[98:101], v[174:177], v[194:197], v[98:101]
	v_mfma_f32_16x16x32_bf16 v[86:89], v[148:151], v[202:205], v[86:89]
	v_mfma_f32_16x16x32_bf16 v[82:85], v[174:177], v[202:205], v[82:85]
	v_mfma_f32_16x16x32_bf16 v[70:73], v[148:151], v[210:213], v[70:73]
	v_mfma_f32_16x16x32_bf16 v[66:69], v[174:177], v[210:213], v[66:69]
	v_mfma_f32_16x16x32_bf16 v[126:129], v[170:173], v[190:193], v[126:129]
	v_mfma_f32_16x16x32_bf16 v[114:117], v[178:181], v[190:193], v[114:117]
	v_mfma_f32_16x16x32_bf16 v[102:105], v[170:173], v[198:201], v[102:105]
	v_mfma_f32_16x16x32_bf16 v[98:101], v[178:181], v[198:201], v[98:101]
	v_mfma_f32_16x16x32_bf16 v[86:89], v[170:173], v[206:209], v[86:89]
	v_mfma_f32_16x16x32_bf16 v[82:85], v[178:181], v[206:209], v[82:85]
	v_mfma_f32_16x16x32_bf16 v[70:73], v[170:173], v[214:217], v[70:73]
	v_mfma_f32_16x16x32_bf16 v[66:69], v[178:181], v[214:217], v[66:69]
	s_setprio 0
	s_barrier
	s_mov_b32 m0, s47
	s_add_u32 s98, s98, 0x80
	s_addc_u32 s99, s99, 0
	s_add_u32 s100, s100, 0x80
	s_addc_u32 s101, s101, 0
	s_add_u32 s38, s38, 0x20080
	ds_read_b128 v[186:189], v184 offset:49152
	ds_read_b128 v[190:193], v184 offset:50176
	ds_read_b128 v[194:197], v184 offset:51200
	ds_read_b128 v[198:201], v184 offset:52224
	ds_read_b128 v[202:205], v184 offset:53248
	ds_read_b128 v[206:209], v184 offset:54272
	ds_read_b128 v[210:213], v184 offset:55296
	ds_read_b128 v[214:217], v184 offset:56320
	global_load_lds_dwordx4 v156, s[98:99]
	s_mov_b32 m0, s68
	s_addc_u32 s39, s39, 0
	global_load_lds_dwordx4 v160, s[98:99]
	s_mov_b32 m0, s56
	s_nop 0
	global_load_lds_dwordx4 v156, s[38:39]
	s_mov_b32 m0, s57
	s_nop 0
	global_load_lds_dwordx4 v160, s[38:39]
	s_mov_b32 m0, s52
	s_nop 0
	global_load_lds_dwordx4 v154, s[100:101]
	s_mov_b32 m0, s53
	s_nop 0
	global_load_lds_dwordx4 v158, s[100:101]
	s_waitcnt vmcnt(8)
	s_waitcnt lgkmcnt(0)
	s_barrier
	s_setprio 1
	v_mfma_f32_16x16x32_bf16 v[58:61], v[132:135], v[186:189], v[58:61]
	v_mfma_f32_16x16x32_bf16 v[54:57], v[140:143], v[186:189], v[54:57]
	v_mfma_f32_16x16x32_bf16 v[46:49], v[132:135], v[194:197], v[46:49]
	v_mfma_f32_16x16x32_bf16 v[42:45], v[140:143], v[194:197], v[42:45]
	v_mfma_f32_16x16x32_bf16 v[30:33], v[132:135], v[202:205], v[30:33]
	v_mfma_f32_16x16x32_bf16 v[26:29], v[140:143], v[202:205], v[26:29]
	v_mfma_f32_16x16x32_bf16 v[14:17], v[132:135], v[210:213], v[14:17]
	v_mfma_f32_16x16x32_bf16 v[10:13], v[140:143], v[210:213], v[10:13]
	v_mfma_f32_16x16x32_bf16 v[58:61], v[136:139], v[190:193], v[58:61]
	v_mfma_f32_16x16x32_bf16 v[54:57], v[144:147], v[190:193], v[54:57]
	v_mfma_f32_16x16x32_bf16 v[46:49], v[136:139], v[198:201], v[46:49]
	v_mfma_f32_16x16x32_bf16 v[42:45], v[144:147], v[198:201], v[42:45]
	v_mfma_f32_16x16x32_bf16 v[30:33], v[136:139], v[206:209], v[30:33]
	v_mfma_f32_16x16x32_bf16 v[26:29], v[144:147], v[206:209], v[26:29]
	v_mfma_f32_16x16x32_bf16 v[14:17], v[136:139], v[214:217], v[14:17]
	v_mfma_f32_16x16x32_bf16 v[10:13], v[144:147], v[214:217], v[10:13]
	s_setprio 0
	s_setprio 1
	v_mfma_f32_16x16x32_bf16 v[62:65], v[148:151], v[186:189], v[62:65]
	v_mfma_f32_16x16x32_bf16 v[50:53], v[174:177], v[186:189], v[50:53]
	v_mfma_f32_16x16x32_bf16 v[38:41], v[148:151], v[194:197], v[38:41]
	v_mfma_f32_16x16x32_bf16 v[34:37], v[174:177], v[194:197], v[34:37]
	v_mfma_f32_16x16x32_bf16 v[22:25], v[148:151], v[202:205], v[22:25]
	v_mfma_f32_16x16x32_bf16 v[18:21], v[174:177], v[202:205], v[18:21]
	v_mfma_f32_16x16x32_bf16 v[6:9], v[148:151], v[210:213], v[6:9]
	v_mfma_f32_16x16x32_bf16 v[2:5], v[174:177], v[210:213], v[2:5]
	v_mfma_f32_16x16x32_bf16 v[62:65], v[170:173], v[190:193], v[62:65]
	v_mfma_f32_16x16x32_bf16 v[50:53], v[178:181], v[190:193], v[50:53]
	v_mfma_f32_16x16x32_bf16 v[38:41], v[170:173], v[198:201], v[38:41]
	v_mfma_f32_16x16x32_bf16 v[34:37], v[178:181], v[198:201], v[34:37]
	v_mfma_f32_16x16x32_bf16 v[22:25], v[170:173], v[206:209], v[22:25]
	v_mfma_f32_16x16x32_bf16 v[18:21], v[178:181], v[206:209], v[18:21]
	v_mfma_f32_16x16x32_bf16 v[6:9], v[170:173], v[214:217], v[6:9]
	v_mfma_f32_16x16x32_bf16 v[2:5], v[178:181], v[214:217], v[2:5]
	s_setprio 0
	s_barrier
	s_add_i32 s69, s69, 2
	s_add_u32 s40, s40, 0x100
	s_addc_u32 s41, s41, 0
	s_add_u32 s26, s26, 0x100
	s_addc_u32 s27, s27, 0
	s_cmp_gt_u32 s69, 5
	s_cbranch_scc0 .LBB0_1261
	s_and_b64 vcc, exec, s[16:17]
	s_cbranch_vccz .LBB0_1264
	s_barrier

;     __host__ __device__ bool next(int i, Unit& u) const { if (!StaticOrder::next(i >> 1, u)) return false; u.seg = i & 1; return true; }
;     ...
;         const bool has_next = S.next(ui + 1, nxt);
;         const char* nA = has_next ? PG8_APTR(nxt) : cA; const char* nB = has_next ? PG8_BPTR(nxt) : cB;
;         const char* pfc = PG8_PFPTR(cA, cB); const char* pfn = PG8_PFPTR(nA, nB);
;         PG8_KITER(0);
.LBB0_1344:
	s_ashr_i32 s25, s24, 31
	ds_read_b128 v[2:5], v150
	ds_read_b128 v[6:9], v150 offset:1024
	ds_read_b128 v[10:13], v150 offset:2048
	ds_read_b128 v[14:17], v150 offset:3072
	ds_read_b128 v[18:21], v151
	ds_read_b128 v[22:25], v151 offset:1024
	ds_read_b128 v[26:29], v151 offset:2048
	ds_read_b128 v[30:33], v151 offset:3072
	s_lshl_b64 s[26:27], s[24:25], 21
	s_add_u32 s28, s36, s26
	s_addc_u32 s29, s37, s27
	s_and_b64 s[26:27], s[4:5], exec
	s_cselect_b32 s1, s29, s41
	s_cselect_b32 s25, s28, s40
	s_and_b32 s8, s65, 0x7fffffff
	s_lshl_b64 s[26:27], s[8:9], 21
	s_add_u32 s30, s96, s26
	s_addc_u32 s31, s97, s27
	s_and_b64 s[26:27], s[4:5], exec
	s_cselect_b32 s8, s31, s39
	s_cselect_b32 s67, s30, s38
	s_add_u32 s26, s40, 0x100080
	s_addc_u32 s27, s41, 0
	s_mov_b32 m0, s53
	v_lshl_add_u64 v[66:67], s[26:27], 0, v[136:137]
	ds_read_b128 v[34:37], v152
	ds_read_b128 v[38:41], v152 offset:1024
	ds_read_b128 v[42:45], v152 offset:2048
	ds_read_b128 v[46:49], v152 offset:3072
	ds_read_b128 v[50:53], v152 offset:4096
	ds_read_b128 v[54:57], v152 offset:5120
	ds_read_b128 v[58:61], v152 offset:6144
	ds_read_b128 v[62:65], v152 offset:7168
	global_load_lds_dwordx4 v[66:67], off
	v_lshl_add_u64 v[66:67], s[26:27], 0, v[132:133]
	s_mov_b32 m0, s54
	s_nop 0
	global_load_lds_dwordx4 v[66:67], off
	s_waitcnt vmcnt(8)
	s_waitcnt lgkmcnt(0)
	s_barrier
	s_setprio 1
	v_mfma_f32_16x16x32_bf16 v[86:89], v[10:13], v[50:53], 0
	v_mfma_f32_16x16x32_bf16 v[90:93], v[14:17], v[54:57], v[86:89]
	v_mfma_f32_16x16x32_bf16 v[86:89], v[2:5], v[58:61], 0
	v_mfma_f32_16x16x32_bf16 v[66:69], v[2:5], v[34:37], 0
	v_mfma_f32_16x16x32_bf16 v[70:73], v[10:13], v[34:37], 0
	v_mfma_f32_16x16x32_bf16 v[74:77], v[2:5], v[42:45], 0
	v_mfma_f32_16x16x32_bf16 v[78:81], v[10:13], v[42:45], 0
	v_mfma_f32_16x16x32_bf16 v[82:85], v[2:5], v[50:53], 0
	v_mfma_f32_16x16x32_bf16 v[94:97], v[6:9], v[62:65], v[86:89]
	v_mfma_f32_16x16x32_bf16 v[86:89], v[10:13], v[58:61], 0
	v_mfma_f32_16x16x32_bf16 v[66:69], v[6:9], v[38:41], v[66:69]
	v_mfma_f32_16x16x32_bf16 v[70:73], v[14:17], v[38:41], v[70:73]
	v_mfma_f32_16x16x32_bf16 v[74:77], v[6:9], v[46:49], v[74:77]
	v_mfma_f32_16x16x32_bf16 v[78:81], v[14:17], v[46:49], v[78:81]
	v_mfma_f32_16x16x32_bf16 v[82:85], v[6:9], v[54:57], v[82:85]
	v_mfma_f32_16x16x32_bf16 v[106:109], v[14:17], v[62:65], v[86:89]
	s_setprio 0
	s_setprio 1
	v_mfma_f32_16x16x32_bf16 v[86:89], v[18:21], v[34:37], 0
	v_mfma_f32_16x16x32_bf16 v[34:37], v[26:29], v[34:37], 0
	v_mfma_f32_16x16x32_bf16 v[110:113], v[22:25], v[38:41], v[86:89]
	v_mfma_f32_16x16x32_bf16 v[34:37], v[30:33], v[38:41], v[34:37]
	v_mfma_f32_16x16x32_bf16 v[38:41], v[18:21], v[42:45], 0
	v_mfma_f32_16x16x32_bf16 v[42:45], v[26:29], v[42:45], 0
	v_mfma_f32_16x16x32_bf16 v[38:41], v[22:25], v[46:49], v[38:41]
	v_mfma_f32_16x16x32_bf16 v[42:45], v[30:33], v[46:49], v[42:45]
	v_mfma_f32_16x16x32_bf16 v[46:49], v[18:21], v[50:53], 0
	v_mfma_f32_16x16x32_bf16 v[50:53], v[26:29], v[50:53], 0
	v_mfma_f32_16x16x32_bf16 v[46:49], v[22:25], v[54:57], v[46:49]
	v_mfma_f32_16x16x32_bf16 v[50:53], v[30:33], v[54:57], v[50:53]
	v_mfma_f32_16x16x32_bf16 v[54:57], v[18:21], v[58:61], 0
	v_mfma_f32_16x16x32_bf16 v[58:61], v[26:29], v[58:61], 0
	v_mfma_f32_16x16x32_bf16 v[54:57], v[22:25], v[62:65], v[54:57]
	v_mfma_f32_16x16x32_bf16 v[58:61], v[30:33], v[62:65], v[58:61]
	s_setprio 0
	s_barrier
	v_lshl_add_u64 v[252:253], s[38:39], 0, v[134:135]
	s_mov_b32 m0, s59
	v_lshl_add_u64 v[146:147], v[252:253], 0, s[20:21]
	v_lshl_add_u64 v[142:143], s[38:39], 0, v[130:131]
	s_add_u32 s26, s38, 0x100100
	ds_read_b128 v[62:65], v152 offset:16384
	ds_read_b128 v[86:89], v152 offset:17408
	ds_read_b128 v[98:101], v152 offset:18432
	ds_read_b128 v[102:105], v152 offset:19456
	ds_read_b128 v[114:117], v152 offset:20480
	ds_read_b128 v[118:121], v152 offset:21504
	ds_read_b128 v[122:125], v152 offset:22528
	ds_read_b128 v[126:129], v152 offset:23552
	global_load_lds_dwordx4 v[146:147], off
	v_lshl_add_u64 v[146:147], v[142:143], 0, s[20:21]
	s_mov_b32 m0, s60
	s_addc_u32 s27, s39, 0
	global_load_lds_dwordx4 v[146:147], off
	v_lshl_add_u64 v[146:147], s[26:27], 0, v[134:135]
	s_mov_b32 m0, s61
	v_lshl_add_u64 v[144:145], s[40:41], 0, v[136:137]
	global_load_lds_dwordx4 v[146:147], off
	v_lshl_add_u64 v[146:147], s[26:27], 0, v[130:131]
	s_mov_b32 m0, s62
	v_lshl_add_u64 v[138:139], s[40:41], 0, v[132:133]
	global_load_lds_dwordx4 v[146:147], off
	v_lshl_add_u64 v[146:147], v[144:145], 0, s[20:21]
	s_mov_b32 m0, s13
	s_nop 0
	global_load_lds_dwordx4 v[146:147], off
	v_lshl_add_u64 v[146:147], v[138:139], 0, s[20:21]
	s_mov_b32 m0, s33
	s_nop 0
	global_load_lds_dwordx4 v[146:147], off
	s_waitcnt vmcnt(8)
	s_waitcnt lgkmcnt(0)
	s_barrier
	s_setprio 1
	v_mfma_f32_16x16x32_bf16 v[146:149], v[2:5], v[62:65], 0
	v_mfma_f32_16x16x32_bf16 v[156:159], v[6:9], v[86:89], v[146:149]
	v_mfma_f32_16x16x32_bf16 v[146:149], v[10:13], v[62:65], 0
	v_mfma_f32_16x16x32_bf16 v[160:163], v[14:17], v[86:89], v[146:149]
	v_mfma_f32_16x16x32_bf16 v[146:149], v[2:5], v[98:101], 0
	v_mfma_f32_16x16x32_bf16 v[164:167], v[6:9], v[102:105], v[146:149]
	v_mfma_f32_16x16x32_bf16 v[146:149], v[10:13], v[98:101], 0
	v_mfma_f32_16x16x32_bf16 v[168:171], v[14:17], v[102:105], v[146:149]
	v_mfma_f32_16x16x32_bf16 v[146:149], v[2:5], v[114:117], 0
	v_mfma_f32_16x16x32_bf16 v[2:5], v[2:5], v[122:125], 0
	v_mfma_f32_16x16x32_bf16 v[172:175], v[6:9], v[118:121], v[146:149]
	v_mfma_f32_16x16x32_bf16 v[2:5], v[6:9], v[126:129], v[2:5]
	v_mfma_f32_16x16x32_bf16 v[6:9], v[10:13], v[122:125], 0
	v_mfma_f32_16x16x32_bf16 v[146:149], v[10:13], v[114:117], 0
	v_mfma_f32_16x16x32_bf16 v[10:13], v[14:17], v[126:129], v[6:9]
	v_mfma_f32_16x16x32_bf16 v[176:179], v[14:17], v[118:121], v[146:149]
	s_setprio 0
	s_setprio 1
	v_mfma_f32_16x16x32_bf16 v[6:9], v[18:21], v[62:65], 0
	v_mfma_f32_16x16x32_bf16 v[14:17], v[22:25], v[86:89], v[6:9]
	v_mfma_f32_16x16x32_bf16 v[6:9], v[26:29], v[62:65], 0
	v_mfma_f32_16x16x32_bf16 v[180:183], v[30:33], v[86:89], v[6:9]
	v_mfma_f32_16x16x32_bf16 v[6:9], v[18:21], v[98:101], 0
	v_mfma_f32_16x16x32_bf16 v[184:187], v[22:25], v[102:105], v[6:9]
	v_mfma_f32_16x16x32_bf16 v[6:9], v[26:29], v[98:101], 0
	v_mfma_f32_16x16x32_bf16 v[188:191], v[30:33], v[102:105], v[6:9]
	v_mfma_f32_16x16x32_bf16 v[6:9], v[18:21], v[114:117], 0
	v_mfma_f32_16x16x32_bf16 v[192:195], v[22:25], v[118:121], v[6:9]
	v_mfma_f32_16x16x32_bf16 v[6:9], v[26:29], v[114:117], 0
	v_mfma_f32_16x16x32_bf16 v[196:199], v[30:33], v[118:121], v[6:9]
	v_mfma_f32_16x16x32_bf16 v[6:9], v[18:21], v[122:125], 0
	v_mfma_f32_16x16x32_bf16 v[200:203], v[22:25], v[126:129], v[6:9]
	v_mfma_f32_16x16x32_bf16 v[6:9], v[26:29], v[122:125], 0
	v_mfma_f32_16x16x32_bf16 v[204:207], v[30:33], v[126:129], v[6:9]
	s_setprio 0
	s_barrier
	s_add_i32 s56, 0, 0x1c000
	v_add_u32_e32 v146, s56, v155
	s_nop 2
	ds_read_b128 v[6:9], v154
	ds_read_b128 v[26:29], v154 offset:1024
	ds_read_b128 v[30:33], v154 offset:2048
	ds_read_b128 v[208:211], v154 offset:3072
	ds_read_b128 v[212:215], v146
	ds_read_b128 v[216:219], v146 offset:1024
	ds_read_b128 v[220:223], v146 offset:2048
	ds_read_b128 v[224:227], v146 offset:3072
	s_add_u32 s26, s40, 0x100100
	s_addc_u32 s27, s41, 0
	s_mov_b32 m0, s48
	v_lshl_add_u64 v[62:63], s[26:27], 0, v[136:137]
	ds_read_b128 v[18:21], v152 offset:32768
	ds_read_b128 v[22:25], v152 offset:33792
	ds_read_b128 v[228:231], v152 offset:34816
	ds_read_b128 v[232:235], v152 offset:35840
	ds_read_b128 v[236:239], v152 offset:36864
	ds_read_b128 v[240:243], v152 offset:37888
	ds_read_b128 v[244:247], v152 offset:38912
	ds_read_b128 v[248:251], v152 offset:39936
	global_load_lds_dwordx4 v[62:63], off
	v_lshl_add_u64 v[62:63], s[26:27], 0, v[132:133]
	s_mov_b32 m0, s49
	s_nop 0
	global_load_lds_dwordx4 v[62:63], off
	s_waitcnt vmcnt(8)
	s_waitcnt lgkmcnt(0)
	s_barrier
	s_setprio 1
	v_mfma_f32_16x16x32_bf16 v[62:65], v[6:9], v[18:21], v[66:69]
	v_mfma_f32_16x16x32_bf16 v[118:121], v[26:29], v[22:25], v[62:65]
	v_mfma_f32_16x16x32_bf16 v[62:65], v[30:33], v[18:21], v[70:73]
	v_mfma_f32_16x16x32_bf16 v[114:117], v[208:211], v[22:25], v[62:65]
	v_mfma_f32_16x16x32_bf16 v[62:65], v[6:9], v[228:231], v[74:77]
	v_mfma_f32_16x16x32_bf16 v[102:105], v[26:29], v[232:235], v[62:65]
	v_mfma_f32_16x16x32_bf16 v[62:65], v[30:33], v[228:231], v[78:81]
	v_mfma_f32_16x16x32_bf16 v[98:101], v[208:211], v[232:235], v[62:65]
	v_mfma_f32_16x16x32_bf16 v[62:65], v[6:9], v[236:239], v[82:85]
	v_mfma_f32_16x16x32_bf16 v[86:89], v[26:29], v[240:243], v[62:65]
	v_mfma_f32_16x16x32_bf16 v[62:65], v[30:33], v[236:239], v[90:93]
	v_mfma_f32_16x16x32_bf16 v[82:85], v[208:211], v[240:243], v[62:65]
	v_mfma_f32_16x16x32_bf16 v[62:65], v[6:9], v[244:247], v[94:97]
	v_mfma_f32_16x16x32_bf16 v[66:69], v[26:29], v[248:251], v[62:65]
	v_mfma_f32_16x16x32_bf16 v[62:65], v[30:33], v[244:247], v[106:109]
	v_mfma_f32_16x16x32_bf16 v[62:65], v[208:211], v[248:251], v[62:65]
	s_setprio 0
	s_setprio 1
	v_mfma_f32_16x16x32_bf16 v[70:73], v[212:215], v[18:21], v[110:113]
	v_mfma_f32_16x16x32_bf16 v[18:21], v[220:223], v[18:21], v[34:37]
	v_mfma_f32_16x16x32_bf16 v[122:125], v[224:227], v[22:25], v[18:21]
	v_mfma_f32_16x16x32_bf16 v[18:21], v[212:215], v[228:231], v[38:41]
	v_mfma_f32_16x16x32_bf16 v[110:113], v[216:219], v[232:235], v[18:21]
	v_mfma_f32_16x16x32_bf16 v[18:21], v[220:223], v[228:231], v[42:45]
	v_mfma_f32_16x16x32_bf16 v[106:109], v[224:227], v[232:235], v[18:21]
	v_mfma_f32_16x16x32_bf16 v[18:21], v[212:215], v[236:239], v[46:49]
	v_mfma_f32_16x16x32_bf16 v[94:97], v[216:219], v[240:243], v[18:21]
	v_mfma_f32_16x16x32_bf16 v[18:21], v[220:223], v[236:239], v[50:53]
	v_mfma_f32_16x16x32_bf16 v[90:93], v[224:227], v[240:243], v[18:21]
	v_mfma_f32_16x16x32_bf16 v[18:21], v[212:215], v[244:247], v[54:57]
	v_mfma_f32_16x16x32_bf16 v[78:81], v[216:219], v[248:251], v[18:21]
	v_mfma_f32_16x16x32_bf16 v[18:21], v[220:223], v[244:247], v[58:61]
	v_mfma_f32_16x16x32_bf16 v[126:129], v[216:219], v[22:25], v[70:73]
	v_mfma_f32_16x16x32_bf16 v[74:77], v[224:227], v[248:251], v[18:21]
	s_setprio 0
	s_barrier
	s_add_i32 s46, s63, s10
	s_add_i32 s47, s46, 0x2000
	s_nop 1
	v_lshl_add_u64 v[18:19], v[252:253], 0, s[22:23]
	s_mov_b32 m0, s46
	s_add_u32 s26, s38, 0x100180
	ds_read_b128 v[42:45], v152 offset:49152
	ds_read_b128 v[46:49], v152 offset:50176
	ds_read_b128 v[228:231], v152 offset:51200
	ds_read_b128 v[232:235], v152 offset:52224
	ds_read_b128 v[236:239], v152 offset:53248
	ds_read_b128 v[240:243], v152 offset:54272
	ds_read_b128 v[244:247], v152 offset:55296
	ds_read_b128 v[248:251], v152 offset:56320
	global_load_lds_dwordx4 v[18:19], off
	v_lshl_add_u64 v[18:19], v[142:143], 0, s[22:23]
	s_mov_b32 m0, s47
	s_addc_u32 s27, s39, 0
	s_add_i32 s56, s56, s10
	global_load_lds_dwordx4 v[18:19], off
	v_lshl_add_u64 v[18:19], s[26:27], 0, v[134:135]
	s_mov_b32 m0, s56
	s_add_i32 s57, s56, 0x2000
	global_load_lds_dwordx4 v[18:19], off
	v_lshl_add_u64 v[18:19], s[26:27], 0, v[130:131]
	s_mov_b32 m0, s57
	s_nop 0
	global_load_lds_dwordx4 v[18:19], off
	v_lshl_add_u64 v[18:19], v[144:145], 0, s[22:23]
	s_mov_b32 m0, s50
	s_nop 0
	global_load_lds_dwordx4 v[18:19], off
	v_lshl_add_u64 v[18:19], v[138:139], 0, s[22:23]
	s_mov_b32 m0, s51
	s_nop 0
	global_load_lds_dwordx4 v[18:19], off
	s_waitcnt vmcnt(8)
	s_waitcnt lgkmcnt(0)
	s_barrier
	s_setprio 1
	v_mfma_f32_16x16x32_bf16 v[18:21], v[6:9], v[42:45], v[156:159]
	v_mfma_f32_16x16x32_bf16 v[54:57], v[26:29], v[46:49], v[18:21]
	v_mfma_f32_16x16x32_bf16 v[18:21], v[30:33], v[42:45], v[160:163]
	v_mfma_f32_16x16x32_bf16 v[50:53], v[208:211], v[46:49], v[18:21]
	v_mfma_f32_16x16x32_bf16 v[18:21], v[6:9], v[228:231], v[164:167]
	v_mfma_f32_16x16x32_bf16 v[38:41], v[26:29], v[232:235], v[18:21]
	v_mfma_f32_16x16x32_bf16 v[18:21], v[30:33], v[228:231], v[168:171]
	v_mfma_f32_16x16x32_bf16 v[34:37], v[208:211], v[232:235], v[18:21]
	v_mfma_f32_16x16x32_bf16 v[18:21], v[6:9], v[236:239], v[172:175]
	v_mfma_f32_16x16x32_bf16 v[2:5], v[6:9], v[244:247], v[2:5]
	v_mfma_f32_16x16x32_bf16 v[22:25], v[26:29], v[240:243], v[18:21]
	v_mfma_f32_16x16x32_bf16 v[18:21], v[30:33], v[236:239], v[176:179]
	v_mfma_f32_16x16x32_bf16 v[6:9], v[26:29], v[248:251], v[2:5]
	v_mfma_f32_16x16x32_bf16 v[2:5], v[30:33], v[244:247], v[10:13]
	v_mfma_f32_16x16x32_bf16 v[18:21], v[208:211], v[240:243], v[18:21]
	v_mfma_f32_16x16x32_bf16 v[2:5], v[208:211], v[248:251], v[2:5]
	s_setprio 0
	s_setprio 1
	v_mfma_f32_16x16x32_bf16 v[10:13], v[212:215], v[42:45], v[14:17]
	v_mfma_f32_16x16x32_bf16 v[70:73], v[216:219], v[46:49], v[10:13]
	v_mfma_f32_16x16x32_bf16 v[10:13], v[220:223], v[42:45], v[180:183]
	v_mfma_f32_16x16x32_bf16 v[58:61], v[224:227], v[46:49], v[10:13]
	v_mfma_f32_16x16x32_bf16 v[10:13], v[212:215], v[228:231], v[184:187]
	v_mfma_f32_16x16x32_bf16 v[46:49], v[216:219], v[232:235], v[10:13]
	v_mfma_f32_16x16x32_bf16 v[10:13], v[220:223], v[228:231], v[188:191]
	v_mfma_f32_16x16x32_bf16 v[42:45], v[224:227], v[232:235], v[10:13]
	v_mfma_f32_16x16x32_bf16 v[10:13], v[212:215], v[236:239], v[192:195]
	v_mfma_f32_16x16x32_bf16 v[30:33], v[216:219], v[240:243], v[10:13]
	v_mfma_f32_16x16x32_bf16 v[10:13], v[220:223], v[236:239], v[196:199]
	v_mfma_f32_16x16x32_bf16 v[26:29], v[224:227], v[240:243], v[10:13]
	v_mfma_f32_16x16x32_bf16 v[10:13], v[212:215], v[244:247], v[200:203]
	v_mfma_f32_16x16x32_bf16 v[14:17], v[216:219], v[248:251], v[10:13]
	v_mfma_f32_16x16x32_bf16 v[10:13], v[220:223], v[244:247], v[204:207]
	v_mfma_f32_16x16x32_bf16 v[10:13], v[224:227], v[248:251], v[10:13]
	s_setprio 0
	s_barrier
	s_add_u32 s40, s40, 0x100180
	s_addc_u32 s41, s41, 0
	s_add_u32 s26, s38, 0x200
	s_addc_u32 s27, s39, 0
	s_mov_b32 s68, 0
.LBB0_1345:
	ds_read_b128 v[156:159], v150
	ds_read_b128 v[160:163], v150 offset:1024
	ds_read_b128 v[164:167], v150 offset:2048
	ds_read_b128 v[168:171], v150 offset:3072
	ds_read_b128 v[172:175], v151
	ds_read_b128 v[176:179], v151 offset:1024
	ds_read_b128 v[180:183], v151 offset:2048
	ds_read_b128 v[184:187], v151 offset:3072
	s_add_u32 s38, s40, 0xfff00080
	s_addc_u32 s39, s41, -1
	s_cmp_eq_u32 s68, 60
	s_cselect_b32 s43, s1, s39
	s_cselect_b32 s42, s25, s38
	s_cselect_b32 s39, s8, s27
	s_cselect_b32 s38, s67, s26
	s_mov_b32 m0, s53
	ds_read_b128 v[188:191], v152
	ds_read_b128 v[192:195], v152 offset:1024
	ds_read_b128 v[196:199], v152 offset:2048
	ds_read_b128 v[200:203], v152 offset:3072
	ds_read_b128 v[204:207], v152 offset:4096
	ds_read_b128 v[208:211], v152 offset:5120
	ds_read_b128 v[212:215], v152 offset:6144
	ds_read_b128 v[216:219], v152 offset:7168
	global_load_lds_dwordx4 v0, s[40:41]
	s_mov_b32 m0, s54
	s_nop 0
	global_load_lds_dwordx4 v140, s[40:41]
	s_waitcnt vmcnt(8)
	s_waitcnt lgkmcnt(0)
	s_barrier
	s_setprio 1
	v_mfma_f32_16x16x32_bf16 v[118:121], v[156:159], v[188:191], v[118:121]
	v_mfma_f32_16x16x32_bf16 v[114:117], v[164:167], v[188:191], v[114:117]
	v_mfma_f32_16x16x32_bf16 v[102:105], v[156:159], v[196:199], v[102:105]
	v_mfma_f32_16x16x32_bf16 v[98:101], v[164:167], v[196:199], v[98:101]
	v_mfma_f32_16x16x32_bf16 v[86:89], v[156:159], v[204:207], v[86:89]
	v_mfma_f32_16x16x32_bf16 v[82:85], v[164:167], v[204:207], v[82:85]
	v_mfma_f32_16x16x32_bf16 v[66:69], v[156:159], v[212:215], v[66:69]
	v_mfma_f32_16x16x32_bf16 v[62:65], v[164:167], v[212:215], v[62:65]
	v_mfma_f32_16x16x32_bf16 v[118:121], v[160:163], v[192:195], v[118:121]
	v_mfma_f32_16x16x32_bf16 v[114:117], v[168:171], v[192:195], v[114:117]
	v_mfma_f32_16x16x32_bf16 v[102:105], v[160:163], v[200:203], v[102:105]
	v_mfma_f32_16x16x32_bf16 v[98:101], v[168:171], v[200:203], v[98:101]
	v_mfma_f32_16x16x32_bf16 v[86:89], v[160:163], v[208:211], v[86:89]
	v_mfma_f32_16x16x32_bf16 v[82:85], v[168:171], v[208:211], v[82:85]
	v_mfma_f32_16x16x32_bf16 v[66:69], v[160:163], v[216:219], v[66:69]
	v_mfma_f32_16x16x32_bf16 v[62:65], v[168:171], v[216:219], v[62:65]
	s_setprio 0
	s_setprio 1
	v_mfma_f32_16x16x32_bf16 v[126:129], v[172:175], v[188:191], v[126:129]
	v_mfma_f32_16x16x32_bf16 v[122:125], v[180:183], v[188:191], v[122:125]
	v_mfma_f32_16x16x32_bf16 v[110:113], v[172:175], v[196:199], v[110:113]
	v_mfma_f32_16x16x32_bf16 v[106:109], v[180:183], v[196:199], v[106:109]
	v_mfma_f32_16x16x32_bf16 v[94:97], v[172:175], v[204:207], v[94:97]
	v_mfma_f32_16x16x32_bf16 v[90:93], v[180:183], v[204:207], v[90:93]
	v_mfma_f32_16x16x32_bf16 v[78:81], v[172:175], v[212:215], v[78:81]
	v_mfma_f32_16x16x32_bf16 v[74:77], v[180:183], v[212:215], v[74:77]
	v_mfma_f32_16x16x32_bf16 v[126:129], v[176:179], v[192:195], v[126:129]
	v_mfma_f32_16x16x32_bf16 v[122:125], v[184:187], v[192:195], v[122:125]
	v_mfma_f32_16x16x32_bf16 v[110:113], v[176:179], v[200:203], v[110:113]
	v_mfma_f32_16x16x32_bf16 v[106:109], v[184:187], v[200:203], v[106:109]
	v_mfma_f32_16x16x32_bf16 v[94:97], v[176:179], v[208:211], v[94:97]
	v_mfma_f32_16x16x32_bf16 v[90:93], v[184:187], v[208:211], v[90:93]
	v_mfma_f32_16x16x32_bf16 v[78:81], v[176:179], v[216:219], v[78:81]
	v_mfma_f32_16x16x32_bf16 v[74:77], v[184:187], v[216:219], v[74:77]
	s_setprio 0
	s_barrier
	s_mov_b32 m0, s59
	s_mov_b64 s[98:99], s[38:39]
	s_add_u32 s70, s38, 0x100000
	ds_read_b128 v[188:191], v152 offset:16384
	ds_read_b128 v[192:195], v152 offset:17408
	ds_read_b128 v[196:199], v152 offset:18432
	ds_read_b128 v[200:203], v152 offset:19456
	ds_read_b128 v[204:207], v152 offset:20480
	ds_read_b128 v[208:211], v152 offset:21504
	ds_read_b128 v[212:215], v152 offset:22528
	ds_read_b128 v[216:219], v152 offset:23552
	global_load_lds_dwordx4 v134, s[38:39]
	s_mov_b32 m0, s60
	s_addc_u32 s71, s39, 0
	global_load_lds_dwordx4 v130, s[38:39]
	s_mov_b32 m0, s61
	s_mov_b64 s[100:101], s[42:43]
	global_load_lds_dwordx4 v134, s[70:71]
	s_mov_b32 m0, s62
	s_nop 0
	global_load_lds_dwordx4 v130, s[70:71]
	s_mov_b32 m0, s13
	s_nop 0
	global_load_lds_dwordx4 v136, s[42:43]
	s_mov_b32 m0, s33
	s_nop 0
	global_load_lds_dwordx4 v132, s[42:43]
	s_waitcnt vmcnt(8)
	s_waitcnt lgkmcnt(0)
	s_barrier
	s_setprio 1
	v_mfma_f32_16x16x32_bf16 v[54:57], v[156:159], v[188:191], v[54:57]
	v_mfma_f32_16x16x32_bf16 v[50:53], v[164:167], v[188:191], v[50:53]
	v_mfma_f32_16x16x32_bf16 v[38:41], v[156:159], v[196:199], v[38:41]
	v_mfma_f32_16x16x32_bf16 v[34:37], v[164:167], v[196:199], v[34:37]
	v_mfma_f32_16x16x32_bf16 v[22:25], v[156:159], v[204:207], v[22:25]
	v_mfma_f32_16x16x32_bf16 v[18:21], v[164:167], v[204:207], v[18:21]
	v_mfma_f32_16x16x32_bf16 v[6:9], v[156:159], v[212:215], v[6:9]
	v_mfma_f32_16x16x32_bf16 v[2:5], v[164:167], v[212:215], v[2:5]
	v_mfma_f32_16x16x32_bf16 v[54:57], v[160:163], v[192:195], v[54:57]
	v_mfma_f32_16x16x32_bf16 v[50:53], v[168:171], v[192:195], v[50:53]
	v_mfma_f32_16x16x32_bf16 v[38:41], v[160:163], v[200:203], v[38:41]
	v_mfma_f32_16x16x32_bf16 v[34:37], v[168:171], v[200:203], v[34:37]
	v_mfma_f32_16x16x32_bf16 v[22:25], v[160:163], v[208:211], v[22:25]
	v_mfma_f32_16x16x32_bf16 v[18:21], v[168:171], v[208:211], v[18:21]
	v_mfma_f32_16x16x32_bf16 v[6:9], v[160:163], v[216:219], v[6:9]
	v_mfma_f32_16x16x32_bf16 v[2:5], v[168:171], v[216:219], v[2:5]
	s_setprio 0
	s_setprio 1
	v_mfma_f32_16x16x32_bf16 v[70:73], v[172:175], v[188:191], v[70:73]
	v_mfma_f32_16x16x32_bf16 v[58:61], v[180:183], v[188:191], v[58:61]
	v_mfma_f32_16x16x32_bf16 v[46:49], v[172:175], v[196:199], v[46:49]
	v_mfma_f32_16x16x32_bf16 v[42:45], v[180:183], v[196:199], v[42:45]
	v_mfma_f32_16x16x32_bf16 v[30:33], v[172:175], v[204:207], v[30:33]
	v_mfma_f32_16x16x32_bf16 v[26:29], v[180:183], v[204:207], v[26:29]
	v_mfma_f32_16x16x32_bf16 v[14:17], v[172:175], v[212:215], v[14:17]
	v_mfma_f32_16x16x32_bf16 v[10:13], v[180:183], v[212:215], v[10:13]
	v_mfma_f32_16x16x32_bf16 v[70:73], v[176:179], v[192:195], v[70:73]
	v_mfma_f32_16x16x32_bf16 v[58:61], v[184:187], v[192:195], v[58:61]
	v_mfma_f32_16x16x32_bf16 v[46:49], v[176:179], v[200:203], v[46:49]
	v_mfma_f32_16x16x32_bf16 v[42:45], v[184:187], v[200:203], v[42:45]
	v_mfma_f32_16x16x32_bf16 v[30:33], v[176:179], v[208:211], v[30:33]
	v_mfma_f32_16x16x32_bf16 v[26:29], v[184:187], v[208:211], v[26:29]
	v_mfma_f32_16x16x32_bf16 v[14:17], v[176:179], v[216:219], v[14:17]
	v_mfma_f32_16x16x32_bf16 v[10:13], v[184:187], v[216:219], v[10:13]
	s_setprio 0
	s_barrier
	ds_read_b128 v[156:159], v154
	ds_read_b128 v[160:163], v154 offset:1024
	ds_read_b128 v[164:167], v154 offset:2048
	ds_read_b128 v[168:171], v154 offset:3072
	ds_read_b128 v[172:175], v146
	ds_read_b128 v[176:179], v146 offset:1024
	ds_read_b128 v[180:183], v146 offset:2048
	ds_read_b128 v[184:187], v146 offset:3072
	s_add_u32 s42, s42, 0x100000
	s_addc_u32 s43, s43, 0
	s_mov_b32 m0, s48
	ds_read_b128 v[188:191], v152 offset:32768
	ds_read_b128 v[192:195], v152 offset:33792
	ds_read_b128 v[196:199], v152 offset:34816
	ds_read_b128 v[200:203], v152 offset:35840
	ds_read_b128 v[204:207], v152 offset:36864
	ds_read_b128 v[208:211], v152 offset:37888
	ds_read_b128 v[212:215], v152 offset:38912
	ds_read_b128 v[216:219], v152 offset:39936
	global_load_lds_dwordx4 v136, s[42:43]
	s_mov_b32 m0, s49
	s_nop 0
	global_load_lds_dwordx4 v132, s[42:43]
	s_waitcnt vmcnt(8)
	s_waitcnt lgkmcnt(0)
	s_barrier
	s_setprio 1
	v_mfma_f32_16x16x32_bf16 v[118:121], v[156:159], v[188:191], v[118:121]
	v_mfma_f32_16x16x32_bf16 v[114:117], v[164:167], v[188:191], v[114:117]
	v_mfma_f32_16x16x32_bf16 v[102:105], v[156:159], v[196:199], v[102:105]
	v_mfma_f32_16x16x32_bf16 v[98:101], v[164:167], v[196:199], v[98:101]
	v_mfma_f32_16x16x32_bf16 v[86:89], v[156:159], v[204:207], v[86:89]
	v_mfma_f32_16x16x32_bf16 v[82:85], v[164:167], v[204:207], v[82:85]
	v_mfma_f32_16x16x32_bf16 v[66:69], v[156:159], v[212:215], v[66:69]
	v_mfma_f32_16x16x32_bf16 v[62:65], v[164:167], v[212:215], v[62:65]
	v_mfma_f32_16x16x32_bf16 v[118:121], v[160:163], v[192:195], v[118:121]
	v_mfma_f32_16x16x32_bf16 v[114:117], v[168:171], v[192:195], v[114:117]
	v_mfma_f32_16x16x32_bf16 v[102:105], v[160:163], v[200:203], v[102:105]
	v_mfma_f32_16x16x32_bf16 v[98:101], v[168:171], v[200:203], v[98:101]
	v_mfma_f32_16x16x32_bf16 v[86:89], v[160:163], v[208:211], v[86:89]
	v_mfma_f32_16x16x32_bf16 v[82:85], v[168:171], v[208:211], v[82:85]
	v_mfma_f32_16x16x32_bf16 v[66:69], v[160:163], v[216:219], v[66:69]
	v_mfma_f32_16x16x32_bf16 v[62:65], v[168:171], v[216:219], v[62:65]
	s_setprio 0
	s_setprio 1
	v_mfma_f32_16x16x32_bf16 v[126:129], v[172:175], v[188:191], v[126:129]
	v_mfma_f32_16x16x32_bf16 v[122:125], v[180:183], v[188:191], v[122:125]
	v_mfma_f32_16x16x32_bf16 v[110:113], v[172:175], v[196:199], v[110:113]
	v_mfma_f32_16x16x32_bf16 v[106:109], v[180:183], v[196:199], v[106:109]
	v_mfma_f32_16x16x32_bf16 v[94:97], v[172:175], v[204:207], v[94:97]
	v_mfma_f32_16x16x32_bf16 v[90:93], v[180:183], v[204:207], v[90:93]
	v_mfma_f32_16x16x32_bf16 v[78:81], v[172:175], v[212:215], v[78:81]
	v_mfma_f32_16x16x32_bf16 v[74:77], v[180:183], v[212:215], v[74:77]
	v_mfma_f32_16x16x32_bf16 v[126:129], v[176:179], v[192:195], v[126:129]
	v_mfma_f32_16x16x32_bf16 v[122:125], v[184:187], v[192:195], v[122:125]
	v_mfma_f32_16x16x32_bf16 v[110:113], v[176:179], v[200:203], v[110:113]
	v_mfma_f32_16x16x32_bf16 v[106:109], v[184:187], v[200:203], v[106:109]
	v_mfma_f32_16x16x32_bf16 v[94:97], v[176:179], v[208:211], v[94:97]
	v_mfma_f32_16x16x32_bf16 v[90:93], v[184:187], v[208:211], v[90:93]
	v_mfma_f32_16x16x32_bf16 v[78:81], v[176:179], v[216:219], v[78:81]
	v_mfma_f32_16x16x32_bf16 v[74:77], v[184:187], v[216:219], v[74:77]
	s_setprio 0
	s_barrier
	s_mov_b32 m0, s46
	s_add_u32 s98, s98, 0x80
	s_addc_u32 s99, s99, 0
	s_add_u32 s100, s100, 0x80
	s_addc_u32 s101, s101, 0
	s_add_u32 s38, s38, 0x100080
	ds_read_b128 v[188:191], v152 offset:49152
	ds_read_b128 v[192:195], v152 offset:50176
	ds_read_b128 v[196:199], v152 offset:51200
	ds_read_b128 v[200:203], v152 offset:52224
	ds_read_b128 v[204:207], v152 offset:53248
	ds_read_b128 v[208:211], v152 offset:54272
	ds_read_b128 v[212:215], v152 offset:55296
	ds_read_b128 v[216:219], v152 offset:56320
	global_load_lds_dwordx4 v134, s[98:99]
	s_mov_b32 m0, s47
	s_addc_u32 s39, s39, 0
	global_load_lds_dwordx4 v130, s[98:99]
	s_mov_b32 m0, s56
	s_nop 0
	global_load_lds_dwordx4 v134, s[38:39]
	s_mov_b32 m0, s57
	s_nop 0
	global_load_lds_dwordx4 v130, s[38:39]
	s_mov_b32 m0, s50
	s_nop 0
	global_load_lds_dwordx4 v136, s[100:101]
	s_mov_b32 m0, s51
	s_nop 0
	global_load_lds_dwordx4 v132, s[100:101]
	s_waitcnt vmcnt(8)
	s_waitcnt lgkmcnt(0)
	s_barrier
	s_setprio 1
	v_mfma_f32_16x16x32_bf16 v[54:57], v[156:159], v[188:191], v[54:57]
	v_mfma_f32_16x16x32_bf16 v[50:53], v[164:167], v[188:191], v[50:53]
	v_mfma_f32_16x16x32_bf16 v[38:41], v[156:159], v[196:199], v[38:41]
	v_mfma_f32_16x16x32_bf16 v[34:37], v[164:167], v[196:199], v[34:37]
	v_mfma_f32_16x16x32_bf16 v[22:25], v[156:159], v[204:207], v[22:25]
	v_mfma_f32_16x16x32_bf16 v[18:21], v[164:167], v[204:207], v[18:21]
	v_mfma_f32_16x16x32_bf16 v[6:9], v[156:159], v[212:215], v[6:9]
	v_mfma_f32_16x16x32_bf16 v[2:5], v[164:167], v[212:215], v[2:5]
	v_mfma_f32_16x16x32_bf16 v[54:57], v[160:163], v[192:195], v[54:57]
	v_mfma_f32_16x16x32_bf16 v[50:53], v[168:171], v[192:195], v[50:53]
	v_mfma_f32_16x16x32_bf16 v[38:41], v[160:163], v[200:203], v[38:41]
	v_mfma_f32_16x16x32_bf16 v[34:37], v[168:171], v[200:203], v[34:37]
	v_mfma_f32_16x16x32_bf16 v[22:25], v[160:163], v[208:211], v[22:25]
	v_mfma_f32_16x16x32_bf16 v[18:21], v[168:171], v[208:211], v[18:21]
	v_mfma_f32_16x16x32_bf16 v[6:9], v[160:163], v[216:219], v[6:9]
	v_mfma_f32_16x16x32_bf16 v[2:5], v[168:171], v[216:219], v[2:5]
	s_setprio 0
	s_setprio 1
	v_mfma_f32_16x16x32_bf16 v[70:73], v[172:175], v[188:191], v[70:73]
	v_mfma_f32_16x16x32_bf16 v[58:61], v[180:183], v[188:191], v[58:61]
	v_mfma_f32_16x16x32_bf16 v[46:49], v[172:175], v[196:199], v[46:49]
	v_mfma_f32_16x16x32_bf16 v[42:45], v[180:183], v[196:199], v[42:45]
	v_mfma_f32_16x16x32_bf16 v[30:33], v[172:175], v[204:207], v[30:33]
	v_mfma_f32_16x16x32_bf16 v[26:29], v[180:183], v[204:207], v[26:29]
	v_mfma_f32_16x16x32_bf16 v[14:17], v[172:175], v[212:215], v[14:17]
	v_mfma_f32_16x16x32_bf16 v[10:13], v[180:183], v[212:215], v[10:13]
	v_mfma_f32_16x16x32_bf16 v[70:73], v[176:179], v[192:195], v[70:73]
	v_mfma_f32_16x16x32_bf16 v[58:61], v[184:187], v[192:195], v[58:61]
	v_mfma_f32_16x16x32_bf16 v[46:49], v[176:179], v[200:203], v[46:49]
	v_mfma_f32_16x16x32_bf16 v[42:45], v[184:187], v[200:203], v[42:45]
	v_mfma_f32_16x16x32_bf16 v[30:33], v[176:179], v[208:211], v[30:33]
	v_mfma_f32_16x16x32_bf16 v[26:29], v[184:187], v[208:211], v[26:29]
	v_mfma_f32_16x16x32_bf16 v[14:17], v[176:179], v[216:219], v[14:17]
	v_mfma_f32_16x16x32_bf16 v[10:13], v[184:187], v[216:219], v[10:13]
	s_setprio 0
	s_barrier
	s_add_i32 s68, s68, 2
	s_add_u32 s40, s40, 0x100
	s_addc_u32 s41, s41, 0
	s_add_u32 s26, s26, 0x100
	s_addc_u32 s27, s27, 0
	s_cmp_gt_u32 s68, 61
	s_cbranch_scc0 .LBB0_1345
	s_and_b64 vcc, exec, s[18:19]
	s_cbranch_vccz .LBB0_1348
	s_barrier

.LBB0_1424:
	ds_read_b128 v[2:5], v152
	ds_read_b128 v[6:9], v152 offset:1024
	ds_read_b128 v[10:13], v152 offset:2048
	ds_read_b128 v[14:17], v152 offset:3072
	ds_read_b128 v[18:21], v153
	ds_read_b128 v[22:25], v153 offset:1024
	ds_read_b128 v[26:29], v153 offset:2048
	ds_read_b128 v[30:33], v153 offset:3072
	s_add_u32 s22, s18, 0x2b0080
	s_addc_u32 s23, s19, 0
	s_add_i32 s49, s28, 0xc000
	v_lshl_add_u64 v[66:67], s[22:23], 0, v[130:131]
	s_mov_b32 m0, s49
	s_add_i32 s50, s28, 0xe000
	ds_read_b128 v[34:37], v154
	ds_read_b128 v[38:41], v154 offset:1024
	ds_read_b128 v[42:45], v154 offset:2048
	ds_read_b128 v[46:49], v154 offset:3072
	ds_read_b128 v[50:53], v154 offset:4096
	ds_read_b128 v[54:57], v154 offset:5120
	ds_read_b128 v[58:61], v154 offset:6144
	ds_read_b128 v[62:65], v154 offset:7168
	global_load_lds_dwordx4 v[66:67], off
	v_lshl_add_u64 v[66:67], s[22:23], 0, v[134:135]
	s_mov_b32 m0, s50
	s_nop 0
	global_load_lds_dwordx4 v[66:67], off
	s_waitcnt vmcnt(8)
	s_waitcnt lgkmcnt(0)
	s_barrier
	s_setprio 1
	v_mfma_f32_16x16x32_bf16 v[90:93], v[2:5], v[58:61], 0
	v_mfma_f32_16x16x32_bf16 v[66:69], v[2:5], v[34:37], 0
	v_mfma_f32_16x16x32_bf16 v[70:73], v[10:13], v[34:37], 0
	v_mfma_f32_16x16x32_bf16 v[74:77], v[2:5], v[42:45], 0
	v_mfma_f32_16x16x32_bf16 v[78:81], v[10:13], v[42:45], 0
	v_mfma_f32_16x16x32_bf16 v[82:85], v[2:5], v[50:53], 0
	v_mfma_f32_16x16x32_bf16 v[86:89], v[10:13], v[50:53], 0
	v_mfma_f32_16x16x32_bf16 v[98:101], v[6:9], v[62:65], v[90:93]
	v_mfma_f32_16x16x32_bf16 v[90:93], v[10:13], v[58:61], 0
	v_mfma_f32_16x16x32_bf16 v[66:69], v[6:9], v[38:41], v[66:69]
	v_mfma_f32_16x16x32_bf16 v[70:73], v[14:17], v[38:41], v[70:73]
	v_mfma_f32_16x16x32_bf16 v[74:77], v[6:9], v[46:49], v[74:77]
	v_mfma_f32_16x16x32_bf16 v[78:81], v[14:17], v[46:49], v[78:81]
	v_mfma_f32_16x16x32_bf16 v[82:85], v[6:9], v[54:57], v[82:85]
	v_mfma_f32_16x16x32_bf16 v[86:89], v[14:17], v[54:57], v[86:89]
	v_mfma_f32_16x16x32_bf16 v[102:105], v[14:17], v[62:65], v[90:93]
	s_setprio 0
	s_setprio 1
	v_mfma_f32_16x16x32_bf16 v[90:93], v[18:21], v[34:37], 0
	v_mfma_f32_16x16x32_bf16 v[34:37], v[26:29], v[34:37], 0
	v_mfma_f32_16x16x32_bf16 v[114:117], v[22:25], v[38:41], v[90:93]
	v_mfma_f32_16x16x32_bf16 v[34:37], v[30:33], v[38:41], v[34:37]
	v_mfma_f32_16x16x32_bf16 v[38:41], v[18:21], v[42:45], 0
	v_mfma_f32_16x16x32_bf16 v[42:45], v[26:29], v[42:45], 0
	v_mfma_f32_16x16x32_bf16 v[38:41], v[22:25], v[46:49], v[38:41]
	v_mfma_f32_16x16x32_bf16 v[42:45], v[30:33], v[46:49], v[42:45]
	v_mfma_f32_16x16x32_bf16 v[46:49], v[18:21], v[50:53], 0
	v_mfma_f32_16x16x32_bf16 v[50:53], v[26:29], v[50:53], 0
	v_mfma_f32_16x16x32_bf16 v[46:49], v[22:25], v[54:57], v[46:49]
	v_mfma_f32_16x16x32_bf16 v[50:53], v[30:33], v[54:57], v[50:53]
	v_mfma_f32_16x16x32_bf16 v[54:57], v[18:21], v[58:61], 0
	v_mfma_f32_16x16x32_bf16 v[58:61], v[26:29], v[58:61], 0
	v_mfma_f32_16x16x32_bf16 v[54:57], v[22:25], v[62:65], v[54:57]
	v_mfma_f32_16x16x32_bf16 v[58:61], v[30:33], v[62:65], v[58:61]
	s_setprio 0
	s_barrier
	s_add_i32 s51, s39, s25
	v_lshl_add_u64 v[248:249], s[20:21], 0, v[132:133]
	s_add_i32 s52, s51, 0x2000
	v_lshl_add_u64 v[146:147], v[248:249], 0, s[12:13]
	s_mov_b32 m0, s51
	v_lshl_add_u64 v[250:251], s[20:21], 0, v[136:137]
	s_add_u32 s22, s20, 0x2b0100
	ds_read_b128 v[62:65], v154 offset:16384
	ds_read_b128 v[90:93], v154 offset:17408
	ds_read_b128 v[94:97], v154 offset:18432
	ds_read_b128 v[106:109], v154 offset:19456
	ds_read_b128 v[110:113], v154 offset:20480
	ds_read_b128 v[118:121], v154 offset:21504
	ds_read_b128 v[122:125], v154 offset:22528
	ds_read_b128 v[126:129], v154 offset:23552
	global_load_lds_dwordx4 v[146:147], off
	v_lshl_add_u64 v[146:147], v[250:251], 0, s[12:13]
	s_mov_b32 m0, s52
	s_addc_u32 s23, s21, 0
	s_add_i32 s46, s40, s25
	global_load_lds_dwordx4 v[146:147], off
	v_lshl_add_u64 v[146:147], s[22:23], 0, v[132:133]
	s_mov_b32 m0, s46
	s_add_i32 s47, s46, 0x2000
	global_load_lds_dwordx4 v[146:147], off
	v_lshl_add_u64 v[146:147], s[22:23], 0, v[136:137]
	s_mov_b32 m0, s47
	v_lshl_add_u64 v[252:253], s[18:19], 0, v[130:131]
	global_load_lds_dwordx4 v[146:147], off
	v_lshl_add_u64 v[146:147], v[252:253], 0, s[12:13]
	s_mov_b32 m0, s28
	v_lshl_add_u64 v[142:143], s[18:19], 0, v[134:135]
	global_load_lds_dwordx4 v[146:147], off
	v_lshl_add_u64 v[146:147], v[142:143], 0, s[12:13]
	s_mov_b32 m0, s29
	s_nop 0
	global_load_lds_dwordx4 v[146:147], off
	s_waitcnt vmcnt(8)
	s_waitcnt lgkmcnt(0)
	s_barrier
	s_setprio 1
	v_mfma_f32_16x16x32_bf16 v[146:149], v[2:5], v[62:65], 0
	v_mfma_f32_16x16x32_bf16 v[160:163], v[2:5], v[94:97], 0
	v_mfma_f32_16x16x32_bf16 v[168:171], v[2:5], v[110:113], 0
	v_mfma_f32_16x16x32_bf16 v[2:5], v[2:5], v[122:125], 0
	v_mfma_f32_16x16x32_bf16 v[148:151], v[6:9], v[90:93], v[146:149]
	v_mfma_f32_16x16x32_bf16 v[160:163], v[6:9], v[106:109], v[160:163]
	v_mfma_f32_16x16x32_bf16 v[168:171], v[6:9], v[118:121], v[168:171]
	v_mfma_f32_16x16x32_bf16 v[2:5], v[6:9], v[126:129], v[2:5]
	v_mfma_f32_16x16x32_bf16 v[6:9], v[10:13], v[122:125], 0
	v_mfma_f32_16x16x32_bf16 v[156:159], v[10:13], v[62:65], 0
	v_mfma_f32_16x16x32_bf16 v[164:167], v[10:13], v[94:97], 0
	v_mfma_f32_16x16x32_bf16 v[172:175], v[10:13], v[110:113], 0
	v_mfma_f32_16x16x32_bf16 v[6:9], v[14:17], v[126:129], v[6:9]
	v_mfma_f32_16x16x32_bf16 v[156:159], v[14:17], v[90:93], v[156:159]
	v_mfma_f32_16x16x32_bf16 v[164:167], v[14:17], v[106:109], v[164:167]
	v_mfma_f32_16x16x32_bf16 v[172:175], v[14:17], v[118:121], v[172:175]
	s_setprio 0
	s_setprio 1
	v_mfma_f32_16x16x32_bf16 v[10:13], v[18:21], v[62:65], 0
	v_mfma_f32_16x16x32_bf16 v[176:179], v[22:25], v[90:93], v[10:13]
	v_mfma_f32_16x16x32_bf16 v[10:13], v[26:29], v[62:65], 0
	v_mfma_f32_16x16x32_bf16 v[180:183], v[30:33], v[90:93], v[10:13]
	v_mfma_f32_16x16x32_bf16 v[10:13], v[18:21], v[94:97], 0
	v_mfma_f32_16x16x32_bf16 v[184:187], v[22:25], v[106:109], v[10:13]
	v_mfma_f32_16x16x32_bf16 v[10:13], v[26:29], v[94:97], 0
	v_mfma_f32_16x16x32_bf16 v[188:191], v[30:33], v[106:109], v[10:13]
	v_mfma_f32_16x16x32_bf16 v[10:13], v[18:21], v[110:113], 0
	v_mfma_f32_16x16x32_bf16 v[192:195], v[22:25], v[118:121], v[10:13]
	v_mfma_f32_16x16x32_bf16 v[10:13], v[26:29], v[110:113], 0
	v_mfma_f32_16x16x32_bf16 v[196:199], v[30:33], v[118:121], v[10:13]
	v_mfma_f32_16x16x32_bf16 v[10:13], v[18:21], v[122:125], 0
	v_mfma_f32_16x16x32_bf16 v[200:203], v[22:25], v[126:129], v[10:13]
	v_mfma_f32_16x16x32_bf16 v[10:13], v[26:29], v[122:125], 0
	v_mfma_f32_16x16x32_bf16 v[204:207], v[30:33], v[126:129], v[10:13]
	s_setprio 0
	s_barrier
	s_add_i32 s53, 0, 0x18000
	s_add_i32 s55, 0, 0x1c000
	v_add_u32_e32 v146, s53, v1
	v_add_u32_e32 v147, s55, v1
	s_nop 0
	ds_read_b128 v[10:13], v146
	ds_read_b128 v[14:17], v146 offset:1024
	ds_read_b128 v[18:21], v146 offset:2048
	ds_read_b128 v[22:25], v146 offset:3072
	ds_read_b128 v[208:211], v147
	ds_read_b128 v[212:215], v147 offset:1024
	ds_read_b128 v[216:219], v147 offset:2048
	ds_read_b128 v[220:223], v147 offset:3072
	s_add_u32 s22, s18, 0x2b0100
	s_addc_u32 s23, s19, 0
	s_mov_b32 m0, s30
	v_lshl_add_u64 v[90:91], s[22:23], 0, v[130:131]
	ds_read_b128 v[26:29], v154 offset:32768
	ds_read_b128 v[30:33], v154 offset:33792
	ds_read_b128 v[62:65], v154 offset:34816
	ds_read_b128 v[224:227], v154 offset:35840
	ds_read_b128 v[228:231], v154 offset:36864
	ds_read_b128 v[232:235], v154 offset:37888
	ds_read_b128 v[236:239], v154 offset:38912
	ds_read_b128 v[240:243], v154 offset:39936
	global_load_lds_dwordx4 v[90:91], off
	v_lshl_add_u64 v[90:91], s[22:23], 0, v[134:135]
	s_mov_b32 m0, s31
	s_nop 0
	global_load_lds_dwordx4 v[90:91], off
	s_waitcnt vmcnt(8)
	s_waitcnt lgkmcnt(0)
	s_barrier
	s_setprio 1
	v_mfma_f32_16x16x32_bf16 v[66:69], v[10:13], v[26:29], v[66:69]
	v_mfma_f32_16x16x32_bf16 v[126:129], v[14:17], v[30:33], v[66:69]
	v_mfma_f32_16x16x32_bf16 v[66:69], v[18:21], v[26:29], v[70:73]
	v_mfma_f32_16x16x32_bf16 v[122:125], v[22:25], v[30:33], v[66:69]
	v_mfma_f32_16x16x32_bf16 v[66:69], v[10:13], v[62:65], v[74:77]
	v_mfma_f32_16x16x32_bf16 v[110:113], v[14:17], v[224:227], v[66:69]
	v_mfma_f32_16x16x32_bf16 v[66:69], v[18:21], v[62:65], v[78:81]
	v_mfma_f32_16x16x32_bf16 v[106:109], v[22:25], v[224:227], v[66:69]
	v_mfma_f32_16x16x32_bf16 v[66:69], v[10:13], v[228:231], v[82:85]
	v_mfma_f32_16x16x32_bf16 v[94:97], v[14:17], v[232:235], v[66:69]
	v_mfma_f32_16x16x32_bf16 v[66:69], v[18:21], v[228:231], v[86:89]
	v_mfma_f32_16x16x32_bf16 v[90:93], v[22:25], v[232:235], v[66:69]
	v_mfma_f32_16x16x32_bf16 v[66:69], v[10:13], v[236:239], v[98:101]
	v_mfma_f32_16x16x32_bf16 v[78:81], v[14:17], v[240:243], v[66:69]
	v_mfma_f32_16x16x32_bf16 v[66:69], v[18:21], v[236:239], v[102:105]
	v_mfma_f32_16x16x32_bf16 v[74:77], v[22:25], v[240:243], v[66:69]
	s_setprio 0
	s_setprio 1
	v_mfma_f32_16x16x32_bf16 v[66:69], v[208:211], v[26:29], v[114:117]
	v_mfma_f32_16x16x32_bf16 v[26:29], v[216:219], v[26:29], v[34:37]
	v_mfma_f32_16x16x32_bf16 v[114:117], v[220:223], v[30:33], v[26:29]
	v_mfma_f32_16x16x32_bf16 v[26:29], v[208:211], v[62:65], v[38:41]
	v_mfma_f32_16x16x32_bf16 v[102:105], v[212:215], v[224:227], v[26:29]
	v_mfma_f32_16x16x32_bf16 v[26:29], v[216:219], v[62:65], v[42:45]
	v_mfma_f32_16x16x32_bf16 v[98:101], v[220:223], v[224:227], v[26:29]
	v_mfma_f32_16x16x32_bf16 v[26:29], v[208:211], v[228:231], v[46:49]
	v_mfma_f32_16x16x32_bf16 v[86:89], v[212:215], v[232:235], v[26:29]
	v_mfma_f32_16x16x32_bf16 v[26:29], v[216:219], v[228:231], v[50:53]
	v_mfma_f32_16x16x32_bf16 v[82:85], v[220:223], v[232:235], v[26:29]
	v_mfma_f32_16x16x32_bf16 v[26:29], v[208:211], v[236:239], v[54:57]
	v_mfma_f32_16x16x32_bf16 v[70:73], v[212:215], v[240:243], v[26:29]
	v_mfma_f32_16x16x32_bf16 v[26:29], v[216:219], v[236:239], v[58:61]
	v_mfma_f32_16x16x32_bf16 v[118:121], v[212:215], v[30:33], v[66:69]
	v_mfma_f32_16x16x32_bf16 v[66:69], v[220:223], v[240:243], v[26:29]
	s_setprio 0
	s_barrier
	s_add_i32 s53, s53, s25
	s_add_i32 s54, s53, 0x2000
	s_nop 1
	v_lshl_add_u64 v[26:27], v[248:249], 0, s[14:15]
	s_mov_b32 m0, s53
	s_add_u32 s22, s20, 0x2b0180
	ds_read_b128 v[34:37], v154 offset:49152
	ds_read_b128 v[38:41], v154 offset:50176
	ds_read_b128 v[224:227], v154 offset:51200
	ds_read_b128 v[228:231], v154 offset:52224
	ds_read_b128 v[232:235], v154 offset:53248
	ds_read_b128 v[236:239], v154 offset:54272
	ds_read_b128 v[240:243], v154 offset:55296
	ds_read_b128 v[244:247], v154 offset:56320
	global_load_lds_dwordx4 v[26:27], off
	v_lshl_add_u64 v[26:27], v[250:251], 0, s[14:15]
	s_mov_b32 m0, s54
	s_addc_u32 s23, s21, 0
	s_add_i32 s55, s55, s25
	global_load_lds_dwordx4 v[26:27], off
	v_lshl_add_u64 v[26:27], s[22:23], 0, v[132:133]
	s_mov_b32 m0, s55
	s_add_i32 s56, s55, 0x2000
	global_load_lds_dwordx4 v[26:27], off
	v_lshl_add_u64 v[26:27], s[22:23], 0, v[136:137]
	s_mov_b32 m0, s56
	s_nop 0
	global_load_lds_dwordx4 v[26:27], off
	v_lshl_add_u64 v[26:27], v[252:253], 0, s[14:15]
	s_mov_b32 m0, s34
	s_nop 0
	global_load_lds_dwordx4 v[26:27], off
	v_lshl_add_u64 v[26:27], v[142:143], 0, s[14:15]
	s_mov_b32 m0, s35
	s_nop 0
	global_load_lds_dwordx4 v[26:27], off
	s_waitcnt vmcnt(8)
	s_waitcnt lgkmcnt(0)
	s_barrier
	s_setprio 1
	v_mfma_f32_16x16x32_bf16 v[26:29], v[10:13], v[34:37], v[148:151]
	v_mfma_f32_16x16x32_bf16 v[62:65], v[14:17], v[38:41], v[26:29]
	v_mfma_f32_16x16x32_bf16 v[26:29], v[18:21], v[34:37], v[156:159]
	v_mfma_f32_16x16x32_bf16 v[58:61], v[22:25], v[38:41], v[26:29]
	v_mfma_f32_16x16x32_bf16 v[26:29], v[10:13], v[224:227], v[160:163]
	v_mfma_f32_16x16x32_bf16 v[46:49], v[14:17], v[228:231], v[26:29]
	v_mfma_f32_16x16x32_bf16 v[26:29], v[18:21], v[224:227], v[164:167]
	v_mfma_f32_16x16x32_bf16 v[42:45], v[22:25], v[228:231], v[26:29]
	v_mfma_f32_16x16x32_bf16 v[26:29], v[10:13], v[232:235], v[168:171]
	v_mfma_f32_16x16x32_bf16 v[2:5], v[10:13], v[240:243], v[2:5]
	v_mfma_f32_16x16x32_bf16 v[30:33], v[14:17], v[236:239], v[26:29]
	v_mfma_f32_16x16x32_bf16 v[26:29], v[18:21], v[232:235], v[172:175]
	v_mfma_f32_16x16x32_bf16 v[14:17], v[14:17], v[244:247], v[2:5]
	v_mfma_f32_16x16x32_bf16 v[2:5], v[18:21], v[240:243], v[6:9]
	v_mfma_f32_16x16x32_bf16 v[26:29], v[22:25], v[236:239], v[26:29]
	v_mfma_f32_16x16x32_bf16 v[10:13], v[22:25], v[244:247], v[2:5]
	s_setprio 0
	s_setprio 1
	v_mfma_f32_16x16x32_bf16 v[2:5], v[208:211], v[34:37], v[176:179]
	v_mfma_f32_16x16x32_bf16 v[54:57], v[212:215], v[38:41], v[2:5]
	v_mfma_f32_16x16x32_bf16 v[2:5], v[216:219], v[34:37], v[180:183]
	v_mfma_f32_16x16x32_bf16 v[50:53], v[220:223], v[38:41], v[2:5]
	v_mfma_f32_16x16x32_bf16 v[2:5], v[208:211], v[224:227], v[184:187]
	v_mfma_f32_16x16x32_bf16 v[38:41], v[212:215], v[228:231], v[2:5]
	v_mfma_f32_16x16x32_bf16 v[2:5], v[216:219], v[224:227], v[188:191]
	v_mfma_f32_16x16x32_bf16 v[34:37], v[220:223], v[228:231], v[2:5]
	v_mfma_f32_16x16x32_bf16 v[2:5], v[208:211], v[232:235], v[192:195]
	v_mfma_f32_16x16x32_bf16 v[22:25], v[212:215], v[236:239], v[2:5]
	v_mfma_f32_16x16x32_bf16 v[2:5], v[216:219], v[232:235], v[196:199]
	v_mfma_f32_16x16x32_bf16 v[18:21], v[220:223], v[236:239], v[2:5]
	v_mfma_f32_16x16x32_bf16 v[2:5], v[208:211], v[240:243], v[200:203]
	v_mfma_f32_16x16x32_bf16 v[6:9], v[212:215], v[244:247], v[2:5]
	v_mfma_f32_16x16x32_bf16 v[2:5], v[216:219], v[240:243], v[204:207]
	v_mfma_f32_16x16x32_bf16 v[2:5], v[220:223], v[244:247], v[2:5]
	s_setprio 0
	s_barrier
	s_add_u32 s26, s20, 0x200
	s_addc_u32 s27, s21, 0
	s_mov_b32 s57, 0
.LBB0_1425:
	ds_read_b128 v[148:151], v152
	ds_read_b128 v[156:159], v152 offset:1024
	ds_read_b128 v[160:163], v152 offset:2048
	ds_read_b128 v[164:167], v152 offset:3072
	ds_read_b128 v[168:171], v153
	ds_read_b128 v[172:175], v153 offset:1024
	ds_read_b128 v[176:179], v153 offset:2048
	ds_read_b128 v[180:183], v153 offset:3072
	s_add_u32 s20, s18, 0x200
	s_addc_u32 s21, s19, 0
	s_cmpk_eq_i32 s57, 0xa8
	s_cselect_b32 s23, s5, s21
	s_cselect_b32 s22, s4, s20
	s_cselect_b32 s21, s17, s27
	s_cselect_b32 s20, s16, s26
	s_mov_b32 m0, s49
	ds_read_b128 v[184:187], v154
	ds_read_b128 v[188:191], v154 offset:1024
	ds_read_b128 v[192:195], v154 offset:2048
	ds_read_b128 v[196:199], v154 offset:3072
	ds_read_b128 v[200:203], v154 offset:4096
	ds_read_b128 v[204:207], v154 offset:5120
	ds_read_b128 v[208:211], v154 offset:6144
	ds_read_b128 v[212:215], v154 offset:7168
	global_load_lds_dwordx4 v138, s[18:19]
	s_mov_b32 m0, s50
	s_nop 0
	global_load_lds_dwordx4 v140, s[18:19]
	s_waitcnt vmcnt(8)
	s_waitcnt lgkmcnt(0)
	s_barrier
	s_setprio 1
	v_mfma_f32_16x16x32_bf16 v[126:129], v[148:151], v[184:187], v[126:129]
	v_mfma_f32_16x16x32_bf16 v[122:125], v[160:163], v[184:187], v[122:125]
	v_mfma_f32_16x16x32_bf16 v[110:113], v[148:151], v[192:195], v[110:113]
	v_mfma_f32_16x16x32_bf16 v[106:109], v[160:163], v[192:195], v[106:109]
	v_mfma_f32_16x16x32_bf16 v[94:97], v[148:151], v[200:203], v[94:97]
	v_mfma_f32_16x16x32_bf16 v[90:93], v[160:163], v[200:203], v[90:93]
	v_mfma_f32_16x16x32_bf16 v[78:81], v[148:151], v[208:211], v[78:81]
	v_mfma_f32_16x16x32_bf16 v[74:77], v[160:163], v[208:211], v[74:77]
	v_mfma_f32_16x16x32_bf16 v[126:129], v[156:159], v[188:191], v[126:129]
	v_mfma_f32_16x16x32_bf16 v[122:125], v[164:167], v[188:191], v[122:125]
	v_mfma_f32_16x16x32_bf16 v[110:113], v[156:159], v[196:199], v[110:113]
	v_mfma_f32_16x16x32_bf16 v[106:109], v[164:167], v[196:199], v[106:109]
	v_mfma_f32_16x16x32_bf16 v[94:97], v[156:159], v[204:207], v[94:97]
	v_mfma_f32_16x16x32_bf16 v[90:93], v[164:167], v[204:207], v[90:93]
	v_mfma_f32_16x16x32_bf16 v[78:81], v[156:159], v[212:215], v[78:81]
	v_mfma_f32_16x16x32_bf16 v[74:77], v[164:167], v[212:215], v[74:77]
	s_setprio 0
	s_setprio 1
	v_mfma_f32_16x16x32_bf16 v[118:121], v[168:171], v[184:187], v[118:121]
	v_mfma_f32_16x16x32_bf16 v[114:117], v[176:179], v[184:187], v[114:117]
	v_mfma_f32_16x16x32_bf16 v[102:105], v[168:171], v[192:195], v[102:105]
	v_mfma_f32_16x16x32_bf16 v[98:101], v[176:179], v[192:195], v[98:101]
	v_mfma_f32_16x16x32_bf16 v[86:89], v[168:171], v[200:203], v[86:89]
	v_mfma_f32_16x16x32_bf16 v[82:85], v[176:179], v[200:203], v[82:85]
	v_mfma_f32_16x16x32_bf16 v[70:73], v[168:171], v[208:211], v[70:73]
	v_mfma_f32_16x16x32_bf16 v[66:69], v[176:179], v[208:211], v[66:69]
	v_mfma_f32_16x16x32_bf16 v[118:121], v[172:175], v[188:191], v[118:121]
	v_mfma_f32_16x16x32_bf16 v[114:117], v[180:183], v[188:191], v[114:117]
	v_mfma_f32_16x16x32_bf16 v[102:105], v[172:175], v[196:199], v[102:105]
	v_mfma_f32_16x16x32_bf16 v[98:101], v[180:183], v[196:199], v[98:101]
	v_mfma_f32_16x16x32_bf16 v[86:89], v[172:175], v[204:207], v[86:89]
	v_mfma_f32_16x16x32_bf16 v[82:85], v[180:183], v[204:207], v[82:85]
	v_mfma_f32_16x16x32_bf16 v[70:73], v[172:175], v[212:215], v[70:73]
	v_mfma_f32_16x16x32_bf16 v[66:69], v[180:183], v[212:215], v[66:69]
	s_setprio 0
	s_barrier
	s_mov_b32 m0, s51
	s_mov_b64 s[98:99], s[20:21]
	s_add_u32 s58, s20, 0x2b0000
	ds_read_b128 v[184:187], v154 offset:16384
	ds_read_b128 v[188:191], v154 offset:17408
	ds_read_b128 v[192:195], v154 offset:18432
	ds_read_b128 v[196:199], v154 offset:19456
	ds_read_b128 v[200:203], v154 offset:20480
	ds_read_b128 v[204:207], v154 offset:21504
	ds_read_b128 v[208:211], v154 offset:22528
	ds_read_b128 v[212:215], v154 offset:23552
	global_load_lds_dwordx4 v132, s[20:21]
	s_mov_b32 m0, s52
	s_addc_u32 s59, s21, 0
	global_load_lds_dwordx4 v136, s[20:21]
	s_mov_b32 m0, s46
	s_mov_b64 s[100:101], s[22:23]
	global_load_lds_dwordx4 v132, s[58:59]
	s_mov_b32 m0, s47
	s_nop 0
	global_load_lds_dwordx4 v136, s[58:59]
	s_mov_b32 m0, s28
	s_nop 0
	global_load_lds_dwordx4 v130, s[22:23]
	s_mov_b32 m0, s29
	s_nop 0
	global_load_lds_dwordx4 v134, s[22:23]
	s_waitcnt vmcnt(8)
	s_waitcnt lgkmcnt(0)
	s_barrier
	s_setprio 1
	v_mfma_f32_16x16x32_bf16 v[62:65], v[148:151], v[184:187], v[62:65]
	v_mfma_f32_16x16x32_bf16 v[58:61], v[160:163], v[184:187], v[58:61]
	v_mfma_f32_16x16x32_bf16 v[46:49], v[148:151], v[192:195], v[46:49]
	v_mfma_f32_16x16x32_bf16 v[42:45], v[160:163], v[192:195], v[42:45]
	v_mfma_f32_16x16x32_bf16 v[30:33], v[148:151], v[200:203], v[30:33]
	v_mfma_f32_16x16x32_bf16 v[26:29], v[160:163], v[200:203], v[26:29]
	v_mfma_f32_16x16x32_bf16 v[14:17], v[148:151], v[208:211], v[14:17]
	v_mfma_f32_16x16x32_bf16 v[10:13], v[160:163], v[208:211], v[10:13]
	v_mfma_f32_16x16x32_bf16 v[62:65], v[156:159], v[188:191], v[62:65]
	v_mfma_f32_16x16x32_bf16 v[58:61], v[164:167], v[188:191], v[58:61]
	v_mfma_f32_16x16x32_bf16 v[46:49], v[156:159], v[196:199], v[46:49]
	v_mfma_f32_16x16x32_bf16 v[42:45], v[164:167], v[196:199], v[42:45]
	v_mfma_f32_16x16x32_bf16 v[30:33], v[156:159], v[204:207], v[30:33]
	v_mfma_f32_16x16x32_bf16 v[26:29], v[164:167], v[204:207], v[26:29]
	v_mfma_f32_16x16x32_bf16 v[14:17], v[156:159], v[212:215], v[14:17]
	v_mfma_f32_16x16x32_bf16 v[10:13], v[164:167], v[212:215], v[10:13]
	s_setprio 0
	s_setprio 1
	v_mfma_f32_16x16x32_bf16 v[54:57], v[168:171], v[184:187], v[54:57]
	v_mfma_f32_16x16x32_bf16 v[50:53], v[176:179], v[184:187], v[50:53]
	v_mfma_f32_16x16x32_bf16 v[38:41], v[168:171], v[192:195], v[38:41]
	v_mfma_f32_16x16x32_bf16 v[34:37], v[176:179], v[192:195], v[34:37]
	v_mfma_f32_16x16x32_bf16 v[22:25], v[168:171], v[200:203], v[22:25]
	v_mfma_f32_16x16x32_bf16 v[18:21], v[176:179], v[200:203], v[18:21]
	v_mfma_f32_16x16x32_bf16 v[6:9], v[168:171], v[208:211], v[6:9]
	v_mfma_f32_16x16x32_bf16 v[2:5], v[176:179], v[208:211], v[2:5]
	v_mfma_f32_16x16x32_bf16 v[54:57], v[172:175], v[188:191], v[54:57]
	v_mfma_f32_16x16x32_bf16 v[50:53], v[180:183], v[188:191], v[50:53]
	v_mfma_f32_16x16x32_bf16 v[38:41], v[172:175], v[196:199], v[38:41]
	v_mfma_f32_16x16x32_bf16 v[34:37], v[180:183], v[196:199], v[34:37]
	v_mfma_f32_16x16x32_bf16 v[22:25], v[172:175], v[204:207], v[22:25]
	v_mfma_f32_16x16x32_bf16 v[18:21], v[180:183], v[204:207], v[18:21]
	v_mfma_f32_16x16x32_bf16 v[6:9], v[172:175], v[212:215], v[6:9]
	v_mfma_f32_16x16x32_bf16 v[2:5], v[180:183], v[212:215], v[2:5]
	s_setprio 0
	s_barrier
	ds_read_b128 v[148:151], v146
	ds_read_b128 v[156:159], v146 offset:1024
	ds_read_b128 v[160:163], v146 offset:2048
	ds_read_b128 v[164:167], v146 offset:3072
	ds_read_b128 v[168:171], v147
	ds_read_b128 v[172:175], v147 offset:1024
	ds_read_b128 v[176:179], v147 offset:2048
	ds_read_b128 v[180:183], v147 offset:3072
	s_add_u32 s22, s22, 0x2b0000
	s_addc_u32 s23, s23, 0
	s_mov_b32 m0, s30
	ds_read_b128 v[184:187], v154 offset:32768
	ds_read_b128 v[188:191], v154 offset:33792
	ds_read_b128 v[192:195], v154 offset:34816
	ds_read_b128 v[196:199], v154 offset:35840
	ds_read_b128 v[200:203], v154 offset:36864
	ds_read_b128 v[204:207], v154 offset:37888
	ds_read_b128 v[208:211], v154 offset:38912
	ds_read_b128 v[212:215], v154 offset:39936
	global_load_lds_dwordx4 v130, s[22:23]
	s_mov_b32 m0, s31
	s_nop 0
	global_load_lds_dwordx4 v134, s[22:23]
	s_waitcnt vmcnt(8)
	s_waitcnt lgkmcnt(0)
	s_barrier
	s_setprio 1
	v_mfma_f32_16x16x32_bf16 v[126:129], v[148:151], v[184:187], v[126:129]
	v_mfma_f32_16x16x32_bf16 v[122:125], v[160:163], v[184:187], v[122:125]
	v_mfma_f32_16x16x32_bf16 v[110:113], v[148:151], v[192:195], v[110:113]
	v_mfma_f32_16x16x32_bf16 v[106:109], v[160:163], v[192:195], v[106:109]
	v_mfma_f32_16x16x32_bf16 v[94:97], v[148:151], v[200:203], v[94:97]
	v_mfma_f32_16x16x32_bf16 v[90:93], v[160:163], v[200:203], v[90:93]
	v_mfma_f32_16x16x32_bf16 v[78:81], v[148:151], v[208:211], v[78:81]
	v_mfma_f32_16x16x32_bf16 v[74:77], v[160:163], v[208:211], v[74:77]
	v_mfma_f32_16x16x32_bf16 v[126:129], v[156:159], v[188:191], v[126:129]
	v_mfma_f32_16x16x32_bf16 v[122:125], v[164:167], v[188:191], v[122:125]
	v_mfma_f32_16x16x32_bf16 v[110:113], v[156:159], v[196:199], v[110:113]
	v_mfma_f32_16x16x32_bf16 v[106:109], v[164:167], v[196:199], v[106:109]
	v_mfma_f32_16x16x32_bf16 v[94:97], v[156:159], v[204:207], v[94:97]
	v_mfma_f32_16x16x32_bf16 v[90:93], v[164:167], v[204:207], v[90:93]
	v_mfma_f32_16x16x32_bf16 v[78:81], v[156:159], v[212:215], v[78:81]
	v_mfma_f32_16x16x32_bf16 v[74:77], v[164:167], v[212:215], v[74:77]
	s_setprio 0
	s_setprio 1
	v_mfma_f32_16x16x32_bf16 v[118:121], v[168:171], v[184:187], v[118:121]
	v_mfma_f32_16x16x32_bf16 v[114:117], v[176:179], v[184:187], v[114:117]
	v_mfma_f32_16x16x32_bf16 v[102:105], v[168:171], v[192:195], v[102:105]
	v_mfma_f32_16x16x32_bf16 v[98:101], v[176:179], v[192:195], v[98:101]
	v_mfma_f32_16x16x32_bf16 v[86:89], v[168:171], v[200:203], v[86:89]
	v_mfma_f32_16x16x32_bf16 v[82:85], v[176:179], v[200:203], v[82:85]
	v_mfma_f32_16x16x32_bf16 v[70:73], v[168:171], v[208:211], v[70:73]
	v_mfma_f32_16x16x32_bf16 v[66:69], v[176:179], v[208:211], v[66:69]
	v_mfma_f32_16x16x32_bf16 v[118:121], v[172:175], v[188:191], v[118:121]
	v_mfma_f32_16x16x32_bf16 v[114:117], v[180:183], v[188:191], v[114:117]
	v_mfma_f32_16x16x32_bf16 v[102:105], v[172:175], v[196:199], v[102:105]
	v_mfma_f32_16x16x32_bf16 v[98:101], v[180:183], v[196:199], v[98:101]
	v_mfma_f32_16x16x32_bf16 v[86:89], v[172:175], v[204:207], v[86:89]
	v_mfma_f32_16x16x32_bf16 v[82:85], v[180:183], v[204:207], v[82:85]
	v_mfma_f32_16x16x32_bf16 v[70:73], v[172:175], v[212:215], v[70:73]
	v_mfma_f32_16x16x32_bf16 v[66:69], v[180:183], v[212:215], v[66:69]
	s_setprio 0
	s_barrier
	s_mov_b32 m0, s53
	s_add_u32 s98, s98, 0x80
	s_addc_u32 s99, s99, 0
	s_add_u32 s100, s100, 0x80
	s_addc_u32 s101, s101, 0
	s_add_u32 s20, s20, 0x2b0080
	ds_read_b128 v[184:187], v154 offset:49152
	ds_read_b128 v[188:191], v154 offset:50176
	ds_read_b128 v[192:195], v154 offset:51200
	ds_read_b128 v[196:199], v154 offset:52224
	ds_read_b128 v[200:203], v154 offset:53248
	ds_read_b128 v[204:207], v154 offset:54272
	ds_read_b128 v[208:211], v154 offset:55296
	ds_read_b128 v[212:215], v154 offset:56320
	global_load_lds_dwordx4 v132, s[98:99]
	s_mov_b32 m0, s54
	s_addc_u32 s21, s21, 0
	global_load_lds_dwordx4 v136, s[98:99]
	s_mov_b32 m0, s55
	s_nop 0
	global_load_lds_dwordx4 v132, s[20:21]
	s_mov_b32 m0, s56
	s_nop 0
	global_load_lds_dwordx4 v136, s[20:21]
	s_mov_b32 m0, s34
	s_nop 0
	global_load_lds_dwordx4 v130, s[100:101]
	s_mov_b32 m0, s35
	s_nop 0
	global_load_lds_dwordx4 v134, s[100:101]
	s_waitcnt vmcnt(8)
	s_waitcnt lgkmcnt(0)
	s_barrier
	s_setprio 1
	v_mfma_f32_16x16x32_bf16 v[62:65], v[148:151], v[184:187], v[62:65]
	v_mfma_f32_16x16x32_bf16 v[58:61], v[160:163], v[184:187], v[58:61]
	v_mfma_f32_16x16x32_bf16 v[46:49], v[148:151], v[192:195], v[46:49]
	v_mfma_f32_16x16x32_bf16 v[42:45], v[160:163], v[192:195], v[42:45]
	v_mfma_f32_16x16x32_bf16 v[30:33], v[148:151], v[200:203], v[30:33]
	v_mfma_f32_16x16x32_bf16 v[26:29], v[160:163], v[200:203], v[26:29]
	v_mfma_f32_16x16x32_bf16 v[14:17], v[148:151], v[208:211], v[14:17]
	v_mfma_f32_16x16x32_bf16 v[10:13], v[160:163], v[208:211], v[10:13]
	v_mfma_f32_16x16x32_bf16 v[62:65], v[156:159], v[188:191], v[62:65]
	v_mfma_f32_16x16x32_bf16 v[58:61], v[164:167], v[188:191], v[58:61]
	v_mfma_f32_16x16x32_bf16 v[46:49], v[156:159], v[196:199], v[46:49]
	v_mfma_f32_16x16x32_bf16 v[42:45], v[164:167], v[196:199], v[42:45]
	v_mfma_f32_16x16x32_bf16 v[30:33], v[156:159], v[204:207], v[30:33]
	v_mfma_f32_16x16x32_bf16 v[26:29], v[164:167], v[204:207], v[26:29]
	v_mfma_f32_16x16x32_bf16 v[14:17], v[156:159], v[212:215], v[14:17]
	v_mfma_f32_16x16x32_bf16 v[10:13], v[164:167], v[212:215], v[10:13]
	s_setprio 0
	s_setprio 1
	v_mfma_f32_16x16x32_bf16 v[54:57], v[168:171], v[184:187], v[54:57]
	v_mfma_f32_16x16x32_bf16 v[50:53], v[176:179], v[184:187], v[50:53]
	v_mfma_f32_16x16x32_bf16 v[38:41], v[168:171], v[192:195], v[38:41]
	v_mfma_f32_16x16x32_bf16 v[34:37], v[176:179], v[192:195], v[34:37]
	v_mfma_f32_16x16x32_bf16 v[22:25], v[168:171], v[200:203], v[22:25]
	v_mfma_f32_16x16x32_bf16 v[18:21], v[176:179], v[200:203], v[18:21]
	v_mfma_f32_16x16x32_bf16 v[6:9], v[168:171], v[208:211], v[6:9]
	v_mfma_f32_16x16x32_bf16 v[2:5], v[176:179], v[208:211], v[2:5]
	v_mfma_f32_16x16x32_bf16 v[54:57], v[172:175], v[188:191], v[54:57]
	v_mfma_f32_16x16x32_bf16 v[50:53], v[180:183], v[188:191], v[50:53]
	v_mfma_f32_16x16x32_bf16 v[38:41], v[172:175], v[196:199], v[38:41]
	v_mfma_f32_16x16x32_bf16 v[34:37], v[180:183], v[196:199], v[34:37]
	v_mfma_f32_16x16x32_bf16 v[22:25], v[172:175], v[204:207], v[22:25]
	v_mfma_f32_16x16x32_bf16 v[18:21], v[180:183], v[204:207], v[18:21]
	v_mfma_f32_16x16x32_bf16 v[6:9], v[172:175], v[212:215], v[6:9]
	v_mfma_f32_16x16x32_bf16 v[2:5], v[180:183], v[212:215], v[2:5]
	s_setprio 0
	s_barrier
	s_add_i32 s57, s57, 2
	s_add_u32 s18, s18, 0x100
	s_addc_u32 s19, s19, 0
	s_add_u32 s26, s26, 0x100
	s_addc_u32 s27, s27, 0
	s_cmpk_gt_u32 s57, 0xa9
	s_cbranch_scc0 .LBB0_1425
	s_and_b64 vcc, exec, s[10:11]
	s_cbranch_vccz .LBB0_1428
	s_barrier
